# K-loops: removed the redundant s_setprio 0 / s_setprio 1 pair between the two 16-MFMA blocks of each MFMA segment (56 pairs), loop exits padded to keep 64B phase
# speedup vs baseline: 1.0046x; 1.0022x over previous
; #define PG8_STAGE(bufoff, gbase, voff) do { _Pragma("unroll") for (int _i = 0; _i < 2; ++_i) \
;         __builtin_amdgcn_global_load_lds((const unsigned*)((const char*)(gbase) + (voff)[_i]), (PG8_LAS unsigned*)(lds + (bufoff) + ldsw + _i * 8192), 16, 0, 0); } while (0)
; #define PG8_LDA(dst, b, h) do { _Pragma("unroll") for (int m = 0; m < 4; ++m) _Pragma("unroll") for (int k = 0; k < 2; ++k) dst[m][k] = *(const PG8_LAS bf16x8*)(lds + PG8_SA(b, h) + aoff + m * 2048 + k * 1024); } while (0)
; #define PG8_LDB(dst, b, h) do { _Pragma("unroll") for (int n = 0; n < 2; ++n) _Pragma("unroll") for (int k = 0; k < 2; ++k) dst[n][k] = *(const PG8_LAS bf16x8*)(lds + PG8_SB(b, h) + boff + n * 2048 + k * 1024); } while (0)
; #define PG8_MMA(ai, bj, At, Bt) do { __builtin_amdgcn_s_setprio(1); _Pragma("unroll") for (int m = 0; m < 4; ++m) _Pragma("unroll") for (int n = 0; n < 2; ++n) _Pragma("unroll") for (int k = 0; k < 2; ++k) \
;         acc[ai][bj][m][n] = __builtin_amdgcn_mfma_f32_16x16x32_bf16(Bt[n][k], At[m][k], acc[ai][bj][m][n], 0, 0, 0); __builtin_amdgcn_s_setprio(0); } while (0)
; #define PG8_WAIT_V(n) asm volatile("s_waitcnt vmcnt(" #n ")" ::: "memory")
; #define PG8_WAIT_L(n) asm volatile("s_waitcnt lgkmcnt(" #n ")" ::: "memory")
; #define PG8_BAR __builtin_amdgcn_s_barrier()
; #define PG8_SCHED __builtin_amdgcn_sched_barrier(0)
; template <class Epi, class Sched, bool ALIGN_EPI = false, bool SP2 = false>
; __device__ __forceinline__ void gemm_phase(PG8_LAS unsigned char* lds, const Gemm g, const Sched& S, const Epi& E, int wave0) {
;     ...
;             PG8_LDB(B0, 0, 0); PG8_LDB(B1, 0, 1); PG8_SCHED; PG8_LDA(At, 0, 0); PG8_STAGE(PG8_SA(1, 1), a1 + hstep, voffA);
;             PG8_WAIT_V(8); PG8_WAIT_L(0); PG8_BAR; PG8_MMA(0, 0, At, B0); PG8_MMA(0, 1, At, B1); PG8_BAR; PG8_SCHED;
;             PG8_LDA(At, 0, 1); PG8_STAGE(PG8_SB(0, 0), b2, voffB); PG8_STAGE(PG8_SB(0, 1), b2 + hstep, voffB); PG8_STAGE(PG8_SA(0, 0), a2, voffA);
;             PG8_WAIT_V(8); PG8_WAIT_L(0); PG8_BAR; if (!cur.half) { PG8_MMA(1, 0, At, B0); PG8_MMA(1, 1, At, B1); } PG8_BAR; PG8_SCHED;
.LBB0_94:
	ds_read_b128 v[144:147], v169
	ds_read_b128 v[148:151], v169 offset:1024
	ds_read_b128 v[152:155], v169 offset:2048
	ds_read_b128 v[156:159], v169 offset:3072
	ds_read_b128 v[160:163], v170
	ds_read_b128 v[174:177], v170 offset:1024
	ds_read_b128 v[178:181], v170 offset:2048
	ds_read_b128 v[182:185], v170 offset:3072
	s_add_u32 s14, s52, 0xfffc0080
	s_addc_u32 s15, s53, -1
	s_cmp_eq_u32 s68, 12
	s_cselect_b32 s63, s3, s15
	s_cselect_b32 s62, s7, s14
	s_cselect_b32 s57, s43, vcc_hi
	s_cselect_b32 s56, s45, vcc_lo
	v_lshl_add_u64 v[164:165], s[52:53], 0, v[136:137]
	s_add_i32 m0, s19, 0xc000
	ds_read_b128 v[186:189], v171
	ds_read_b128 v[190:193], v171 offset:1024
	ds_read_b128 v[194:197], v171 offset:2048
	ds_read_b128 v[198:201], v171 offset:3072
	ds_read_b128 v[202:205], v171 offset:4096
	ds_read_b128 v[206:209], v171 offset:5120
	ds_read_b128 v[210:213], v171 offset:6144
	ds_read_b128 v[218:221], v171 offset:7168
	global_load_lds_dwordx4 v[164:165], off
	v_lshl_add_u64 v[164:165], s[52:53], 0, v[138:139]
	s_add_i32 m0, s19, 0xe000
	s_nop 0
	global_load_lds_dwordx4 v[164:165], off
	s_waitcnt vmcnt(8)
	s_waitcnt lgkmcnt(0)
	s_barrier
	s_setprio 1
	s_waitcnt lgkmcnt(0)
	v_mfma_f32_16x16x32_bf16 v[124:127], v[144:147], v[186:189], v[124:127]
	v_mfma_f32_16x16x32_bf16 v[120:123], v[152:155], v[186:189], v[120:123]
	v_mfma_f32_16x16x32_bf16 v[108:111], v[144:147], v[194:197], v[108:111]
	v_mfma_f32_16x16x32_bf16 v[104:107], v[152:155], v[194:197], v[104:107]
	v_mfma_f32_16x16x32_bf16 v[92:95], v[144:147], v[202:205], v[92:95]
	v_mfma_f32_16x16x32_bf16 v[88:91], v[152:155], v[202:205], v[88:91]
	v_mfma_f32_16x16x32_bf16 v[76:79], v[144:147], v[210:213], v[76:79]
	v_mfma_f32_16x16x32_bf16 v[72:75], v[152:155], v[210:213], v[72:75]
	v_mfma_f32_16x16x32_bf16 v[124:127], v[148:151], v[190:193], v[124:127]
	v_mfma_f32_16x16x32_bf16 v[120:123], v[156:159], v[190:193], v[120:123]
	v_mfma_f32_16x16x32_bf16 v[108:111], v[148:151], v[198:201], v[108:111]
	v_mfma_f32_16x16x32_bf16 v[104:107], v[156:159], v[198:201], v[104:107]
	v_mfma_f32_16x16x32_bf16 v[92:95], v[148:151], v[206:209], v[92:95]
	v_mfma_f32_16x16x32_bf16 v[88:91], v[156:159], v[206:209], v[88:91]
	v_mfma_f32_16x16x32_bf16 v[76:79], v[148:151], v[218:221], v[76:79]
	v_mfma_f32_16x16x32_bf16 v[72:75], v[156:159], v[218:221], v[72:75]
	v_mfma_f32_16x16x32_bf16 v[116:119], v[160:163], v[186:189], v[116:119]
	v_mfma_f32_16x16x32_bf16 v[112:115], v[178:181], v[186:189], v[112:115]
	v_mfma_f32_16x16x32_bf16 v[100:103], v[160:163], v[194:197], v[100:103]
	v_mfma_f32_16x16x32_bf16 v[96:99], v[178:181], v[194:197], v[96:99]
	v_mfma_f32_16x16x32_bf16 v[84:87], v[160:163], v[202:205], v[84:87]
	v_mfma_f32_16x16x32_bf16 v[80:83], v[178:181], v[202:205], v[80:83]
	v_mfma_f32_16x16x32_bf16 v[68:71], v[160:163], v[210:213], v[68:71]
	v_mfma_f32_16x16x32_bf16 v[64:67], v[178:181], v[210:213], v[64:67]
	v_mfma_f32_16x16x32_bf16 v[116:119], v[174:177], v[190:193], v[116:119]
	v_mfma_f32_16x16x32_bf16 v[112:115], v[182:185], v[190:193], v[112:115]
	v_mfma_f32_16x16x32_bf16 v[100:103], v[174:177], v[198:201], v[100:103]
	v_mfma_f32_16x16x32_bf16 v[96:99], v[182:185], v[198:201], v[96:99]
	v_mfma_f32_16x16x32_bf16 v[84:87], v[174:177], v[206:209], v[84:87]
	v_mfma_f32_16x16x32_bf16 v[80:83], v[182:185], v[206:209], v[80:83]
	v_mfma_f32_16x16x32_bf16 v[68:71], v[174:177], v[218:221], v[68:71]
	v_mfma_f32_16x16x32_bf16 v[64:67], v[182:185], v[218:221], v[64:67]
	s_setprio 0
	s_barrier
	s_add_i32 s14, s85, s17
	v_lshl_add_u64 v[164:165], s[56:57], 0, v[130:131]
	s_mov_b32 m0, s14
	ds_read_b128 v[186:189], v171 offset:16384
	ds_read_b128 v[190:193], v171 offset:17408
	ds_read_b128 v[194:197], v171 offset:18432
	ds_read_b128 v[198:201], v171 offset:19456
	ds_read_b128 v[202:205], v171 offset:20480
	ds_read_b128 v[206:209], v171 offset:21504
	ds_read_b128 v[210:213], v171 offset:22528
	ds_read_b128 v[218:221], v171 offset:23552
	global_load_lds_dwordx4 v[164:165], off
	s_add_i32 m0, s14, 0x2000
	s_add_u32 s14, s56, 0x40000
	v_lshl_add_u64 v[214:215], s[56:57], 0, v[134:135]
	s_addc_u32 s15, s57, 0
	s_add_i32 s69, s86, s17
	global_load_lds_dwordx4 v[214:215], off
	v_lshl_add_u64 v[222:223], s[14:15], 0, v[130:131]
	s_mov_b32 m0, s69
	v_lshl_add_u64 v[224:225], s[62:63], 0, v[132:133]
	global_load_lds_dwordx4 v[222:223], off
	v_lshl_add_u64 v[222:223], s[14:15], 0, v[134:135]
	s_add_i32 m0, s69, 0x2000
	s_nop 0
	global_load_lds_dwordx4 v[222:223], off
	v_lshl_add_u64 v[222:223], s[62:63], 0, v[128:129]
	s_mov_b32 m0, s19
	s_nop 0
	global_load_lds_dwordx4 v[222:223], off
	s_mov_b32 m0, s21
	s_nop 0
	global_load_lds_dwordx4 v[224:225], off
	s_waitcnt vmcnt(8)
	s_waitcnt lgkmcnt(0)
	s_barrier
; #define PG8_STAGE(bufoff, gbase, voff) do { _Pragma("unroll") for (int _i = 0; _i < 2; ++_i) \
;         __builtin_amdgcn_global_load_lds((const unsigned*)((const char*)(gbase) + (voff)[_i]), (PG8_LAS unsigned*)(lds + (bufoff) + ldsw + _i * 8192), 16, 0, 0); } while (0)
; #define PG8_LDA(dst, b, h) do { _Pragma("unroll") for (int m = 0; m < 4; ++m) _Pragma("unroll") for (int k = 0; k < 2; ++k) dst[m][k] = *(const PG8_LAS bf16x8*)(lds + PG8_SA(b, h) + aoff + m * 2048 + k * 1024); } while (0)
; #define PG8_LDB(dst, b, h) do { _Pragma("unroll") for (int n = 0; n < 2; ++n) _Pragma("unroll") for (int k = 0; k < 2; ++k) dst[n][k] = *(const PG8_LAS bf16x8*)(lds + PG8_SB(b, h) + boff + n * 2048 + k * 1024); } while (0)
; #define PG8_MMA(ai, bj, At, Bt) do { __builtin_amdgcn_s_setprio(1); _Pragma("unroll") for (int m = 0; m < 4; ++m) _Pragma("unroll") for (int n = 0; n < 2; ++n) _Pragma("unroll") for (int k = 0; k < 2; ++k) \
;         acc[ai][bj][m][n] = __builtin_amdgcn_mfma_f32_16x16x32_bf16(Bt[n][k], At[m][k], acc[ai][bj][m][n], 0, 0, 0); __builtin_amdgcn_s_setprio(0); } while (0)
; #define PG8_WAIT_V(n) asm volatile("s_waitcnt vmcnt(" #n ")" ::: "memory")
; #define PG8_WAIT_L(n) asm volatile("s_waitcnt lgkmcnt(" #n ")" ::: "memory")
; #define PG8_BAR __builtin_amdgcn_s_barrier()
; #define PG8_SCHED __builtin_amdgcn_sched_barrier(0)
; template <class Epi, class Sched, bool ALIGN_EPI = false, bool SP2 = false>
; __device__ __forceinline__ void gemm_phase(PG8_LAS unsigned char* lds, const Gemm g, const Sched& S, const Epi& E, int wave0) {
;     ...
;             PG8_WAIT_V(8); PG8_WAIT_L(0); PG8_BAR; if (!cur.half) { PG8_MMA(1, 0, At, B0); PG8_MMA(1, 1, At, B1); } PG8_BAR; PG8_SCHED;
;             PG8_LDB(B0, 1, 0); PG8_LDB(B1, 1, 1); PG8_SCHED; PG8_LDA(At, 1, 0); PG8_STAGE(PG8_SA(0, 1), a2 + hstep, voffA);
;             PG8_WAIT_V(8); PG8_WAIT_L(0); PG8_BAR; PG8_MMA(0, 0, At, B0); PG8_MMA(0, 1, At, B1); PG8_BAR; PG8_SCHED;
	s_setprio 1
	s_waitcnt lgkmcnt(0)
	v_mfma_f32_16x16x32_bf16 v[60:63], v[144:147], v[186:189], v[60:63]
	v_mfma_f32_16x16x32_bf16 v[56:59], v[152:155], v[186:189], v[56:59]
	v_mfma_f32_16x16x32_bf16 v[44:47], v[144:147], v[194:197], v[44:47]
	v_mfma_f32_16x16x32_bf16 v[40:43], v[152:155], v[194:197], v[40:43]
	v_mfma_f32_16x16x32_bf16 v[28:31], v[144:147], v[202:205], v[28:31]
	v_mfma_f32_16x16x32_bf16 v[24:27], v[152:155], v[202:205], v[24:27]
	v_mfma_f32_16x16x32_bf16 v[12:15], v[144:147], v[210:213], v[12:15]
	v_mfma_f32_16x16x32_bf16 v[8:11], v[152:155], v[210:213], v[8:11]
	v_mfma_f32_16x16x32_bf16 v[60:63], v[148:151], v[190:193], v[60:63]
	v_mfma_f32_16x16x32_bf16 v[56:59], v[156:159], v[190:193], v[56:59]
	v_mfma_f32_16x16x32_bf16 v[44:47], v[148:151], v[198:201], v[44:47]
	v_mfma_f32_16x16x32_bf16 v[40:43], v[156:159], v[198:201], v[40:43]
	v_mfma_f32_16x16x32_bf16 v[28:31], v[148:151], v[206:209], v[28:31]
	v_mfma_f32_16x16x32_bf16 v[24:27], v[156:159], v[206:209], v[24:27]
	v_mfma_f32_16x16x32_bf16 v[12:15], v[148:151], v[218:221], v[12:15]
	v_mfma_f32_16x16x32_bf16 v[8:11], v[156:159], v[218:221], v[8:11]
	v_mfma_f32_16x16x32_bf16 v[52:55], v[160:163], v[186:189], v[52:55]
	v_mfma_f32_16x16x32_bf16 v[48:51], v[178:181], v[186:189], v[48:51]
	v_mfma_f32_16x16x32_bf16 v[36:39], v[160:163], v[194:197], v[36:39]
	v_mfma_f32_16x16x32_bf16 v[32:35], v[178:181], v[194:197], v[32:35]
	v_mfma_f32_16x16x32_bf16 v[20:23], v[160:163], v[202:205], v[20:23]
	v_mfma_f32_16x16x32_bf16 v[16:19], v[178:181], v[202:205], v[16:19]
	v_mfma_f32_16x16x32_bf16 v[4:7], v[160:163], v[210:213], v[4:7]
	v_mfma_f32_16x16x32_bf16 v[0:3], v[178:181], v[210:213], v[0:3]
	v_mfma_f32_16x16x32_bf16 v[52:55], v[174:177], v[190:193], v[52:55]
	v_mfma_f32_16x16x32_bf16 v[48:51], v[182:185], v[190:193], v[48:51]
	v_mfma_f32_16x16x32_bf16 v[36:39], v[174:177], v[198:201], v[36:39]
	v_mfma_f32_16x16x32_bf16 v[32:35], v[182:185], v[198:201], v[32:35]
	v_mfma_f32_16x16x32_bf16 v[20:23], v[174:177], v[206:209], v[20:23]
	v_mfma_f32_16x16x32_bf16 v[16:19], v[182:185], v[206:209], v[16:19]
	v_mfma_f32_16x16x32_bf16 v[4:7], v[174:177], v[218:221], v[4:7]
	v_mfma_f32_16x16x32_bf16 v[0:3], v[182:185], v[218:221], v[0:3]
	s_setprio 0
	s_barrier
	s_add_i32 s69, 0, 0x18000
	s_add_i32 s35, 0, 0x1c000
	v_add_u32_e32 v156, s69, v168
	v_add_u32_e32 v182, s35, v168
	ds_read_b128 v[144:147], v156
	ds_read_b128 v[148:151], v156 offset:1024
	ds_read_b128 v[152:155], v156 offset:2048
	ds_read_b128 v[156:159], v156 offset:3072
	ds_read_b128 v[160:163], v182
	ds_read_b128 v[174:177], v182 offset:1024
	ds_read_b128 v[178:181], v182 offset:2048
	ds_read_b128 v[182:185], v182 offset:3072
	s_add_u32 s14, s62, 0x40000
	s_addc_u32 s15, s63, 0
	s_mov_b32 m0, s29
	v_lshl_add_u64 v[226:227], s[14:15], 0, v[128:129]
	ds_read_b128 v[186:189], v171 offset:32768
	ds_read_b128 v[190:193], v171 offset:33792
	ds_read_b128 v[194:197], v171 offset:34816
	ds_read_b128 v[198:201], v171 offset:35840
	ds_read_b128 v[202:205], v171 offset:36864
	ds_read_b128 v[206:209], v171 offset:37888
	ds_read_b128 v[210:213], v171 offset:38912
	ds_read_b128 v[218:221], v171 offset:39936
	global_load_lds_dwordx4 v[226:227], off
	v_lshl_add_u64 v[226:227], s[14:15], 0, v[132:133]
	s_mov_b32 m0, s31
	s_nop 0
	global_load_lds_dwordx4 v[226:227], off
	s_waitcnt vmcnt(8)
	s_waitcnt lgkmcnt(0)
	s_barrier
	s_setprio 1
	s_waitcnt lgkmcnt(0)
	v_mfma_f32_16x16x32_bf16 v[124:127], v[144:147], v[186:189], v[124:127]
	v_mfma_f32_16x16x32_bf16 v[120:123], v[152:155], v[186:189], v[120:123]
	v_mfma_f32_16x16x32_bf16 v[108:111], v[144:147], v[194:197], v[108:111]
	v_mfma_f32_16x16x32_bf16 v[104:107], v[152:155], v[194:197], v[104:107]
	v_mfma_f32_16x16x32_bf16 v[92:95], v[144:147], v[202:205], v[92:95]
	v_mfma_f32_16x16x32_bf16 v[88:91], v[152:155], v[202:205], v[88:91]
	v_mfma_f32_16x16x32_bf16 v[76:79], v[144:147], v[210:213], v[76:79]
	v_mfma_f32_16x16x32_bf16 v[72:75], v[152:155], v[210:213], v[72:75]
	v_mfma_f32_16x16x32_bf16 v[124:127], v[148:151], v[190:193], v[124:127]
	v_mfma_f32_16x16x32_bf16 v[120:123], v[156:159], v[190:193], v[120:123]
	v_mfma_f32_16x16x32_bf16 v[108:111], v[148:151], v[198:201], v[108:111]
	v_mfma_f32_16x16x32_bf16 v[104:107], v[156:159], v[198:201], v[104:107]
	v_mfma_f32_16x16x32_bf16 v[92:95], v[148:151], v[206:209], v[92:95]
	v_mfma_f32_16x16x32_bf16 v[88:91], v[156:159], v[206:209], v[88:91]
	v_mfma_f32_16x16x32_bf16 v[76:79], v[148:151], v[218:221], v[76:79]
	v_mfma_f32_16x16x32_bf16 v[72:75], v[156:159], v[218:221], v[72:75]
	v_mfma_f32_16x16x32_bf16 v[116:119], v[160:163], v[186:189], v[116:119]
	v_mfma_f32_16x16x32_bf16 v[112:115], v[178:181], v[186:189], v[112:115]
	v_mfma_f32_16x16x32_bf16 v[100:103], v[160:163], v[194:197], v[100:103]
	v_mfma_f32_16x16x32_bf16 v[96:99], v[178:181], v[194:197], v[96:99]
	v_mfma_f32_16x16x32_bf16 v[84:87], v[160:163], v[202:205], v[84:87]
	v_mfma_f32_16x16x32_bf16 v[80:83], v[178:181], v[202:205], v[80:83]
	v_mfma_f32_16x16x32_bf16 v[68:71], v[160:163], v[210:213], v[68:71]
	v_mfma_f32_16x16x32_bf16 v[64:67], v[178:181], v[210:213], v[64:67]
	v_mfma_f32_16x16x32_bf16 v[116:119], v[174:177], v[190:193], v[116:119]
	v_mfma_f32_16x16x32_bf16 v[112:115], v[182:185], v[190:193], v[112:115]
	v_mfma_f32_16x16x32_bf16 v[100:103], v[174:177], v[198:201], v[100:103]
	v_mfma_f32_16x16x32_bf16 v[96:99], v[182:185], v[198:201], v[96:99]
	v_mfma_f32_16x16x32_bf16 v[84:87], v[174:177], v[206:209], v[84:87]
	v_mfma_f32_16x16x32_bf16 v[80:83], v[182:185], v[206:209], v[80:83]
	v_mfma_f32_16x16x32_bf16 v[68:71], v[174:177], v[218:221], v[68:71]
	v_mfma_f32_16x16x32_bf16 v[64:67], v[182:185], v[218:221], v[64:67]
	s_setprio 0
	s_barrier
; #define PG8_STAGE(bufoff, gbase, voff) do { _Pragma("unroll") for (int _i = 0; _i < 2; ++_i) \
;         __builtin_amdgcn_global_load_lds((const unsigned*)((const char*)(gbase) + (voff)[_i]), (PG8_LAS unsigned*)(lds + (bufoff) + ldsw + _i * 8192), 16, 0, 0); } while (0)
; #define PG8_LDA(dst, b, h) do { _Pragma("unroll") for (int m = 0; m < 4; ++m) _Pragma("unroll") for (int k = 0; k < 2; ++k) dst[m][k] = *(const PG8_LAS bf16x8*)(lds + PG8_SA(b, h) + aoff + m * 2048 + k * 1024); } while (0)
; #define PG8_MMA(ai, bj, At, Bt) do { __builtin_amdgcn_s_setprio(1); _Pragma("unroll") for (int m = 0; m < 4; ++m) _Pragma("unroll") for (int n = 0; n < 2; ++n) _Pragma("unroll") for (int k = 0; k < 2; ++k) \
;         acc[ai][bj][m][n] = __builtin_amdgcn_mfma_f32_16x16x32_bf16(Bt[n][k], At[m][k], acc[ai][bj][m][n], 0, 0, 0); __builtin_amdgcn_s_setprio(0); } while (0)
; #define PG8_WAIT_V(n) asm volatile("s_waitcnt vmcnt(" #n ")" ::: "memory")
; #define PG8_WAIT_L(n) asm volatile("s_waitcnt lgkmcnt(" #n ")" ::: "memory")
; #define PG8_BAR __builtin_amdgcn_s_barrier()
; #define PG8_SCHED __builtin_amdgcn_sched_barrier(0)
; template <class Epi, class Sched, bool ALIGN_EPI = false, bool SP2 = false>
; __device__ __forceinline__ void gemm_phase(PG8_LAS unsigned char* lds, const Gemm g, const Sched& S, const Epi& E, int wave0) {
;     ...
;         for (int t = 0; t < nt; t += 2) {
;             const bool last = (t == nt - 2);
;             const char* a1 = cA + (size_t)(t + 1) * kstep;
;             const char* a2 = last ? nA : cA + (size_t)(t + 2) * kstep; const char* b2 = last ? nB : cB + (size_t)(t + 2) * kstep;
;     ...
;             PG8_LDA(At, 1, 1); PG8_STAGE(PG8_SB(1, 0), b3, voffB); PG8_STAGE(PG8_SB(1, 1), b3 + hstep, voffB); PG8_STAGE(PG8_SA(1, 0), a3, voffA);
;             PG8_WAIT_V(8); PG8_WAIT_L(0); PG8_BAR; if (!cur.half) { PG8_MMA(1, 0, At, B0); PG8_MMA(1, 1, At, B1); } PG8_BAR; PG8_SCHED;
	s_add_i32 s14, s69, s17
	v_lshl_add_u64 v[164:165], v[164:165], 0, s[10:11]
	s_mov_b32 m0, s14
	ds_read_b128 v[186:189], v171 offset:49152
	ds_read_b128 v[190:193], v171 offset:50176
	ds_read_b128 v[194:197], v171 offset:51200
	ds_read_b128 v[198:201], v171 offset:52224
	ds_read_b128 v[202:205], v171 offset:53248
	ds_read_b128 v[206:209], v171 offset:54272
	ds_read_b128 v[210:213], v171 offset:55296
	ds_read_b128 v[218:221], v171 offset:56320
	global_load_lds_dwordx4 v[164:165], off
	s_add_i32 m0, s14, 0x2000
	s_add_u32 s14, s56, 0x40080
	v_lshl_add_u64 v[164:165], v[214:215], 0, s[10:11]
	s_addc_u32 s15, s57, 0
	s_add_i32 s35, s35, s17
	global_load_lds_dwordx4 v[164:165], off
	v_lshl_add_u64 v[164:165], s[14:15], 0, v[130:131]
	s_mov_b32 m0, s35
	s_nop 0
	global_load_lds_dwordx4 v[164:165], off
	v_lshl_add_u64 v[164:165], s[14:15], 0, v[134:135]
	s_add_i32 m0, s35, 0x2000
	s_nop 0
	global_load_lds_dwordx4 v[164:165], off
	v_lshl_add_u64 v[164:165], v[222:223], 0, s[10:11]
	s_mov_b32 m0, s39
	s_nop 0
	global_load_lds_dwordx4 v[164:165], off
	v_lshl_add_u64 v[164:165], v[224:225], 0, s[10:11]
	s_mov_b32 m0, s41
	s_nop 0
	global_load_lds_dwordx4 v[164:165], off
	s_waitcnt vmcnt(8)
	s_waitcnt lgkmcnt(0)
	s_barrier
	s_setprio 1
	s_waitcnt lgkmcnt(0)
	v_mfma_f32_16x16x32_bf16 v[60:63], v[144:147], v[186:189], v[60:63]
	v_mfma_f32_16x16x32_bf16 v[56:59], v[152:155], v[186:189], v[56:59]
	v_mfma_f32_16x16x32_bf16 v[44:47], v[144:147], v[194:197], v[44:47]
	v_mfma_f32_16x16x32_bf16 v[40:43], v[152:155], v[194:197], v[40:43]
	v_mfma_f32_16x16x32_bf16 v[28:31], v[144:147], v[202:205], v[28:31]
	v_mfma_f32_16x16x32_bf16 v[24:27], v[152:155], v[202:205], v[24:27]
	v_mfma_f32_16x16x32_bf16 v[12:15], v[144:147], v[210:213], v[12:15]
	v_mfma_f32_16x16x32_bf16 v[8:11], v[152:155], v[210:213], v[8:11]
	v_mfma_f32_16x16x32_bf16 v[60:63], v[148:151], v[190:193], v[60:63]
	v_mfma_f32_16x16x32_bf16 v[56:59], v[156:159], v[190:193], v[56:59]
	v_mfma_f32_16x16x32_bf16 v[44:47], v[148:151], v[198:201], v[44:47]
	v_mfma_f32_16x16x32_bf16 v[40:43], v[156:159], v[198:201], v[40:43]
	v_mfma_f32_16x16x32_bf16 v[28:31], v[148:151], v[206:209], v[28:31]
	v_mfma_f32_16x16x32_bf16 v[24:27], v[156:159], v[206:209], v[24:27]
	v_mfma_f32_16x16x32_bf16 v[12:15], v[148:151], v[218:221], v[12:15]
	v_mfma_f32_16x16x32_bf16 v[8:11], v[156:159], v[218:221], v[8:11]
	v_mfma_f32_16x16x32_bf16 v[52:55], v[160:163], v[186:189], v[52:55]
	v_mfma_f32_16x16x32_bf16 v[48:51], v[178:181], v[186:189], v[48:51]
	v_mfma_f32_16x16x32_bf16 v[36:39], v[160:163], v[194:197], v[36:39]
	v_mfma_f32_16x16x32_bf16 v[32:35], v[178:181], v[194:197], v[32:35]
	v_mfma_f32_16x16x32_bf16 v[20:23], v[160:163], v[202:205], v[20:23]
	v_mfma_f32_16x16x32_bf16 v[16:19], v[178:181], v[202:205], v[16:19]
	v_mfma_f32_16x16x32_bf16 v[4:7], v[160:163], v[210:213], v[4:7]
	v_mfma_f32_16x16x32_bf16 v[0:3], v[178:181], v[210:213], v[0:3]
	v_mfma_f32_16x16x32_bf16 v[52:55], v[174:177], v[190:193], v[52:55]
	v_mfma_f32_16x16x32_bf16 v[48:51], v[182:185], v[190:193], v[48:51]
	v_mfma_f32_16x16x32_bf16 v[36:39], v[174:177], v[198:201], v[36:39]
	v_mfma_f32_16x16x32_bf16 v[32:35], v[182:185], v[198:201], v[32:35]
	v_mfma_f32_16x16x32_bf16 v[20:23], v[174:177], v[206:209], v[20:23]
	v_mfma_f32_16x16x32_bf16 v[16:19], v[182:185], v[206:209], v[16:19]
	v_mfma_f32_16x16x32_bf16 v[4:7], v[174:177], v[218:221], v[4:7]
	v_mfma_f32_16x16x32_bf16 v[0:3], v[182:185], v[218:221], v[0:3]
	s_setprio 0
	s_barrier
	s_add_i32 s68, s68, 2
	s_add_u32 s52, s52, 0x100
	s_addc_u32 s53, s53, 0
	s_add_u32 vcc_lo, vcc_lo, 0x100
	s_addc_u32 vcc_hi, vcc_hi, 0
	s_cmp_gt_u32 s68, 13
	s_cbranch_scc0 .LBB0_94
	s_nop 0
	s_nop 0
	s_nop 0
	s_nop 0
	s_nop 0
	s_nop 0
	s_nop 0
	s_nop 0
	s_and_b64 vcc, exec, s[64:65]
	s_cbranch_vccz .LBB0_97
	s_barrier

; #define PG8_STAGE(bufoff, gbase, voff) do { _Pragma("unroll") for (int _i = 0; _i < 2; ++_i) \
;         __builtin_amdgcn_global_load_lds((const unsigned*)((const char*)(gbase) + (voff)[_i]), (PG8_LAS unsigned*)(lds + (bufoff) + ldsw + _i * 8192), 16, 0, 0); } while (0)
; #define PG8_LDA(dst, b, h) do { _Pragma("unroll") for (int m = 0; m < 4; ++m) _Pragma("unroll") for (int k = 0; k < 2; ++k) dst[m][k] = *(const PG8_LAS bf16x8*)(lds + PG8_SA(b, h) + aoff + m * 2048 + k * 1024); } while (0)
; #define PG8_LDB(dst, b, h) do { _Pragma("unroll") for (int n = 0; n < 2; ++n) _Pragma("unroll") for (int k = 0; k < 2; ++k) dst[n][k] = *(const PG8_LAS bf16x8*)(lds + PG8_SB(b, h) + boff + n * 2048 + k * 1024); } while (0)
; #define PG8_MMA(ai, bj, At, Bt) do { __builtin_amdgcn_s_setprio(1); _Pragma("unroll") for (int m = 0; m < 4; ++m) _Pragma("unroll") for (int n = 0; n < 2; ++n) _Pragma("unroll") for (int k = 0; k < 2; ++k) \
;         acc[ai][bj][m][n] = __builtin_amdgcn_mfma_f32_16x16x32_bf16(Bt[n][k], At[m][k], acc[ai][bj][m][n], 0, 0, 0); __builtin_amdgcn_s_setprio(0); } while (0)
; #define PG8_WAIT_V(n) asm volatile("s_waitcnt vmcnt(" #n ")" ::: "memory")
; #define PG8_WAIT_L(n) asm volatile("s_waitcnt lgkmcnt(" #n ")" ::: "memory")
; #define PG8_BAR __builtin_amdgcn_s_barrier()
; #define PG8_SCHED __builtin_amdgcn_sched_barrier(0)
; template <class Epi, class Sched, bool ALIGN_EPI = false, bool SP2 = false>
; __device__ __forceinline__ void gemm_phase(PG8_LAS unsigned char* lds, const Gemm g, const Sched& S, const Epi& E, int wave0) {
;     ...
;             PG8_LDB(B0, 0, 0); PG8_LDB(B1, 0, 1); PG8_SCHED; PG8_LDA(At, 0, 0); PG8_STAGE(PG8_SA(1, 1), a1 + hstep, voffA);
;             PG8_WAIT_V(8); PG8_WAIT_L(0); PG8_BAR; PG8_MMA(0, 0, At, B0); PG8_MMA(0, 1, At, B1); PG8_BAR; PG8_SCHED;
;             PG8_LDA(At, 0, 1); PG8_STAGE(PG8_SB(0, 0), b2, voffB); PG8_STAGE(PG8_SB(0, 1), b2 + hstep, voffB); PG8_STAGE(PG8_SA(0, 0), a2, voffA);
;             PG8_WAIT_V(8); PG8_WAIT_L(0); PG8_BAR; if (!cur.half) { PG8_MMA(1, 0, At, B0); PG8_MMA(1, 1, At, B1); } PG8_BAR; PG8_SCHED;
.LBB0_363:
	ds_read_b128 v[128:131], v165
	ds_read_b128 v[132:135], v165 offset:1024
	ds_read_b128 v[152:155], v165 offset:2048
	ds_read_b128 v[156:159], v165 offset:3072
	ds_read_b128 v[170:173], v166
	ds_read_b128 v[174:177], v166 offset:1024
	ds_read_b128 v[178:181], v166 offset:2048
	ds_read_b128 v[182:185], v166 offset:3072
	s_add_u32 s30, s28, 0xfffc0080
	s_addc_u32 s31, s29, -1
	s_cmp_eq_u32 s53, 12
	s_cselect_b32 s35, s1, s31
	s_cselect_b32 s34, s17, s30
	s_cselect_b32 s31, s15, s52
	s_cselect_b32 s30, s50, s51
	v_lshl_add_u64 v[160:161], s[28:29], 0, v[144:145]
	s_add_i32 m0, s7, 0xc000
	ds_read_b128 v[186:189], v167
	ds_read_b128 v[190:193], v167 offset:1024
	ds_read_b128 v[194:197], v167 offset:2048
	ds_read_b128 v[198:201], v167 offset:3072
	ds_read_b128 v[202:205], v167 offset:4096
	ds_read_b128 v[206:209], v167 offset:5120
	ds_read_b128 v[210:213], v167 offset:6144
	ds_read_b128 v[218:221], v167 offset:7168
	global_load_lds_dwordx4 v[160:161], off
	v_lshl_add_u64 v[160:161], s[28:29], 0, v[146:147]
	s_add_i32 m0, s7, 0xe000
	s_nop 0
	global_load_lds_dwordx4 v[160:161], off
	s_waitcnt vmcnt(8)
	s_waitcnt lgkmcnt(0)
	s_barrier
	s_setprio 1
	s_waitcnt lgkmcnt(0)
	v_mfma_f32_16x16x32_bf16 v[124:127], v[128:131], v[186:189], v[124:127]
	v_mfma_f32_16x16x32_bf16 v[120:123], v[152:155], v[186:189], v[120:123]
	v_mfma_f32_16x16x32_bf16 v[108:111], v[128:131], v[194:197], v[108:111]
	v_mfma_f32_16x16x32_bf16 v[104:107], v[152:155], v[194:197], v[104:107]
	v_mfma_f32_16x16x32_bf16 v[92:95], v[128:131], v[202:205], v[92:95]
	v_mfma_f32_16x16x32_bf16 v[88:91], v[152:155], v[202:205], v[88:91]
	v_mfma_f32_16x16x32_bf16 v[76:79], v[128:131], v[210:213], v[76:79]
	v_mfma_f32_16x16x32_bf16 v[72:75], v[152:155], v[210:213], v[72:75]
	v_mfma_f32_16x16x32_bf16 v[124:127], v[132:135], v[190:193], v[124:127]
	v_mfma_f32_16x16x32_bf16 v[120:123], v[156:159], v[190:193], v[120:123]
	v_mfma_f32_16x16x32_bf16 v[108:111], v[132:135], v[198:201], v[108:111]
	v_mfma_f32_16x16x32_bf16 v[104:107], v[156:159], v[198:201], v[104:107]
	v_mfma_f32_16x16x32_bf16 v[92:95], v[132:135], v[206:209], v[92:95]
	v_mfma_f32_16x16x32_bf16 v[88:91], v[156:159], v[206:209], v[88:91]
	v_mfma_f32_16x16x32_bf16 v[76:79], v[132:135], v[218:221], v[76:79]
	v_mfma_f32_16x16x32_bf16 v[72:75], v[156:159], v[218:221], v[72:75]
	v_mfma_f32_16x16x32_bf16 v[116:119], v[170:173], v[186:189], v[116:119]
	v_mfma_f32_16x16x32_bf16 v[112:115], v[178:181], v[186:189], v[112:115]
	v_mfma_f32_16x16x32_bf16 v[100:103], v[170:173], v[194:197], v[100:103]
	v_mfma_f32_16x16x32_bf16 v[96:99], v[178:181], v[194:197], v[96:99]
	v_mfma_f32_16x16x32_bf16 v[84:87], v[170:173], v[202:205], v[84:87]
	v_mfma_f32_16x16x32_bf16 v[80:83], v[178:181], v[202:205], v[80:83]
	v_mfma_f32_16x16x32_bf16 v[68:71], v[170:173], v[210:213], v[68:71]
	v_mfma_f32_16x16x32_bf16 v[64:67], v[178:181], v[210:213], v[64:67]
	v_mfma_f32_16x16x32_bf16 v[116:119], v[174:177], v[190:193], v[116:119]
	v_mfma_f32_16x16x32_bf16 v[112:115], v[182:185], v[190:193], v[112:115]
	v_mfma_f32_16x16x32_bf16 v[100:103], v[174:177], v[198:201], v[100:103]
	v_mfma_f32_16x16x32_bf16 v[96:99], v[182:185], v[198:201], v[96:99]
	v_mfma_f32_16x16x32_bf16 v[84:87], v[174:177], v[206:209], v[84:87]
	v_mfma_f32_16x16x32_bf16 v[80:83], v[182:185], v[206:209], v[80:83]
	v_mfma_f32_16x16x32_bf16 v[68:71], v[174:177], v[218:221], v[68:71]
	v_mfma_f32_16x16x32_bf16 v[64:67], v[182:185], v[218:221], v[64:67]
	s_setprio 0
	s_barrier
	s_add_i32 s54, s46, s6
	v_lshl_add_u64 v[160:161], s[30:31], 0, v[138:139]
	s_mov_b32 m0, s54
	ds_read_b128 v[186:189], v167 offset:16384
	ds_read_b128 v[190:193], v167 offset:17408
	ds_read_b128 v[194:197], v167 offset:18432
	ds_read_b128 v[198:201], v167 offset:19456
	ds_read_b128 v[202:205], v167 offset:20480
	ds_read_b128 v[206:209], v167 offset:21504
	ds_read_b128 v[210:213], v167 offset:22528
	ds_read_b128 v[218:221], v167 offset:23552
	global_load_lds_dwordx4 v[160:161], off
	s_add_i32 m0, s54, 0x2000
	s_add_u32 s54, s30, 0x40000
	v_lshl_add_u64 v[214:215], s[30:31], 0, v[142:143]
	s_addc_u32 s55, s31, 0
	s_add_i32 s56, s47, s6
	global_load_lds_dwordx4 v[214:215], off
	v_lshl_add_u64 v[222:223], s[54:55], 0, v[138:139]
	s_mov_b32 m0, s56
	v_lshl_add_u64 v[224:225], s[34:35], 0, v[140:141]
	global_load_lds_dwordx4 v[222:223], off
	v_lshl_add_u64 v[222:223], s[54:55], 0, v[142:143]
	s_add_i32 m0, s56, 0x2000
	s_nop 0
	global_load_lds_dwordx4 v[222:223], off
	v_lshl_add_u64 v[222:223], s[34:35], 0, v[136:137]
	s_mov_b32 m0, s7
	s_nop 0
	global_load_lds_dwordx4 v[222:223], off
	s_mov_b32 m0, s33
	s_nop 0
	global_load_lds_dwordx4 v[224:225], off
	s_waitcnt vmcnt(8)
	s_waitcnt lgkmcnt(0)
	s_barrier
; #define PG8_STAGE(bufoff, gbase, voff) do { _Pragma("unroll") for (int _i = 0; _i < 2; ++_i) \
;         __builtin_amdgcn_global_load_lds((const unsigned*)((const char*)(gbase) + (voff)[_i]), (PG8_LAS unsigned*)(lds + (bufoff) + ldsw + _i * 8192), 16, 0, 0); } while (0)
; #define PG8_LDA(dst, b, h) do { _Pragma("unroll") for (int m = 0; m < 4; ++m) _Pragma("unroll") for (int k = 0; k < 2; ++k) dst[m][k] = *(const PG8_LAS bf16x8*)(lds + PG8_SA(b, h) + aoff + m * 2048 + k * 1024); } while (0)
; #define PG8_LDB(dst, b, h) do { _Pragma("unroll") for (int n = 0; n < 2; ++n) _Pragma("unroll") for (int k = 0; k < 2; ++k) dst[n][k] = *(const PG8_LAS bf16x8*)(lds + PG8_SB(b, h) + boff + n * 2048 + k * 1024); } while (0)
; #define PG8_MMA(ai, bj, At, Bt) do { __builtin_amdgcn_s_setprio(1); _Pragma("unroll") for (int m = 0; m < 4; ++m) _Pragma("unroll") for (int n = 0; n < 2; ++n) _Pragma("unroll") for (int k = 0; k < 2; ++k) \
;         acc[ai][bj][m][n] = __builtin_amdgcn_mfma_f32_16x16x32_bf16(Bt[n][k], At[m][k], acc[ai][bj][m][n], 0, 0, 0); __builtin_amdgcn_s_setprio(0); } while (0)
; #define PG8_WAIT_V(n) asm volatile("s_waitcnt vmcnt(" #n ")" ::: "memory")
; #define PG8_WAIT_L(n) asm volatile("s_waitcnt lgkmcnt(" #n ")" ::: "memory")
; #define PG8_BAR __builtin_amdgcn_s_barrier()
; #define PG8_SCHED __builtin_amdgcn_sched_barrier(0)
; template <class Epi, class Sched, bool ALIGN_EPI = false, bool SP2 = false>
; __device__ __forceinline__ void gemm_phase(PG8_LAS unsigned char* lds, const Gemm g, const Sched& S, const Epi& E, int wave0) {
;     ...
;             PG8_WAIT_V(8); PG8_WAIT_L(0); PG8_BAR; if (!cur.half) { PG8_MMA(1, 0, At, B0); PG8_MMA(1, 1, At, B1); } PG8_BAR; PG8_SCHED;
;             PG8_LDB(B0, 1, 0); PG8_LDB(B1, 1, 1); PG8_SCHED; PG8_LDA(At, 1, 0); PG8_STAGE(PG8_SA(0, 1), a2 + hstep, voffA);
;             PG8_WAIT_V(8); PG8_WAIT_L(0); PG8_BAR; PG8_MMA(0, 0, At, B0); PG8_MMA(0, 1, At, B1); PG8_BAR; PG8_SCHED;
	s_setprio 1
	s_waitcnt lgkmcnt(0)
	v_mfma_f32_16x16x32_bf16 v[60:63], v[128:131], v[186:189], v[60:63]
	v_mfma_f32_16x16x32_bf16 v[56:59], v[152:155], v[186:189], v[56:59]
	v_mfma_f32_16x16x32_bf16 v[44:47], v[128:131], v[194:197], v[44:47]
	v_mfma_f32_16x16x32_bf16 v[40:43], v[152:155], v[194:197], v[40:43]
	v_mfma_f32_16x16x32_bf16 v[28:31], v[128:131], v[202:205], v[28:31]
	v_mfma_f32_16x16x32_bf16 v[24:27], v[152:155], v[202:205], v[24:27]
	v_mfma_f32_16x16x32_bf16 v[12:15], v[128:131], v[210:213], v[12:15]
	v_mfma_f32_16x16x32_bf16 v[8:11], v[152:155], v[210:213], v[8:11]
	v_mfma_f32_16x16x32_bf16 v[60:63], v[132:135], v[190:193], v[60:63]
	v_mfma_f32_16x16x32_bf16 v[56:59], v[156:159], v[190:193], v[56:59]
	v_mfma_f32_16x16x32_bf16 v[44:47], v[132:135], v[198:201], v[44:47]
	v_mfma_f32_16x16x32_bf16 v[40:43], v[156:159], v[198:201], v[40:43]
	v_mfma_f32_16x16x32_bf16 v[28:31], v[132:135], v[206:209], v[28:31]
	v_mfma_f32_16x16x32_bf16 v[24:27], v[156:159], v[206:209], v[24:27]
	v_mfma_f32_16x16x32_bf16 v[12:15], v[132:135], v[218:221], v[12:15]
	v_mfma_f32_16x16x32_bf16 v[8:11], v[156:159], v[218:221], v[8:11]
	v_mfma_f32_16x16x32_bf16 v[52:55], v[170:173], v[186:189], v[52:55]
	v_mfma_f32_16x16x32_bf16 v[48:51], v[178:181], v[186:189], v[48:51]
	v_mfma_f32_16x16x32_bf16 v[36:39], v[170:173], v[194:197], v[36:39]
	v_mfma_f32_16x16x32_bf16 v[32:35], v[178:181], v[194:197], v[32:35]
	v_mfma_f32_16x16x32_bf16 v[20:23], v[170:173], v[202:205], v[20:23]
	v_mfma_f32_16x16x32_bf16 v[16:19], v[178:181], v[202:205], v[16:19]
	v_mfma_f32_16x16x32_bf16 v[4:7], v[170:173], v[210:213], v[4:7]
	v_mfma_f32_16x16x32_bf16 v[0:3], v[178:181], v[210:213], v[0:3]
	v_mfma_f32_16x16x32_bf16 v[52:55], v[174:177], v[190:193], v[52:55]
	v_mfma_f32_16x16x32_bf16 v[48:51], v[182:185], v[190:193], v[48:51]
	v_mfma_f32_16x16x32_bf16 v[36:39], v[174:177], v[198:201], v[36:39]
	v_mfma_f32_16x16x32_bf16 v[32:35], v[182:185], v[198:201], v[32:35]
	v_mfma_f32_16x16x32_bf16 v[20:23], v[174:177], v[206:209], v[20:23]
	v_mfma_f32_16x16x32_bf16 v[16:19], v[182:185], v[206:209], v[16:19]
	v_mfma_f32_16x16x32_bf16 v[4:7], v[174:177], v[218:221], v[4:7]
	v_mfma_f32_16x16x32_bf16 v[0:3], v[182:185], v[218:221], v[0:3]
	s_setprio 0
	s_barrier
	s_add_i32 s54, 0, 0x18000
	s_add_i32 s55, 0, 0x1c000
	v_add_u32_e32 v156, s54, v164
	v_add_u32_e32 v169, s55, v164
	ds_read_b128 v[128:131], v156
	ds_read_b128 v[132:135], v156 offset:1024
	ds_read_b128 v[152:155], v156 offset:2048
	ds_read_b128 v[156:159], v156 offset:3072
	ds_read_b128 v[170:173], v169
	ds_read_b128 v[174:177], v169 offset:1024
	ds_read_b128 v[178:181], v169 offset:2048
	ds_read_b128 v[182:185], v169 offset:3072
	s_add_u32 s34, s34, 0x40000
	s_addc_u32 s35, s35, 0
	s_mov_b32 m0, s36
	v_lshl_add_u64 v[226:227], s[34:35], 0, v[136:137]
	ds_read_b128 v[186:189], v167 offset:32768
	ds_read_b128 v[190:193], v167 offset:33792
	ds_read_b128 v[194:197], v167 offset:34816
	ds_read_b128 v[198:201], v167 offset:35840
	ds_read_b128 v[202:205], v167 offset:36864
	ds_read_b128 v[206:209], v167 offset:37888
	ds_read_b128 v[210:213], v167 offset:38912
	ds_read_b128 v[218:221], v167 offset:39936
	global_load_lds_dwordx4 v[226:227], off
	v_lshl_add_u64 v[226:227], s[34:35], 0, v[140:141]
	s_mov_b32 m0, s37
	s_nop 0
	global_load_lds_dwordx4 v[226:227], off
	s_waitcnt vmcnt(8)
	s_waitcnt lgkmcnt(0)
	s_barrier
	s_setprio 1
	s_waitcnt lgkmcnt(0)
	v_mfma_f32_16x16x32_bf16 v[124:127], v[128:131], v[186:189], v[124:127]
	v_mfma_f32_16x16x32_bf16 v[120:123], v[152:155], v[186:189], v[120:123]
	v_mfma_f32_16x16x32_bf16 v[108:111], v[128:131], v[194:197], v[108:111]
	v_mfma_f32_16x16x32_bf16 v[104:107], v[152:155], v[194:197], v[104:107]
	v_mfma_f32_16x16x32_bf16 v[92:95], v[128:131], v[202:205], v[92:95]
	v_mfma_f32_16x16x32_bf16 v[88:91], v[152:155], v[202:205], v[88:91]
	v_mfma_f32_16x16x32_bf16 v[76:79], v[128:131], v[210:213], v[76:79]
	v_mfma_f32_16x16x32_bf16 v[72:75], v[152:155], v[210:213], v[72:75]
	v_mfma_f32_16x16x32_bf16 v[124:127], v[132:135], v[190:193], v[124:127]
	v_mfma_f32_16x16x32_bf16 v[120:123], v[156:159], v[190:193], v[120:123]
	v_mfma_f32_16x16x32_bf16 v[108:111], v[132:135], v[198:201], v[108:111]
	v_mfma_f32_16x16x32_bf16 v[104:107], v[156:159], v[198:201], v[104:107]
	v_mfma_f32_16x16x32_bf16 v[92:95], v[132:135], v[206:209], v[92:95]
	v_mfma_f32_16x16x32_bf16 v[88:91], v[156:159], v[206:209], v[88:91]
	v_mfma_f32_16x16x32_bf16 v[76:79], v[132:135], v[218:221], v[76:79]
	v_mfma_f32_16x16x32_bf16 v[72:75], v[156:159], v[218:221], v[72:75]
	v_mfma_f32_16x16x32_bf16 v[116:119], v[170:173], v[186:189], v[116:119]
	v_mfma_f32_16x16x32_bf16 v[112:115], v[178:181], v[186:189], v[112:115]
	v_mfma_f32_16x16x32_bf16 v[100:103], v[170:173], v[194:197], v[100:103]
	v_mfma_f32_16x16x32_bf16 v[96:99], v[178:181], v[194:197], v[96:99]
	v_mfma_f32_16x16x32_bf16 v[84:87], v[170:173], v[202:205], v[84:87]
	v_mfma_f32_16x16x32_bf16 v[80:83], v[178:181], v[202:205], v[80:83]
	v_mfma_f32_16x16x32_bf16 v[68:71], v[170:173], v[210:213], v[68:71]
	v_mfma_f32_16x16x32_bf16 v[64:67], v[178:181], v[210:213], v[64:67]
	v_mfma_f32_16x16x32_bf16 v[116:119], v[174:177], v[190:193], v[116:119]
	v_mfma_f32_16x16x32_bf16 v[112:115], v[182:185], v[190:193], v[112:115]
	v_mfma_f32_16x16x32_bf16 v[100:103], v[174:177], v[198:201], v[100:103]
	v_mfma_f32_16x16x32_bf16 v[96:99], v[182:185], v[198:201], v[96:99]
	v_mfma_f32_16x16x32_bf16 v[84:87], v[174:177], v[206:209], v[84:87]
	v_mfma_f32_16x16x32_bf16 v[80:83], v[182:185], v[206:209], v[80:83]
	v_mfma_f32_16x16x32_bf16 v[68:71], v[174:177], v[218:221], v[68:71]
	v_mfma_f32_16x16x32_bf16 v[64:67], v[182:185], v[218:221], v[64:67]
	s_setprio 0
	s_barrier
; #define PG8_STAGE(bufoff, gbase, voff) do { _Pragma("unroll") for (int _i = 0; _i < 2; ++_i) \
;         __builtin_amdgcn_global_load_lds((const unsigned*)((const char*)(gbase) + (voff)[_i]), (PG8_LAS unsigned*)(lds + (bufoff) + ldsw + _i * 8192), 16, 0, 0); } while (0)
; #define PG8_LDA(dst, b, h) do { _Pragma("unroll") for (int m = 0; m < 4; ++m) _Pragma("unroll") for (int k = 0; k < 2; ++k) dst[m][k] = *(const PG8_LAS bf16x8*)(lds + PG8_SA(b, h) + aoff + m * 2048 + k * 1024); } while (0)
; #define PG8_MMA(ai, bj, At, Bt) do { __builtin_amdgcn_s_setprio(1); _Pragma("unroll") for (int m = 0; m < 4; ++m) _Pragma("unroll") for (int n = 0; n < 2; ++n) _Pragma("unroll") for (int k = 0; k < 2; ++k) \
;         acc[ai][bj][m][n] = __builtin_amdgcn_mfma_f32_16x16x32_bf16(Bt[n][k], At[m][k], acc[ai][bj][m][n], 0, 0, 0); __builtin_amdgcn_s_setprio(0); } while (0)
; #define PG8_WAIT_V(n) asm volatile("s_waitcnt vmcnt(" #n ")" ::: "memory")
; #define PG8_WAIT_L(n) asm volatile("s_waitcnt lgkmcnt(" #n ")" ::: "memory")
; #define PG8_BAR __builtin_amdgcn_s_barrier()
; #define PG8_SCHED __builtin_amdgcn_sched_barrier(0)
; template <class Epi, class Sched, bool ALIGN_EPI = false, bool SP2 = false>
; __device__ __forceinline__ void gemm_phase(PG8_LAS unsigned char* lds, const Gemm g, const Sched& S, const Epi& E, int wave0) {
;     ...
;         for (int t = 0; t < nt; t += 2) {
;             const bool last = (t == nt - 2);
;             const char* a1 = cA + (size_t)(t + 1) * kstep;
;             const char* a2 = last ? nA : cA + (size_t)(t + 2) * kstep; const char* b2 = last ? nB : cB + (size_t)(t + 2) * kstep;
;     ...
;             PG8_LDA(At, 1, 1); PG8_STAGE(PG8_SB(1, 0), b3, voffB); PG8_STAGE(PG8_SB(1, 1), b3 + hstep, voffB); PG8_STAGE(PG8_SA(1, 0), a3, voffA);
;             PG8_WAIT_V(8); PG8_WAIT_L(0); PG8_BAR; if (!cur.half) { PG8_MMA(1, 0, At, B0); PG8_MMA(1, 1, At, B1); } PG8_BAR; PG8_SCHED;
	s_add_i32 s34, s54, s6
	v_lshl_add_u64 v[160:161], v[160:161], 0, s[8:9]
	s_mov_b32 m0, s34
	ds_read_b128 v[186:189], v167 offset:49152
	ds_read_b128 v[190:193], v167 offset:50176
	ds_read_b128 v[194:197], v167 offset:51200
	ds_read_b128 v[198:201], v167 offset:52224
	ds_read_b128 v[202:205], v167 offset:53248
	ds_read_b128 v[206:209], v167 offset:54272
	ds_read_b128 v[210:213], v167 offset:55296
	ds_read_b128 v[218:221], v167 offset:56320
	global_load_lds_dwordx4 v[160:161], off
	s_add_i32 m0, s34, 0x2000
	s_add_u32 s30, s30, 0x40080
	v_lshl_add_u64 v[160:161], v[214:215], 0, s[8:9]
	s_addc_u32 s31, s31, 0
	s_add_i32 s34, s55, s6
	global_load_lds_dwordx4 v[160:161], off
	v_lshl_add_u64 v[160:161], s[30:31], 0, v[138:139]
	s_mov_b32 m0, s34
	s_nop 0
	global_load_lds_dwordx4 v[160:161], off
	v_lshl_add_u64 v[160:161], s[30:31], 0, v[142:143]
	s_add_i32 m0, s34, 0x2000
	s_nop 0
	global_load_lds_dwordx4 v[160:161], off
	v_lshl_add_u64 v[160:161], v[222:223], 0, s[8:9]
	s_mov_b32 m0, s41
	s_nop 0
	global_load_lds_dwordx4 v[160:161], off
	v_lshl_add_u64 v[160:161], v[224:225], 0, s[8:9]
	s_mov_b32 m0, s42
	s_nop 0
	global_load_lds_dwordx4 v[160:161], off
	s_waitcnt vmcnt(8)
	s_waitcnt lgkmcnt(0)
	s_barrier
	s_setprio 1
	s_waitcnt lgkmcnt(0)
	v_mfma_f32_16x16x32_bf16 v[60:63], v[128:131], v[186:189], v[60:63]
	v_mfma_f32_16x16x32_bf16 v[56:59], v[152:155], v[186:189], v[56:59]
	v_mfma_f32_16x16x32_bf16 v[44:47], v[128:131], v[194:197], v[44:47]
	v_mfma_f32_16x16x32_bf16 v[40:43], v[152:155], v[194:197], v[40:43]
	v_mfma_f32_16x16x32_bf16 v[28:31], v[128:131], v[202:205], v[28:31]
	v_mfma_f32_16x16x32_bf16 v[24:27], v[152:155], v[202:205], v[24:27]
	v_mfma_f32_16x16x32_bf16 v[12:15], v[128:131], v[210:213], v[12:15]
	v_mfma_f32_16x16x32_bf16 v[8:11], v[152:155], v[210:213], v[8:11]
	v_mfma_f32_16x16x32_bf16 v[60:63], v[132:135], v[190:193], v[60:63]
	v_mfma_f32_16x16x32_bf16 v[56:59], v[156:159], v[190:193], v[56:59]
	v_mfma_f32_16x16x32_bf16 v[44:47], v[132:135], v[198:201], v[44:47]
	v_mfma_f32_16x16x32_bf16 v[40:43], v[156:159], v[198:201], v[40:43]
	v_mfma_f32_16x16x32_bf16 v[28:31], v[132:135], v[206:209], v[28:31]
	v_mfma_f32_16x16x32_bf16 v[24:27], v[156:159], v[206:209], v[24:27]
	v_mfma_f32_16x16x32_bf16 v[12:15], v[132:135], v[218:221], v[12:15]
	v_mfma_f32_16x16x32_bf16 v[8:11], v[156:159], v[218:221], v[8:11]
	v_mfma_f32_16x16x32_bf16 v[52:55], v[170:173], v[186:189], v[52:55]
	v_mfma_f32_16x16x32_bf16 v[48:51], v[178:181], v[186:189], v[48:51]
	v_mfma_f32_16x16x32_bf16 v[36:39], v[170:173], v[194:197], v[36:39]
	v_mfma_f32_16x16x32_bf16 v[32:35], v[178:181], v[194:197], v[32:35]
	v_mfma_f32_16x16x32_bf16 v[20:23], v[170:173], v[202:205], v[20:23]
	v_mfma_f32_16x16x32_bf16 v[16:19], v[178:181], v[202:205], v[16:19]
	v_mfma_f32_16x16x32_bf16 v[4:7], v[170:173], v[210:213], v[4:7]
	v_mfma_f32_16x16x32_bf16 v[0:3], v[178:181], v[210:213], v[0:3]
	v_mfma_f32_16x16x32_bf16 v[52:55], v[174:177], v[190:193], v[52:55]
	v_mfma_f32_16x16x32_bf16 v[48:51], v[182:185], v[190:193], v[48:51]
	v_mfma_f32_16x16x32_bf16 v[36:39], v[174:177], v[198:201], v[36:39]
	v_mfma_f32_16x16x32_bf16 v[32:35], v[182:185], v[198:201], v[32:35]
	v_mfma_f32_16x16x32_bf16 v[20:23], v[174:177], v[206:209], v[20:23]
	v_mfma_f32_16x16x32_bf16 v[16:19], v[182:185], v[206:209], v[16:19]
	v_mfma_f32_16x16x32_bf16 v[4:7], v[174:177], v[218:221], v[4:7]
	v_mfma_f32_16x16x32_bf16 v[0:3], v[182:185], v[218:221], v[0:3]
	s_setprio 0
	s_barrier
	s_add_i32 s53, s53, 2
	s_add_u32 s28, s28, 0x100
	s_addc_u32 s29, s29, 0
	s_add_u32 s51, s51, 0x100
	s_addc_u32 s52, s52, 0
	s_cmp_gt_u32 s53, 13
	s_cbranch_scc0 .LBB0_363
	s_nop 0
	s_nop 0
	s_nop 0
	s_nop 0
	s_nop 0
	s_nop 0
	s_nop 0
	s_nop 0
	s_and_b64 vcc, exec, s[10:11]
	s_cbranch_vccz .LBB0_366
	s_barrier

; #define PG8_STAGE(bufoff, gbase, voff) do { _Pragma("unroll") for (int _i = 0; _i < 2; ++_i) \
;         __builtin_amdgcn_global_load_lds((const unsigned*)((const char*)(gbase) + (voff)[_i]), (PG8_LAS unsigned*)(lds + (bufoff) + ldsw + _i * 8192), 16, 0, 0); } while (0)
; #define PG8_LDA(dst, b, h) do { _Pragma("unroll") for (int m = 0; m < 4; ++m) _Pragma("unroll") for (int k = 0; k < 2; ++k) dst[m][k] = *(const PG8_LAS bf16x8*)(lds + PG8_SA(b, h) + aoff + m * 2048 + k * 1024); } while (0)
; #define PG8_LDB(dst, b, h) do { _Pragma("unroll") for (int n = 0; n < 2; ++n) _Pragma("unroll") for (int k = 0; k < 2; ++k) dst[n][k] = *(const PG8_LAS bf16x8*)(lds + PG8_SB(b, h) + boff + n * 2048 + k * 1024); } while (0)
; #define PG8_MMA(ai, bj, At, Bt) do { __builtin_amdgcn_s_setprio(1); _Pragma("unroll") for (int m = 0; m < 4; ++m) _Pragma("unroll") for (int n = 0; n < 2; ++n) _Pragma("unroll") for (int k = 0; k < 2; ++k) \
;         acc[ai][bj][m][n] = __builtin_amdgcn_mfma_f32_16x16x32_bf16(Bt[n][k], At[m][k], acc[ai][bj][m][n], 0, 0, 0); __builtin_amdgcn_s_setprio(0); } while (0)
; #define PG8_WAIT_V(n) asm volatile("s_waitcnt vmcnt(" #n ")" ::: "memory")
; #define PG8_WAIT_L(n) asm volatile("s_waitcnt lgkmcnt(" #n ")" ::: "memory")
; #define PG8_BAR __builtin_amdgcn_s_barrier()
; #define PG8_SCHED __builtin_amdgcn_sched_barrier(0)
; template <class Epi, class Sched, bool ALIGN_EPI = false, bool SP2 = false>
; __device__ __forceinline__ void gemm_phase(PG8_LAS unsigned char* lds, const Gemm g, const Sched& S, const Epi& E, int wave0) {
;     ...
;             PG8_LDB(B0, 0, 0); PG8_LDB(B1, 0, 1); PG8_SCHED; PG8_LDA(At, 0, 0); PG8_STAGE(PG8_SA(1, 1), a1 + hstep, voffA);
;             PG8_WAIT_V(8); PG8_WAIT_L(0); PG8_BAR; PG8_MMA(0, 0, At, B0); PG8_MMA(0, 1, At, B1); PG8_BAR; PG8_SCHED;
;             PG8_LDA(At, 0, 1); PG8_STAGE(PG8_SB(0, 0), b2, voffB); PG8_STAGE(PG8_SB(0, 1), b2 + hstep, voffB); PG8_STAGE(PG8_SA(0, 0), a2, voffA);
;             PG8_WAIT_V(8); PG8_WAIT_L(0); PG8_BAR; if (!cur.half) { PG8_MMA(1, 0, At, B0); PG8_MMA(1, 1, At, B1); } PG8_BAR; PG8_SCHED;
.LBB0_480:
	ds_read_b128 v[144:147], v169
	ds_read_b128 v[148:151], v169 offset:1024
	ds_read_b128 v[152:155], v169 offset:2048
	ds_read_b128 v[156:159], v169 offset:3072
	ds_read_b128 v[160:163], v170
	ds_read_b128 v[174:177], v170 offset:1024
	ds_read_b128 v[178:181], v170 offset:2048
	ds_read_b128 v[182:185], v170 offset:3072
	s_add_u32 s52, s50, 0xfffc0080
	s_addc_u32 s53, s51, -1
	s_cmp_eq_u32 s68, 12
	s_cselect_b32 s55, s3, s53
	s_cselect_b32 s54, s11, s52
	s_cselect_b32 s53, s43, s86
	s_cselect_b32 s52, s45, s85
	v_lshl_add_u64 v[164:165], s[50:51], 0, v[136:137]
	s_add_i32 m0, s7, 0xc000
	ds_read_b128 v[186:189], v171
	ds_read_b128 v[190:193], v171 offset:1024
	ds_read_b128 v[194:197], v171 offset:2048
	ds_read_b128 v[198:201], v171 offset:3072
	ds_read_b128 v[202:205], v171 offset:4096
	ds_read_b128 v[206:209], v171 offset:5120
	ds_read_b128 v[210:213], v171 offset:6144
	ds_read_b128 v[218:221], v171 offset:7168
	global_load_lds_dwordx4 v[164:165], off
	v_lshl_add_u64 v[164:165], s[50:51], 0, v[138:139]
	s_add_i32 m0, s7, 0xe000
	s_nop 0
	global_load_lds_dwordx4 v[164:165], off
	s_waitcnt vmcnt(8)
	s_waitcnt lgkmcnt(0)
	s_barrier
	s_setprio 1
	s_waitcnt lgkmcnt(0)
	v_mfma_f32_16x16x32_bf16 v[124:127], v[144:147], v[186:189], v[124:127]
	v_mfma_f32_16x16x32_bf16 v[120:123], v[152:155], v[186:189], v[120:123]
	v_mfma_f32_16x16x32_bf16 v[108:111], v[144:147], v[194:197], v[108:111]
	v_mfma_f32_16x16x32_bf16 v[104:107], v[152:155], v[194:197], v[104:107]
	v_mfma_f32_16x16x32_bf16 v[92:95], v[144:147], v[202:205], v[92:95]
	v_mfma_f32_16x16x32_bf16 v[88:91], v[152:155], v[202:205], v[88:91]
	v_mfma_f32_16x16x32_bf16 v[76:79], v[144:147], v[210:213], v[76:79]
	v_mfma_f32_16x16x32_bf16 v[72:75], v[152:155], v[210:213], v[72:75]
	v_mfma_f32_16x16x32_bf16 v[124:127], v[148:151], v[190:193], v[124:127]
	v_mfma_f32_16x16x32_bf16 v[120:123], v[156:159], v[190:193], v[120:123]
	v_mfma_f32_16x16x32_bf16 v[108:111], v[148:151], v[198:201], v[108:111]
	v_mfma_f32_16x16x32_bf16 v[104:107], v[156:159], v[198:201], v[104:107]
	v_mfma_f32_16x16x32_bf16 v[92:95], v[148:151], v[206:209], v[92:95]
	v_mfma_f32_16x16x32_bf16 v[88:91], v[156:159], v[206:209], v[88:91]
	v_mfma_f32_16x16x32_bf16 v[76:79], v[148:151], v[218:221], v[76:79]
	v_mfma_f32_16x16x32_bf16 v[72:75], v[156:159], v[218:221], v[72:75]
	v_mfma_f32_16x16x32_bf16 v[116:119], v[160:163], v[186:189], v[116:119]
	v_mfma_f32_16x16x32_bf16 v[112:115], v[178:181], v[186:189], v[112:115]
	v_mfma_f32_16x16x32_bf16 v[100:103], v[160:163], v[194:197], v[100:103]
	v_mfma_f32_16x16x32_bf16 v[96:99], v[178:181], v[194:197], v[96:99]
	v_mfma_f32_16x16x32_bf16 v[84:87], v[160:163], v[202:205], v[84:87]
	v_mfma_f32_16x16x32_bf16 v[80:83], v[178:181], v[202:205], v[80:83]
	v_mfma_f32_16x16x32_bf16 v[68:71], v[160:163], v[210:213], v[68:71]
	v_mfma_f32_16x16x32_bf16 v[64:67], v[178:181], v[210:213], v[64:67]
	v_mfma_f32_16x16x32_bf16 v[116:119], v[174:177], v[190:193], v[116:119]
	v_mfma_f32_16x16x32_bf16 v[112:115], v[182:185], v[190:193], v[112:115]
	v_mfma_f32_16x16x32_bf16 v[100:103], v[174:177], v[198:201], v[100:103]
	v_mfma_f32_16x16x32_bf16 v[96:99], v[182:185], v[198:201], v[96:99]
	v_mfma_f32_16x16x32_bf16 v[84:87], v[174:177], v[206:209], v[84:87]
	v_mfma_f32_16x16x32_bf16 v[80:83], v[182:185], v[206:209], v[80:83]
	v_mfma_f32_16x16x32_bf16 v[68:71], v[174:177], v[218:221], v[68:71]
	v_mfma_f32_16x16x32_bf16 v[64:67], v[182:185], v[218:221], v[64:67]
	s_setprio 0
	s_barrier
	s_add_i32 s69, s57, s6
	v_lshl_add_u64 v[164:165], s[52:53], 0, v[130:131]
	s_mov_b32 m0, s69
	ds_read_b128 v[186:189], v171 offset:16384
	ds_read_b128 v[190:193], v171 offset:17408
	ds_read_b128 v[194:197], v171 offset:18432
	ds_read_b128 v[198:201], v171 offset:19456
	ds_read_b128 v[202:205], v171 offset:20480
	ds_read_b128 v[206:209], v171 offset:21504
	ds_read_b128 v[210:213], v171 offset:22528
	ds_read_b128 v[218:221], v171 offset:23552
	global_load_lds_dwordx4 v[164:165], off
	s_add_i32 m0, s69, 0x2000
	s_add_u32 vcc_lo, s52, 0x40000
	v_lshl_add_u64 v[214:215], s[52:53], 0, v[134:135]
	s_addc_u32 vcc_hi, s53, 0
	s_add_i32 s69, s62, s6
	global_load_lds_dwordx4 v[214:215], off
	v_lshl_add_u64 v[222:223], vcc, 0, v[130:131]
	s_mov_b32 m0, s69
	v_lshl_add_u64 v[224:225], s[54:55], 0, v[132:133]
	global_load_lds_dwordx4 v[222:223], off
	v_lshl_add_u64 v[222:223], vcc, 0, v[134:135]
	s_add_i32 m0, s69, 0x2000
	s_nop 0
	global_load_lds_dwordx4 v[222:223], off
	v_lshl_add_u64 v[222:223], s[54:55], 0, v[128:129]
	s_mov_b32 m0, s7
	s_nop 0
	global_load_lds_dwordx4 v[222:223], off
	s_mov_b32 m0, s17
	s_nop 0
	global_load_lds_dwordx4 v[224:225], off
	s_waitcnt vmcnt(8)
	s_waitcnt lgkmcnt(0)
	s_barrier
; #define PG8_STAGE(bufoff, gbase, voff) do { _Pragma("unroll") for (int _i = 0; _i < 2; ++_i) \
;         __builtin_amdgcn_global_load_lds((const unsigned*)((const char*)(gbase) + (voff)[_i]), (PG8_LAS unsigned*)(lds + (bufoff) + ldsw + _i * 8192), 16, 0, 0); } while (0)
; #define PG8_LDA(dst, b, h) do { _Pragma("unroll") for (int m = 0; m < 4; ++m) _Pragma("unroll") for (int k = 0; k < 2; ++k) dst[m][k] = *(const PG8_LAS bf16x8*)(lds + PG8_SA(b, h) + aoff + m * 2048 + k * 1024); } while (0)
; #define PG8_LDB(dst, b, h) do { _Pragma("unroll") for (int n = 0; n < 2; ++n) _Pragma("unroll") for (int k = 0; k < 2; ++k) dst[n][k] = *(const PG8_LAS bf16x8*)(lds + PG8_SB(b, h) + boff + n * 2048 + k * 1024); } while (0)
; #define PG8_MMA(ai, bj, At, Bt) do { __builtin_amdgcn_s_setprio(1); _Pragma("unroll") for (int m = 0; m < 4; ++m) _Pragma("unroll") for (int n = 0; n < 2; ++n) _Pragma("unroll") for (int k = 0; k < 2; ++k) \
;         acc[ai][bj][m][n] = __builtin_amdgcn_mfma_f32_16x16x32_bf16(Bt[n][k], At[m][k], acc[ai][bj][m][n], 0, 0, 0); __builtin_amdgcn_s_setprio(0); } while (0)
; #define PG8_WAIT_V(n) asm volatile("s_waitcnt vmcnt(" #n ")" ::: "memory")
; #define PG8_WAIT_L(n) asm volatile("s_waitcnt lgkmcnt(" #n ")" ::: "memory")
; #define PG8_BAR __builtin_amdgcn_s_barrier()
; #define PG8_SCHED __builtin_amdgcn_sched_barrier(0)
; template <class Epi, class Sched, bool ALIGN_EPI = false, bool SP2 = false>
; __device__ __forceinline__ void gemm_phase(PG8_LAS unsigned char* lds, const Gemm g, const Sched& S, const Epi& E, int wave0) {
;     ...
;             PG8_WAIT_V(8); PG8_WAIT_L(0); PG8_BAR; if (!cur.half) { PG8_MMA(1, 0, At, B0); PG8_MMA(1, 1, At, B1); } PG8_BAR; PG8_SCHED;
;             PG8_LDB(B0, 1, 0); PG8_LDB(B1, 1, 1); PG8_SCHED; PG8_LDA(At, 1, 0); PG8_STAGE(PG8_SA(0, 1), a2 + hstep, voffA);
;             PG8_WAIT_V(8); PG8_WAIT_L(0); PG8_BAR; PG8_MMA(0, 0, At, B0); PG8_MMA(0, 1, At, B1); PG8_BAR; PG8_SCHED;
	s_setprio 1
	s_waitcnt lgkmcnt(0)
	v_mfma_f32_16x16x32_bf16 v[60:63], v[144:147], v[186:189], v[60:63]
	v_mfma_f32_16x16x32_bf16 v[56:59], v[152:155], v[186:189], v[56:59]
	v_mfma_f32_16x16x32_bf16 v[44:47], v[144:147], v[194:197], v[44:47]
	v_mfma_f32_16x16x32_bf16 v[40:43], v[152:155], v[194:197], v[40:43]
	v_mfma_f32_16x16x32_bf16 v[28:31], v[144:147], v[202:205], v[28:31]
	v_mfma_f32_16x16x32_bf16 v[24:27], v[152:155], v[202:205], v[24:27]
	v_mfma_f32_16x16x32_bf16 v[12:15], v[144:147], v[210:213], v[12:15]
	v_mfma_f32_16x16x32_bf16 v[8:11], v[152:155], v[210:213], v[8:11]
	v_mfma_f32_16x16x32_bf16 v[60:63], v[148:151], v[190:193], v[60:63]
	v_mfma_f32_16x16x32_bf16 v[56:59], v[156:159], v[190:193], v[56:59]
	v_mfma_f32_16x16x32_bf16 v[44:47], v[148:151], v[198:201], v[44:47]
	v_mfma_f32_16x16x32_bf16 v[40:43], v[156:159], v[198:201], v[40:43]
	v_mfma_f32_16x16x32_bf16 v[28:31], v[148:151], v[206:209], v[28:31]
	v_mfma_f32_16x16x32_bf16 v[24:27], v[156:159], v[206:209], v[24:27]
	v_mfma_f32_16x16x32_bf16 v[12:15], v[148:151], v[218:221], v[12:15]
	v_mfma_f32_16x16x32_bf16 v[8:11], v[156:159], v[218:221], v[8:11]
	v_mfma_f32_16x16x32_bf16 v[52:55], v[160:163], v[186:189], v[52:55]
	v_mfma_f32_16x16x32_bf16 v[48:51], v[178:181], v[186:189], v[48:51]
	v_mfma_f32_16x16x32_bf16 v[36:39], v[160:163], v[194:197], v[36:39]
	v_mfma_f32_16x16x32_bf16 v[32:35], v[178:181], v[194:197], v[32:35]
	v_mfma_f32_16x16x32_bf16 v[20:23], v[160:163], v[202:205], v[20:23]
	v_mfma_f32_16x16x32_bf16 v[16:19], v[178:181], v[202:205], v[16:19]
	v_mfma_f32_16x16x32_bf16 v[4:7], v[160:163], v[210:213], v[4:7]
	v_mfma_f32_16x16x32_bf16 v[0:3], v[178:181], v[210:213], v[0:3]
	v_mfma_f32_16x16x32_bf16 v[52:55], v[174:177], v[190:193], v[52:55]
	v_mfma_f32_16x16x32_bf16 v[48:51], v[182:185], v[190:193], v[48:51]
	v_mfma_f32_16x16x32_bf16 v[36:39], v[174:177], v[198:201], v[36:39]
	v_mfma_f32_16x16x32_bf16 v[32:35], v[182:185], v[198:201], v[32:35]
	v_mfma_f32_16x16x32_bf16 v[20:23], v[174:177], v[206:209], v[20:23]
	v_mfma_f32_16x16x32_bf16 v[16:19], v[182:185], v[206:209], v[16:19]
	v_mfma_f32_16x16x32_bf16 v[4:7], v[174:177], v[218:221], v[4:7]
	v_mfma_f32_16x16x32_bf16 v[0:3], v[182:185], v[218:221], v[0:3]
	s_setprio 0
	s_barrier
	s_add_i32 s69, 0, 0x18000
	s_add_i32 s87, 0, 0x1c000
	v_add_u32_e32 v156, s69, v168
	v_add_u32_e32 v182, s87, v168
	ds_read_b128 v[144:147], v156
	ds_read_b128 v[148:151], v156 offset:1024
	ds_read_b128 v[152:155], v156 offset:2048
	ds_read_b128 v[156:159], v156 offset:3072
	ds_read_b128 v[160:163], v182
	ds_read_b128 v[174:177], v182 offset:1024
	ds_read_b128 v[178:181], v182 offset:2048
	ds_read_b128 v[182:185], v182 offset:3072
	s_add_u32 s54, s54, 0x40000
	s_addc_u32 s55, s55, 0
	s_mov_b32 m0, s19
	v_lshl_add_u64 v[226:227], s[54:55], 0, v[128:129]
	ds_read_b128 v[186:189], v171 offset:32768
	ds_read_b128 v[190:193], v171 offset:33792
	ds_read_b128 v[194:197], v171 offset:34816
	ds_read_b128 v[198:201], v171 offset:35840
	ds_read_b128 v[202:205], v171 offset:36864
	ds_read_b128 v[206:209], v171 offset:37888
	ds_read_b128 v[210:213], v171 offset:38912
	ds_read_b128 v[218:221], v171 offset:39936
	global_load_lds_dwordx4 v[226:227], off
	v_lshl_add_u64 v[226:227], s[54:55], 0, v[132:133]
	s_mov_b32 m0, s21
	s_nop 0
	global_load_lds_dwordx4 v[226:227], off
	s_waitcnt vmcnt(8)
	s_waitcnt lgkmcnt(0)
	s_barrier
	s_setprio 1
	s_waitcnt lgkmcnt(0)
	v_mfma_f32_16x16x32_bf16 v[124:127], v[144:147], v[186:189], v[124:127]
	v_mfma_f32_16x16x32_bf16 v[120:123], v[152:155], v[186:189], v[120:123]
	v_mfma_f32_16x16x32_bf16 v[108:111], v[144:147], v[194:197], v[108:111]
	v_mfma_f32_16x16x32_bf16 v[104:107], v[152:155], v[194:197], v[104:107]
	v_mfma_f32_16x16x32_bf16 v[92:95], v[144:147], v[202:205], v[92:95]
	v_mfma_f32_16x16x32_bf16 v[88:91], v[152:155], v[202:205], v[88:91]
	v_mfma_f32_16x16x32_bf16 v[76:79], v[144:147], v[210:213], v[76:79]
	v_mfma_f32_16x16x32_bf16 v[72:75], v[152:155], v[210:213], v[72:75]
	v_mfma_f32_16x16x32_bf16 v[124:127], v[148:151], v[190:193], v[124:127]
	v_mfma_f32_16x16x32_bf16 v[120:123], v[156:159], v[190:193], v[120:123]
	v_mfma_f32_16x16x32_bf16 v[108:111], v[148:151], v[198:201], v[108:111]
	v_mfma_f32_16x16x32_bf16 v[104:107], v[156:159], v[198:201], v[104:107]
	v_mfma_f32_16x16x32_bf16 v[92:95], v[148:151], v[206:209], v[92:95]
	v_mfma_f32_16x16x32_bf16 v[88:91], v[156:159], v[206:209], v[88:91]
	v_mfma_f32_16x16x32_bf16 v[76:79], v[148:151], v[218:221], v[76:79]
	v_mfma_f32_16x16x32_bf16 v[72:75], v[156:159], v[218:221], v[72:75]
	v_mfma_f32_16x16x32_bf16 v[116:119], v[160:163], v[186:189], v[116:119]
	v_mfma_f32_16x16x32_bf16 v[112:115], v[178:181], v[186:189], v[112:115]
	v_mfma_f32_16x16x32_bf16 v[100:103], v[160:163], v[194:197], v[100:103]
	v_mfma_f32_16x16x32_bf16 v[96:99], v[178:181], v[194:197], v[96:99]
	v_mfma_f32_16x16x32_bf16 v[84:87], v[160:163], v[202:205], v[84:87]
	v_mfma_f32_16x16x32_bf16 v[80:83], v[178:181], v[202:205], v[80:83]
	v_mfma_f32_16x16x32_bf16 v[68:71], v[160:163], v[210:213], v[68:71]
	v_mfma_f32_16x16x32_bf16 v[64:67], v[178:181], v[210:213], v[64:67]
	v_mfma_f32_16x16x32_bf16 v[116:119], v[174:177], v[190:193], v[116:119]
	v_mfma_f32_16x16x32_bf16 v[112:115], v[182:185], v[190:193], v[112:115]
	v_mfma_f32_16x16x32_bf16 v[100:103], v[174:177], v[198:201], v[100:103]
	v_mfma_f32_16x16x32_bf16 v[96:99], v[182:185], v[198:201], v[96:99]
	v_mfma_f32_16x16x32_bf16 v[84:87], v[174:177], v[206:209], v[84:87]
	v_mfma_f32_16x16x32_bf16 v[80:83], v[182:185], v[206:209], v[80:83]
	v_mfma_f32_16x16x32_bf16 v[68:71], v[174:177], v[218:221], v[68:71]
	v_mfma_f32_16x16x32_bf16 v[64:67], v[182:185], v[218:221], v[64:67]
	s_setprio 0
	s_barrier
; #define PG8_STAGE(bufoff, gbase, voff) do { _Pragma("unroll") for (int _i = 0; _i < 2; ++_i) \
;         __builtin_amdgcn_global_load_lds((const unsigned*)((const char*)(gbase) + (voff)[_i]), (PG8_LAS unsigned*)(lds + (bufoff) + ldsw + _i * 8192), 16, 0, 0); } while (0)
; #define PG8_LDA(dst, b, h) do { _Pragma("unroll") for (int m = 0; m < 4; ++m) _Pragma("unroll") for (int k = 0; k < 2; ++k) dst[m][k] = *(const PG8_LAS bf16x8*)(lds + PG8_SA(b, h) + aoff + m * 2048 + k * 1024); } while (0)
; #define PG8_MMA(ai, bj, At, Bt) do { __builtin_amdgcn_s_setprio(1); _Pragma("unroll") for (int m = 0; m < 4; ++m) _Pragma("unroll") for (int n = 0; n < 2; ++n) _Pragma("unroll") for (int k = 0; k < 2; ++k) \
;         acc[ai][bj][m][n] = __builtin_amdgcn_mfma_f32_16x16x32_bf16(Bt[n][k], At[m][k], acc[ai][bj][m][n], 0, 0, 0); __builtin_amdgcn_s_setprio(0); } while (0)
; #define PG8_WAIT_V(n) asm volatile("s_waitcnt vmcnt(" #n ")" ::: "memory")
; #define PG8_WAIT_L(n) asm volatile("s_waitcnt lgkmcnt(" #n ")" ::: "memory")
; #define PG8_BAR __builtin_amdgcn_s_barrier()
; #define PG8_SCHED __builtin_amdgcn_sched_barrier(0)
; template <class Epi, class Sched, bool ALIGN_EPI = false, bool SP2 = false>
; __device__ __forceinline__ void gemm_phase(PG8_LAS unsigned char* lds, const Gemm g, const Sched& S, const Epi& E, int wave0) {
;     ...
;         for (int t = 0; t < nt; t += 2) {
;             const bool last = (t == nt - 2);
;             const char* a1 = cA + (size_t)(t + 1) * kstep;
;             const char* a2 = last ? nA : cA + (size_t)(t + 2) * kstep; const char* b2 = last ? nB : cB + (size_t)(t + 2) * kstep;
;     ...
;             PG8_LDA(At, 1, 1); PG8_STAGE(PG8_SB(1, 0), b3, voffB); PG8_STAGE(PG8_SB(1, 1), b3 + hstep, voffB); PG8_STAGE(PG8_SA(1, 0), a3, voffA);
;             PG8_WAIT_V(8); PG8_WAIT_L(0); PG8_BAR; if (!cur.half) { PG8_MMA(1, 0, At, B0); PG8_MMA(1, 1, At, B1); } PG8_BAR; PG8_SCHED;
	s_add_i32 s54, s69, s6
	v_lshl_add_u64 v[164:165], v[164:165], 0, s[4:5]
	s_mov_b32 m0, s54
	ds_read_b128 v[186:189], v171 offset:49152
	ds_read_b128 v[190:193], v171 offset:50176
	ds_read_b128 v[194:197], v171 offset:51200
	ds_read_b128 v[198:201], v171 offset:52224
	ds_read_b128 v[202:205], v171 offset:53248
	ds_read_b128 v[206:209], v171 offset:54272
	ds_read_b128 v[210:213], v171 offset:55296
	ds_read_b128 v[218:221], v171 offset:56320
	global_load_lds_dwordx4 v[164:165], off
	s_add_i32 m0, s54, 0x2000
	s_add_u32 s52, s52, 0x40080
	v_lshl_add_u64 v[164:165], v[214:215], 0, s[4:5]
	s_addc_u32 s53, s53, 0
	s_add_i32 s54, s87, s6
	global_load_lds_dwordx4 v[164:165], off
	v_lshl_add_u64 v[164:165], s[52:53], 0, v[130:131]
	s_mov_b32 m0, s54
	s_nop 0
	global_load_lds_dwordx4 v[164:165], off
	v_lshl_add_u64 v[164:165], s[52:53], 0, v[134:135]
	s_add_i32 m0, s54, 0x2000
	s_nop 0
	global_load_lds_dwordx4 v[164:165], off
	v_lshl_add_u64 v[164:165], v[222:223], 0, s[4:5]
	s_mov_b32 m0, s35
	s_nop 0
	global_load_lds_dwordx4 v[164:165], off
	v_lshl_add_u64 v[164:165], v[224:225], 0, s[4:5]
	s_mov_b32 m0, s37
	s_nop 0
	global_load_lds_dwordx4 v[164:165], off
	s_waitcnt vmcnt(8)
	s_waitcnt lgkmcnt(0)
	s_barrier
	s_setprio 1
	s_waitcnt lgkmcnt(0)
	v_mfma_f32_16x16x32_bf16 v[60:63], v[144:147], v[186:189], v[60:63]
	v_mfma_f32_16x16x32_bf16 v[56:59], v[152:155], v[186:189], v[56:59]
	v_mfma_f32_16x16x32_bf16 v[44:47], v[144:147], v[194:197], v[44:47]
	v_mfma_f32_16x16x32_bf16 v[40:43], v[152:155], v[194:197], v[40:43]
	v_mfma_f32_16x16x32_bf16 v[28:31], v[144:147], v[202:205], v[28:31]
	v_mfma_f32_16x16x32_bf16 v[24:27], v[152:155], v[202:205], v[24:27]
	v_mfma_f32_16x16x32_bf16 v[12:15], v[144:147], v[210:213], v[12:15]
	v_mfma_f32_16x16x32_bf16 v[8:11], v[152:155], v[210:213], v[8:11]
	v_mfma_f32_16x16x32_bf16 v[60:63], v[148:151], v[190:193], v[60:63]
	v_mfma_f32_16x16x32_bf16 v[56:59], v[156:159], v[190:193], v[56:59]
	v_mfma_f32_16x16x32_bf16 v[44:47], v[148:151], v[198:201], v[44:47]
	v_mfma_f32_16x16x32_bf16 v[40:43], v[156:159], v[198:201], v[40:43]
	v_mfma_f32_16x16x32_bf16 v[28:31], v[148:151], v[206:209], v[28:31]
	v_mfma_f32_16x16x32_bf16 v[24:27], v[156:159], v[206:209], v[24:27]
	v_mfma_f32_16x16x32_bf16 v[12:15], v[148:151], v[218:221], v[12:15]
	v_mfma_f32_16x16x32_bf16 v[8:11], v[156:159], v[218:221], v[8:11]
	v_mfma_f32_16x16x32_bf16 v[52:55], v[160:163], v[186:189], v[52:55]
	v_mfma_f32_16x16x32_bf16 v[48:51], v[178:181], v[186:189], v[48:51]
	v_mfma_f32_16x16x32_bf16 v[36:39], v[160:163], v[194:197], v[36:39]
	v_mfma_f32_16x16x32_bf16 v[32:35], v[178:181], v[194:197], v[32:35]
	v_mfma_f32_16x16x32_bf16 v[20:23], v[160:163], v[202:205], v[20:23]
	v_mfma_f32_16x16x32_bf16 v[16:19], v[178:181], v[202:205], v[16:19]
	v_mfma_f32_16x16x32_bf16 v[4:7], v[160:163], v[210:213], v[4:7]
	v_mfma_f32_16x16x32_bf16 v[0:3], v[178:181], v[210:213], v[0:3]
	v_mfma_f32_16x16x32_bf16 v[52:55], v[174:177], v[190:193], v[52:55]
	v_mfma_f32_16x16x32_bf16 v[48:51], v[182:185], v[190:193], v[48:51]
	v_mfma_f32_16x16x32_bf16 v[36:39], v[174:177], v[198:201], v[36:39]
	v_mfma_f32_16x16x32_bf16 v[32:35], v[182:185], v[198:201], v[32:35]
	v_mfma_f32_16x16x32_bf16 v[20:23], v[174:177], v[206:209], v[20:23]
	v_mfma_f32_16x16x32_bf16 v[16:19], v[182:185], v[206:209], v[16:19]
	v_mfma_f32_16x16x32_bf16 v[4:7], v[174:177], v[218:221], v[4:7]
	v_mfma_f32_16x16x32_bf16 v[0:3], v[182:185], v[218:221], v[0:3]
	s_setprio 0
	s_barrier
	s_add_i32 s68, s68, 2
	s_add_u32 s50, s50, 0x100
	s_addc_u32 s51, s51, 0
	s_add_u32 s85, s85, 0x100
	s_addc_u32 s86, s86, 0
	s_cmp_gt_u32 s68, 13
	s_cbranch_scc0 .LBB0_480
	s_nop 0
	s_nop 0
	s_nop 0
	s_nop 0
	s_nop 0
	s_nop 0
	s_nop 0
	s_nop 0
	s_and_b64 vcc, exec, s[14:15]
	s_cbranch_vccz .LBB0_483
	s_barrier

; #define PG8_STAGE(bufoff, gbase, voff) do { _Pragma("unroll") for (int _i = 0; _i < 2; ++_i) \
;         __builtin_amdgcn_global_load_lds((const unsigned*)((const char*)(gbase) + (voff)[_i]), (PG8_LAS unsigned*)(lds + (bufoff) + ldsw + _i * 8192), 16, 0, 0); } while (0)
; #define PG8_LDA(dst, b, h) do { _Pragma("unroll") for (int m = 0; m < 4; ++m) _Pragma("unroll") for (int k = 0; k < 2; ++k) dst[m][k] = *(const PG8_LAS bf16x8*)(lds + PG8_SA(b, h) + aoff + m * 2048 + k * 1024); } while (0)
; #define PG8_LDB(dst, b, h) do { _Pragma("unroll") for (int n = 0; n < 2; ++n) _Pragma("unroll") for (int k = 0; k < 2; ++k) dst[n][k] = *(const PG8_LAS bf16x8*)(lds + PG8_SB(b, h) + boff + n * 2048 + k * 1024); } while (0)
; #define PG8_MMA(ai, bj, At, Bt) do { __builtin_amdgcn_s_setprio(1); _Pragma("unroll") for (int m = 0; m < 4; ++m) _Pragma("unroll") for (int n = 0; n < 2; ++n) _Pragma("unroll") for (int k = 0; k < 2; ++k) \
;         acc[ai][bj][m][n] = __builtin_amdgcn_mfma_f32_16x16x32_bf16(Bt[n][k], At[m][k], acc[ai][bj][m][n], 0, 0, 0); __builtin_amdgcn_s_setprio(0); } while (0)
; #define PG8_WAIT_V(n) asm volatile("s_waitcnt vmcnt(" #n ")" ::: "memory")
; #define PG8_WAIT_L(n) asm volatile("s_waitcnt lgkmcnt(" #n ")" ::: "memory")
; #define PG8_BAR __builtin_amdgcn_s_barrier()
; #define PG8_SCHED __builtin_amdgcn_sched_barrier(0)
; template <class Epi, class Sched, bool ALIGN_EPI = false, bool SP2 = false>
; __device__ __forceinline__ void gemm_phase(PG8_LAS unsigned char* lds, const Gemm g, const Sched& S, const Epi& E, int wave0) {
;     ...
;             PG8_LDB(B0, 0, 0); PG8_LDB(B1, 0, 1); PG8_SCHED; PG8_LDA(At, 0, 0); PG8_STAGE(PG8_SA(1, 1), a1 + hstep, voffA);
;             PG8_WAIT_V(8); PG8_WAIT_L(0); PG8_BAR; PG8_MMA(0, 0, At, B0); PG8_MMA(0, 1, At, B1); PG8_BAR; PG8_SCHED;
;             PG8_LDA(At, 0, 1); PG8_STAGE(PG8_SB(0, 0), b2, voffB); PG8_STAGE(PG8_SB(0, 1), b2 + hstep, voffB); PG8_STAGE(PG8_SA(0, 0), a2, voffA);
;             PG8_WAIT_V(8); PG8_WAIT_L(0); PG8_BAR; if (!cur.half) { PG8_MMA(1, 0, At, B0); PG8_MMA(1, 1, At, B1); } PG8_BAR; PG8_SCHED;
.LBB0_705:
	ds_read_b128 v[128:131], v165
	ds_read_b128 v[132:135], v165 offset:1024
	ds_read_b128 v[152:155], v165 offset:2048
	ds_read_b128 v[156:159], v165 offset:3072
	ds_read_b128 v[170:173], v166
	ds_read_b128 v[174:177], v166 offset:1024
	ds_read_b128 v[178:181], v166 offset:2048
	ds_read_b128 v[182:185], v166 offset:3072
	s_add_u32 s36, s2, 0xfffe0080
	s_addc_u32 s37, s3, -1
	s_cmp_eq_u32 s55, 4
	s_cselect_b32 s39, s1, s37
	s_cselect_b32 s38, s29, s36
	s_cselect_b32 s37, s21, s54
	s_cselect_b32 s36, s52, s53
	v_lshl_add_u64 v[160:161], s[2:3], 0, v[144:145]
	s_add_i32 m0, s5, 0xc000
	ds_read_b128 v[186:189], v167
	ds_read_b128 v[190:193], v167 offset:1024
	ds_read_b128 v[194:197], v167 offset:2048
	ds_read_b128 v[198:201], v167 offset:3072
	ds_read_b128 v[202:205], v167 offset:4096
	ds_read_b128 v[206:209], v167 offset:5120
	ds_read_b128 v[210:213], v167 offset:6144
	ds_read_b128 v[218:221], v167 offset:7168
	global_load_lds_dwordx4 v[160:161], off
	v_lshl_add_u64 v[160:161], s[2:3], 0, v[146:147]
	s_add_i32 m0, s5, 0xe000
	s_nop 0
	global_load_lds_dwordx4 v[160:161], off
	s_waitcnt vmcnt(8)
	s_waitcnt lgkmcnt(0)
	s_barrier
	s_setprio 1
	s_waitcnt lgkmcnt(0)
	v_mfma_f32_16x16x32_bf16 v[124:127], v[128:131], v[186:189], v[124:127]
	v_mfma_f32_16x16x32_bf16 v[120:123], v[152:155], v[186:189], v[120:123]
	v_mfma_f32_16x16x32_bf16 v[108:111], v[128:131], v[194:197], v[108:111]
	v_mfma_f32_16x16x32_bf16 v[104:107], v[152:155], v[194:197], v[104:107]
	v_mfma_f32_16x16x32_bf16 v[92:95], v[128:131], v[202:205], v[92:95]
	v_mfma_f32_16x16x32_bf16 v[88:91], v[152:155], v[202:205], v[88:91]
	v_mfma_f32_16x16x32_bf16 v[76:79], v[128:131], v[210:213], v[76:79]
	v_mfma_f32_16x16x32_bf16 v[72:75], v[152:155], v[210:213], v[72:75]
	v_mfma_f32_16x16x32_bf16 v[124:127], v[132:135], v[190:193], v[124:127]
	v_mfma_f32_16x16x32_bf16 v[120:123], v[156:159], v[190:193], v[120:123]
	v_mfma_f32_16x16x32_bf16 v[108:111], v[132:135], v[198:201], v[108:111]
	v_mfma_f32_16x16x32_bf16 v[104:107], v[156:159], v[198:201], v[104:107]
	v_mfma_f32_16x16x32_bf16 v[92:95], v[132:135], v[206:209], v[92:95]
	v_mfma_f32_16x16x32_bf16 v[88:91], v[156:159], v[206:209], v[88:91]
	v_mfma_f32_16x16x32_bf16 v[76:79], v[132:135], v[218:221], v[76:79]
	v_mfma_f32_16x16x32_bf16 v[72:75], v[156:159], v[218:221], v[72:75]
	v_mfma_f32_16x16x32_bf16 v[116:119], v[170:173], v[186:189], v[116:119]
	v_mfma_f32_16x16x32_bf16 v[112:115], v[178:181], v[186:189], v[112:115]
	v_mfma_f32_16x16x32_bf16 v[100:103], v[170:173], v[194:197], v[100:103]
	v_mfma_f32_16x16x32_bf16 v[96:99], v[178:181], v[194:197], v[96:99]
	v_mfma_f32_16x16x32_bf16 v[84:87], v[170:173], v[202:205], v[84:87]
	v_mfma_f32_16x16x32_bf16 v[80:83], v[178:181], v[202:205], v[80:83]
	v_mfma_f32_16x16x32_bf16 v[68:71], v[170:173], v[210:213], v[68:71]
	v_mfma_f32_16x16x32_bf16 v[64:67], v[178:181], v[210:213], v[64:67]
	v_mfma_f32_16x16x32_bf16 v[116:119], v[174:177], v[190:193], v[116:119]
	v_mfma_f32_16x16x32_bf16 v[112:115], v[182:185], v[190:193], v[112:115]
	v_mfma_f32_16x16x32_bf16 v[100:103], v[174:177], v[198:201], v[100:103]
	v_mfma_f32_16x16x32_bf16 v[96:99], v[182:185], v[198:201], v[96:99]
	v_mfma_f32_16x16x32_bf16 v[84:87], v[174:177], v[206:209], v[84:87]
	v_mfma_f32_16x16x32_bf16 v[80:83], v[182:185], v[206:209], v[80:83]
	v_mfma_f32_16x16x32_bf16 v[68:71], v[174:177], v[218:221], v[68:71]
	v_mfma_f32_16x16x32_bf16 v[64:67], v[182:185], v[218:221], v[64:67]
	s_setprio 0
	s_barrier
	s_add_i32 s56, s48, s4
	v_lshl_add_u64 v[160:161], s[36:37], 0, v[138:139]
	s_mov_b32 m0, s56
	ds_read_b128 v[186:189], v167 offset:16384
	ds_read_b128 v[190:193], v167 offset:17408
	ds_read_b128 v[194:197], v167 offset:18432
	ds_read_b128 v[198:201], v167 offset:19456
	ds_read_b128 v[202:205], v167 offset:20480
	ds_read_b128 v[206:209], v167 offset:21504
	ds_read_b128 v[210:213], v167 offset:22528
	ds_read_b128 v[218:221], v167 offset:23552
	global_load_lds_dwordx4 v[160:161], off
	s_add_i32 m0, s56, 0x2000
	s_add_u32 s56, s36, 0x20000
	v_lshl_add_u64 v[214:215], s[36:37], 0, v[142:143]
	s_addc_u32 s57, s37, 0
	s_add_i32 s62, s49, s4
	global_load_lds_dwordx4 v[214:215], off
	v_lshl_add_u64 v[222:223], s[56:57], 0, v[138:139]
	s_mov_b32 m0, s62
	v_lshl_add_u64 v[224:225], s[38:39], 0, v[140:141]
	global_load_lds_dwordx4 v[222:223], off
	v_lshl_add_u64 v[222:223], s[56:57], 0, v[142:143]
	s_add_i32 m0, s62, 0x2000
	s_nop 0
	global_load_lds_dwordx4 v[222:223], off
	v_lshl_add_u64 v[222:223], s[38:39], 0, v[136:137]
	s_mov_b32 m0, s5
	s_nop 0
	global_load_lds_dwordx4 v[222:223], off
	s_mov_b32 m0, s6
	s_nop 0
	global_load_lds_dwordx4 v[224:225], off
	s_waitcnt vmcnt(8)
	s_waitcnt lgkmcnt(0)
	s_barrier
; #define PG8_STAGE(bufoff, gbase, voff) do { _Pragma("unroll") for (int _i = 0; _i < 2; ++_i) \
;         __builtin_amdgcn_global_load_lds((const unsigned*)((const char*)(gbase) + (voff)[_i]), (PG8_LAS unsigned*)(lds + (bufoff) + ldsw + _i * 8192), 16, 0, 0); } while (0)
; #define PG8_LDA(dst, b, h) do { _Pragma("unroll") for (int m = 0; m < 4; ++m) _Pragma("unroll") for (int k = 0; k < 2; ++k) dst[m][k] = *(const PG8_LAS bf16x8*)(lds + PG8_SA(b, h) + aoff + m * 2048 + k * 1024); } while (0)
; #define PG8_LDB(dst, b, h) do { _Pragma("unroll") for (int n = 0; n < 2; ++n) _Pragma("unroll") for (int k = 0; k < 2; ++k) dst[n][k] = *(const PG8_LAS bf16x8*)(lds + PG8_SB(b, h) + boff + n * 2048 + k * 1024); } while (0)
; #define PG8_MMA(ai, bj, At, Bt) do { __builtin_amdgcn_s_setprio(1); _Pragma("unroll") for (int m = 0; m < 4; ++m) _Pragma("unroll") for (int n = 0; n < 2; ++n) _Pragma("unroll") for (int k = 0; k < 2; ++k) \
;         acc[ai][bj][m][n] = __builtin_amdgcn_mfma_f32_16x16x32_bf16(Bt[n][k], At[m][k], acc[ai][bj][m][n], 0, 0, 0); __builtin_amdgcn_s_setprio(0); } while (0)
; #define PG8_WAIT_V(n) asm volatile("s_waitcnt vmcnt(" #n ")" ::: "memory")
; #define PG8_WAIT_L(n) asm volatile("s_waitcnt lgkmcnt(" #n ")" ::: "memory")
; #define PG8_BAR __builtin_amdgcn_s_barrier()
; #define PG8_SCHED __builtin_amdgcn_sched_barrier(0)
; template <class Epi, class Sched, bool ALIGN_EPI = false, bool SP2 = false>
; __device__ __forceinline__ void gemm_phase(PG8_LAS unsigned char* lds, const Gemm g, const Sched& S, const Epi& E, int wave0) {
;     ...
;             PG8_WAIT_V(8); PG8_WAIT_L(0); PG8_BAR; if (!cur.half) { PG8_MMA(1, 0, At, B0); PG8_MMA(1, 1, At, B1); } PG8_BAR; PG8_SCHED;
;             PG8_LDB(B0, 1, 0); PG8_LDB(B1, 1, 1); PG8_SCHED; PG8_LDA(At, 1, 0); PG8_STAGE(PG8_SA(0, 1), a2 + hstep, voffA);
;             PG8_WAIT_V(8); PG8_WAIT_L(0); PG8_BAR; PG8_MMA(0, 0, At, B0); PG8_MMA(0, 1, At, B1); PG8_BAR; PG8_SCHED;
	s_setprio 1
	s_waitcnt lgkmcnt(0)
	v_mfma_f32_16x16x32_bf16 v[60:63], v[128:131], v[186:189], v[60:63]
	v_mfma_f32_16x16x32_bf16 v[56:59], v[152:155], v[186:189], v[56:59]
	v_mfma_f32_16x16x32_bf16 v[44:47], v[128:131], v[194:197], v[44:47]
	v_mfma_f32_16x16x32_bf16 v[40:43], v[152:155], v[194:197], v[40:43]
	v_mfma_f32_16x16x32_bf16 v[28:31], v[128:131], v[202:205], v[28:31]
	v_mfma_f32_16x16x32_bf16 v[24:27], v[152:155], v[202:205], v[24:27]
	v_mfma_f32_16x16x32_bf16 v[12:15], v[128:131], v[210:213], v[12:15]
	v_mfma_f32_16x16x32_bf16 v[8:11], v[152:155], v[210:213], v[8:11]
	v_mfma_f32_16x16x32_bf16 v[60:63], v[132:135], v[190:193], v[60:63]
	v_mfma_f32_16x16x32_bf16 v[56:59], v[156:159], v[190:193], v[56:59]
	v_mfma_f32_16x16x32_bf16 v[44:47], v[132:135], v[198:201], v[44:47]
	v_mfma_f32_16x16x32_bf16 v[40:43], v[156:159], v[198:201], v[40:43]
	v_mfma_f32_16x16x32_bf16 v[28:31], v[132:135], v[206:209], v[28:31]
	v_mfma_f32_16x16x32_bf16 v[24:27], v[156:159], v[206:209], v[24:27]
	v_mfma_f32_16x16x32_bf16 v[12:15], v[132:135], v[218:221], v[12:15]
	v_mfma_f32_16x16x32_bf16 v[8:11], v[156:159], v[218:221], v[8:11]
	v_mfma_f32_16x16x32_bf16 v[52:55], v[170:173], v[186:189], v[52:55]
	v_mfma_f32_16x16x32_bf16 v[48:51], v[178:181], v[186:189], v[48:51]
	v_mfma_f32_16x16x32_bf16 v[36:39], v[170:173], v[194:197], v[36:39]
	v_mfma_f32_16x16x32_bf16 v[32:35], v[178:181], v[194:197], v[32:35]
	v_mfma_f32_16x16x32_bf16 v[20:23], v[170:173], v[202:205], v[20:23]
	v_mfma_f32_16x16x32_bf16 v[16:19], v[178:181], v[202:205], v[16:19]
	v_mfma_f32_16x16x32_bf16 v[4:7], v[170:173], v[210:213], v[4:7]
	v_mfma_f32_16x16x32_bf16 v[0:3], v[178:181], v[210:213], v[0:3]
	v_mfma_f32_16x16x32_bf16 v[52:55], v[174:177], v[190:193], v[52:55]
	v_mfma_f32_16x16x32_bf16 v[48:51], v[182:185], v[190:193], v[48:51]
	v_mfma_f32_16x16x32_bf16 v[36:39], v[174:177], v[198:201], v[36:39]
	v_mfma_f32_16x16x32_bf16 v[32:35], v[182:185], v[198:201], v[32:35]
	v_mfma_f32_16x16x32_bf16 v[20:23], v[174:177], v[206:209], v[20:23]
	v_mfma_f32_16x16x32_bf16 v[16:19], v[182:185], v[206:209], v[16:19]
	v_mfma_f32_16x16x32_bf16 v[4:7], v[174:177], v[218:221], v[4:7]
	v_mfma_f32_16x16x32_bf16 v[0:3], v[182:185], v[218:221], v[0:3]
	s_setprio 0
	s_barrier
	s_add_i32 s56, 0, 0x18000
	s_add_i32 s57, 0, 0x1c000
	v_add_u32_e32 v156, s56, v164
	v_add_u32_e32 v169, s57, v164
	ds_read_b128 v[128:131], v156
	ds_read_b128 v[132:135], v156 offset:1024
	ds_read_b128 v[152:155], v156 offset:2048
	ds_read_b128 v[156:159], v156 offset:3072
	ds_read_b128 v[170:173], v169
	ds_read_b128 v[174:177], v169 offset:1024
	ds_read_b128 v[178:181], v169 offset:2048
	ds_read_b128 v[182:185], v169 offset:3072
	s_add_u32 s38, s38, 0x20000
	s_addc_u32 s39, s39, 0
	s_mov_b32 m0, s7
	v_lshl_add_u64 v[226:227], s[38:39], 0, v[136:137]
	ds_read_b128 v[186:189], v167 offset:32768
	ds_read_b128 v[190:193], v167 offset:33792
	ds_read_b128 v[194:197], v167 offset:34816
	ds_read_b128 v[198:201], v167 offset:35840
	ds_read_b128 v[202:205], v167 offset:36864
	ds_read_b128 v[206:209], v167 offset:37888
	ds_read_b128 v[210:213], v167 offset:38912
	ds_read_b128 v[218:221], v167 offset:39936
	global_load_lds_dwordx4 v[226:227], off
	v_lshl_add_u64 v[226:227], s[38:39], 0, v[140:141]
	s_mov_b32 m0, s33
	s_nop 0
	global_load_lds_dwordx4 v[226:227], off
	s_waitcnt vmcnt(8)
	s_waitcnt lgkmcnt(0)
	s_barrier
	s_setprio 1
	s_waitcnt lgkmcnt(0)
	v_mfma_f32_16x16x32_bf16 v[124:127], v[128:131], v[186:189], v[124:127]
	v_mfma_f32_16x16x32_bf16 v[120:123], v[152:155], v[186:189], v[120:123]
	v_mfma_f32_16x16x32_bf16 v[108:111], v[128:131], v[194:197], v[108:111]
	v_mfma_f32_16x16x32_bf16 v[104:107], v[152:155], v[194:197], v[104:107]
	v_mfma_f32_16x16x32_bf16 v[92:95], v[128:131], v[202:205], v[92:95]
	v_mfma_f32_16x16x32_bf16 v[88:91], v[152:155], v[202:205], v[88:91]
	v_mfma_f32_16x16x32_bf16 v[76:79], v[128:131], v[210:213], v[76:79]
	v_mfma_f32_16x16x32_bf16 v[72:75], v[152:155], v[210:213], v[72:75]
	v_mfma_f32_16x16x32_bf16 v[124:127], v[132:135], v[190:193], v[124:127]
	v_mfma_f32_16x16x32_bf16 v[120:123], v[156:159], v[190:193], v[120:123]
	v_mfma_f32_16x16x32_bf16 v[108:111], v[132:135], v[198:201], v[108:111]
	v_mfma_f32_16x16x32_bf16 v[104:107], v[156:159], v[198:201], v[104:107]
	v_mfma_f32_16x16x32_bf16 v[92:95], v[132:135], v[206:209], v[92:95]
	v_mfma_f32_16x16x32_bf16 v[88:91], v[156:159], v[206:209], v[88:91]
	v_mfma_f32_16x16x32_bf16 v[76:79], v[132:135], v[218:221], v[76:79]
	v_mfma_f32_16x16x32_bf16 v[72:75], v[156:159], v[218:221], v[72:75]
	v_mfma_f32_16x16x32_bf16 v[116:119], v[170:173], v[186:189], v[116:119]
	v_mfma_f32_16x16x32_bf16 v[112:115], v[178:181], v[186:189], v[112:115]
	v_mfma_f32_16x16x32_bf16 v[100:103], v[170:173], v[194:197], v[100:103]
	v_mfma_f32_16x16x32_bf16 v[96:99], v[178:181], v[194:197], v[96:99]
	v_mfma_f32_16x16x32_bf16 v[84:87], v[170:173], v[202:205], v[84:87]
	v_mfma_f32_16x16x32_bf16 v[80:83], v[178:181], v[202:205], v[80:83]
	v_mfma_f32_16x16x32_bf16 v[68:71], v[170:173], v[210:213], v[68:71]
	v_mfma_f32_16x16x32_bf16 v[64:67], v[178:181], v[210:213], v[64:67]
	v_mfma_f32_16x16x32_bf16 v[116:119], v[174:177], v[190:193], v[116:119]
	v_mfma_f32_16x16x32_bf16 v[112:115], v[182:185], v[190:193], v[112:115]
	v_mfma_f32_16x16x32_bf16 v[100:103], v[174:177], v[198:201], v[100:103]
	v_mfma_f32_16x16x32_bf16 v[96:99], v[182:185], v[198:201], v[96:99]
	v_mfma_f32_16x16x32_bf16 v[84:87], v[174:177], v[206:209], v[84:87]
	v_mfma_f32_16x16x32_bf16 v[80:83], v[182:185], v[206:209], v[80:83]
	v_mfma_f32_16x16x32_bf16 v[68:71], v[174:177], v[218:221], v[68:71]
	v_mfma_f32_16x16x32_bf16 v[64:67], v[182:185], v[218:221], v[64:67]
	s_setprio 0
	s_barrier
; #define PG8_STAGE(bufoff, gbase, voff) do { _Pragma("unroll") for (int _i = 0; _i < 2; ++_i) \
;         __builtin_amdgcn_global_load_lds((const unsigned*)((const char*)(gbase) + (voff)[_i]), (PG8_LAS unsigned*)(lds + (bufoff) + ldsw + _i * 8192), 16, 0, 0); } while (0)
; #define PG8_LDA(dst, b, h) do { _Pragma("unroll") for (int m = 0; m < 4; ++m) _Pragma("unroll") for (int k = 0; k < 2; ++k) dst[m][k] = *(const PG8_LAS bf16x8*)(lds + PG8_SA(b, h) + aoff + m * 2048 + k * 1024); } while (0)
; #define PG8_MMA(ai, bj, At, Bt) do { __builtin_amdgcn_s_setprio(1); _Pragma("unroll") for (int m = 0; m < 4; ++m) _Pragma("unroll") for (int n = 0; n < 2; ++n) _Pragma("unroll") for (int k = 0; k < 2; ++k) \
;         acc[ai][bj][m][n] = __builtin_amdgcn_mfma_f32_16x16x32_bf16(Bt[n][k], At[m][k], acc[ai][bj][m][n], 0, 0, 0); __builtin_amdgcn_s_setprio(0); } while (0)
; #define PG8_WAIT_V(n) asm volatile("s_waitcnt vmcnt(" #n ")" ::: "memory")
; #define PG8_WAIT_L(n) asm volatile("s_waitcnt lgkmcnt(" #n ")" ::: "memory")
; #define PG8_BAR __builtin_amdgcn_s_barrier()
; #define PG8_SCHED __builtin_amdgcn_sched_barrier(0)
; template <class Epi, class Sched, bool ALIGN_EPI = false, bool SP2 = false>
; __device__ __forceinline__ void gemm_phase(PG8_LAS unsigned char* lds, const Gemm g, const Sched& S, const Epi& E, int wave0) {
;     ...
;         for (int t = 0; t < nt; t += 2) {
;             const bool last = (t == nt - 2);
;             const char* a1 = cA + (size_t)(t + 1) * kstep;
;             const char* a2 = last ? nA : cA + (size_t)(t + 2) * kstep; const char* b2 = last ? nB : cB + (size_t)(t + 2) * kstep;
;     ...
;             PG8_LDA(At, 1, 1); PG8_STAGE(PG8_SB(1, 0), b3, voffB); PG8_STAGE(PG8_SB(1, 1), b3 + hstep, voffB); PG8_STAGE(PG8_SA(1, 0), a3, voffA);
;             PG8_WAIT_V(8); PG8_WAIT_L(0); PG8_BAR; if (!cur.half) { PG8_MMA(1, 0, At, B0); PG8_MMA(1, 1, At, B1); } PG8_BAR; PG8_SCHED;
	s_add_i32 s38, s56, s4
	v_lshl_add_u64 v[160:161], v[160:161], 0, s[16:17]
	s_mov_b32 m0, s38
	ds_read_b128 v[186:189], v167 offset:49152
	ds_read_b128 v[190:193], v167 offset:50176
	ds_read_b128 v[194:197], v167 offset:51200
	ds_read_b128 v[198:201], v167 offset:52224
	ds_read_b128 v[202:205], v167 offset:53248
	ds_read_b128 v[206:209], v167 offset:54272
	ds_read_b128 v[210:213], v167 offset:55296
	ds_read_b128 v[218:221], v167 offset:56320
	global_load_lds_dwordx4 v[160:161], off
	s_add_i32 m0, s38, 0x2000
	s_add_u32 s36, s36, 0x20080
	v_lshl_add_u64 v[160:161], v[214:215], 0, s[16:17]
	s_addc_u32 s37, s37, 0
	s_add_i32 s38, s57, s4
	global_load_lds_dwordx4 v[160:161], off
	v_lshl_add_u64 v[160:161], s[36:37], 0, v[138:139]
	s_mov_b32 m0, s38
	s_nop 0
	global_load_lds_dwordx4 v[160:161], off
	v_lshl_add_u64 v[160:161], s[36:37], 0, v[142:143]
	s_add_i32 m0, s38, 0x2000
	s_nop 0
	global_load_lds_dwordx4 v[160:161], off
	v_lshl_add_u64 v[160:161], v[222:223], 0, s[16:17]
	s_mov_b32 m0, s43
	s_nop 0
	global_load_lds_dwordx4 v[160:161], off
	v_lshl_add_u64 v[160:161], v[224:225], 0, s[16:17]
	s_mov_b32 m0, s44
	s_nop 0
	global_load_lds_dwordx4 v[160:161], off
	s_waitcnt vmcnt(8)
	s_waitcnt lgkmcnt(0)
	s_barrier
	s_setprio 1
	s_waitcnt lgkmcnt(0)
	v_mfma_f32_16x16x32_bf16 v[60:63], v[128:131], v[186:189], v[60:63]
	v_mfma_f32_16x16x32_bf16 v[56:59], v[152:155], v[186:189], v[56:59]
	v_mfma_f32_16x16x32_bf16 v[44:47], v[128:131], v[194:197], v[44:47]
	v_mfma_f32_16x16x32_bf16 v[40:43], v[152:155], v[194:197], v[40:43]
	v_mfma_f32_16x16x32_bf16 v[28:31], v[128:131], v[202:205], v[28:31]
	v_mfma_f32_16x16x32_bf16 v[24:27], v[152:155], v[202:205], v[24:27]
	v_mfma_f32_16x16x32_bf16 v[12:15], v[128:131], v[210:213], v[12:15]
	v_mfma_f32_16x16x32_bf16 v[8:11], v[152:155], v[210:213], v[8:11]
	v_mfma_f32_16x16x32_bf16 v[60:63], v[132:135], v[190:193], v[60:63]
	v_mfma_f32_16x16x32_bf16 v[56:59], v[156:159], v[190:193], v[56:59]
	v_mfma_f32_16x16x32_bf16 v[44:47], v[132:135], v[198:201], v[44:47]
	v_mfma_f32_16x16x32_bf16 v[40:43], v[156:159], v[198:201], v[40:43]
	v_mfma_f32_16x16x32_bf16 v[28:31], v[132:135], v[206:209], v[28:31]
	v_mfma_f32_16x16x32_bf16 v[24:27], v[156:159], v[206:209], v[24:27]
	v_mfma_f32_16x16x32_bf16 v[12:15], v[132:135], v[218:221], v[12:15]
	v_mfma_f32_16x16x32_bf16 v[8:11], v[156:159], v[218:221], v[8:11]
	v_mfma_f32_16x16x32_bf16 v[52:55], v[170:173], v[186:189], v[52:55]
	v_mfma_f32_16x16x32_bf16 v[48:51], v[178:181], v[186:189], v[48:51]
	v_mfma_f32_16x16x32_bf16 v[36:39], v[170:173], v[194:197], v[36:39]
	v_mfma_f32_16x16x32_bf16 v[32:35], v[178:181], v[194:197], v[32:35]
	v_mfma_f32_16x16x32_bf16 v[20:23], v[170:173], v[202:205], v[20:23]
	v_mfma_f32_16x16x32_bf16 v[16:19], v[178:181], v[202:205], v[16:19]
	v_mfma_f32_16x16x32_bf16 v[4:7], v[170:173], v[210:213], v[4:7]
	v_mfma_f32_16x16x32_bf16 v[0:3], v[178:181], v[210:213], v[0:3]
	v_mfma_f32_16x16x32_bf16 v[52:55], v[174:177], v[190:193], v[52:55]
	v_mfma_f32_16x16x32_bf16 v[48:51], v[182:185], v[190:193], v[48:51]
	v_mfma_f32_16x16x32_bf16 v[36:39], v[174:177], v[198:201], v[36:39]
	v_mfma_f32_16x16x32_bf16 v[32:35], v[182:185], v[198:201], v[32:35]
	v_mfma_f32_16x16x32_bf16 v[20:23], v[174:177], v[206:209], v[20:23]
	v_mfma_f32_16x16x32_bf16 v[16:19], v[182:185], v[206:209], v[16:19]
	v_mfma_f32_16x16x32_bf16 v[4:7], v[174:177], v[218:221], v[4:7]
	v_mfma_f32_16x16x32_bf16 v[0:3], v[182:185], v[218:221], v[0:3]
	s_setprio 0
	s_barrier
	s_add_i32 s55, s55, 2
	s_add_u32 s2, s2, 0x100
	s_addc_u32 s3, s3, 0
	s_add_u32 s53, s53, 0x100
	s_addc_u32 s54, s54, 0
	s_cmp_gt_u32 s55, 5
	s_cbranch_scc0 .LBB0_705
	s_nop 0
	s_nop 0
	s_nop 0
	s_nop 0
	s_nop 0
	s_nop 0
	s_nop 0
	s_nop 0
	s_and_b64 vcc, exec, s[18:19]
	s_cbranch_vccz .LBB0_708
	s_barrier

; #define PG8_STAGE(bufoff, gbase, voff) do { _Pragma("unroll") for (int _i = 0; _i < 2; ++_i) \
;         __builtin_amdgcn_global_load_lds((const unsigned*)((const char*)(gbase) + (voff)[_i]), (PG8_LAS unsigned*)(lds + (bufoff) + ldsw + _i * 8192), 16, 0, 0); } while (0)
; #define PG8_LDA(dst, b, h) do { _Pragma("unroll") for (int m = 0; m < 4; ++m) _Pragma("unroll") for (int k = 0; k < 2; ++k) dst[m][k] = *(const PG8_LAS bf16x8*)(lds + PG8_SA(b, h) + aoff + m * 2048 + k * 1024); } while (0)
; #define PG8_LDB(dst, b, h) do { _Pragma("unroll") for (int n = 0; n < 2; ++n) _Pragma("unroll") for (int k = 0; k < 2; ++k) dst[n][k] = *(const PG8_LAS bf16x8*)(lds + PG8_SB(b, h) + boff + n * 2048 + k * 1024); } while (0)
; #define PG8_MMA(ai, bj, At, Bt) do { __builtin_amdgcn_s_setprio(1); _Pragma("unroll") for (int m = 0; m < 4; ++m) _Pragma("unroll") for (int n = 0; n < 2; ++n) _Pragma("unroll") for (int k = 0; k < 2; ++k) \
;         acc[ai][bj][m][n] = __builtin_amdgcn_mfma_f32_16x16x32_bf16(Bt[n][k], At[m][k], acc[ai][bj][m][n], 0, 0, 0); __builtin_amdgcn_s_setprio(0); } while (0)
; #define PG8_WAIT_V(n) asm volatile("s_waitcnt vmcnt(" #n ")" ::: "memory")
; #define PG8_WAIT_L(n) asm volatile("s_waitcnt lgkmcnt(" #n ")" ::: "memory")
; #define PG8_BAR __builtin_amdgcn_s_barrier()
; #define PG8_SCHED __builtin_amdgcn_sched_barrier(0)
; template <class Epi, class Sched, bool ALIGN_EPI = false, bool SP2 = false>
; __device__ __forceinline__ void gemm_phase(PG8_LAS unsigned char* lds, const Gemm g, const Sched& S, const Epi& E, int wave0) {
;     ...
;             PG8_LDB(B0, 0, 0); PG8_LDB(B1, 0, 1); PG8_SCHED; PG8_LDA(At, 0, 0); PG8_STAGE(PG8_SA(1, 1), a1 + hstep, voffA);
;             PG8_WAIT_V(8); PG8_WAIT_L(0); PG8_BAR; PG8_MMA(0, 0, At, B0); PG8_MMA(0, 1, At, B1); PG8_BAR; PG8_SCHED;
;             PG8_LDA(At, 0, 1); PG8_STAGE(PG8_SB(0, 0), b2, voffB); PG8_STAGE(PG8_SB(0, 1), b2 + hstep, voffB); PG8_STAGE(PG8_SA(0, 0), a2, voffA);
;             PG8_WAIT_V(8); PG8_WAIT_L(0); PG8_BAR; if (!cur.half) { PG8_MMA(1, 0, At, B0); PG8_MMA(1, 1, At, B1); } PG8_BAR; PG8_SCHED;
.LBB0_822:
	ds_read_b128 v[148:151], v221
	ds_read_b128 v[152:155], v221 offset:1024
	ds_read_b128 v[156:159], v221 offset:2048
	ds_read_b128 v[160:163], v221 offset:3072
	ds_read_b128 v[132:135], v222
	ds_read_b128 v[136:139], v222 offset:1024
	ds_read_b128 v[140:143], v222 offset:2048
	ds_read_b128 v[144:147], v222 offset:3072
	s_add_u32 s8, s42, 0xfffc0080
	s_addc_u32 s9, s43, -1
	s_cmp_eq_u32 s85, 12
	s_cselect_b32 s47, s1, s9
	s_cselect_b32 s46, s29, s8
	s_cselect_b32 s45, s21, s69
	s_cselect_b32 s44, s39, s68
	v_lshl_add_u64 v[2:3], s[42:43], 0, v[204:205]
	s_add_i32 m0, s7, 0xc000
	s_waitcnt lgkmcnt(0)
	ds_read_b128 v[164:167], v223
	ds_read_b128 v[168:171], v223 offset:1024
	ds_read_b128 v[172:175], v223 offset:2048
	ds_read_b128 v[176:179], v223 offset:3072
	ds_read_b128 v[180:183], v223 offset:4096
	ds_read_b128 v[184:187], v223 offset:5120
	ds_read_b128 v[188:191], v223 offset:6144
	ds_read_b128 v[192:195], v223 offset:7168
	global_load_lds_dwordx4 v[2:3], off
	v_lshl_add_u64 v[2:3], s[42:43], 0, v[206:207]
	s_add_i32 m0, s7, 0xe000
	s_nop 0
	global_load_lds_dwordx4 v[2:3], off
	s_waitcnt vmcnt(8)
	s_waitcnt lgkmcnt(0)
	s_barrier
	s_setprio 1
	s_waitcnt lgkmcnt(0)
	v_mfma_f32_16x16x32_bf16 v[128:131], v[148:151], v[164:167], v[128:131]
	v_mfma_f32_16x16x32_bf16 v[124:127], v[156:159], v[164:167], v[124:127]
	v_mfma_f32_16x16x32_bf16 v[112:115], v[148:151], v[172:175], v[112:115]
	v_mfma_f32_16x16x32_bf16 v[108:111], v[156:159], v[172:175], v[108:111]
	v_mfma_f32_16x16x32_bf16 v[96:99], v[148:151], v[180:183], v[96:99]
	v_mfma_f32_16x16x32_bf16 v[92:95], v[156:159], v[180:183], v[92:95]
	v_mfma_f32_16x16x32_bf16 v[80:83], v[148:151], v[188:191], v[80:83]
	v_mfma_f32_16x16x32_bf16 v[76:79], v[156:159], v[188:191], v[76:79]
	v_mfma_f32_16x16x32_bf16 v[128:131], v[152:155], v[168:171], v[128:131]
	v_mfma_f32_16x16x32_bf16 v[124:127], v[160:163], v[168:171], v[124:127]
	v_mfma_f32_16x16x32_bf16 v[112:115], v[152:155], v[176:179], v[112:115]
	v_mfma_f32_16x16x32_bf16 v[108:111], v[160:163], v[176:179], v[108:111]
	v_mfma_f32_16x16x32_bf16 v[96:99], v[152:155], v[184:187], v[96:99]
	v_mfma_f32_16x16x32_bf16 v[92:95], v[160:163], v[184:187], v[92:95]
	v_mfma_f32_16x16x32_bf16 v[80:83], v[152:155], v[192:195], v[80:83]
	v_mfma_f32_16x16x32_bf16 v[76:79], v[160:163], v[192:195], v[76:79]
	v_mfma_f32_16x16x32_bf16 v[120:123], v[132:135], v[164:167], v[120:123]
	v_mfma_f32_16x16x32_bf16 v[116:119], v[140:143], v[164:167], v[116:119]
	v_mfma_f32_16x16x32_bf16 v[104:107], v[132:135], v[172:175], v[104:107]
	v_mfma_f32_16x16x32_bf16 v[100:103], v[140:143], v[172:175], v[100:103]
	v_mfma_f32_16x16x32_bf16 v[88:91], v[132:135], v[180:183], v[88:91]
	v_mfma_f32_16x16x32_bf16 v[84:87], v[140:143], v[180:183], v[84:87]
	v_mfma_f32_16x16x32_bf16 v[72:75], v[132:135], v[188:191], v[72:75]
	v_mfma_f32_16x16x32_bf16 v[68:71], v[140:143], v[188:191], v[68:71]
	v_mfma_f32_16x16x32_bf16 v[120:123], v[136:139], v[168:171], v[120:123]
	v_mfma_f32_16x16x32_bf16 v[116:119], v[144:147], v[168:171], v[116:119]
	v_mfma_f32_16x16x32_bf16 v[104:107], v[136:139], v[176:179], v[104:107]
	v_mfma_f32_16x16x32_bf16 v[100:103], v[144:147], v[176:179], v[100:103]
	v_mfma_f32_16x16x32_bf16 v[88:91], v[136:139], v[184:187], v[88:91]
	v_mfma_f32_16x16x32_bf16 v[84:87], v[144:147], v[184:187], v[84:87]
	v_mfma_f32_16x16x32_bf16 v[72:75], v[136:139], v[192:195], v[72:75]
	v_mfma_f32_16x16x32_bf16 v[68:71], v[144:147], v[192:195], v[68:71]
	s_setprio 0
	s_barrier
	s_add_i32 s8, s55, s6
	v_lshl_add_u64 v[2:3], s[44:45], 0, v[198:199]
	s_mov_b32 m0, s8
	ds_read_b128 v[188:191], v223 offset:16384
	ds_read_b128 v[192:195], v223 offset:17408
	ds_read_b128 v[180:183], v223 offset:18432
	ds_read_b128 v[184:187], v223 offset:19456
	ds_read_b128 v[172:175], v223 offset:20480
	ds_read_b128 v[176:179], v223 offset:21504
	ds_read_b128 v[164:167], v223 offset:22528
	ds_read_b128 v[168:171], v223 offset:23552
	global_load_lds_dwordx4 v[2:3], off
	s_add_i32 m0, s8, 0x2000
	s_add_u32 s8, s44, 0x40000
	v_lshl_add_u64 v[210:211], s[44:45], 0, v[202:203]
	s_addc_u32 s9, s45, 0
	s_add_i32 s86, s56, s6
	global_load_lds_dwordx4 v[210:211], off
	v_lshl_add_u64 v[212:213], s[8:9], 0, v[198:199]
	s_mov_b32 m0, s86
	v_lshl_add_u64 v[214:215], s[46:47], 0, v[200:201]
	global_load_lds_dwordx4 v[212:213], off
	v_lshl_add_u64 v[212:213], s[8:9], 0, v[202:203]
	s_add_i32 m0, s86, 0x2000
	v_cmp_ne_u32_e64 s[8:9], 1, v225
	global_load_lds_dwordx4 v[212:213], off
	v_lshl_add_u64 v[212:213], s[46:47], 0, v[196:197]
	s_mov_b32 m0, s7
	s_andn2_b64 vcc, exec, s[40:41]
	global_load_lds_dwordx4 v[212:213], off
	s_mov_b32 m0, s33
	s_nop 0
	global_load_lds_dwordx4 v[214:215], off
	s_waitcnt vmcnt(8)
	s_waitcnt lgkmcnt(0)
	s_barrier
	s_cbranch_vccnz .LBB0_824
	s_setprio 1
	s_waitcnt lgkmcnt(0)
	v_mfma_f32_16x16x32_bf16 v[64:67], v[148:151], v[188:191], v[64:67]
	v_mfma_f32_16x16x32_bf16 v[60:63], v[156:159], v[188:191], v[60:63]
	v_mfma_f32_16x16x32_bf16 v[48:51], v[148:151], v[180:183], v[48:51]
	v_mfma_f32_16x16x32_bf16 v[44:47], v[156:159], v[180:183], v[44:47]
	v_mfma_f32_16x16x32_bf16 v[32:35], v[148:151], v[172:175], v[32:35]
	v_mfma_f32_16x16x32_bf16 v[28:31], v[156:159], v[172:175], v[28:31]
	v_mfma_f32_16x16x32_bf16 v[16:19], v[148:151], v[164:167], v[16:19]
	v_mfma_f32_16x16x32_bf16 v[12:15], v[156:159], v[164:167], v[12:15]
	v_mfma_f32_16x16x32_bf16 v[64:67], v[152:155], v[192:195], v[64:67]
	v_mfma_f32_16x16x32_bf16 v[60:63], v[160:163], v[192:195], v[60:63]
	v_mfma_f32_16x16x32_bf16 v[48:51], v[152:155], v[184:187], v[48:51]
	v_mfma_f32_16x16x32_bf16 v[44:47], v[160:163], v[184:187], v[44:47]
	v_mfma_f32_16x16x32_bf16 v[32:35], v[152:155], v[176:179], v[32:35]
	v_mfma_f32_16x16x32_bf16 v[28:31], v[160:163], v[176:179], v[28:31]
	v_mfma_f32_16x16x32_bf16 v[16:19], v[152:155], v[168:171], v[16:19]
	v_mfma_f32_16x16x32_bf16 v[12:15], v[160:163], v[168:171], v[12:15]
	v_mfma_f32_16x16x32_bf16 v[56:59], v[132:135], v[188:191], v[56:59]
	v_mfma_f32_16x16x32_bf16 v[52:55], v[140:143], v[188:191], v[52:55]
	v_mfma_f32_16x16x32_bf16 v[40:43], v[132:135], v[180:183], v[40:43]
	v_mfma_f32_16x16x32_bf16 v[36:39], v[140:143], v[180:183], v[36:39]
	v_mfma_f32_16x16x32_bf16 v[24:27], v[132:135], v[172:175], v[24:27]
	v_mfma_f32_16x16x32_bf16 v[20:23], v[140:143], v[172:175], v[20:23]
	v_mfma_f32_16x16x32_bf16 v[8:11], v[132:135], v[164:167], v[8:11]
	v_mfma_f32_16x16x32_bf16 v[4:7], v[140:143], v[164:167], v[4:7]
	v_mfma_f32_16x16x32_bf16 v[56:59], v[136:139], v[192:195], v[56:59]
	v_mfma_f32_16x16x32_bf16 v[52:55], v[144:147], v[192:195], v[52:55]
	v_mfma_f32_16x16x32_bf16 v[40:43], v[136:139], v[184:187], v[40:43]
	v_mfma_f32_16x16x32_bf16 v[36:39], v[144:147], v[184:187], v[36:39]
	v_mfma_f32_16x16x32_bf16 v[24:27], v[136:139], v[176:179], v[24:27]
	v_mfma_f32_16x16x32_bf16 v[20:23], v[144:147], v[176:179], v[20:23]
	v_mfma_f32_16x16x32_bf16 v[8:11], v[136:139], v[168:171], v[8:11]
	v_mfma_f32_16x16x32_bf16 v[4:7], v[144:147], v[168:171], v[4:7]
	s_setprio 0
; #define PG8_STAGE(bufoff, gbase, voff) do { _Pragma("unroll") for (int _i = 0; _i < 2; ++_i) \
;         __builtin_amdgcn_global_load_lds((const unsigned*)((const char*)(gbase) + (voff)[_i]), (PG8_LAS unsigned*)(lds + (bufoff) + ldsw + _i * 8192), 16, 0, 0); } while (0)
; #define PG8_LDA(dst, b, h) do { _Pragma("unroll") for (int m = 0; m < 4; ++m) _Pragma("unroll") for (int k = 0; k < 2; ++k) dst[m][k] = *(const PG8_LAS bf16x8*)(lds + PG8_SA(b, h) + aoff + m * 2048 + k * 1024); } while (0)
; #define PG8_LDB(dst, b, h) do { _Pragma("unroll") for (int n = 0; n < 2; ++n) _Pragma("unroll") for (int k = 0; k < 2; ++k) dst[n][k] = *(const PG8_LAS bf16x8*)(lds + PG8_SB(b, h) + boff + n * 2048 + k * 1024); } while (0)
; #define PG8_MMA(ai, bj, At, Bt) do { __builtin_amdgcn_s_setprio(1); _Pragma("unroll") for (int m = 0; m < 4; ++m) _Pragma("unroll") for (int n = 0; n < 2; ++n) _Pragma("unroll") for (int k = 0; k < 2; ++k) \
;         acc[ai][bj][m][n] = __builtin_amdgcn_mfma_f32_16x16x32_bf16(Bt[n][k], At[m][k], acc[ai][bj][m][n], 0, 0, 0); __builtin_amdgcn_s_setprio(0); } while (0)
; #define PG8_WAIT_V(n) asm volatile("s_waitcnt vmcnt(" #n ")" ::: "memory")
; #define PG8_WAIT_L(n) asm volatile("s_waitcnt lgkmcnt(" #n ")" ::: "memory")
; #define PG8_BAR __builtin_amdgcn_s_barrier()
; #define PG8_SCHED __builtin_amdgcn_sched_barrier(0)
; template <class Epi, class Sched, bool ALIGN_EPI = false, bool SP2 = false>
; __device__ __forceinline__ void gemm_phase(PG8_LAS unsigned char* lds, const Gemm g, const Sched& S, const Epi& E, int wave0) {
;     ...
;             PG8_WAIT_V(8); PG8_WAIT_L(0); PG8_BAR; if (!cur.half) { PG8_MMA(1, 0, At, B0); PG8_MMA(1, 1, At, B1); } PG8_BAR; PG8_SCHED;
;             PG8_LDB(B0, 1, 0); PG8_LDB(B1, 1, 1); PG8_SCHED; PG8_LDA(At, 1, 0); PG8_STAGE(PG8_SA(0, 1), a2 + hstep, voffA);
;             PG8_WAIT_V(8); PG8_WAIT_L(0); PG8_BAR; PG8_MMA(0, 0, At, B0); PG8_MMA(0, 1, At, B1); PG8_BAR; PG8_SCHED;
;             PG8_LDA(At, 1, 1); PG8_STAGE(PG8_SB(1, 0), b3, voffB); PG8_STAGE(PG8_SB(1, 1), b3 + hstep, voffB); PG8_STAGE(PG8_SA(1, 0), a3, voffA);
;             PG8_WAIT_V(8); PG8_WAIT_L(0); PG8_BAR; if (!cur.half) { PG8_MMA(1, 0, At, B0); PG8_MMA(1, 1, At, B1); } PG8_BAR; PG8_SCHED;
.LBB0_824:
	s_barrier
	s_add_i32 s86, 0, 0x18000
	v_add_u32_e32 v1, s86, v220
	s_add_i32 s87, 0, 0x1c000
	ds_read_b128 v[148:151], v1
	ds_read_b128 v[152:155], v1 offset:1024
	ds_read_b128 v[156:159], v1 offset:2048
	ds_read_b128 v[160:163], v1 offset:3072
	v_add_u32_e32 v1, s87, v220
	ds_read_b128 v[132:135], v1
	ds_read_b128 v[136:139], v1 offset:1024
	ds_read_b128 v[140:143], v1 offset:2048
	ds_read_b128 v[144:147], v1 offset:3072
	s_add_u32 s46, s46, 0x40000
	s_addc_u32 s47, s47, 0
	s_mov_b32 m0, s48
	v_lshl_add_u64 v[226:227], s[46:47], 0, v[196:197]
	s_waitcnt lgkmcnt(0)
	ds_read_b128 v[164:167], v223 offset:32768
	ds_read_b128 v[168:171], v223 offset:33792
	ds_read_b128 v[172:175], v223 offset:34816
	ds_read_b128 v[176:179], v223 offset:35840
	ds_read_b128 v[180:183], v223 offset:36864
	ds_read_b128 v[184:187], v223 offset:37888
	ds_read_b128 v[188:191], v223 offset:38912
	ds_read_b128 v[192:195], v223 offset:39936
	global_load_lds_dwordx4 v[226:227], off
	v_lshl_add_u64 v[226:227], s[46:47], 0, v[200:201]
	s_mov_b32 m0, s49
	s_nop 0
	global_load_lds_dwordx4 v[226:227], off
	s_waitcnt vmcnt(8)
	s_waitcnt lgkmcnt(0)
	s_barrier
	s_setprio 1
	s_waitcnt lgkmcnt(0)
	v_mfma_f32_16x16x32_bf16 v[128:131], v[148:151], v[164:167], v[128:131]
	v_mfma_f32_16x16x32_bf16 v[124:127], v[156:159], v[164:167], v[124:127]
	v_mfma_f32_16x16x32_bf16 v[112:115], v[148:151], v[172:175], v[112:115]
	v_mfma_f32_16x16x32_bf16 v[108:111], v[156:159], v[172:175], v[108:111]
	v_mfma_f32_16x16x32_bf16 v[96:99], v[148:151], v[180:183], v[96:99]
	v_mfma_f32_16x16x32_bf16 v[92:95], v[156:159], v[180:183], v[92:95]
	v_mfma_f32_16x16x32_bf16 v[80:83], v[148:151], v[188:191], v[80:83]
	v_mfma_f32_16x16x32_bf16 v[76:79], v[156:159], v[188:191], v[76:79]
	v_mfma_f32_16x16x32_bf16 v[128:131], v[152:155], v[168:171], v[128:131]
	v_mfma_f32_16x16x32_bf16 v[124:127], v[160:163], v[168:171], v[124:127]
	v_mfma_f32_16x16x32_bf16 v[112:115], v[152:155], v[176:179], v[112:115]
	v_mfma_f32_16x16x32_bf16 v[108:111], v[160:163], v[176:179], v[108:111]
	v_mfma_f32_16x16x32_bf16 v[96:99], v[152:155], v[184:187], v[96:99]
	v_mfma_f32_16x16x32_bf16 v[92:95], v[160:163], v[184:187], v[92:95]
	v_mfma_f32_16x16x32_bf16 v[80:83], v[152:155], v[192:195], v[80:83]
	v_mfma_f32_16x16x32_bf16 v[76:79], v[160:163], v[192:195], v[76:79]
	v_mfma_f32_16x16x32_bf16 v[120:123], v[132:135], v[164:167], v[120:123]
	v_mfma_f32_16x16x32_bf16 v[116:119], v[140:143], v[164:167], v[116:119]
	v_mfma_f32_16x16x32_bf16 v[104:107], v[132:135], v[172:175], v[104:107]
	v_mfma_f32_16x16x32_bf16 v[100:103], v[140:143], v[172:175], v[100:103]
	v_mfma_f32_16x16x32_bf16 v[88:91], v[132:135], v[180:183], v[88:91]
	v_mfma_f32_16x16x32_bf16 v[84:87], v[140:143], v[180:183], v[84:87]
	v_mfma_f32_16x16x32_bf16 v[72:75], v[132:135], v[188:191], v[72:75]
	v_mfma_f32_16x16x32_bf16 v[68:71], v[140:143], v[188:191], v[68:71]
	v_mfma_f32_16x16x32_bf16 v[120:123], v[136:139], v[168:171], v[120:123]
	v_mfma_f32_16x16x32_bf16 v[116:119], v[144:147], v[168:171], v[116:119]
	v_mfma_f32_16x16x32_bf16 v[104:107], v[136:139], v[176:179], v[104:107]
	v_mfma_f32_16x16x32_bf16 v[100:103], v[144:147], v[176:179], v[100:103]
	v_mfma_f32_16x16x32_bf16 v[88:91], v[136:139], v[184:187], v[88:91]
	v_mfma_f32_16x16x32_bf16 v[84:87], v[144:147], v[184:187], v[84:87]
	v_mfma_f32_16x16x32_bf16 v[72:75], v[136:139], v[192:195], v[72:75]
	v_mfma_f32_16x16x32_bf16 v[68:71], v[144:147], v[192:195], v[68:71]
	s_setprio 0
	s_barrier
	s_add_i32 s46, s86, s6
	v_lshl_add_u64 v[2:3], v[2:3], 0, s[16:17]
	s_mov_b32 m0, s46
	ds_read_b128 v[188:191], v223 offset:49152
	ds_read_b128 v[192:195], v223 offset:50176
	ds_read_b128 v[180:183], v223 offset:51200
	ds_read_b128 v[184:187], v223 offset:52224
	ds_read_b128 v[172:175], v223 offset:53248
	ds_read_b128 v[176:179], v223 offset:54272
	ds_read_b128 v[164:167], v223 offset:55296
	ds_read_b128 v[168:171], v223 offset:56320
	global_load_lds_dwordx4 v[2:3], off
	s_add_i32 m0, s46, 0x2000
	s_add_u32 s44, s44, 0x40080
	v_lshl_add_u64 v[2:3], v[210:211], 0, s[16:17]
	s_addc_u32 s45, s45, 0
	s_add_i32 s46, s87, s6
	global_load_lds_dwordx4 v[2:3], off
	v_lshl_add_u64 v[2:3], s[44:45], 0, v[198:199]
	s_mov_b32 m0, s46
	s_and_b64 vcc, exec, s[8:9]
	global_load_lds_dwordx4 v[2:3], off
	v_lshl_add_u64 v[2:3], s[44:45], 0, v[202:203]
	s_add_i32 m0, s46, 0x2000
	s_nop 0
	global_load_lds_dwordx4 v[2:3], off
	v_lshl_add_u64 v[2:3], v[212:213], 0, s[16:17]
	s_mov_b32 m0, s53
	s_nop 0
	global_load_lds_dwordx4 v[2:3], off
	v_lshl_add_u64 v[2:3], v[214:215], 0, s[16:17]
	s_mov_b32 m0, s54
	s_nop 0
	global_load_lds_dwordx4 v[2:3], off
	s_waitcnt vmcnt(8)
	s_waitcnt lgkmcnt(0)
	s_barrier
	s_cbranch_vccnz .LBB0_821
	s_setprio 1
	s_waitcnt lgkmcnt(0)
	v_mfma_f32_16x16x32_bf16 v[64:67], v[148:151], v[188:191], v[64:67]
	v_mfma_f32_16x16x32_bf16 v[60:63], v[156:159], v[188:191], v[60:63]
	v_mfma_f32_16x16x32_bf16 v[48:51], v[148:151], v[180:183], v[48:51]
	v_mfma_f32_16x16x32_bf16 v[44:47], v[156:159], v[180:183], v[44:47]
	v_mfma_f32_16x16x32_bf16 v[32:35], v[148:151], v[172:175], v[32:35]
	v_mfma_f32_16x16x32_bf16 v[28:31], v[156:159], v[172:175], v[28:31]
	v_mfma_f32_16x16x32_bf16 v[16:19], v[148:151], v[164:167], v[16:19]
	v_mfma_f32_16x16x32_bf16 v[12:15], v[156:159], v[164:167], v[12:15]
	v_mfma_f32_16x16x32_bf16 v[64:67], v[152:155], v[192:195], v[64:67]
	v_mfma_f32_16x16x32_bf16 v[60:63], v[160:163], v[192:195], v[60:63]
	v_mfma_f32_16x16x32_bf16 v[48:51], v[152:155], v[184:187], v[48:51]
	v_mfma_f32_16x16x32_bf16 v[44:47], v[160:163], v[184:187], v[44:47]
	v_mfma_f32_16x16x32_bf16 v[32:35], v[152:155], v[176:179], v[32:35]
	v_mfma_f32_16x16x32_bf16 v[28:31], v[160:163], v[176:179], v[28:31]
	v_mfma_f32_16x16x32_bf16 v[16:19], v[152:155], v[168:171], v[16:19]
	v_mfma_f32_16x16x32_bf16 v[12:15], v[160:163], v[168:171], v[12:15]
	v_mfma_f32_16x16x32_bf16 v[56:59], v[132:135], v[188:191], v[56:59]
	v_mfma_f32_16x16x32_bf16 v[52:55], v[140:143], v[188:191], v[52:55]
	v_mfma_f32_16x16x32_bf16 v[40:43], v[132:135], v[180:183], v[40:43]
	v_mfma_f32_16x16x32_bf16 v[36:39], v[140:143], v[180:183], v[36:39]
	v_mfma_f32_16x16x32_bf16 v[24:27], v[132:135], v[172:175], v[24:27]
	v_mfma_f32_16x16x32_bf16 v[20:23], v[140:143], v[172:175], v[20:23]
	v_mfma_f32_16x16x32_bf16 v[8:11], v[132:135], v[164:167], v[8:11]
	v_mfma_f32_16x16x32_bf16 v[2:5], v[140:143], v[164:167], v[4:7]
	v_mfma_f32_16x16x32_bf16 v[56:59], v[136:139], v[192:195], v[56:59]
	v_mfma_f32_16x16x32_bf16 v[52:55], v[144:147], v[192:195], v[52:55]
	v_mfma_f32_16x16x32_bf16 v[40:43], v[136:139], v[184:187], v[40:43]
	v_mfma_f32_16x16x32_bf16 v[36:39], v[144:147], v[184:187], v[36:39]
	v_mfma_f32_16x16x32_bf16 v[24:27], v[136:139], v[176:179], v[24:27]
	v_mfma_f32_16x16x32_bf16 v[20:23], v[144:147], v[176:179], v[20:23]
	v_mfma_f32_16x16x32_bf16 v[8:11], v[136:139], v[168:171], v[8:11]
	v_mfma_f32_16x16x32_bf16 v[4:7], v[144:147], v[168:171], v[2:5]
	s_setprio 0
	s_branch .LBB0_821
	s_nop 0
	s_nop 0
	s_nop 0
	s_nop 0
	s_nop 0
	s_nop 0
	s_nop 0
	s_nop 0

; #define PG8_STAGE(bufoff, gbase, voff) do { _Pragma("unroll") for (int _i = 0; _i < 2; ++_i) \
;         __builtin_amdgcn_global_load_lds((const unsigned*)((const char*)(gbase) + (voff)[_i]), (PG8_LAS unsigned*)(lds + (bufoff) + ldsw + _i * 8192), 16, 0, 0); } while (0)
; #define PG8_LDA(dst, b, h) do { _Pragma("unroll") for (int m = 0; m < 4; ++m) _Pragma("unroll") for (int k = 0; k < 2; ++k) dst[m][k] = *(const PG8_LAS bf16x8*)(lds + PG8_SA(b, h) + aoff + m * 2048 + k * 1024); } while (0)
; #define PG8_LDB(dst, b, h) do { _Pragma("unroll") for (int n = 0; n < 2; ++n) _Pragma("unroll") for (int k = 0; k < 2; ++k) dst[n][k] = *(const PG8_LAS bf16x8*)(lds + PG8_SB(b, h) + boff + n * 2048 + k * 1024); } while (0)
; #define PG8_MMA(ai, bj, At, Bt) do { __builtin_amdgcn_s_setprio(1); _Pragma("unroll") for (int m = 0; m < 4; ++m) _Pragma("unroll") for (int n = 0; n < 2; ++n) _Pragma("unroll") for (int k = 0; k < 2; ++k) \
;         acc[ai][bj][m][n] = __builtin_amdgcn_mfma_f32_16x16x32_bf16(Bt[n][k], At[m][k], acc[ai][bj][m][n], 0, 0, 0); __builtin_amdgcn_s_setprio(0); } while (0)
; #define PG8_WAIT_V(n) asm volatile("s_waitcnt vmcnt(" #n ")" ::: "memory")
; #define PG8_WAIT_L(n) asm volatile("s_waitcnt lgkmcnt(" #n ")" ::: "memory")
; #define PG8_BAR __builtin_amdgcn_s_barrier()
; #define PG8_SCHED __builtin_amdgcn_sched_barrier(0)
; template <class Epi, class Sched, bool ALIGN_EPI = false, bool SP2 = false>
; __device__ __forceinline__ void gemm_phase(PG8_LAS unsigned char* lds, const Gemm g, const Sched& S, const Epi& E, int wave0) {
;     ...
;             PG8_LDB(B0, 0, 0); PG8_LDB(B1, 0, 1); PG8_SCHED; PG8_LDA(At, 0, 0); PG8_STAGE(PG8_SA(1, 1), a1 + hstep, voffA);
;             PG8_WAIT_V(8); PG8_WAIT_L(0); PG8_BAR; PG8_MMA(0, 0, At, B0); PG8_MMA(0, 1, At, B1); PG8_BAR; PG8_SCHED;
;             PG8_LDA(At, 0, 1); PG8_STAGE(PG8_SB(0, 0), b2, voffB); PG8_STAGE(PG8_SB(0, 1), b2 + hstep, voffB); PG8_STAGE(PG8_SA(0, 0), a2, voffA);
;             PG8_WAIT_V(8); PG8_WAIT_L(0); PG8_BAR; if (!cur.half) { PG8_MMA(1, 0, At, B0); PG8_MMA(1, 1, At, B1); } PG8_BAR; PG8_SCHED;
.LBB0_1001:
	ds_read_b128 v[148:151], v221
	ds_read_b128 v[152:155], v221 offset:1024
	ds_read_b128 v[156:159], v221 offset:2048
	ds_read_b128 v[160:163], v221 offset:3072
	ds_read_b128 v[132:135], v222
	ds_read_b128 v[136:139], v222 offset:1024
	ds_read_b128 v[140:143], v222 offset:2048
	ds_read_b128 v[144:147], v222 offset:3072
	s_add_u32 s0, s8, 0xfffc0080
	s_addc_u32 s1, s9, -1
	s_cmp_eq_u32 s49, 12
	s_cselect_b32 s87, s3, s1
	s_cselect_b32 s86, s29, s0
	s_cselect_b32 s11, s51, s69
	s_cselect_b32 s10, s53, s68
	v_lshl_add_u64 v[2:3], s[8:9], 0, v[204:205]
	s_add_i32 m0, s33, 0xc000
	s_waitcnt lgkmcnt(0)
	ds_read_b128 v[164:167], v223
	ds_read_b128 v[168:171], v223 offset:1024
	ds_read_b128 v[172:175], v223 offset:2048
	ds_read_b128 v[176:179], v223 offset:3072
	ds_read_b128 v[180:183], v223 offset:4096
	ds_read_b128 v[184:187], v223 offset:5120
	ds_read_b128 v[188:191], v223 offset:6144
	ds_read_b128 v[192:195], v223 offset:7168
	global_load_lds_dwordx4 v[2:3], off
	v_lshl_add_u64 v[2:3], s[8:9], 0, v[206:207]
	s_add_i32 m0, s33, 0xe000
	s_nop 0
	global_load_lds_dwordx4 v[2:3], off
	s_waitcnt vmcnt(8)
	s_waitcnt lgkmcnt(0)
	s_barrier
	s_setprio 1
	s_waitcnt lgkmcnt(0)
	v_mfma_f32_16x16x32_bf16 v[128:131], v[148:151], v[164:167], v[128:131]
	v_mfma_f32_16x16x32_bf16 v[124:127], v[156:159], v[164:167], v[124:127]
	v_mfma_f32_16x16x32_bf16 v[120:123], v[148:151], v[172:175], v[120:123]
	v_mfma_f32_16x16x32_bf16 v[116:119], v[156:159], v[172:175], v[116:119]
	v_mfma_f32_16x16x32_bf16 v[112:115], v[148:151], v[180:183], v[112:115]
	v_mfma_f32_16x16x32_bf16 v[108:111], v[156:159], v[180:183], v[108:111]
	v_mfma_f32_16x16x32_bf16 v[104:107], v[148:151], v[188:191], v[104:107]
	v_mfma_f32_16x16x32_bf16 v[100:103], v[156:159], v[188:191], v[100:103]
	v_mfma_f32_16x16x32_bf16 v[128:131], v[152:155], v[168:171], v[128:131]
	v_mfma_f32_16x16x32_bf16 v[124:127], v[160:163], v[168:171], v[124:127]
	v_mfma_f32_16x16x32_bf16 v[120:123], v[152:155], v[176:179], v[120:123]
	v_mfma_f32_16x16x32_bf16 v[116:119], v[160:163], v[176:179], v[116:119]
	v_mfma_f32_16x16x32_bf16 v[112:115], v[152:155], v[184:187], v[112:115]
	v_mfma_f32_16x16x32_bf16 v[108:111], v[160:163], v[184:187], v[108:111]
	v_mfma_f32_16x16x32_bf16 v[104:107], v[152:155], v[192:195], v[104:107]
	v_mfma_f32_16x16x32_bf16 v[100:103], v[160:163], v[192:195], v[100:103]
	v_mfma_f32_16x16x32_bf16 v[68:71], v[132:135], v[164:167], v[68:71]
	v_mfma_f32_16x16x32_bf16 v[60:63], v[140:143], v[164:167], v[60:63]
	v_mfma_f32_16x16x32_bf16 v[56:59], v[132:135], v[172:175], v[56:59]
	v_mfma_f32_16x16x32_bf16 v[52:55], v[140:143], v[172:175], v[52:55]
	v_mfma_f32_16x16x32_bf16 v[48:51], v[132:135], v[180:183], v[48:51]
	v_mfma_f32_16x16x32_bf16 v[44:47], v[140:143], v[180:183], v[44:47]
	v_mfma_f32_16x16x32_bf16 v[40:43], v[132:135], v[188:191], v[40:43]
	v_mfma_f32_16x16x32_bf16 v[36:39], v[140:143], v[188:191], v[36:39]
	v_mfma_f32_16x16x32_bf16 v[68:71], v[136:139], v[168:171], v[68:71]
	v_mfma_f32_16x16x32_bf16 v[60:63], v[144:147], v[168:171], v[60:63]
	v_mfma_f32_16x16x32_bf16 v[56:59], v[136:139], v[176:179], v[56:59]
	v_mfma_f32_16x16x32_bf16 v[52:55], v[144:147], v[176:179], v[52:55]
	v_mfma_f32_16x16x32_bf16 v[48:51], v[136:139], v[184:187], v[48:51]
	v_mfma_f32_16x16x32_bf16 v[44:47], v[144:147], v[184:187], v[44:47]
	v_mfma_f32_16x16x32_bf16 v[40:43], v[136:139], v[192:195], v[40:43]
	v_mfma_f32_16x16x32_bf16 v[36:39], v[144:147], v[192:195], v[36:39]
	s_setprio 0
	s_barrier
	s_add_i32 s0, s15, s31
	v_lshl_add_u64 v[2:3], s[10:11], 0, v[198:199]
	s_mov_b32 m0, s0
	ds_read_b128 v[188:191], v223 offset:16384
	ds_read_b128 v[192:195], v223 offset:17408
	ds_read_b128 v[180:183], v223 offset:18432
	ds_read_b128 v[184:187], v223 offset:19456
	ds_read_b128 v[172:175], v223 offset:20480
	ds_read_b128 v[176:179], v223 offset:21504
	ds_read_b128 v[164:167], v223 offset:22528
	ds_read_b128 v[168:171], v223 offset:23552
	global_load_lds_dwordx4 v[2:3], off
	s_add_i32 m0, s0, 0x2000
	s_add_u32 s0, s10, 0x40000
	v_lshl_add_u64 v[210:211], s[10:11], 0, v[202:203]
	s_addc_u32 s1, s11, 0
	s_add_i32 vcc_lo, s4, s31
	global_load_lds_dwordx4 v[210:211], off
	v_lshl_add_u64 v[212:213], s[0:1], 0, v[198:199]
	s_mov_b32 m0, vcc_lo
	v_lshl_add_u64 v[214:215], s[86:87], 0, v[200:201]
	global_load_lds_dwordx4 v[212:213], off
	v_lshl_add_u64 v[212:213], s[0:1], 0, v[202:203]
	s_add_i32 m0, vcc_lo, 0x2000
	v_cmp_ne_u32_e64 s[0:1], 1, v226
	global_load_lds_dwordx4 v[212:213], off
	v_lshl_add_u64 v[212:213], s[86:87], 0, v[196:197]
	s_mov_b32 m0, s33
	s_andn2_b64 vcc, exec, s[84:85]
	global_load_lds_dwordx4 v[212:213], off
	s_mov_b32 m0, s35
	s_nop 0
	global_load_lds_dwordx4 v[214:215], off
	s_waitcnt vmcnt(8)
	s_waitcnt lgkmcnt(0)
	s_barrier
	s_cbranch_vccnz .LBB0_1003
	s_setprio 1
	s_waitcnt lgkmcnt(0)
	v_mfma_f32_16x16x32_bf16 v[96:99], v[148:151], v[188:191], v[96:99]
	v_mfma_f32_16x16x32_bf16 v[92:95], v[156:159], v[188:191], v[92:95]
	v_mfma_f32_16x16x32_bf16 v[88:91], v[148:151], v[180:183], v[88:91]
	v_mfma_f32_16x16x32_bf16 v[84:87], v[156:159], v[180:183], v[84:87]
	v_mfma_f32_16x16x32_bf16 v[80:83], v[148:151], v[172:175], v[80:83]
	v_mfma_f32_16x16x32_bf16 v[76:79], v[156:159], v[172:175], v[76:79]
	v_mfma_f32_16x16x32_bf16 v[72:75], v[148:151], v[164:167], v[72:75]
	v_mfma_f32_16x16x32_bf16 v[64:67], v[156:159], v[164:167], v[64:67]
	v_mfma_f32_16x16x32_bf16 v[96:99], v[152:155], v[192:195], v[96:99]
	v_mfma_f32_16x16x32_bf16 v[92:95], v[160:163], v[192:195], v[92:95]
	v_mfma_f32_16x16x32_bf16 v[88:91], v[152:155], v[184:187], v[88:91]
	v_mfma_f32_16x16x32_bf16 v[84:87], v[160:163], v[184:187], v[84:87]
	v_mfma_f32_16x16x32_bf16 v[80:83], v[152:155], v[176:179], v[80:83]
	v_mfma_f32_16x16x32_bf16 v[76:79], v[160:163], v[176:179], v[76:79]
	v_mfma_f32_16x16x32_bf16 v[72:75], v[152:155], v[168:171], v[72:75]
	v_mfma_f32_16x16x32_bf16 v[64:67], v[160:163], v[168:171], v[64:67]
	v_mfma_f32_16x16x32_bf16 v[32:35], v[132:135], v[188:191], v[32:35]
	v_mfma_f32_16x16x32_bf16 v[28:31], v[140:143], v[188:191], v[28:31]
	v_mfma_f32_16x16x32_bf16 v[24:27], v[132:135], v[180:183], v[24:27]
	v_mfma_f32_16x16x32_bf16 v[20:23], v[140:143], v[180:183], v[20:23]
	v_mfma_f32_16x16x32_bf16 v[16:19], v[132:135], v[172:175], v[16:19]
	v_mfma_f32_16x16x32_bf16 v[12:15], v[140:143], v[172:175], v[12:15]
	v_mfma_f32_16x16x32_bf16 v[8:11], v[132:135], v[164:167], v[8:11]
	v_mfma_f32_16x16x32_bf16 v[4:7], v[140:143], v[164:167], v[4:7]
	v_mfma_f32_16x16x32_bf16 v[32:35], v[136:139], v[192:195], v[32:35]
	v_mfma_f32_16x16x32_bf16 v[28:31], v[144:147], v[192:195], v[28:31]
	v_mfma_f32_16x16x32_bf16 v[24:27], v[136:139], v[184:187], v[24:27]
	v_mfma_f32_16x16x32_bf16 v[20:23], v[144:147], v[184:187], v[20:23]
	v_mfma_f32_16x16x32_bf16 v[16:19], v[136:139], v[176:179], v[16:19]
	v_mfma_f32_16x16x32_bf16 v[12:15], v[144:147], v[176:179], v[12:15]
	v_mfma_f32_16x16x32_bf16 v[8:11], v[136:139], v[168:171], v[8:11]
	v_mfma_f32_16x16x32_bf16 v[4:7], v[144:147], v[168:171], v[4:7]
	s_setprio 0
; #define PG8_STAGE(bufoff, gbase, voff) do { _Pragma("unroll") for (int _i = 0; _i < 2; ++_i) \
;         __builtin_amdgcn_global_load_lds((const unsigned*)((const char*)(gbase) + (voff)[_i]), (PG8_LAS unsigned*)(lds + (bufoff) + ldsw + _i * 8192), 16, 0, 0); } while (0)
; #define PG8_LDA(dst, b, h) do { _Pragma("unroll") for (int m = 0; m < 4; ++m) _Pragma("unroll") for (int k = 0; k < 2; ++k) dst[m][k] = *(const PG8_LAS bf16x8*)(lds + PG8_SA(b, h) + aoff + m * 2048 + k * 1024); } while (0)
; #define PG8_LDB(dst, b, h) do { _Pragma("unroll") for (int n = 0; n < 2; ++n) _Pragma("unroll") for (int k = 0; k < 2; ++k) dst[n][k] = *(const PG8_LAS bf16x8*)(lds + PG8_SB(b, h) + boff + n * 2048 + k * 1024); } while (0)
; #define PG8_MMA(ai, bj, At, Bt) do { __builtin_amdgcn_s_setprio(1); _Pragma("unroll") for (int m = 0; m < 4; ++m) _Pragma("unroll") for (int n = 0; n < 2; ++n) _Pragma("unroll") for (int k = 0; k < 2; ++k) \
;         acc[ai][bj][m][n] = __builtin_amdgcn_mfma_f32_16x16x32_bf16(Bt[n][k], At[m][k], acc[ai][bj][m][n], 0, 0, 0); __builtin_amdgcn_s_setprio(0); } while (0)
; #define PG8_WAIT_V(n) asm volatile("s_waitcnt vmcnt(" #n ")" ::: "memory")
; #define PG8_WAIT_L(n) asm volatile("s_waitcnt lgkmcnt(" #n ")" ::: "memory")
; #define PG8_BAR __builtin_amdgcn_s_barrier()
; #define PG8_SCHED __builtin_amdgcn_sched_barrier(0)
; template <class Epi, class Sched, bool ALIGN_EPI = false, bool SP2 = false>
; __device__ __forceinline__ void gemm_phase(PG8_LAS unsigned char* lds, const Gemm g, const Sched& S, const Epi& E, int wave0) {
;     ...
;             PG8_WAIT_V(8); PG8_WAIT_L(0); PG8_BAR; if (!cur.half) { PG8_MMA(1, 0, At, B0); PG8_MMA(1, 1, At, B1); } PG8_BAR; PG8_SCHED;
;             PG8_LDB(B0, 1, 0); PG8_LDB(B1, 1, 1); PG8_SCHED; PG8_LDA(At, 1, 0); PG8_STAGE(PG8_SA(0, 1), a2 + hstep, voffA);
;             PG8_WAIT_V(8); PG8_WAIT_L(0); PG8_BAR; PG8_MMA(0, 0, At, B0); PG8_MMA(0, 1, At, B1); PG8_BAR; PG8_SCHED;
.LBB0_1003:
	s_barrier
	s_add_i32 vcc_lo, 0, 0x18000
	v_add_u32_e32 v1, vcc_lo, v220
	s_add_i32 vcc_hi, 0, 0x1c000
	ds_read_b128 v[148:151], v1
	ds_read_b128 v[152:155], v1 offset:1024
	ds_read_b128 v[156:159], v1 offset:2048
	ds_read_b128 v[160:163], v1 offset:3072
	v_add_u32_e32 v1, vcc_hi, v220
	ds_read_b128 v[132:135], v1
	ds_read_b128 v[136:139], v1 offset:1024
	ds_read_b128 v[140:143], v1 offset:2048
	ds_read_b128 v[144:147], v1 offset:3072
	s_add_u32 s86, s86, 0x40000
	s_addc_u32 s87, s87, 0
	s_mov_b32 m0, s37
	v_lshl_add_u64 v[228:229], s[86:87], 0, v[196:197]
	s_waitcnt lgkmcnt(0)
	ds_read_b128 v[164:167], v223 offset:32768
	ds_read_b128 v[168:171], v223 offset:33792
	ds_read_b128 v[172:175], v223 offset:34816
	ds_read_b128 v[176:179], v223 offset:35840
	ds_read_b128 v[180:183], v223 offset:36864
	ds_read_b128 v[184:187], v223 offset:37888
	ds_read_b128 v[188:191], v223 offset:38912
	ds_read_b128 v[192:195], v223 offset:39936
	global_load_lds_dwordx4 v[228:229], off
	v_lshl_add_u64 v[228:229], s[86:87], 0, v[200:201]
	s_mov_b32 m0, s39
	s_nop 0
	global_load_lds_dwordx4 v[228:229], off
	s_waitcnt vmcnt(8)
	s_waitcnt lgkmcnt(0)
	s_barrier
	s_setprio 1
	s_waitcnt lgkmcnt(0)
	v_mfma_f32_16x16x32_bf16 v[128:131], v[148:151], v[164:167], v[128:131]
	v_mfma_f32_16x16x32_bf16 v[124:127], v[156:159], v[164:167], v[124:127]
	v_mfma_f32_16x16x32_bf16 v[120:123], v[148:151], v[172:175], v[120:123]
	v_mfma_f32_16x16x32_bf16 v[116:119], v[156:159], v[172:175], v[116:119]
	v_mfma_f32_16x16x32_bf16 v[112:115], v[148:151], v[180:183], v[112:115]
	v_mfma_f32_16x16x32_bf16 v[108:111], v[156:159], v[180:183], v[108:111]
	v_mfma_f32_16x16x32_bf16 v[104:107], v[148:151], v[188:191], v[104:107]
	v_mfma_f32_16x16x32_bf16 v[100:103], v[156:159], v[188:191], v[100:103]
	v_mfma_f32_16x16x32_bf16 v[128:131], v[152:155], v[168:171], v[128:131]
	v_mfma_f32_16x16x32_bf16 v[124:127], v[160:163], v[168:171], v[124:127]
	v_mfma_f32_16x16x32_bf16 v[120:123], v[152:155], v[176:179], v[120:123]
	v_mfma_f32_16x16x32_bf16 v[116:119], v[160:163], v[176:179], v[116:119]
	v_mfma_f32_16x16x32_bf16 v[112:115], v[152:155], v[184:187], v[112:115]
	v_mfma_f32_16x16x32_bf16 v[108:111], v[160:163], v[184:187], v[108:111]
	v_mfma_f32_16x16x32_bf16 v[104:107], v[152:155], v[192:195], v[104:107]
	v_mfma_f32_16x16x32_bf16 v[100:103], v[160:163], v[192:195], v[100:103]
	v_mfma_f32_16x16x32_bf16 v[68:71], v[132:135], v[164:167], v[68:71]
	v_mfma_f32_16x16x32_bf16 v[60:63], v[140:143], v[164:167], v[60:63]
	v_mfma_f32_16x16x32_bf16 v[56:59], v[132:135], v[172:175], v[56:59]
	v_mfma_f32_16x16x32_bf16 v[52:55], v[140:143], v[172:175], v[52:55]
	v_mfma_f32_16x16x32_bf16 v[48:51], v[132:135], v[180:183], v[48:51]
	v_mfma_f32_16x16x32_bf16 v[44:47], v[140:143], v[180:183], v[44:47]
	v_mfma_f32_16x16x32_bf16 v[40:43], v[132:135], v[188:191], v[40:43]
	v_mfma_f32_16x16x32_bf16 v[36:39], v[140:143], v[188:191], v[36:39]
	v_mfma_f32_16x16x32_bf16 v[68:71], v[136:139], v[168:171], v[68:71]
	v_mfma_f32_16x16x32_bf16 v[60:63], v[144:147], v[168:171], v[60:63]
	v_mfma_f32_16x16x32_bf16 v[56:59], v[136:139], v[176:179], v[56:59]
	v_mfma_f32_16x16x32_bf16 v[52:55], v[144:147], v[176:179], v[52:55]
	v_mfma_f32_16x16x32_bf16 v[48:51], v[136:139], v[184:187], v[48:51]
	v_mfma_f32_16x16x32_bf16 v[44:47], v[144:147], v[184:187], v[44:47]
	v_mfma_f32_16x16x32_bf16 v[40:43], v[136:139], v[192:195], v[40:43]
	v_mfma_f32_16x16x32_bf16 v[36:39], v[144:147], v[192:195], v[36:39]
	s_setprio 0
	s_barrier
; #define PG8_STAGE(bufoff, gbase, voff) do { _Pragma("unroll") for (int _i = 0; _i < 2; ++_i) \
;         __builtin_amdgcn_global_load_lds((const unsigned*)((const char*)(gbase) + (voff)[_i]), (PG8_LAS unsigned*)(lds + (bufoff) + ldsw + _i * 8192), 16, 0, 0); } while (0)
; #define PG8_LDA(dst, b, h) do { _Pragma("unroll") for (int m = 0; m < 4; ++m) _Pragma("unroll") for (int k = 0; k < 2; ++k) dst[m][k] = *(const PG8_LAS bf16x8*)(lds + PG8_SA(b, h) + aoff + m * 2048 + k * 1024); } while (0)
; #define PG8_MMA(ai, bj, At, Bt) do { __builtin_amdgcn_s_setprio(1); _Pragma("unroll") for (int m = 0; m < 4; ++m) _Pragma("unroll") for (int n = 0; n < 2; ++n) _Pragma("unroll") for (int k = 0; k < 2; ++k) \
;         acc[ai][bj][m][n] = __builtin_amdgcn_mfma_f32_16x16x32_bf16(Bt[n][k], At[m][k], acc[ai][bj][m][n], 0, 0, 0); __builtin_amdgcn_s_setprio(0); } while (0)
; #define PG8_WAIT_V(n) asm volatile("s_waitcnt vmcnt(" #n ")" ::: "memory")
; #define PG8_WAIT_L(n) asm volatile("s_waitcnt lgkmcnt(" #n ")" ::: "memory")
; #define PG8_BAR __builtin_amdgcn_s_barrier()
; #define PG8_SCHED __builtin_amdgcn_sched_barrier(0)
; template <class Epi, class Sched, bool ALIGN_EPI = false, bool SP2 = false>
; __device__ __forceinline__ void gemm_phase(PG8_LAS unsigned char* lds, const Gemm g, const Sched& S, const Epi& E, int wave0) {
;     ...
;             PG8_LDA(At, 1, 1); PG8_STAGE(PG8_SB(1, 0), b3, voffB); PG8_STAGE(PG8_SB(1, 1), b3 + hstep, voffB); PG8_STAGE(PG8_SA(1, 0), a3, voffA);
;             PG8_WAIT_V(8); PG8_WAIT_L(0); PG8_BAR; if (!cur.half) { PG8_MMA(1, 0, At, B0); PG8_MMA(1, 1, At, B1); } PG8_BAR; PG8_SCHED;
	s_add_i32 s86, vcc_lo, s31
	v_lshl_add_u64 v[2:3], v[2:3], 0, s[20:21]
	s_mov_b32 m0, s86
	ds_read_b128 v[188:191], v223 offset:49152
	ds_read_b128 v[192:195], v223 offset:50176
	ds_read_b128 v[180:183], v223 offset:51200
	ds_read_b128 v[184:187], v223 offset:52224
	ds_read_b128 v[172:175], v223 offset:53248
	ds_read_b128 v[176:179], v223 offset:54272
	ds_read_b128 v[164:167], v223 offset:55296
	ds_read_b128 v[168:171], v223 offset:56320
	global_load_lds_dwordx4 v[2:3], off
	s_add_i32 m0, s86, 0x2000
	s_add_u32 s10, s10, 0x40080
	v_lshl_add_u64 v[2:3], v[210:211], 0, s[20:21]
	s_addc_u32 s11, s11, 0
	s_add_i32 s86, vcc_hi, s31
	global_load_lds_dwordx4 v[2:3], off
	v_lshl_add_u64 v[2:3], s[10:11], 0, v[198:199]
	s_mov_b32 m0, s86
	s_and_b64 vcc, exec, s[0:1]
	global_load_lds_dwordx4 v[2:3], off
	v_lshl_add_u64 v[2:3], s[10:11], 0, v[202:203]
	s_add_i32 m0, s86, 0x2000
	s_nop 0
	global_load_lds_dwordx4 v[2:3], off
	v_lshl_add_u64 v[2:3], v[212:213], 0, s[20:21]
	s_mov_b32 m0, s71
	s_nop 0
	global_load_lds_dwordx4 v[2:3], off
	v_lshl_add_u64 v[2:3], v[214:215], 0, s[20:21]
	s_mov_b32 m0, s14
	s_nop 0
	global_load_lds_dwordx4 v[2:3], off
	s_waitcnt vmcnt(8)
	s_waitcnt lgkmcnt(0)
	s_barrier
	s_cbranch_vccnz .LBB0_1000
	s_setprio 1
	s_waitcnt lgkmcnt(0)
	v_mfma_f32_16x16x32_bf16 v[96:99], v[148:151], v[188:191], v[96:99]
	v_mfma_f32_16x16x32_bf16 v[92:95], v[156:159], v[188:191], v[92:95]
	v_mfma_f32_16x16x32_bf16 v[88:91], v[148:151], v[180:183], v[88:91]
	v_mfma_f32_16x16x32_bf16 v[84:87], v[156:159], v[180:183], v[84:87]
	v_mfma_f32_16x16x32_bf16 v[80:83], v[148:151], v[172:175], v[80:83]
	v_mfma_f32_16x16x32_bf16 v[76:79], v[156:159], v[172:175], v[76:79]
	v_mfma_f32_16x16x32_bf16 v[72:75], v[148:151], v[164:167], v[72:75]
	v_mfma_f32_16x16x32_bf16 v[64:67], v[156:159], v[164:167], v[64:67]
	v_mfma_f32_16x16x32_bf16 v[96:99], v[152:155], v[192:195], v[96:99]
	v_mfma_f32_16x16x32_bf16 v[92:95], v[160:163], v[192:195], v[92:95]
	v_mfma_f32_16x16x32_bf16 v[88:91], v[152:155], v[184:187], v[88:91]
	v_mfma_f32_16x16x32_bf16 v[84:87], v[160:163], v[184:187], v[84:87]
	v_mfma_f32_16x16x32_bf16 v[80:83], v[152:155], v[176:179], v[80:83]
	v_mfma_f32_16x16x32_bf16 v[76:79], v[160:163], v[176:179], v[76:79]
	v_mfma_f32_16x16x32_bf16 v[72:75], v[152:155], v[168:171], v[72:75]
	v_mfma_f32_16x16x32_bf16 v[64:67], v[160:163], v[168:171], v[64:67]
	v_mfma_f32_16x16x32_bf16 v[32:35], v[132:135], v[188:191], v[32:35]
	v_mfma_f32_16x16x32_bf16 v[28:31], v[140:143], v[188:191], v[28:31]
	v_mfma_f32_16x16x32_bf16 v[24:27], v[132:135], v[180:183], v[24:27]
	v_mfma_f32_16x16x32_bf16 v[20:23], v[140:143], v[180:183], v[20:23]
	v_mfma_f32_16x16x32_bf16 v[16:19], v[132:135], v[172:175], v[16:19]
	v_mfma_f32_16x16x32_bf16 v[12:15], v[140:143], v[172:175], v[12:15]
	v_mfma_f32_16x16x32_bf16 v[8:11], v[132:135], v[164:167], v[8:11]
	v_mfma_f32_16x16x32_bf16 v[2:5], v[140:143], v[164:167], v[4:7]
	v_mfma_f32_16x16x32_bf16 v[32:35], v[136:139], v[192:195], v[32:35]
	v_mfma_f32_16x16x32_bf16 v[28:31], v[144:147], v[192:195], v[28:31]
	v_mfma_f32_16x16x32_bf16 v[24:27], v[136:139], v[184:187], v[24:27]
	v_mfma_f32_16x16x32_bf16 v[20:23], v[144:147], v[184:187], v[20:23]
	v_mfma_f32_16x16x32_bf16 v[16:19], v[136:139], v[176:179], v[16:19]
	v_mfma_f32_16x16x32_bf16 v[12:15], v[144:147], v[176:179], v[12:15]
	v_mfma_f32_16x16x32_bf16 v[8:11], v[136:139], v[168:171], v[8:11]
	v_mfma_f32_16x16x32_bf16 v[4:7], v[144:147], v[168:171], v[2:5]
	s_setprio 0
	s_branch .LBB0_1000
	s_nop 0
	s_nop 0
	s_nop 0
	s_nop 0
	s_nop 0
	s_nop 0
	s_nop 0
	s_nop 0

; #define PG8_STAGE(bufoff, gbase, voff) do { _Pragma("unroll") for (int _i = 0; _i < 2; ++_i) \
;         __builtin_amdgcn_global_load_lds((const unsigned*)((const char*)(gbase) + (voff)[_i]), (PG8_LAS unsigned*)(lds + (bufoff) + ldsw + _i * 8192), 16, 0, 0); } while (0)
; #define PG8_LDA(dst, b, h) do { _Pragma("unroll") for (int m = 0; m < 4; ++m) _Pragma("unroll") for (int k = 0; k < 2; ++k) dst[m][k] = *(const PG8_LAS bf16x8*)(lds + PG8_SA(b, h) + aoff + m * 2048 + k * 1024); } while (0)
; #define PG8_LDB(dst, b, h) do { _Pragma("unroll") for (int n = 0; n < 2; ++n) _Pragma("unroll") for (int k = 0; k < 2; ++k) dst[n][k] = *(const PG8_LAS bf16x8*)(lds + PG8_SB(b, h) + boff + n * 2048 + k * 1024); } while (0)
; #define PG8_MMA(ai, bj, At, Bt) do { __builtin_amdgcn_s_setprio(1); _Pragma("unroll") for (int m = 0; m < 4; ++m) _Pragma("unroll") for (int n = 0; n < 2; ++n) _Pragma("unroll") for (int k = 0; k < 2; ++k) \
;         acc[ai][bj][m][n] = __builtin_amdgcn_mfma_f32_16x16x32_bf16(Bt[n][k], At[m][k], acc[ai][bj][m][n], 0, 0, 0); __builtin_amdgcn_s_setprio(0); } while (0)
; #define PG8_WAIT_V(n) asm volatile("s_waitcnt vmcnt(" #n ")" ::: "memory")
; #define PG8_WAIT_L(n) asm volatile("s_waitcnt lgkmcnt(" #n ")" ::: "memory")
; #define PG8_BAR __builtin_amdgcn_s_barrier()
; #define PG8_SCHED __builtin_amdgcn_sched_barrier(0)
; template <class Epi, class Sched, bool ALIGN_EPI = false, bool SP2 = false>
; __device__ __forceinline__ void gemm_phase(PG8_LAS unsigned char* lds, const Gemm g, const Sched& S, const Epi& E, int wave0) {
;     ...
;             PG8_LDB(B0, 0, 0); PG8_LDB(B1, 0, 1); PG8_SCHED; PG8_LDA(At, 0, 0); PG8_STAGE(PG8_SA(1, 1), a1 + hstep, voffA);
;             PG8_WAIT_V(8); PG8_WAIT_L(0); PG8_BAR; PG8_MMA(0, 0, At, B0); PG8_MMA(0, 1, At, B1); PG8_BAR; PG8_SCHED;
;             PG8_LDA(At, 0, 1); PG8_STAGE(PG8_SB(0, 0), b2, voffB); PG8_STAGE(PG8_SB(0, 1), b2 + hstep, voffB); PG8_STAGE(PG8_SA(0, 0), a2, voffA);
;             PG8_WAIT_V(8); PG8_WAIT_L(0); PG8_BAR; if (!cur.half) { PG8_MMA(1, 0, At, B0); PG8_MMA(1, 1, At, B1); } PG8_BAR; PG8_SCHED;
.LBB0_1101:
	ds_read_b128 v[128:131], v165
	ds_read_b128 v[132:135], v165 offset:1024
	ds_read_b128 v[152:155], v165 offset:2048
	ds_read_b128 v[156:159], v165 offset:3072
	ds_read_b128 v[170:173], v166
	ds_read_b128 v[174:177], v166 offset:1024
	ds_read_b128 v[178:181], v166 offset:2048
	ds_read_b128 v[182:185], v166 offset:3072
	s_add_u32 s0, s2, 0x100
	s_addc_u32 s1, s3, 0
	s_cmp_eq_u32 s50, 40
	s_cselect_b32 s35, s21, s1
	s_cselect_b32 s34, s20, s0
	s_cselect_b32 s31, s29, s49
	s_cselect_b32 s30, s28, s48
	v_lshl_add_u64 v[160:161], s[2:3], 0, v[144:145]
	s_add_i32 m0, s5, 0xc000
	ds_read_b128 v[186:189], v167
	ds_read_b128 v[190:193], v167 offset:1024
	ds_read_b128 v[194:197], v167 offset:2048
	ds_read_b128 v[198:201], v167 offset:3072
	ds_read_b128 v[202:205], v167 offset:4096
	ds_read_b128 v[206:209], v167 offset:5120
	ds_read_b128 v[210:213], v167 offset:6144
	ds_read_b128 v[218:221], v167 offset:7168
	global_load_lds_dwordx4 v[160:161], off
	v_lshl_add_u64 v[160:161], s[2:3], 0, v[146:147]
	s_add_i32 m0, s5, 0xe000
	s_nop 0
	global_load_lds_dwordx4 v[160:161], off
	s_waitcnt vmcnt(8)
	s_waitcnt lgkmcnt(0)
	s_barrier
	s_setprio 1
	s_waitcnt lgkmcnt(0)
	v_mfma_f32_16x16x32_bf16 v[124:127], v[128:131], v[186:189], v[124:127]
	v_mfma_f32_16x16x32_bf16 v[120:123], v[152:155], v[186:189], v[120:123]
	v_mfma_f32_16x16x32_bf16 v[108:111], v[128:131], v[194:197], v[108:111]
	v_mfma_f32_16x16x32_bf16 v[104:107], v[152:155], v[194:197], v[104:107]
	v_mfma_f32_16x16x32_bf16 v[92:95], v[128:131], v[202:205], v[92:95]
	v_mfma_f32_16x16x32_bf16 v[88:91], v[152:155], v[202:205], v[88:91]
	v_mfma_f32_16x16x32_bf16 v[76:79], v[128:131], v[210:213], v[76:79]
	v_mfma_f32_16x16x32_bf16 v[72:75], v[152:155], v[210:213], v[72:75]
	v_mfma_f32_16x16x32_bf16 v[124:127], v[132:135], v[190:193], v[124:127]
	v_mfma_f32_16x16x32_bf16 v[120:123], v[156:159], v[190:193], v[120:123]
	v_mfma_f32_16x16x32_bf16 v[108:111], v[132:135], v[198:201], v[108:111]
	v_mfma_f32_16x16x32_bf16 v[104:107], v[156:159], v[198:201], v[104:107]
	v_mfma_f32_16x16x32_bf16 v[92:95], v[132:135], v[206:209], v[92:95]
	v_mfma_f32_16x16x32_bf16 v[88:91], v[156:159], v[206:209], v[88:91]
	v_mfma_f32_16x16x32_bf16 v[76:79], v[132:135], v[218:221], v[76:79]
	v_mfma_f32_16x16x32_bf16 v[72:75], v[156:159], v[218:221], v[72:75]
	v_mfma_f32_16x16x32_bf16 v[116:119], v[170:173], v[186:189], v[116:119]
	v_mfma_f32_16x16x32_bf16 v[112:115], v[178:181], v[186:189], v[112:115]
	v_mfma_f32_16x16x32_bf16 v[100:103], v[170:173], v[194:197], v[100:103]
	v_mfma_f32_16x16x32_bf16 v[96:99], v[178:181], v[194:197], v[96:99]
	v_mfma_f32_16x16x32_bf16 v[84:87], v[170:173], v[202:205], v[84:87]
	v_mfma_f32_16x16x32_bf16 v[80:83], v[178:181], v[202:205], v[80:83]
	v_mfma_f32_16x16x32_bf16 v[68:71], v[170:173], v[210:213], v[68:71]
	v_mfma_f32_16x16x32_bf16 v[64:67], v[178:181], v[210:213], v[64:67]
	v_mfma_f32_16x16x32_bf16 v[116:119], v[174:177], v[190:193], v[116:119]
	v_mfma_f32_16x16x32_bf16 v[112:115], v[182:185], v[190:193], v[112:115]
	v_mfma_f32_16x16x32_bf16 v[100:103], v[174:177], v[198:201], v[100:103]
	v_mfma_f32_16x16x32_bf16 v[96:99], v[182:185], v[198:201], v[96:99]
	v_mfma_f32_16x16x32_bf16 v[84:87], v[174:177], v[206:209], v[84:87]
	v_mfma_f32_16x16x32_bf16 v[80:83], v[182:185], v[206:209], v[80:83]
	v_mfma_f32_16x16x32_bf16 v[68:71], v[174:177], v[218:221], v[68:71]
	v_mfma_f32_16x16x32_bf16 v[64:67], v[182:185], v[218:221], v[64:67]
	s_setprio 0
	s_barrier
	s_add_i32 s2, s41, s4
	v_lshl_add_u64 v[160:161], s[30:31], 0, v[138:139]
	s_mov_b32 m0, s2
	ds_read_b128 v[186:189], v167 offset:16384
	ds_read_b128 v[190:193], v167 offset:17408
	ds_read_b128 v[194:197], v167 offset:18432
	ds_read_b128 v[198:201], v167 offset:19456
	ds_read_b128 v[202:205], v167 offset:20480
	ds_read_b128 v[206:209], v167 offset:21504
	ds_read_b128 v[210:213], v167 offset:22528
	ds_read_b128 v[218:221], v167 offset:23552
	global_load_lds_dwordx4 v[160:161], off
	s_add_i32 m0, s2, 0x2000
	s_add_u32 s2, s30, 0xb0000
	v_lshl_add_u64 v[214:215], s[30:31], 0, v[142:143]
	s_addc_u32 s3, s31, 0
	s_add_i32 s51, s42, s4
	global_load_lds_dwordx4 v[214:215], off
	v_lshl_add_u64 v[222:223], s[2:3], 0, v[138:139]
	s_mov_b32 m0, s51
	v_lshl_add_u64 v[224:225], s[34:35], 0, v[140:141]
	global_load_lds_dwordx4 v[222:223], off
	v_lshl_add_u64 v[222:223], s[2:3], 0, v[142:143]
	s_add_i32 m0, s51, 0x2000
	s_nop 0
	global_load_lds_dwordx4 v[222:223], off
	v_lshl_add_u64 v[222:223], s[34:35], 0, v[136:137]
	s_mov_b32 m0, s5
	s_nop 0
	global_load_lds_dwordx4 v[222:223], off
	s_mov_b32 m0, s6
	s_nop 0
	global_load_lds_dwordx4 v[224:225], off
	s_waitcnt vmcnt(8)
	s_waitcnt lgkmcnt(0)
	s_barrier
; #define PG8_STAGE(bufoff, gbase, voff) do { _Pragma("unroll") for (int _i = 0; _i < 2; ++_i) \
;         __builtin_amdgcn_global_load_lds((const unsigned*)((const char*)(gbase) + (voff)[_i]), (PG8_LAS unsigned*)(lds + (bufoff) + ldsw + _i * 8192), 16, 0, 0); } while (0)
; #define PG8_LDA(dst, b, h) do { _Pragma("unroll") for (int m = 0; m < 4; ++m) _Pragma("unroll") for (int k = 0; k < 2; ++k) dst[m][k] = *(const PG8_LAS bf16x8*)(lds + PG8_SA(b, h) + aoff + m * 2048 + k * 1024); } while (0)
; #define PG8_LDB(dst, b, h) do { _Pragma("unroll") for (int n = 0; n < 2; ++n) _Pragma("unroll") for (int k = 0; k < 2; ++k) dst[n][k] = *(const PG8_LAS bf16x8*)(lds + PG8_SB(b, h) + boff + n * 2048 + k * 1024); } while (0)
; #define PG8_MMA(ai, bj, At, Bt) do { __builtin_amdgcn_s_setprio(1); _Pragma("unroll") for (int m = 0; m < 4; ++m) _Pragma("unroll") for (int n = 0; n < 2; ++n) _Pragma("unroll") for (int k = 0; k < 2; ++k) \
;         acc[ai][bj][m][n] = __builtin_amdgcn_mfma_f32_16x16x32_bf16(Bt[n][k], At[m][k], acc[ai][bj][m][n], 0, 0, 0); __builtin_amdgcn_s_setprio(0); } while (0)
; #define PG8_WAIT_V(n) asm volatile("s_waitcnt vmcnt(" #n ")" ::: "memory")
; #define PG8_WAIT_L(n) asm volatile("s_waitcnt lgkmcnt(" #n ")" ::: "memory")
; #define PG8_BAR __builtin_amdgcn_s_barrier()
; #define PG8_SCHED __builtin_amdgcn_sched_barrier(0)
; template <class Epi, class Sched, bool ALIGN_EPI = false, bool SP2 = false>
; __device__ __forceinline__ void gemm_phase(PG8_LAS unsigned char* lds, const Gemm g, const Sched& S, const Epi& E, int wave0) {
;     ...
;             PG8_WAIT_V(8); PG8_WAIT_L(0); PG8_BAR; if (!cur.half) { PG8_MMA(1, 0, At, B0); PG8_MMA(1, 1, At, B1); } PG8_BAR; PG8_SCHED;
;             PG8_LDB(B0, 1, 0); PG8_LDB(B1, 1, 1); PG8_SCHED; PG8_LDA(At, 1, 0); PG8_STAGE(PG8_SA(0, 1), a2 + hstep, voffA);
;             PG8_WAIT_V(8); PG8_WAIT_L(0); PG8_BAR; PG8_MMA(0, 0, At, B0); PG8_MMA(0, 1, At, B1); PG8_BAR; PG8_SCHED;
	s_setprio 1
	s_waitcnt lgkmcnt(0)
	v_mfma_f32_16x16x32_bf16 v[60:63], v[128:131], v[186:189], v[60:63]
	v_mfma_f32_16x16x32_bf16 v[56:59], v[152:155], v[186:189], v[56:59]
	v_mfma_f32_16x16x32_bf16 v[44:47], v[128:131], v[194:197], v[44:47]
	v_mfma_f32_16x16x32_bf16 v[40:43], v[152:155], v[194:197], v[40:43]
	v_mfma_f32_16x16x32_bf16 v[28:31], v[128:131], v[202:205], v[28:31]
	v_mfma_f32_16x16x32_bf16 v[24:27], v[152:155], v[202:205], v[24:27]
	v_mfma_f32_16x16x32_bf16 v[12:15], v[128:131], v[210:213], v[12:15]
	v_mfma_f32_16x16x32_bf16 v[8:11], v[152:155], v[210:213], v[8:11]
	v_mfma_f32_16x16x32_bf16 v[60:63], v[132:135], v[190:193], v[60:63]
	v_mfma_f32_16x16x32_bf16 v[56:59], v[156:159], v[190:193], v[56:59]
	v_mfma_f32_16x16x32_bf16 v[44:47], v[132:135], v[198:201], v[44:47]
	v_mfma_f32_16x16x32_bf16 v[40:43], v[156:159], v[198:201], v[40:43]
	v_mfma_f32_16x16x32_bf16 v[28:31], v[132:135], v[206:209], v[28:31]
	v_mfma_f32_16x16x32_bf16 v[24:27], v[156:159], v[206:209], v[24:27]
	v_mfma_f32_16x16x32_bf16 v[12:15], v[132:135], v[218:221], v[12:15]
	v_mfma_f32_16x16x32_bf16 v[8:11], v[156:159], v[218:221], v[8:11]
	v_mfma_f32_16x16x32_bf16 v[52:55], v[170:173], v[186:189], v[52:55]
	v_mfma_f32_16x16x32_bf16 v[48:51], v[178:181], v[186:189], v[48:51]
	v_mfma_f32_16x16x32_bf16 v[36:39], v[170:173], v[194:197], v[36:39]
	v_mfma_f32_16x16x32_bf16 v[32:35], v[178:181], v[194:197], v[32:35]
	v_mfma_f32_16x16x32_bf16 v[20:23], v[170:173], v[202:205], v[20:23]
	v_mfma_f32_16x16x32_bf16 v[16:19], v[178:181], v[202:205], v[16:19]
	v_mfma_f32_16x16x32_bf16 v[4:7], v[170:173], v[210:213], v[4:7]
	v_mfma_f32_16x16x32_bf16 v[0:3], v[178:181], v[210:213], v[0:3]
	v_mfma_f32_16x16x32_bf16 v[52:55], v[174:177], v[190:193], v[52:55]
	v_mfma_f32_16x16x32_bf16 v[48:51], v[182:185], v[190:193], v[48:51]
	v_mfma_f32_16x16x32_bf16 v[36:39], v[174:177], v[198:201], v[36:39]
	v_mfma_f32_16x16x32_bf16 v[32:35], v[182:185], v[198:201], v[32:35]
	v_mfma_f32_16x16x32_bf16 v[20:23], v[174:177], v[206:209], v[20:23]
	v_mfma_f32_16x16x32_bf16 v[16:19], v[182:185], v[206:209], v[16:19]
	v_mfma_f32_16x16x32_bf16 v[4:7], v[174:177], v[218:221], v[4:7]
	v_mfma_f32_16x16x32_bf16 v[0:3], v[182:185], v[218:221], v[0:3]
	s_setprio 0
	s_barrier
	s_add_i32 s51, 0, 0x18000
	s_add_i32 s52, 0, 0x1c000
	v_add_u32_e32 v156, s51, v164
	v_add_u32_e32 v169, s52, v164
	ds_read_b128 v[128:131], v156
	ds_read_b128 v[132:135], v156 offset:1024
	ds_read_b128 v[152:155], v156 offset:2048
	ds_read_b128 v[156:159], v156 offset:3072
	ds_read_b128 v[170:173], v169
	ds_read_b128 v[174:177], v169 offset:1024
	ds_read_b128 v[178:181], v169 offset:2048
	ds_read_b128 v[182:185], v169 offset:3072
	s_add_u32 s2, s34, 0xb0000
	s_addc_u32 s3, s35, 0
	s_mov_b32 m0, s7
	v_lshl_add_u64 v[226:227], s[2:3], 0, v[136:137]
	ds_read_b128 v[186:189], v167 offset:32768
	ds_read_b128 v[190:193], v167 offset:33792
	ds_read_b128 v[194:197], v167 offset:34816
	ds_read_b128 v[198:201], v167 offset:35840
	ds_read_b128 v[202:205], v167 offset:36864
	ds_read_b128 v[206:209], v167 offset:37888
	ds_read_b128 v[210:213], v167 offset:38912
	ds_read_b128 v[218:221], v167 offset:39936
	global_load_lds_dwordx4 v[226:227], off
	v_lshl_add_u64 v[226:227], s[2:3], 0, v[140:141]
	s_mov_b32 m0, s33
	s_nop 0
	global_load_lds_dwordx4 v[226:227], off
	s_waitcnt vmcnt(8)
	s_waitcnt lgkmcnt(0)
	s_barrier
	s_setprio 1
	s_waitcnt lgkmcnt(0)
	v_mfma_f32_16x16x32_bf16 v[124:127], v[128:131], v[186:189], v[124:127]
	v_mfma_f32_16x16x32_bf16 v[120:123], v[152:155], v[186:189], v[120:123]
	v_mfma_f32_16x16x32_bf16 v[108:111], v[128:131], v[194:197], v[108:111]
	v_mfma_f32_16x16x32_bf16 v[104:107], v[152:155], v[194:197], v[104:107]
	v_mfma_f32_16x16x32_bf16 v[92:95], v[128:131], v[202:205], v[92:95]
	v_mfma_f32_16x16x32_bf16 v[88:91], v[152:155], v[202:205], v[88:91]
	v_mfma_f32_16x16x32_bf16 v[76:79], v[128:131], v[210:213], v[76:79]
	v_mfma_f32_16x16x32_bf16 v[72:75], v[152:155], v[210:213], v[72:75]
	v_mfma_f32_16x16x32_bf16 v[124:127], v[132:135], v[190:193], v[124:127]
	v_mfma_f32_16x16x32_bf16 v[120:123], v[156:159], v[190:193], v[120:123]
	v_mfma_f32_16x16x32_bf16 v[108:111], v[132:135], v[198:201], v[108:111]
	v_mfma_f32_16x16x32_bf16 v[104:107], v[156:159], v[198:201], v[104:107]
	v_mfma_f32_16x16x32_bf16 v[92:95], v[132:135], v[206:209], v[92:95]
	v_mfma_f32_16x16x32_bf16 v[88:91], v[156:159], v[206:209], v[88:91]
	v_mfma_f32_16x16x32_bf16 v[76:79], v[132:135], v[218:221], v[76:79]
	v_mfma_f32_16x16x32_bf16 v[72:75], v[156:159], v[218:221], v[72:75]
	v_mfma_f32_16x16x32_bf16 v[116:119], v[170:173], v[186:189], v[116:119]
	v_mfma_f32_16x16x32_bf16 v[112:115], v[178:181], v[186:189], v[112:115]
	v_mfma_f32_16x16x32_bf16 v[100:103], v[170:173], v[194:197], v[100:103]
	v_mfma_f32_16x16x32_bf16 v[96:99], v[178:181], v[194:197], v[96:99]
	v_mfma_f32_16x16x32_bf16 v[84:87], v[170:173], v[202:205], v[84:87]
	v_mfma_f32_16x16x32_bf16 v[80:83], v[178:181], v[202:205], v[80:83]
	v_mfma_f32_16x16x32_bf16 v[68:71], v[170:173], v[210:213], v[68:71]
	v_mfma_f32_16x16x32_bf16 v[64:67], v[178:181], v[210:213], v[64:67]
	v_mfma_f32_16x16x32_bf16 v[116:119], v[174:177], v[190:193], v[116:119]
	v_mfma_f32_16x16x32_bf16 v[112:115], v[182:185], v[190:193], v[112:115]
	v_mfma_f32_16x16x32_bf16 v[100:103], v[174:177], v[198:201], v[100:103]
	v_mfma_f32_16x16x32_bf16 v[96:99], v[182:185], v[198:201], v[96:99]
	v_mfma_f32_16x16x32_bf16 v[84:87], v[174:177], v[206:209], v[84:87]
	v_mfma_f32_16x16x32_bf16 v[80:83], v[182:185], v[206:209], v[80:83]
	v_mfma_f32_16x16x32_bf16 v[68:71], v[174:177], v[218:221], v[68:71]
	v_mfma_f32_16x16x32_bf16 v[64:67], v[182:185], v[218:221], v[64:67]
	s_setprio 0
	s_barrier
; #define PG8_STAGE(bufoff, gbase, voff) do { _Pragma("unroll") for (int _i = 0; _i < 2; ++_i) \
;         __builtin_amdgcn_global_load_lds((const unsigned*)((const char*)(gbase) + (voff)[_i]), (PG8_LAS unsigned*)(lds + (bufoff) + ldsw + _i * 8192), 16, 0, 0); } while (0)
; #define PG8_LDA(dst, b, h) do { _Pragma("unroll") for (int m = 0; m < 4; ++m) _Pragma("unroll") for (int k = 0; k < 2; ++k) dst[m][k] = *(const PG8_LAS bf16x8*)(lds + PG8_SA(b, h) + aoff + m * 2048 + k * 1024); } while (0)
; #define PG8_MMA(ai, bj, At, Bt) do { __builtin_amdgcn_s_setprio(1); _Pragma("unroll") for (int m = 0; m < 4; ++m) _Pragma("unroll") for (int n = 0; n < 2; ++n) _Pragma("unroll") for (int k = 0; k < 2; ++k) \
;         acc[ai][bj][m][n] = __builtin_amdgcn_mfma_f32_16x16x32_bf16(Bt[n][k], At[m][k], acc[ai][bj][m][n], 0, 0, 0); __builtin_amdgcn_s_setprio(0); } while (0)
; #define PG8_WAIT_V(n) asm volatile("s_waitcnt vmcnt(" #n ")" ::: "memory")
; #define PG8_WAIT_L(n) asm volatile("s_waitcnt lgkmcnt(" #n ")" ::: "memory")
; #define PG8_BAR __builtin_amdgcn_s_barrier()
; #define PG8_SCHED __builtin_amdgcn_sched_barrier(0)
; template <class Epi, class Sched, bool ALIGN_EPI = false, bool SP2 = false>
; __device__ __forceinline__ void gemm_phase(PG8_LAS unsigned char* lds, const Gemm g, const Sched& S, const Epi& E, int wave0) {
;     ...
;         for (int t = 0; t < nt; t += 2) {
;             const bool last = (t == nt - 2);
;             const char* a1 = cA + (size_t)(t + 1) * kstep;
;             const char* a2 = last ? nA : cA + (size_t)(t + 2) * kstep; const char* b2 = last ? nB : cB + (size_t)(t + 2) * kstep;
;     ...
;             PG8_LDA(At, 1, 1); PG8_STAGE(PG8_SB(1, 0), b3, voffB); PG8_STAGE(PG8_SB(1, 1), b3 + hstep, voffB); PG8_STAGE(PG8_SA(1, 0), a3, voffA);
;             PG8_WAIT_V(8); PG8_WAIT_L(0); PG8_BAR; if (!cur.half) { PG8_MMA(1, 0, At, B0); PG8_MMA(1, 1, At, B1); } PG8_BAR; PG8_SCHED;
	s_add_i32 s2, s51, s4
	v_lshl_add_u64 v[160:161], v[160:161], 0, s[16:17]
	s_mov_b32 m0, s2
	ds_read_b128 v[186:189], v167 offset:49152
	ds_read_b128 v[190:193], v167 offset:50176
	ds_read_b128 v[194:197], v167 offset:51200
	ds_read_b128 v[198:201], v167 offset:52224
	ds_read_b128 v[202:205], v167 offset:53248
	ds_read_b128 v[206:209], v167 offset:54272
	ds_read_b128 v[210:213], v167 offset:55296
	ds_read_b128 v[218:221], v167 offset:56320
	global_load_lds_dwordx4 v[160:161], off
	s_add_i32 m0, s2, 0x2000
	s_add_u32 s2, s30, 0xb0080
	v_lshl_add_u64 v[160:161], v[214:215], 0, s[16:17]
	s_addc_u32 s3, s31, 0
	s_add_i32 s30, s52, s4
	global_load_lds_dwordx4 v[160:161], off
	v_lshl_add_u64 v[160:161], s[2:3], 0, v[138:139]
	s_mov_b32 m0, s30
	s_nop 0
	global_load_lds_dwordx4 v[160:161], off
	v_lshl_add_u64 v[160:161], s[2:3], 0, v[142:143]
	s_add_i32 m0, s30, 0x2000
	s_nop 0
	global_load_lds_dwordx4 v[160:161], off
	v_lshl_add_u64 v[160:161], v[222:223], 0, s[16:17]
	s_mov_b32 m0, s39
	s_nop 0
	global_load_lds_dwordx4 v[160:161], off
	v_lshl_add_u64 v[160:161], v[224:225], 0, s[16:17]
	s_mov_b32 m0, s40
	s_nop 0
	global_load_lds_dwordx4 v[160:161], off
	s_waitcnt vmcnt(8)
	s_waitcnt lgkmcnt(0)
	s_barrier
	s_setprio 1
	s_waitcnt lgkmcnt(0)
	v_mfma_f32_16x16x32_bf16 v[60:63], v[128:131], v[186:189], v[60:63]
	v_mfma_f32_16x16x32_bf16 v[56:59], v[152:155], v[186:189], v[56:59]
	v_mfma_f32_16x16x32_bf16 v[44:47], v[128:131], v[194:197], v[44:47]
	v_mfma_f32_16x16x32_bf16 v[40:43], v[152:155], v[194:197], v[40:43]
	v_mfma_f32_16x16x32_bf16 v[28:31], v[128:131], v[202:205], v[28:31]
	v_mfma_f32_16x16x32_bf16 v[24:27], v[152:155], v[202:205], v[24:27]
	v_mfma_f32_16x16x32_bf16 v[12:15], v[128:131], v[210:213], v[12:15]
	v_mfma_f32_16x16x32_bf16 v[8:11], v[152:155], v[210:213], v[8:11]
	v_mfma_f32_16x16x32_bf16 v[60:63], v[132:135], v[190:193], v[60:63]
	v_mfma_f32_16x16x32_bf16 v[56:59], v[156:159], v[190:193], v[56:59]
	v_mfma_f32_16x16x32_bf16 v[44:47], v[132:135], v[198:201], v[44:47]
	v_mfma_f32_16x16x32_bf16 v[40:43], v[156:159], v[198:201], v[40:43]
	v_mfma_f32_16x16x32_bf16 v[28:31], v[132:135], v[206:209], v[28:31]
	v_mfma_f32_16x16x32_bf16 v[24:27], v[156:159], v[206:209], v[24:27]
	v_mfma_f32_16x16x32_bf16 v[12:15], v[132:135], v[218:221], v[12:15]
	v_mfma_f32_16x16x32_bf16 v[8:11], v[156:159], v[218:221], v[8:11]
	v_mfma_f32_16x16x32_bf16 v[52:55], v[170:173], v[186:189], v[52:55]
	v_mfma_f32_16x16x32_bf16 v[48:51], v[178:181], v[186:189], v[48:51]
	v_mfma_f32_16x16x32_bf16 v[36:39], v[170:173], v[194:197], v[36:39]
	v_mfma_f32_16x16x32_bf16 v[32:35], v[178:181], v[194:197], v[32:35]
	v_mfma_f32_16x16x32_bf16 v[20:23], v[170:173], v[202:205], v[20:23]
	v_mfma_f32_16x16x32_bf16 v[16:19], v[178:181], v[202:205], v[16:19]
	v_mfma_f32_16x16x32_bf16 v[4:7], v[170:173], v[210:213], v[4:7]
	v_mfma_f32_16x16x32_bf16 v[0:3], v[178:181], v[210:213], v[0:3]
	v_mfma_f32_16x16x32_bf16 v[52:55], v[174:177], v[190:193], v[52:55]
	v_mfma_f32_16x16x32_bf16 v[48:51], v[182:185], v[190:193], v[48:51]
	v_mfma_f32_16x16x32_bf16 v[36:39], v[174:177], v[198:201], v[36:39]
	v_mfma_f32_16x16x32_bf16 v[32:35], v[182:185], v[198:201], v[32:35]
	v_mfma_f32_16x16x32_bf16 v[20:23], v[174:177], v[206:209], v[20:23]
	v_mfma_f32_16x16x32_bf16 v[16:19], v[182:185], v[206:209], v[16:19]
	v_mfma_f32_16x16x32_bf16 v[4:7], v[174:177], v[218:221], v[4:7]
	v_mfma_f32_16x16x32_bf16 v[0:3], v[182:185], v[218:221], v[0:3]
	s_setprio 0
	s_barrier
	s_add_i32 s50, s50, 2
	s_add_u32 s48, s48, 0x100
	s_addc_u32 s49, s49, 0
	s_cmp_gt_u32 s50, 41
	s_mov_b64 s[2:3], s[0:1]
	s_cbranch_scc0 .LBB0_1101
	s_nop 0
	s_nop 0
	s_nop 0
	s_nop 0
	s_nop 0
	s_nop 0
	s_nop 0
	s_nop 0
	s_and_b64 vcc, exec, s[18:19]
	s_cbranch_vccz .LBB0_1104
	s_barrier

; #define PG8_STAGE(bufoff, gbase, voff) do { _Pragma("unroll") for (int _i = 0; _i < 2; ++_i) \
;         __builtin_amdgcn_global_load_lds((const unsigned*)((const char*)(gbase) + (voff)[_i]), (PG8_LAS unsigned*)(lds + (bufoff) + ldsw + _i * 8192), 16, 0, 0); } while (0)
; #define PG8_LDA(dst, b, h) do { _Pragma("unroll") for (int m = 0; m < 4; ++m) _Pragma("unroll") for (int k = 0; k < 2; ++k) dst[m][k] = *(const PG8_LAS bf16x8*)(lds + PG8_SA(b, h) + aoff + m * 2048 + k * 1024); } while (0)
; #define PG8_LDB(dst, b, h) do { _Pragma("unroll") for (int n = 0; n < 2; ++n) _Pragma("unroll") for (int k = 0; k < 2; ++k) dst[n][k] = *(const PG8_LAS bf16x8*)(lds + PG8_SB(b, h) + boff + n * 2048 + k * 1024); } while (0)
; #define PG8_MMA(ai, bj, At, Bt) do { __builtin_amdgcn_s_setprio(1); _Pragma("unroll") for (int m = 0; m < 4; ++m) _Pragma("unroll") for (int n = 0; n < 2; ++n) _Pragma("unroll") for (int k = 0; k < 2; ++k) \
;         acc[ai][bj][m][n] = __builtin_amdgcn_mfma_f32_16x16x32_bf16(Bt[n][k], At[m][k], acc[ai][bj][m][n], 0, 0, 0); __builtin_amdgcn_s_setprio(0); } while (0)
; #define PG8_WAIT_V(n) asm volatile("s_waitcnt vmcnt(" #n ")" ::: "memory")
; #define PG8_WAIT_L(n) asm volatile("s_waitcnt lgkmcnt(" #n ")" ::: "memory")
; #define PG8_BAR __builtin_amdgcn_s_barrier()
; #define PG8_SCHED __builtin_amdgcn_sched_barrier(0)
; template <class Epi, class Sched, bool ALIGN_EPI = false, bool SP2 = false>
; __device__ __forceinline__ void gemm_phase(PG8_LAS unsigned char* lds, const Gemm g, const Sched& S, const Epi& E, int wave0) {
;     ...
;             PG8_LDB(B0, 0, 0); PG8_LDB(B1, 0, 1); PG8_SCHED; PG8_LDA(At, 0, 0); PG8_STAGE(PG8_SA(1, 1), a1 + hstep, voffA);
;             PG8_WAIT_V(8); PG8_WAIT_L(0); PG8_BAR; PG8_MMA(0, 0, At, B0); PG8_MMA(0, 1, At, B1); PG8_BAR; PG8_SCHED;
;             PG8_LDA(At, 0, 1); PG8_STAGE(PG8_SB(0, 0), b2, voffB); PG8_STAGE(PG8_SB(0, 1), b2 + hstep, voffB); PG8_STAGE(PG8_SA(0, 0), a2, voffA);
;             PG8_WAIT_V(8); PG8_WAIT_L(0); PG8_BAR; if (!cur.half) { PG8_MMA(1, 0, At, B0); PG8_MMA(1, 1, At, B1); } PG8_BAR; PG8_SCHED;
.LBB0_1208:
	ds_read_b128 v[128:131], v163
	ds_read_b128 v[132:135], v163 offset:1024
	ds_read_b128 v[136:139], v163 offset:2048
	ds_read_b128 v[170:173], v163 offset:3072
	ds_read_b128 v[174:177], v165
	ds_read_b128 v[178:181], v165 offset:1024
	ds_read_b128 v[182:185], v165 offset:2048
	ds_read_b128 v[186:189], v165 offset:3072
	s_add_u32 s2, s46, 0xfffc0080
	s_addc_u32 s3, s47, -1
	s_cmp_eq_u32 s68, 12
	s_cselect_b32 s51, s39, s3
	s_cselect_b32 s50, vcc_lo, s2
	s_cselect_b32 s49, s37, s62
	s_cselect_b32 s48, vcc_hi, s57
	v_lshl_add_u64 v[214:215], s[46:47], 0, v[148:149]
	s_add_i32 m0, s6, 0xc000
	ds_read_b128 v[190:193], v167
	ds_read_b128 v[194:197], v167 offset:1024
	ds_read_b128 v[198:201], v167 offset:2048
	ds_read_b128 v[202:205], v167 offset:3072
	ds_read_b128 v[206:209], v167 offset:4096
	ds_read_b128 v[210:213], v167 offset:5120
	ds_read_b128 v[218:221], v167 offset:6144
	ds_read_b128 v[222:225], v167 offset:7168
	global_load_lds_dwordx4 v[214:215], off
	v_lshl_add_u64 v[214:215], s[46:47], 0, v[150:151]
	s_add_i32 m0, s6, 0xe000
	s_nop 0
	global_load_lds_dwordx4 v[214:215], off
	s_waitcnt vmcnt(8)
	s_waitcnt lgkmcnt(0)
	s_barrier
	s_setprio 1
	s_waitcnt lgkmcnt(0)
	v_mfma_f32_16x16x32_bf16 v[124:127], v[128:131], v[190:193], v[124:127]
	v_mfma_f32_16x16x32_bf16 v[120:123], v[136:139], v[190:193], v[120:123]
	v_mfma_f32_16x16x32_bf16 v[108:111], v[128:131], v[198:201], v[108:111]
	v_mfma_f32_16x16x32_bf16 v[104:107], v[136:139], v[198:201], v[104:107]
	v_mfma_f32_16x16x32_bf16 v[96:99], v[128:131], v[206:209], v[96:99]
	v_mfma_f32_16x16x32_bf16 v[88:91], v[136:139], v[206:209], v[88:91]
	v_mfma_f32_16x16x32_bf16 v[80:83], v[128:131], v[218:221], v[80:83]
	v_mfma_f32_16x16x32_bf16 v[72:75], v[136:139], v[218:221], v[72:75]
	v_mfma_f32_16x16x32_bf16 v[124:127], v[132:135], v[194:197], v[124:127]
	v_mfma_f32_16x16x32_bf16 v[120:123], v[170:173], v[194:197], v[120:123]
	v_mfma_f32_16x16x32_bf16 v[108:111], v[132:135], v[202:205], v[108:111]
	v_mfma_f32_16x16x32_bf16 v[104:107], v[170:173], v[202:205], v[104:107]
	v_mfma_f32_16x16x32_bf16 v[96:99], v[132:135], v[210:213], v[96:99]
	v_mfma_f32_16x16x32_bf16 v[88:91], v[170:173], v[210:213], v[88:91]
	v_mfma_f32_16x16x32_bf16 v[80:83], v[132:135], v[222:225], v[80:83]
	v_mfma_f32_16x16x32_bf16 v[72:75], v[170:173], v[222:225], v[72:75]
	v_mfma_f32_16x16x32_bf16 v[116:119], v[174:177], v[190:193], v[116:119]
	v_mfma_f32_16x16x32_bf16 v[112:115], v[182:185], v[190:193], v[112:115]
	v_mfma_f32_16x16x32_bf16 v[100:103], v[174:177], v[198:201], v[100:103]
	v_mfma_f32_16x16x32_bf16 v[92:95], v[182:185], v[198:201], v[92:95]
	v_mfma_f32_16x16x32_bf16 v[84:87], v[174:177], v[206:209], v[84:87]
	v_mfma_f32_16x16x32_bf16 v[76:79], v[182:185], v[206:209], v[76:79]
	v_mfma_f32_16x16x32_bf16 v[68:71], v[174:177], v[218:221], v[68:71]
	v_mfma_f32_16x16x32_bf16 v[64:67], v[182:185], v[218:221], v[64:67]
	v_mfma_f32_16x16x32_bf16 v[116:119], v[178:181], v[194:197], v[116:119]
	v_mfma_f32_16x16x32_bf16 v[112:115], v[186:189], v[194:197], v[112:115]
	v_mfma_f32_16x16x32_bf16 v[100:103], v[178:181], v[202:205], v[100:103]
	v_mfma_f32_16x16x32_bf16 v[92:95], v[186:189], v[202:205], v[92:95]
	v_mfma_f32_16x16x32_bf16 v[84:87], v[178:181], v[210:213], v[84:87]
	v_mfma_f32_16x16x32_bf16 v[76:79], v[186:189], v[210:213], v[76:79]
	v_mfma_f32_16x16x32_bf16 v[68:71], v[178:181], v[222:225], v[68:71]
	v_mfma_f32_16x16x32_bf16 v[64:67], v[186:189], v[222:225], v[64:67]
	s_setprio 0
	s_barrier
	s_add_i32 s2, s84, s4
	v_lshl_add_u64 v[214:215], s[48:49], 0, v[144:145]
	s_mov_b32 m0, s2
	ds_read_b128 v[190:193], v167 offset:16384
	ds_read_b128 v[194:197], v167 offset:17408
	ds_read_b128 v[198:201], v167 offset:18432
	ds_read_b128 v[202:205], v167 offset:19456
	ds_read_b128 v[206:209], v167 offset:20480
	ds_read_b128 v[210:213], v167 offset:21504
	ds_read_b128 v[218:221], v167 offset:22528
	ds_read_b128 v[222:225], v167 offset:23552
	global_load_lds_dwordx4 v[214:215], off
	s_add_i32 m0, s2, 0x2000
	s_add_u32 s2, s48, 0x40000
	v_lshl_add_u64 v[226:227], s[48:49], 0, v[140:141]
	s_addc_u32 s3, s49, 0
	s_add_i32 s69, s85, s4
	global_load_lds_dwordx4 v[226:227], off
	v_lshl_add_u64 v[228:229], s[2:3], 0, v[144:145]
	s_mov_b32 m0, s69
	v_lshl_add_u64 v[230:231], s[50:51], 0, v[142:143]
	global_load_lds_dwordx4 v[228:229], off
	v_lshl_add_u64 v[228:229], s[2:3], 0, v[140:141]
	s_add_i32 m0, s69, 0x2000
	s_nop 0
	global_load_lds_dwordx4 v[228:229], off
	v_lshl_add_u64 v[228:229], s[50:51], 0, v[146:147]
	s_mov_b32 m0, s6
	s_nop 0
	global_load_lds_dwordx4 v[228:229], off
	s_mov_b32 m0, s7
	s_nop 0
	global_load_lds_dwordx4 v[230:231], off
	s_waitcnt vmcnt(8)
	s_waitcnt lgkmcnt(0)
	s_barrier
; #define PG8_STAGE(bufoff, gbase, voff) do { _Pragma("unroll") for (int _i = 0; _i < 2; ++_i) \
;         __builtin_amdgcn_global_load_lds((const unsigned*)((const char*)(gbase) + (voff)[_i]), (PG8_LAS unsigned*)(lds + (bufoff) + ldsw + _i * 8192), 16, 0, 0); } while (0)
; #define PG8_LDA(dst, b, h) do { _Pragma("unroll") for (int m = 0; m < 4; ++m) _Pragma("unroll") for (int k = 0; k < 2; ++k) dst[m][k] = *(const PG8_LAS bf16x8*)(lds + PG8_SA(b, h) + aoff + m * 2048 + k * 1024); } while (0)
; #define PG8_LDB(dst, b, h) do { _Pragma("unroll") for (int n = 0; n < 2; ++n) _Pragma("unroll") for (int k = 0; k < 2; ++k) dst[n][k] = *(const PG8_LAS bf16x8*)(lds + PG8_SB(b, h) + boff + n * 2048 + k * 1024); } while (0)
; #define PG8_MMA(ai, bj, At, Bt) do { __builtin_amdgcn_s_setprio(1); _Pragma("unroll") for (int m = 0; m < 4; ++m) _Pragma("unroll") for (int n = 0; n < 2; ++n) _Pragma("unroll") for (int k = 0; k < 2; ++k) \
;         acc[ai][bj][m][n] = __builtin_amdgcn_mfma_f32_16x16x32_bf16(Bt[n][k], At[m][k], acc[ai][bj][m][n], 0, 0, 0); __builtin_amdgcn_s_setprio(0); } while (0)
; #define PG8_WAIT_V(n) asm volatile("s_waitcnt vmcnt(" #n ")" ::: "memory")
; #define PG8_WAIT_L(n) asm volatile("s_waitcnt lgkmcnt(" #n ")" ::: "memory")
; #define PG8_BAR __builtin_amdgcn_s_barrier()
; #define PG8_SCHED __builtin_amdgcn_sched_barrier(0)
; template <class Epi, class Sched, bool ALIGN_EPI = false, bool SP2 = false>
; __device__ __forceinline__ void gemm_phase(PG8_LAS unsigned char* lds, const Gemm g, const Sched& S, const Epi& E, int wave0) {
;     ...
;             PG8_WAIT_V(8); PG8_WAIT_L(0); PG8_BAR; if (!cur.half) { PG8_MMA(1, 0, At, B0); PG8_MMA(1, 1, At, B1); } PG8_BAR; PG8_SCHED;
;             PG8_LDB(B0, 1, 0); PG8_LDB(B1, 1, 1); PG8_SCHED; PG8_LDA(At, 1, 0); PG8_STAGE(PG8_SA(0, 1), a2 + hstep, voffA);
;             PG8_WAIT_V(8); PG8_WAIT_L(0); PG8_BAR; PG8_MMA(0, 0, At, B0); PG8_MMA(0, 1, At, B1); PG8_BAR; PG8_SCHED;
	s_setprio 1
	s_waitcnt lgkmcnt(0)
	v_mfma_f32_16x16x32_bf16 v[60:63], v[128:131], v[190:193], v[60:63]
	v_mfma_f32_16x16x32_bf16 v[56:59], v[136:139], v[190:193], v[56:59]
	v_mfma_f32_16x16x32_bf16 v[48:51], v[128:131], v[198:201], v[48:51]
	v_mfma_f32_16x16x32_bf16 v[40:43], v[136:139], v[198:201], v[40:43]
	v_mfma_f32_16x16x32_bf16 v[32:35], v[128:131], v[206:209], v[32:35]
	v_mfma_f32_16x16x32_bf16 v[24:27], v[136:139], v[206:209], v[24:27]
	v_mfma_f32_16x16x32_bf16 v[16:19], v[128:131], v[218:221], v[16:19]
	v_mfma_f32_16x16x32_bf16 v[8:11], v[136:139], v[218:221], v[8:11]
	v_mfma_f32_16x16x32_bf16 v[60:63], v[132:135], v[194:197], v[60:63]
	v_mfma_f32_16x16x32_bf16 v[56:59], v[170:173], v[194:197], v[56:59]
	v_mfma_f32_16x16x32_bf16 v[48:51], v[132:135], v[202:205], v[48:51]
	v_mfma_f32_16x16x32_bf16 v[40:43], v[170:173], v[202:205], v[40:43]
	v_mfma_f32_16x16x32_bf16 v[32:35], v[132:135], v[210:213], v[32:35]
	v_mfma_f32_16x16x32_bf16 v[24:27], v[170:173], v[210:213], v[24:27]
	v_mfma_f32_16x16x32_bf16 v[16:19], v[132:135], v[222:225], v[16:19]
	v_mfma_f32_16x16x32_bf16 v[8:11], v[170:173], v[222:225], v[8:11]
	v_mfma_f32_16x16x32_bf16 v[52:55], v[174:177], v[190:193], v[52:55]
	v_mfma_f32_16x16x32_bf16 v[44:47], v[182:185], v[190:193], v[44:47]
	v_mfma_f32_16x16x32_bf16 v[36:39], v[174:177], v[198:201], v[36:39]
	v_mfma_f32_16x16x32_bf16 v[28:31], v[182:185], v[198:201], v[28:31]
	v_mfma_f32_16x16x32_bf16 v[20:23], v[174:177], v[206:209], v[20:23]
	v_mfma_f32_16x16x32_bf16 v[12:15], v[182:185], v[206:209], v[12:15]
	v_mfma_f32_16x16x32_bf16 v[4:7], v[174:177], v[218:221], v[4:7]
	v_mfma_f32_16x16x32_bf16 v[0:3], v[182:185], v[218:221], v[0:3]
	v_mfma_f32_16x16x32_bf16 v[52:55], v[178:181], v[194:197], v[52:55]
	v_mfma_f32_16x16x32_bf16 v[44:47], v[186:189], v[194:197], v[44:47]
	v_mfma_f32_16x16x32_bf16 v[36:39], v[178:181], v[202:205], v[36:39]
	v_mfma_f32_16x16x32_bf16 v[28:31], v[186:189], v[202:205], v[28:31]
	v_mfma_f32_16x16x32_bf16 v[20:23], v[178:181], v[210:213], v[20:23]
	v_mfma_f32_16x16x32_bf16 v[12:15], v[186:189], v[210:213], v[12:15]
	v_mfma_f32_16x16x32_bf16 v[4:7], v[178:181], v[222:225], v[4:7]
	v_mfma_f32_16x16x32_bf16 v[0:3], v[186:189], v[222:225], v[0:3]
	s_setprio 0
	s_barrier
	s_add_i32 s69, 0, 0x18000
	v_add_u32_e32 v156, s69, v161
	s_add_i32 s16, 0, 0x1c000
	ds_read_b128 v[128:131], v156
	ds_read_b128 v[132:135], v156 offset:1024
	ds_read_b128 v[136:139], v156 offset:2048
	ds_read_b128 v[170:173], v156 offset:3072
	v_add_u32_e32 v156, s16, v161
	ds_read_b128 v[174:177], v156
	ds_read_b128 v[178:181], v156 offset:1024
	ds_read_b128 v[182:185], v156 offset:2048
	ds_read_b128 v[186:189], v156 offset:3072
	s_add_u32 s2, s50, 0x40000
	s_addc_u32 s3, s51, 0
	s_mov_b32 m0, s33
	v_lshl_add_u64 v[232:233], s[2:3], 0, v[146:147]
	ds_read_b128 v[190:193], v167 offset:32768
	ds_read_b128 v[194:197], v167 offset:33792
	ds_read_b128 v[198:201], v167 offset:34816
	ds_read_b128 v[202:205], v167 offset:35840
	ds_read_b128 v[206:209], v167 offset:36864
	ds_read_b128 v[210:213], v167 offset:37888
	ds_read_b128 v[218:221], v167 offset:38912
	ds_read_b128 v[222:225], v167 offset:39936
	global_load_lds_dwordx4 v[232:233], off
	v_lshl_add_u64 v[232:233], s[2:3], 0, v[142:143]
	s_mov_b32 m0, s52
	s_nop 0
	global_load_lds_dwordx4 v[232:233], off
	s_waitcnt vmcnt(8)
	s_waitcnt lgkmcnt(0)
	s_barrier
	s_setprio 1
	s_waitcnt lgkmcnt(0)
	v_mfma_f32_16x16x32_bf16 v[124:127], v[128:131], v[190:193], v[124:127]
	v_mfma_f32_16x16x32_bf16 v[120:123], v[136:139], v[190:193], v[120:123]
	v_mfma_f32_16x16x32_bf16 v[108:111], v[128:131], v[198:201], v[108:111]
	v_mfma_f32_16x16x32_bf16 v[104:107], v[136:139], v[198:201], v[104:107]
	v_mfma_f32_16x16x32_bf16 v[96:99], v[128:131], v[206:209], v[96:99]
	v_mfma_f32_16x16x32_bf16 v[88:91], v[136:139], v[206:209], v[88:91]
	v_mfma_f32_16x16x32_bf16 v[80:83], v[128:131], v[218:221], v[80:83]
	v_mfma_f32_16x16x32_bf16 v[72:75], v[136:139], v[218:221], v[72:75]
	v_mfma_f32_16x16x32_bf16 v[124:127], v[132:135], v[194:197], v[124:127]
	v_mfma_f32_16x16x32_bf16 v[120:123], v[170:173], v[194:197], v[120:123]
	v_mfma_f32_16x16x32_bf16 v[108:111], v[132:135], v[202:205], v[108:111]
	v_mfma_f32_16x16x32_bf16 v[104:107], v[170:173], v[202:205], v[104:107]
	v_mfma_f32_16x16x32_bf16 v[96:99], v[132:135], v[210:213], v[96:99]
	v_mfma_f32_16x16x32_bf16 v[88:91], v[170:173], v[210:213], v[88:91]
	v_mfma_f32_16x16x32_bf16 v[80:83], v[132:135], v[222:225], v[80:83]
	v_mfma_f32_16x16x32_bf16 v[72:75], v[170:173], v[222:225], v[72:75]
	v_mfma_f32_16x16x32_bf16 v[116:119], v[174:177], v[190:193], v[116:119]
	v_mfma_f32_16x16x32_bf16 v[112:115], v[182:185], v[190:193], v[112:115]
	v_mfma_f32_16x16x32_bf16 v[100:103], v[174:177], v[198:201], v[100:103]
	v_mfma_f32_16x16x32_bf16 v[92:95], v[182:185], v[198:201], v[92:95]
	v_mfma_f32_16x16x32_bf16 v[84:87], v[174:177], v[206:209], v[84:87]
	v_mfma_f32_16x16x32_bf16 v[76:79], v[182:185], v[206:209], v[76:79]
	v_mfma_f32_16x16x32_bf16 v[68:71], v[174:177], v[218:221], v[68:71]
	v_mfma_f32_16x16x32_bf16 v[64:67], v[182:185], v[218:221], v[64:67]
	v_mfma_f32_16x16x32_bf16 v[116:119], v[178:181], v[194:197], v[116:119]
	v_mfma_f32_16x16x32_bf16 v[112:115], v[186:189], v[194:197], v[112:115]
	v_mfma_f32_16x16x32_bf16 v[100:103], v[178:181], v[202:205], v[100:103]
	v_mfma_f32_16x16x32_bf16 v[92:95], v[186:189], v[202:205], v[92:95]
	v_mfma_f32_16x16x32_bf16 v[84:87], v[178:181], v[210:213], v[84:87]
	v_mfma_f32_16x16x32_bf16 v[76:79], v[186:189], v[210:213], v[76:79]
	v_mfma_f32_16x16x32_bf16 v[68:71], v[178:181], v[222:225], v[68:71]
	v_mfma_f32_16x16x32_bf16 v[64:67], v[186:189], v[222:225], v[64:67]
	s_setprio 0
	s_barrier
; #define PG8_STAGE(bufoff, gbase, voff) do { _Pragma("unroll") for (int _i = 0; _i < 2; ++_i) \
;         __builtin_amdgcn_global_load_lds((const unsigned*)((const char*)(gbase) + (voff)[_i]), (PG8_LAS unsigned*)(lds + (bufoff) + ldsw + _i * 8192), 16, 0, 0); } while (0)
; #define PG8_LDA(dst, b, h) do { _Pragma("unroll") for (int m = 0; m < 4; ++m) _Pragma("unroll") for (int k = 0; k < 2; ++k) dst[m][k] = *(const PG8_LAS bf16x8*)(lds + PG8_SA(b, h) + aoff + m * 2048 + k * 1024); } while (0)
; #define PG8_MMA(ai, bj, At, Bt) do { __builtin_amdgcn_s_setprio(1); _Pragma("unroll") for (int m = 0; m < 4; ++m) _Pragma("unroll") for (int n = 0; n < 2; ++n) _Pragma("unroll") for (int k = 0; k < 2; ++k) \
;         acc[ai][bj][m][n] = __builtin_amdgcn_mfma_f32_16x16x32_bf16(Bt[n][k], At[m][k], acc[ai][bj][m][n], 0, 0, 0); __builtin_amdgcn_s_setprio(0); } while (0)
; #define PG8_WAIT_V(n) asm volatile("s_waitcnt vmcnt(" #n ")" ::: "memory")
; #define PG8_WAIT_L(n) asm volatile("s_waitcnt lgkmcnt(" #n ")" ::: "memory")
; #define PG8_BAR __builtin_amdgcn_s_barrier()
; #define PG8_SCHED __builtin_amdgcn_sched_barrier(0)
; template <class Epi, class Sched, bool ALIGN_EPI = false, bool SP2 = false>
; __device__ __forceinline__ void gemm_phase(PG8_LAS unsigned char* lds, const Gemm g, const Sched& S, const Epi& E, int wave0) {
;     ...
;         for (int t = 0; t < nt; t += 2) {
;             const bool last = (t == nt - 2);
;             const char* a1 = cA + (size_t)(t + 1) * kstep;
;             const char* a2 = last ? nA : cA + (size_t)(t + 2) * kstep; const char* b2 = last ? nB : cB + (size_t)(t + 2) * kstep;
;     ...
;             PG8_LDA(At, 1, 1); PG8_STAGE(PG8_SB(1, 0), b3, voffB); PG8_STAGE(PG8_SB(1, 1), b3 + hstep, voffB); PG8_STAGE(PG8_SA(1, 0), a3, voffA);
;             PG8_WAIT_V(8); PG8_WAIT_L(0); PG8_BAR; if (!cur.half) { PG8_MMA(1, 0, At, B0); PG8_MMA(1, 1, At, B1); } PG8_BAR; PG8_SCHED;
	s_add_i32 s2, s69, s4
	v_lshl_add_u64 v[214:215], v[214:215], 0, s[12:13]
	s_mov_b32 m0, s2
	ds_read_b128 v[190:193], v167 offset:49152
	ds_read_b128 v[194:197], v167 offset:50176
	ds_read_b128 v[198:201], v167 offset:51200
	ds_read_b128 v[202:205], v167 offset:52224
	ds_read_b128 v[206:209], v167 offset:53248
	ds_read_b128 v[210:213], v167 offset:54272
	ds_read_b128 v[218:221], v167 offset:55296
	ds_read_b128 v[222:225], v167 offset:56320
	global_load_lds_dwordx4 v[214:215], off
	s_add_i32 m0, s2, 0x2000
	s_add_u32 s2, s48, 0x40080
	v_lshl_add_u64 v[214:215], v[226:227], 0, s[12:13]
	s_addc_u32 s3, s49, 0
	s_add_i32 s16, s16, s4
	global_load_lds_dwordx4 v[214:215], off
	v_lshl_add_u64 v[214:215], s[2:3], 0, v[144:145]
	s_mov_b32 m0, s16
	s_nop 0
	global_load_lds_dwordx4 v[214:215], off
	v_lshl_add_u64 v[214:215], s[2:3], 0, v[140:141]
	s_add_i32 m0, s16, 0x2000
	s_nop 0
	global_load_lds_dwordx4 v[214:215], off
	v_lshl_add_u64 v[214:215], v[228:229], 0, s[12:13]
	s_mov_b32 m0, s63
	s_nop 0
	global_load_lds_dwordx4 v[214:215], off
	v_lshl_add_u64 v[214:215], v[230:231], 0, s[12:13]
	s_mov_b32 m0, s70
	s_nop 0
	global_load_lds_dwordx4 v[214:215], off
	s_waitcnt vmcnt(8)
	s_waitcnt lgkmcnt(0)
	s_barrier
	s_setprio 1
	s_waitcnt lgkmcnt(0)
	v_mfma_f32_16x16x32_bf16 v[60:63], v[128:131], v[190:193], v[60:63]
	v_mfma_f32_16x16x32_bf16 v[56:59], v[136:139], v[190:193], v[56:59]
	v_mfma_f32_16x16x32_bf16 v[48:51], v[128:131], v[198:201], v[48:51]
	v_mfma_f32_16x16x32_bf16 v[40:43], v[136:139], v[198:201], v[40:43]
	v_mfma_f32_16x16x32_bf16 v[32:35], v[128:131], v[206:209], v[32:35]
	v_mfma_f32_16x16x32_bf16 v[24:27], v[136:139], v[206:209], v[24:27]
	v_mfma_f32_16x16x32_bf16 v[16:19], v[128:131], v[218:221], v[16:19]
	v_mfma_f32_16x16x32_bf16 v[8:11], v[136:139], v[218:221], v[8:11]
	v_mfma_f32_16x16x32_bf16 v[60:63], v[132:135], v[194:197], v[60:63]
	v_mfma_f32_16x16x32_bf16 v[56:59], v[170:173], v[194:197], v[56:59]
	v_mfma_f32_16x16x32_bf16 v[48:51], v[132:135], v[202:205], v[48:51]
	v_mfma_f32_16x16x32_bf16 v[40:43], v[170:173], v[202:205], v[40:43]
	v_mfma_f32_16x16x32_bf16 v[32:35], v[132:135], v[210:213], v[32:35]
	v_mfma_f32_16x16x32_bf16 v[24:27], v[170:173], v[210:213], v[24:27]
	v_mfma_f32_16x16x32_bf16 v[16:19], v[132:135], v[222:225], v[16:19]
	v_mfma_f32_16x16x32_bf16 v[8:11], v[170:173], v[222:225], v[8:11]
	v_mfma_f32_16x16x32_bf16 v[52:55], v[174:177], v[190:193], v[52:55]
	v_mfma_f32_16x16x32_bf16 v[44:47], v[182:185], v[190:193], v[44:47]
	v_mfma_f32_16x16x32_bf16 v[36:39], v[174:177], v[198:201], v[36:39]
	v_mfma_f32_16x16x32_bf16 v[28:31], v[182:185], v[198:201], v[28:31]
	v_mfma_f32_16x16x32_bf16 v[20:23], v[174:177], v[206:209], v[20:23]
	v_mfma_f32_16x16x32_bf16 v[12:15], v[182:185], v[206:209], v[12:15]
	v_mfma_f32_16x16x32_bf16 v[4:7], v[174:177], v[218:221], v[4:7]
	v_mfma_f32_16x16x32_bf16 v[0:3], v[182:185], v[218:221], v[0:3]
	v_mfma_f32_16x16x32_bf16 v[52:55], v[178:181], v[194:197], v[52:55]
	v_mfma_f32_16x16x32_bf16 v[44:47], v[186:189], v[194:197], v[44:47]
	v_mfma_f32_16x16x32_bf16 v[36:39], v[178:181], v[202:205], v[36:39]
	v_mfma_f32_16x16x32_bf16 v[28:31], v[186:189], v[202:205], v[28:31]
	v_mfma_f32_16x16x32_bf16 v[20:23], v[178:181], v[210:213], v[20:23]
	v_mfma_f32_16x16x32_bf16 v[12:15], v[186:189], v[210:213], v[12:15]
	v_mfma_f32_16x16x32_bf16 v[4:7], v[178:181], v[222:225], v[4:7]
	v_mfma_f32_16x16x32_bf16 v[0:3], v[186:189], v[222:225], v[0:3]
	s_setprio 0
	s_barrier
	s_add_i32 s68, s68, 2
	s_add_u32 s46, s46, 0x100
	s_addc_u32 s47, s47, 0
	s_add_u32 s57, s57, 0x100
	s_addc_u32 s62, s62, 0
	s_cmp_gt_u32 s68, 13
	s_cbranch_scc0 .LBB0_1208
	s_nop 0
	s_nop 0
	s_nop 0
	s_nop 0
	s_nop 0
	s_nop 0
	s_nop 0
	s_nop 0
	s_and_b64 vcc, exec, s[14:15]
	s_cbranch_vccz .LBB0_1211
	s_barrier

; #define PG8_STAGE(bufoff, gbase, voff) do { _Pragma("unroll") for (int _i = 0; _i < 2; ++_i) \
;         __builtin_amdgcn_global_load_lds((const unsigned*)((const char*)(gbase) + (voff)[_i]), (PG8_LAS unsigned*)(lds + (bufoff) + ldsw + _i * 8192), 16, 0, 0); } while (0)
; #define PG8_LDA(dst, b, h) do { _Pragma("unroll") for (int m = 0; m < 4; ++m) _Pragma("unroll") for (int k = 0; k < 2; ++k) dst[m][k] = *(const PG8_LAS bf16x8*)(lds + PG8_SA(b, h) + aoff + m * 2048 + k * 1024); } while (0)
; #define PG8_LDB(dst, b, h) do { _Pragma("unroll") for (int n = 0; n < 2; ++n) _Pragma("unroll") for (int k = 0; k < 2; ++k) dst[n][k] = *(const PG8_LAS bf16x8*)(lds + PG8_SB(b, h) + boff + n * 2048 + k * 1024); } while (0)
; #define PG8_MMA(ai, bj, At, Bt) do { __builtin_amdgcn_s_setprio(1); _Pragma("unroll") for (int m = 0; m < 4; ++m) _Pragma("unroll") for (int n = 0; n < 2; ++n) _Pragma("unroll") for (int k = 0; k < 2; ++k) \
;         acc[ai][bj][m][n] = __builtin_amdgcn_mfma_f32_16x16x32_bf16(Bt[n][k], At[m][k], acc[ai][bj][m][n], 0, 0, 0); __builtin_amdgcn_s_setprio(0); } while (0)
; #define PG8_WAIT_V(n) asm volatile("s_waitcnt vmcnt(" #n ")" ::: "memory")
; template <class Epi, class Sched, bool ALIGN_EPI = false, bool SP2 = false>
; __device__ __forceinline__ void gemm_phase(PG8_LAS unsigned char* lds, const Gemm g, const Sched& S, const Epi& E, int wave0) {
;     ...
;         for (int t = 0; t < nt; t += 2) {
;             const bool last = (t == nt - 2);
;             const char* a1 = cA + (size_t)(t + 1) * kstep;
;             const char* a2 = last ? nA : cA + (size_t)(t + 2) * kstep; const char* b2 = last ? nB : cB + (size_t)(t + 2) * kstep;
;             const char* a3 = a2 + kstep; const char* b3 = b2 + kstep;
;             if (last && has_next) S.a_ready(nxt);
;             if constexpr (SP2) {
;             PG8_LDB(B0, 0, 0); PG8_LDB(B1, 0, 1); PG8_SCHED; PG8_LDA(At, 0, 0); PG8_STAGE(PG8_SA(1, 1), a1 + hstep, voffA);
;             PG8_WAIT_V(8); PG8_WAIT_L(0); PG8_BAR; PG8_MMA(0, 0, At, B0); PG8_MMA(0, 1, At, B1); PG8_BAR; PG8_SCHED;
;             PG8_LDA(At, 0, 1); PG8_STAGE(PG8_SB(0, 0), b2, voffB); PG8_STAGE(PG8_SB(0, 1), b2 + hstep, voffB); PG8_STAGE(PG8_SA(0, 0), a2, voffA);
;             PG8_WAIT_V(8); PG8_WAIT_L(0); PG8_BAR; if (!cur.half) { PG8_MMA(1, 0, At, B0); PG8_MMA(1, 1, At, B1); } PG8_BAR; PG8_SCHED;
.LBB0_2493:
	ds_read_b128 v[128:131], v165
	ds_read_b128 v[132:135], v165 offset:1024
	ds_read_b128 v[152:155], v165 offset:2048
	ds_read_b128 v[156:159], v165 offset:3072
	ds_read_b128 v[170:173], v166
	ds_read_b128 v[174:177], v166 offset:1024
	ds_read_b128 v[178:181], v166 offset:2048
	ds_read_b128 v[182:185], v166 offset:3072
	s_add_u32 s26, s24, 0xfffc0080
	s_addc_u32 s27, s25, -1
	s_cmp_eq_u32 s44, 12
	s_cselect_b32 s29, s1, s27
	s_cselect_b32 s28, s19, s26
	s_cselect_b32 s27, s17, s43
	s_cselect_b32 s26, s41, s42
	v_lshl_add_u64 v[160:161], s[24:25], 0, v[144:145]
	s_add_i32 m0, s5, 0xc000
	ds_read_b128 v[186:189], v167
	ds_read_b128 v[190:193], v167 offset:1024
	ds_read_b128 v[194:197], v167 offset:2048
	ds_read_b128 v[198:201], v167 offset:3072
	ds_read_b128 v[202:205], v167 offset:4096
	ds_read_b128 v[206:209], v167 offset:5120
	ds_read_b128 v[210:213], v167 offset:6144
	ds_read_b128 v[218:221], v167 offset:7168
	global_load_lds_dwordx4 v[160:161], off
	v_lshl_add_u64 v[160:161], s[24:25], 0, v[146:147]
	s_add_i32 m0, s5, 0xe000
	s_nop 0
	global_load_lds_dwordx4 v[160:161], off
	s_waitcnt vmcnt(8)
	s_waitcnt lgkmcnt(0)
	s_barrier
	s_setprio 1
	s_waitcnt lgkmcnt(0)
	v_mfma_f32_16x16x32_bf16 v[124:127], v[128:131], v[186:189], v[124:127]
	v_mfma_f32_16x16x32_bf16 v[120:123], v[152:155], v[186:189], v[120:123]
	v_mfma_f32_16x16x32_bf16 v[108:111], v[128:131], v[194:197], v[108:111]
	v_mfma_f32_16x16x32_bf16 v[104:107], v[152:155], v[194:197], v[104:107]
	v_mfma_f32_16x16x32_bf16 v[92:95], v[128:131], v[202:205], v[92:95]
	v_mfma_f32_16x16x32_bf16 v[88:91], v[152:155], v[202:205], v[88:91]
	v_mfma_f32_16x16x32_bf16 v[76:79], v[128:131], v[210:213], v[76:79]
	v_mfma_f32_16x16x32_bf16 v[72:75], v[152:155], v[210:213], v[72:75]
	v_mfma_f32_16x16x32_bf16 v[124:127], v[132:135], v[190:193], v[124:127]
	v_mfma_f32_16x16x32_bf16 v[120:123], v[156:159], v[190:193], v[120:123]
	v_mfma_f32_16x16x32_bf16 v[108:111], v[132:135], v[198:201], v[108:111]
	v_mfma_f32_16x16x32_bf16 v[104:107], v[156:159], v[198:201], v[104:107]
	v_mfma_f32_16x16x32_bf16 v[92:95], v[132:135], v[206:209], v[92:95]
	v_mfma_f32_16x16x32_bf16 v[88:91], v[156:159], v[206:209], v[88:91]
	v_mfma_f32_16x16x32_bf16 v[76:79], v[132:135], v[218:221], v[76:79]
	v_mfma_f32_16x16x32_bf16 v[72:75], v[156:159], v[218:221], v[72:75]
	v_mfma_f32_16x16x32_bf16 v[116:119], v[170:173], v[186:189], v[116:119]
	v_mfma_f32_16x16x32_bf16 v[112:115], v[178:181], v[186:189], v[112:115]
	v_mfma_f32_16x16x32_bf16 v[100:103], v[170:173], v[194:197], v[100:103]
	v_mfma_f32_16x16x32_bf16 v[96:99], v[178:181], v[194:197], v[96:99]
	v_mfma_f32_16x16x32_bf16 v[84:87], v[170:173], v[202:205], v[84:87]
	v_mfma_f32_16x16x32_bf16 v[80:83], v[178:181], v[202:205], v[80:83]
	v_mfma_f32_16x16x32_bf16 v[68:71], v[170:173], v[210:213], v[68:71]
	v_mfma_f32_16x16x32_bf16 v[64:67], v[178:181], v[210:213], v[64:67]
	v_mfma_f32_16x16x32_bf16 v[116:119], v[174:177], v[190:193], v[116:119]
	v_mfma_f32_16x16x32_bf16 v[112:115], v[182:185], v[190:193], v[112:115]
	v_mfma_f32_16x16x32_bf16 v[100:103], v[174:177], v[198:201], v[100:103]
	v_mfma_f32_16x16x32_bf16 v[96:99], v[182:185], v[198:201], v[96:99]
	v_mfma_f32_16x16x32_bf16 v[84:87], v[174:177], v[206:209], v[84:87]
	v_mfma_f32_16x16x32_bf16 v[80:83], v[182:185], v[206:209], v[80:83]
	v_mfma_f32_16x16x32_bf16 v[68:71], v[174:177], v[218:221], v[68:71]
	v_mfma_f32_16x16x32_bf16 v[64:67], v[182:185], v[218:221], v[64:67]
	s_setprio 0
	s_barrier
	s_add_i32 s45, s37, s4
	v_lshl_add_u64 v[160:161], s[26:27], 0, v[138:139]
	s_mov_b32 m0, s45
	ds_read_b128 v[186:189], v167 offset:16384
	ds_read_b128 v[190:193], v167 offset:17408
	ds_read_b128 v[194:197], v167 offset:18432
	ds_read_b128 v[198:201], v167 offset:19456
	ds_read_b128 v[202:205], v167 offset:20480
	ds_read_b128 v[206:209], v167 offset:21504
	ds_read_b128 v[210:213], v167 offset:22528
	ds_read_b128 v[218:221], v167 offset:23552
	global_load_lds_dwordx4 v[160:161], off
	s_add_i32 m0, s45, 0x2000
	s_add_u32 s46, s26, 0x40000
	v_lshl_add_u64 v[214:215], s[26:27], 0, v[142:143]
	s_addc_u32 s47, s27, 0
	s_add_i32 s45, s38, s4
	global_load_lds_dwordx4 v[214:215], off
	v_lshl_add_u64 v[222:223], s[46:47], 0, v[138:139]
	s_mov_b32 m0, s45
	v_lshl_add_u64 v[224:225], s[28:29], 0, v[140:141]
	global_load_lds_dwordx4 v[222:223], off
	v_lshl_add_u64 v[222:223], s[46:47], 0, v[142:143]
	s_add_i32 m0, s45, 0x2000
	s_nop 0
	global_load_lds_dwordx4 v[222:223], off
	v_lshl_add_u64 v[222:223], s[28:29], 0, v[136:137]
	s_mov_b32 m0, s5
	s_nop 0
	global_load_lds_dwordx4 v[222:223], off
	s_mov_b32 m0, s6
	s_nop 0
	global_load_lds_dwordx4 v[224:225], off
	s_waitcnt vmcnt(8)
	s_waitcnt lgkmcnt(0)
	s_barrier
; #define PG8_STAGE(bufoff, gbase, voff) do { _Pragma("unroll") for (int _i = 0; _i < 2; ++_i) \
;         __builtin_amdgcn_global_load_lds((const unsigned*)((const char*)(gbase) + (voff)[_i]), (PG8_LAS unsigned*)(lds + (bufoff) + ldsw + _i * 8192), 16, 0, 0); } while (0)
; #define PG8_LDA(dst, b, h) do { _Pragma("unroll") for (int m = 0; m < 4; ++m) _Pragma("unroll") for (int k = 0; k < 2; ++k) dst[m][k] = *(const PG8_LAS bf16x8*)(lds + PG8_SA(b, h) + aoff + m * 2048 + k * 1024); } while (0)
; #define PG8_LDB(dst, b, h) do { _Pragma("unroll") for (int n = 0; n < 2; ++n) _Pragma("unroll") for (int k = 0; k < 2; ++k) dst[n][k] = *(const PG8_LAS bf16x8*)(lds + PG8_SB(b, h) + boff + n * 2048 + k * 1024); } while (0)
; #define PG8_MMA(ai, bj, At, Bt) do { __builtin_amdgcn_s_setprio(1); _Pragma("unroll") for (int m = 0; m < 4; ++m) _Pragma("unroll") for (int n = 0; n < 2; ++n) _Pragma("unroll") for (int k = 0; k < 2; ++k) \
;         acc[ai][bj][m][n] = __builtin_amdgcn_mfma_f32_16x16x32_bf16(Bt[n][k], At[m][k], acc[ai][bj][m][n], 0, 0, 0); __builtin_amdgcn_s_setprio(0); } while (0)
; #define PG8_WAIT_V(n) asm volatile("s_waitcnt vmcnt(" #n ")" ::: "memory")
; #define PG8_WAIT_L(n) asm volatile("s_waitcnt lgkmcnt(" #n ")" ::: "memory")
; #define PG8_BAR __builtin_amdgcn_s_barrier()
; #define PG8_SCHED __builtin_amdgcn_sched_barrier(0)
; template <class Epi, class Sched, bool ALIGN_EPI = false, bool SP2 = false>
; __device__ __forceinline__ void gemm_phase(PG8_LAS unsigned char* lds, const Gemm g, const Sched& S, const Epi& E, int wave0) {
;     ...
;             PG8_WAIT_V(8); PG8_WAIT_L(0); PG8_BAR; if (!cur.half) { PG8_MMA(1, 0, At, B0); PG8_MMA(1, 1, At, B1); } PG8_BAR; PG8_SCHED;
;             PG8_LDB(B0, 1, 0); PG8_LDB(B1, 1, 1); PG8_SCHED; PG8_LDA(At, 1, 0); PG8_STAGE(PG8_SA(0, 1), a2 + hstep, voffA);
;             PG8_WAIT_V(8); PG8_WAIT_L(0); PG8_BAR; PG8_MMA(0, 0, At, B0); PG8_MMA(0, 1, At, B1); PG8_BAR; PG8_SCHED;
	s_setprio 1
	s_waitcnt lgkmcnt(0)
	v_mfma_f32_16x16x32_bf16 v[60:63], v[128:131], v[186:189], v[60:63]
	v_mfma_f32_16x16x32_bf16 v[56:59], v[152:155], v[186:189], v[56:59]
	v_mfma_f32_16x16x32_bf16 v[44:47], v[128:131], v[194:197], v[44:47]
	v_mfma_f32_16x16x32_bf16 v[40:43], v[152:155], v[194:197], v[40:43]
	v_mfma_f32_16x16x32_bf16 v[28:31], v[128:131], v[202:205], v[28:31]
	v_mfma_f32_16x16x32_bf16 v[24:27], v[152:155], v[202:205], v[24:27]
	v_mfma_f32_16x16x32_bf16 v[12:15], v[128:131], v[210:213], v[12:15]
	v_mfma_f32_16x16x32_bf16 v[8:11], v[152:155], v[210:213], v[8:11]
	v_mfma_f32_16x16x32_bf16 v[60:63], v[132:135], v[190:193], v[60:63]
	v_mfma_f32_16x16x32_bf16 v[56:59], v[156:159], v[190:193], v[56:59]
	v_mfma_f32_16x16x32_bf16 v[44:47], v[132:135], v[198:201], v[44:47]
	v_mfma_f32_16x16x32_bf16 v[40:43], v[156:159], v[198:201], v[40:43]
	v_mfma_f32_16x16x32_bf16 v[28:31], v[132:135], v[206:209], v[28:31]
	v_mfma_f32_16x16x32_bf16 v[24:27], v[156:159], v[206:209], v[24:27]
	v_mfma_f32_16x16x32_bf16 v[12:15], v[132:135], v[218:221], v[12:15]
	v_mfma_f32_16x16x32_bf16 v[8:11], v[156:159], v[218:221], v[8:11]
	v_mfma_f32_16x16x32_bf16 v[52:55], v[170:173], v[186:189], v[52:55]
	v_mfma_f32_16x16x32_bf16 v[48:51], v[178:181], v[186:189], v[48:51]
	v_mfma_f32_16x16x32_bf16 v[36:39], v[170:173], v[194:197], v[36:39]
	v_mfma_f32_16x16x32_bf16 v[32:35], v[178:181], v[194:197], v[32:35]
	v_mfma_f32_16x16x32_bf16 v[20:23], v[170:173], v[202:205], v[20:23]
	v_mfma_f32_16x16x32_bf16 v[16:19], v[178:181], v[202:205], v[16:19]
	v_mfma_f32_16x16x32_bf16 v[4:7], v[170:173], v[210:213], v[4:7]
	v_mfma_f32_16x16x32_bf16 v[0:3], v[178:181], v[210:213], v[0:3]
	v_mfma_f32_16x16x32_bf16 v[52:55], v[174:177], v[190:193], v[52:55]
	v_mfma_f32_16x16x32_bf16 v[48:51], v[182:185], v[190:193], v[48:51]
	v_mfma_f32_16x16x32_bf16 v[36:39], v[174:177], v[198:201], v[36:39]
	v_mfma_f32_16x16x32_bf16 v[32:35], v[182:185], v[198:201], v[32:35]
	v_mfma_f32_16x16x32_bf16 v[20:23], v[174:177], v[206:209], v[20:23]
	v_mfma_f32_16x16x32_bf16 v[16:19], v[182:185], v[206:209], v[16:19]
	v_mfma_f32_16x16x32_bf16 v[4:7], v[174:177], v[218:221], v[4:7]
	v_mfma_f32_16x16x32_bf16 v[0:3], v[182:185], v[218:221], v[0:3]
	s_setprio 0
	s_barrier
	s_add_i32 s45, 0, 0x18000
	s_add_i32 s46, 0, 0x1c000
	v_add_u32_e32 v156, s45, v164
	v_add_u32_e32 v169, s46, v164
	ds_read_b128 v[128:131], v156
	ds_read_b128 v[132:135], v156 offset:1024
	ds_read_b128 v[152:155], v156 offset:2048
	ds_read_b128 v[156:159], v156 offset:3072
	ds_read_b128 v[170:173], v169
	ds_read_b128 v[174:177], v169 offset:1024
	ds_read_b128 v[178:181], v169 offset:2048
	ds_read_b128 v[182:185], v169 offset:3072
	s_add_u32 s28, s28, 0x40000
	s_addc_u32 s29, s29, 0
	s_mov_b32 m0, s7
	v_lshl_add_u64 v[226:227], s[28:29], 0, v[136:137]
	ds_read_b128 v[186:189], v167 offset:32768
	ds_read_b128 v[190:193], v167 offset:33792
	ds_read_b128 v[194:197], v167 offset:34816
	ds_read_b128 v[198:201], v167 offset:35840
	ds_read_b128 v[202:205], v167 offset:36864
	ds_read_b128 v[206:209], v167 offset:37888
	ds_read_b128 v[210:213], v167 offset:38912
	ds_read_b128 v[218:221], v167 offset:39936
	global_load_lds_dwordx4 v[226:227], off
	v_lshl_add_u64 v[226:227], s[28:29], 0, v[140:141]
	s_mov_b32 m0, s30
	s_nop 0
	global_load_lds_dwordx4 v[226:227], off
	s_waitcnt vmcnt(8)
	s_waitcnt lgkmcnt(0)
	s_barrier
	s_setprio 1
	s_waitcnt lgkmcnt(0)
	v_mfma_f32_16x16x32_bf16 v[124:127], v[128:131], v[186:189], v[124:127]
	v_mfma_f32_16x16x32_bf16 v[120:123], v[152:155], v[186:189], v[120:123]
	v_mfma_f32_16x16x32_bf16 v[108:111], v[128:131], v[194:197], v[108:111]
	v_mfma_f32_16x16x32_bf16 v[104:107], v[152:155], v[194:197], v[104:107]
	v_mfma_f32_16x16x32_bf16 v[92:95], v[128:131], v[202:205], v[92:95]
	v_mfma_f32_16x16x32_bf16 v[88:91], v[152:155], v[202:205], v[88:91]
	v_mfma_f32_16x16x32_bf16 v[76:79], v[128:131], v[210:213], v[76:79]
	v_mfma_f32_16x16x32_bf16 v[72:75], v[152:155], v[210:213], v[72:75]
	v_mfma_f32_16x16x32_bf16 v[124:127], v[132:135], v[190:193], v[124:127]
	v_mfma_f32_16x16x32_bf16 v[120:123], v[156:159], v[190:193], v[120:123]
	v_mfma_f32_16x16x32_bf16 v[108:111], v[132:135], v[198:201], v[108:111]
	v_mfma_f32_16x16x32_bf16 v[104:107], v[156:159], v[198:201], v[104:107]
	v_mfma_f32_16x16x32_bf16 v[92:95], v[132:135], v[206:209], v[92:95]
	v_mfma_f32_16x16x32_bf16 v[88:91], v[156:159], v[206:209], v[88:91]
	v_mfma_f32_16x16x32_bf16 v[76:79], v[132:135], v[218:221], v[76:79]
	v_mfma_f32_16x16x32_bf16 v[72:75], v[156:159], v[218:221], v[72:75]
	v_mfma_f32_16x16x32_bf16 v[116:119], v[170:173], v[186:189], v[116:119]
	v_mfma_f32_16x16x32_bf16 v[112:115], v[178:181], v[186:189], v[112:115]
	v_mfma_f32_16x16x32_bf16 v[100:103], v[170:173], v[194:197], v[100:103]
	v_mfma_f32_16x16x32_bf16 v[96:99], v[178:181], v[194:197], v[96:99]
	v_mfma_f32_16x16x32_bf16 v[84:87], v[170:173], v[202:205], v[84:87]
	v_mfma_f32_16x16x32_bf16 v[80:83], v[178:181], v[202:205], v[80:83]
	v_mfma_f32_16x16x32_bf16 v[68:71], v[170:173], v[210:213], v[68:71]
	v_mfma_f32_16x16x32_bf16 v[64:67], v[178:181], v[210:213], v[64:67]
	v_mfma_f32_16x16x32_bf16 v[116:119], v[174:177], v[190:193], v[116:119]
	v_mfma_f32_16x16x32_bf16 v[112:115], v[182:185], v[190:193], v[112:115]
	v_mfma_f32_16x16x32_bf16 v[100:103], v[174:177], v[198:201], v[100:103]
	v_mfma_f32_16x16x32_bf16 v[96:99], v[182:185], v[198:201], v[96:99]
	v_mfma_f32_16x16x32_bf16 v[84:87], v[174:177], v[206:209], v[84:87]
	v_mfma_f32_16x16x32_bf16 v[80:83], v[182:185], v[206:209], v[80:83]
	v_mfma_f32_16x16x32_bf16 v[68:71], v[174:177], v[218:221], v[68:71]
	v_mfma_f32_16x16x32_bf16 v[64:67], v[182:185], v[218:221], v[64:67]
	s_setprio 0
	s_barrier
; #define PG8_STAGE(bufoff, gbase, voff) do { _Pragma("unroll") for (int _i = 0; _i < 2; ++_i) \
;         __builtin_amdgcn_global_load_lds((const unsigned*)((const char*)(gbase) + (voff)[_i]), (PG8_LAS unsigned*)(lds + (bufoff) + ldsw + _i * 8192), 16, 0, 0); } while (0)
; #define PG8_LDA(dst, b, h) do { _Pragma("unroll") for (int m = 0; m < 4; ++m) _Pragma("unroll") for (int k = 0; k < 2; ++k) dst[m][k] = *(const PG8_LAS bf16x8*)(lds + PG8_SA(b, h) + aoff + m * 2048 + k * 1024); } while (0)
; #define PG8_MMA(ai, bj, At, Bt) do { __builtin_amdgcn_s_setprio(1); _Pragma("unroll") for (int m = 0; m < 4; ++m) _Pragma("unroll") for (int n = 0; n < 2; ++n) _Pragma("unroll") for (int k = 0; k < 2; ++k) \
;         acc[ai][bj][m][n] = __builtin_amdgcn_mfma_f32_16x16x32_bf16(Bt[n][k], At[m][k], acc[ai][bj][m][n], 0, 0, 0); __builtin_amdgcn_s_setprio(0); } while (0)
; #define PG8_WAIT_V(n) asm volatile("s_waitcnt vmcnt(" #n ")" ::: "memory")
; #define PG8_WAIT_L(n) asm volatile("s_waitcnt lgkmcnt(" #n ")" ::: "memory")
; #define PG8_BAR __builtin_amdgcn_s_barrier()
; #define PG8_SCHED __builtin_amdgcn_sched_barrier(0)
; template <class Epi, class Sched, bool ALIGN_EPI = false, bool SP2 = false>
; __device__ __forceinline__ void gemm_phase(PG8_LAS unsigned char* lds, const Gemm g, const Sched& S, const Epi& E, int wave0) {
;     ...
;         for (int t = 0; t < nt; t += 2) {
;             const bool last = (t == nt - 2);
;             const char* a1 = cA + (size_t)(t + 1) * kstep;
;             const char* a2 = last ? nA : cA + (size_t)(t + 2) * kstep; const char* b2 = last ? nB : cB + (size_t)(t + 2) * kstep;
;     ...
;             PG8_LDA(At, 1, 1); PG8_STAGE(PG8_SB(1, 0), b3, voffB); PG8_STAGE(PG8_SB(1, 1), b3 + hstep, voffB); PG8_STAGE(PG8_SA(1, 0), a3, voffA);
;             PG8_WAIT_V(8); PG8_WAIT_L(0); PG8_BAR; if (!cur.half) { PG8_MMA(1, 0, At, B0); PG8_MMA(1, 1, At, B1); } PG8_BAR; PG8_SCHED;
	s_add_i32 s28, s45, s4
	v_lshl_add_u64 v[160:161], v[160:161], 0, s[10:11]
	s_mov_b32 m0, s28
	ds_read_b128 v[186:189], v167 offset:49152
	ds_read_b128 v[190:193], v167 offset:50176
	ds_read_b128 v[194:197], v167 offset:51200
	ds_read_b128 v[198:201], v167 offset:52224
	ds_read_b128 v[202:205], v167 offset:53248
	ds_read_b128 v[206:209], v167 offset:54272
	ds_read_b128 v[210:213], v167 offset:55296
	ds_read_b128 v[218:221], v167 offset:56320
	global_load_lds_dwordx4 v[160:161], off
	s_add_i32 m0, s28, 0x2000
	s_add_u32 s26, s26, 0x40080
	v_lshl_add_u64 v[160:161], v[214:215], 0, s[10:11]
	s_addc_u32 s27, s27, 0
	s_add_i32 s28, s46, s4
	global_load_lds_dwordx4 v[160:161], off
	v_lshl_add_u64 v[160:161], s[26:27], 0, v[138:139]
	s_mov_b32 m0, s28
	s_nop 0
	global_load_lds_dwordx4 v[160:161], off
	v_lshl_add_u64 v[160:161], s[26:27], 0, v[142:143]
	s_add_i32 m0, s28, 0x2000
	s_nop 0
	global_load_lds_dwordx4 v[160:161], off
	v_lshl_add_u64 v[160:161], v[222:223], 0, s[10:11]
	s_mov_b32 m0, s35
	s_nop 0
	global_load_lds_dwordx4 v[160:161], off
	v_lshl_add_u64 v[160:161], v[224:225], 0, s[10:11]
	s_mov_b32 m0, s36
	s_nop 0
	global_load_lds_dwordx4 v[160:161], off
	s_waitcnt vmcnt(8)
	s_waitcnt lgkmcnt(0)
	s_barrier
	s_setprio 1
	s_waitcnt lgkmcnt(0)
	v_mfma_f32_16x16x32_bf16 v[60:63], v[128:131], v[186:189], v[60:63]
	v_mfma_f32_16x16x32_bf16 v[56:59], v[152:155], v[186:189], v[56:59]
	v_mfma_f32_16x16x32_bf16 v[44:47], v[128:131], v[194:197], v[44:47]
	v_mfma_f32_16x16x32_bf16 v[40:43], v[152:155], v[194:197], v[40:43]
	v_mfma_f32_16x16x32_bf16 v[28:31], v[128:131], v[202:205], v[28:31]
	v_mfma_f32_16x16x32_bf16 v[24:27], v[152:155], v[202:205], v[24:27]
	v_mfma_f32_16x16x32_bf16 v[12:15], v[128:131], v[210:213], v[12:15]
	v_mfma_f32_16x16x32_bf16 v[8:11], v[152:155], v[210:213], v[8:11]
	v_mfma_f32_16x16x32_bf16 v[60:63], v[132:135], v[190:193], v[60:63]
	v_mfma_f32_16x16x32_bf16 v[56:59], v[156:159], v[190:193], v[56:59]
	v_mfma_f32_16x16x32_bf16 v[44:47], v[132:135], v[198:201], v[44:47]
	v_mfma_f32_16x16x32_bf16 v[40:43], v[156:159], v[198:201], v[40:43]
	v_mfma_f32_16x16x32_bf16 v[28:31], v[132:135], v[206:209], v[28:31]
	v_mfma_f32_16x16x32_bf16 v[24:27], v[156:159], v[206:209], v[24:27]
	v_mfma_f32_16x16x32_bf16 v[12:15], v[132:135], v[218:221], v[12:15]
	v_mfma_f32_16x16x32_bf16 v[8:11], v[156:159], v[218:221], v[8:11]
	v_mfma_f32_16x16x32_bf16 v[52:55], v[170:173], v[186:189], v[52:55]
	v_mfma_f32_16x16x32_bf16 v[48:51], v[178:181], v[186:189], v[48:51]
	v_mfma_f32_16x16x32_bf16 v[36:39], v[170:173], v[194:197], v[36:39]
	v_mfma_f32_16x16x32_bf16 v[32:35], v[178:181], v[194:197], v[32:35]
	v_mfma_f32_16x16x32_bf16 v[20:23], v[170:173], v[202:205], v[20:23]
	v_mfma_f32_16x16x32_bf16 v[16:19], v[178:181], v[202:205], v[16:19]
	v_mfma_f32_16x16x32_bf16 v[4:7], v[170:173], v[210:213], v[4:7]
	v_mfma_f32_16x16x32_bf16 v[0:3], v[178:181], v[210:213], v[0:3]
	v_mfma_f32_16x16x32_bf16 v[52:55], v[174:177], v[190:193], v[52:55]
	v_mfma_f32_16x16x32_bf16 v[48:51], v[182:185], v[190:193], v[48:51]
	v_mfma_f32_16x16x32_bf16 v[36:39], v[174:177], v[198:201], v[36:39]
	v_mfma_f32_16x16x32_bf16 v[32:35], v[182:185], v[198:201], v[32:35]
	v_mfma_f32_16x16x32_bf16 v[20:23], v[174:177], v[206:209], v[20:23]
	v_mfma_f32_16x16x32_bf16 v[16:19], v[182:185], v[206:209], v[16:19]
	v_mfma_f32_16x16x32_bf16 v[4:7], v[174:177], v[218:221], v[4:7]
	v_mfma_f32_16x16x32_bf16 v[0:3], v[182:185], v[218:221], v[0:3]
	s_setprio 0
	s_barrier
	s_add_i32 s44, s44, 2
	s_add_u32 s24, s24, 0x100
	s_addc_u32 s25, s25, 0
	s_add_u32 s42, s42, 0x100
	s_addc_u32 s43, s43, 0
	s_cmp_gt_u32 s44, 13
	s_cbranch_scc0 .LBB0_2493
	s_nop 0
	s_nop 0
	s_nop 0
	s_nop 0
	s_nop 0
	s_nop 0
	s_nop 0
	s_nop 0
	s_and_b64 vcc, exec, s[14:15]
	s_cbranch_vccz .LBB0_2496
	s_barrier

; #define PG8_STAGE(bufoff, gbase, voff) do { _Pragma("unroll") for (int _i = 0; _i < 2; ++_i) \
;         __builtin_amdgcn_global_load_lds((const unsigned*)((const char*)(gbase) + (voff)[_i]), (PG8_LAS unsigned*)(lds + (bufoff) + ldsw + _i * 8192), 16, 0, 0); } while (0)
; #define PG8_LDA(dst, b, h) do { _Pragma("unroll") for (int m = 0; m < 4; ++m) _Pragma("unroll") for (int k = 0; k < 2; ++k) dst[m][k] = *(const PG8_LAS bf16x8*)(lds + PG8_SA(b, h) + aoff + m * 2048 + k * 1024); } while (0)
; #define PG8_LDB(dst, b, h) do { _Pragma("unroll") for (int n = 0; n < 2; ++n) _Pragma("unroll") for (int k = 0; k < 2; ++k) dst[n][k] = *(const PG8_LAS bf16x8*)(lds + PG8_SB(b, h) + boff + n * 2048 + k * 1024); } while (0)
; #define PG8_MMA(ai, bj, At, Bt) do { __builtin_amdgcn_s_setprio(1); _Pragma("unroll") for (int m = 0; m < 4; ++m) _Pragma("unroll") for (int n = 0; n < 2; ++n) _Pragma("unroll") for (int k = 0; k < 2; ++k) \
;         acc[ai][bj][m][n] = __builtin_amdgcn_mfma_f32_16x16x32_bf16(Bt[n][k], At[m][k], acc[ai][bj][m][n], 0, 0, 0); __builtin_amdgcn_s_setprio(0); } while (0)
; #define PG8_WAIT_V(n) asm volatile("s_waitcnt vmcnt(" #n ")" ::: "memory")
; template <class Epi, class Sched, bool ALIGN_EPI = false, bool SP2 = false>
; __device__ __forceinline__ void gemm_phase(PG8_LAS unsigned char* lds, const Gemm g, const Sched& S, const Epi& E, int wave0) {
;     ...
;         for (int t = 0; t < nt; t += 2) {
;             const bool last = (t == nt - 2);
;             const char* a1 = cA + (size_t)(t + 1) * kstep;
;             const char* a2 = last ? nA : cA + (size_t)(t + 2) * kstep; const char* b2 = last ? nB : cB + (size_t)(t + 2) * kstep;
;             const char* a3 = a2 + kstep; const char* b3 = b2 + kstep;
;             if (last && has_next) S.a_ready(nxt);
;             if constexpr (SP2) {
;             PG8_LDB(B0, 0, 0); PG8_LDB(B1, 0, 1); PG8_SCHED; PG8_LDA(At, 0, 0); PG8_STAGE(PG8_SA(1, 1), a1 + hstep, voffA);
;             PG8_WAIT_V(8); PG8_WAIT_L(0); PG8_BAR; PG8_MMA(0, 0, At, B0); PG8_MMA(0, 1, At, B1); PG8_BAR; PG8_SCHED;
;             PG8_LDA(At, 0, 1); PG8_STAGE(PG8_SB(0, 0), b2, voffB); PG8_STAGE(PG8_SB(0, 1), b2 + hstep, voffB); PG8_STAGE(PG8_SA(0, 0), a2, voffA);
;             PG8_WAIT_V(8); PG8_WAIT_L(0); PG8_BAR; if (!cur.half) { PG8_MMA(1, 0, At, B0); PG8_MMA(1, 1, At, B1); } PG8_BAR; PG8_SCHED;
.LBB0_2610:
	ds_read_b128 v[144:147], v169
	ds_read_b128 v[148:151], v169 offset:1024
	ds_read_b128 v[152:155], v169 offset:2048
	ds_read_b128 v[156:159], v169 offset:3072
	ds_read_b128 v[160:163], v170
	ds_read_b128 v[174:177], v170 offset:1024
	ds_read_b128 v[178:181], v170 offset:2048
	ds_read_b128 v[182:185], v170 offset:3072
	s_add_u32 s48, s46, 0xfffc0080
	s_addc_u32 s49, s47, -1
	s_cmp_eq_u32 s62, 12
	s_cselect_b32 s51, s3, s49
	s_cselect_b32 s50, s11, s48
	s_cselect_b32 s49, s39, s57
	s_cselect_b32 s48, s41, s56
	v_lshl_add_u64 v[164:165], s[46:47], 0, v[136:137]
	s_add_i32 m0, s5, 0xc000
	ds_read_b128 v[186:189], v171
	ds_read_b128 v[190:193], v171 offset:1024
	ds_read_b128 v[194:197], v171 offset:2048
	ds_read_b128 v[198:201], v171 offset:3072
	ds_read_b128 v[202:205], v171 offset:4096
	ds_read_b128 v[206:209], v171 offset:5120
	ds_read_b128 v[210:213], v171 offset:6144
	ds_read_b128 v[218:221], v171 offset:7168
	global_load_lds_dwordx4 v[164:165], off
	v_lshl_add_u64 v[164:165], s[46:47], 0, v[138:139]
	s_add_i32 m0, s5, 0xe000
	s_nop 0
	global_load_lds_dwordx4 v[164:165], off
	s_waitcnt vmcnt(8)
	s_waitcnt lgkmcnt(0)
	s_barrier
	s_setprio 1
	s_waitcnt lgkmcnt(0)
	v_mfma_f32_16x16x32_bf16 v[124:127], v[144:147], v[186:189], v[124:127]
	v_mfma_f32_16x16x32_bf16 v[120:123], v[152:155], v[186:189], v[120:123]
	v_mfma_f32_16x16x32_bf16 v[108:111], v[144:147], v[194:197], v[108:111]
	v_mfma_f32_16x16x32_bf16 v[104:107], v[152:155], v[194:197], v[104:107]
	v_mfma_f32_16x16x32_bf16 v[92:95], v[144:147], v[202:205], v[92:95]
	v_mfma_f32_16x16x32_bf16 v[88:91], v[152:155], v[202:205], v[88:91]
	v_mfma_f32_16x16x32_bf16 v[76:79], v[144:147], v[210:213], v[76:79]
	v_mfma_f32_16x16x32_bf16 v[72:75], v[152:155], v[210:213], v[72:75]
	v_mfma_f32_16x16x32_bf16 v[124:127], v[148:151], v[190:193], v[124:127]
	v_mfma_f32_16x16x32_bf16 v[120:123], v[156:159], v[190:193], v[120:123]
	v_mfma_f32_16x16x32_bf16 v[108:111], v[148:151], v[198:201], v[108:111]
	v_mfma_f32_16x16x32_bf16 v[104:107], v[156:159], v[198:201], v[104:107]
	v_mfma_f32_16x16x32_bf16 v[92:95], v[148:151], v[206:209], v[92:95]
	v_mfma_f32_16x16x32_bf16 v[88:91], v[156:159], v[206:209], v[88:91]
	v_mfma_f32_16x16x32_bf16 v[76:79], v[148:151], v[218:221], v[76:79]
	v_mfma_f32_16x16x32_bf16 v[72:75], v[156:159], v[218:221], v[72:75]
	v_mfma_f32_16x16x32_bf16 v[116:119], v[160:163], v[186:189], v[116:119]
	v_mfma_f32_16x16x32_bf16 v[112:115], v[178:181], v[186:189], v[112:115]
	v_mfma_f32_16x16x32_bf16 v[100:103], v[160:163], v[194:197], v[100:103]
	v_mfma_f32_16x16x32_bf16 v[96:99], v[178:181], v[194:197], v[96:99]
	v_mfma_f32_16x16x32_bf16 v[84:87], v[160:163], v[202:205], v[84:87]
	v_mfma_f32_16x16x32_bf16 v[80:83], v[178:181], v[202:205], v[80:83]
	v_mfma_f32_16x16x32_bf16 v[68:71], v[160:163], v[210:213], v[68:71]
	v_mfma_f32_16x16x32_bf16 v[64:67], v[178:181], v[210:213], v[64:67]
	v_mfma_f32_16x16x32_bf16 v[116:119], v[174:177], v[190:193], v[116:119]
	v_mfma_f32_16x16x32_bf16 v[112:115], v[182:185], v[190:193], v[112:115]
	v_mfma_f32_16x16x32_bf16 v[100:103], v[174:177], v[198:201], v[100:103]
	v_mfma_f32_16x16x32_bf16 v[96:99], v[182:185], v[198:201], v[96:99]
	v_mfma_f32_16x16x32_bf16 v[84:87], v[174:177], v[206:209], v[84:87]
	v_mfma_f32_16x16x32_bf16 v[80:83], v[182:185], v[206:209], v[80:83]
	v_mfma_f32_16x16x32_bf16 v[68:71], v[174:177], v[218:221], v[68:71]
	v_mfma_f32_16x16x32_bf16 v[64:67], v[182:185], v[218:221], v[64:67]
	s_setprio 0
	s_barrier
	s_add_i32 s63, s35, s4
	v_lshl_add_u64 v[164:165], s[48:49], 0, v[130:131]
	s_mov_b32 m0, s63
	ds_read_b128 v[186:189], v171 offset:16384
	ds_read_b128 v[190:193], v171 offset:17408
	ds_read_b128 v[194:197], v171 offset:18432
	ds_read_b128 v[198:201], v171 offset:19456
	ds_read_b128 v[202:205], v171 offset:20480
	ds_read_b128 v[206:209], v171 offset:21504
	ds_read_b128 v[210:213], v171 offset:22528
	ds_read_b128 v[218:221], v171 offset:23552
	global_load_lds_dwordx4 v[164:165], off
	s_add_i32 m0, s63, 0x2000
	s_add_u32 s68, s48, 0x40000
	v_lshl_add_u64 v[214:215], s[48:49], 0, v[134:135]
	s_addc_u32 s69, s49, 0
	s_add_i32 s63, s37, s4
	global_load_lds_dwordx4 v[214:215], off
	v_lshl_add_u64 v[222:223], s[68:69], 0, v[130:131]
	s_mov_b32 m0, s63
	v_lshl_add_u64 v[224:225], s[50:51], 0, v[132:133]
	global_load_lds_dwordx4 v[222:223], off
	v_lshl_add_u64 v[222:223], s[68:69], 0, v[134:135]
	s_add_i32 m0, s63, 0x2000
	s_nop 0
	global_load_lds_dwordx4 v[222:223], off
	v_lshl_add_u64 v[222:223], s[50:51], 0, v[128:129]
	s_mov_b32 m0, s5
	s_nop 0
	global_load_lds_dwordx4 v[222:223], off
	s_mov_b32 m0, s19
	s_nop 0
	global_load_lds_dwordx4 v[224:225], off
	s_waitcnt vmcnt(8)
	s_waitcnt lgkmcnt(0)
	s_barrier
; #define PG8_STAGE(bufoff, gbase, voff) do { _Pragma("unroll") for (int _i = 0; _i < 2; ++_i) \
;         __builtin_amdgcn_global_load_lds((const unsigned*)((const char*)(gbase) + (voff)[_i]), (PG8_LAS unsigned*)(lds + (bufoff) + ldsw + _i * 8192), 16, 0, 0); } while (0)
; #define PG8_LDA(dst, b, h) do { _Pragma("unroll") for (int m = 0; m < 4; ++m) _Pragma("unroll") for (int k = 0; k < 2; ++k) dst[m][k] = *(const PG8_LAS bf16x8*)(lds + PG8_SA(b, h) + aoff + m * 2048 + k * 1024); } while (0)
; #define PG8_LDB(dst, b, h) do { _Pragma("unroll") for (int n = 0; n < 2; ++n) _Pragma("unroll") for (int k = 0; k < 2; ++k) dst[n][k] = *(const PG8_LAS bf16x8*)(lds + PG8_SB(b, h) + boff + n * 2048 + k * 1024); } while (0)
; #define PG8_MMA(ai, bj, At, Bt) do { __builtin_amdgcn_s_setprio(1); _Pragma("unroll") for (int m = 0; m < 4; ++m) _Pragma("unroll") for (int n = 0; n < 2; ++n) _Pragma("unroll") for (int k = 0; k < 2; ++k) \
;         acc[ai][bj][m][n] = __builtin_amdgcn_mfma_f32_16x16x32_bf16(Bt[n][k], At[m][k], acc[ai][bj][m][n], 0, 0, 0); __builtin_amdgcn_s_setprio(0); } while (0)
; #define PG8_WAIT_V(n) asm volatile("s_waitcnt vmcnt(" #n ")" ::: "memory")
; #define PG8_WAIT_L(n) asm volatile("s_waitcnt lgkmcnt(" #n ")" ::: "memory")
; #define PG8_BAR __builtin_amdgcn_s_barrier()
; #define PG8_SCHED __builtin_amdgcn_sched_barrier(0)
; template <class Epi, class Sched, bool ALIGN_EPI = false, bool SP2 = false>
; __device__ __forceinline__ void gemm_phase(PG8_LAS unsigned char* lds, const Gemm g, const Sched& S, const Epi& E, int wave0) {
;     ...
;             PG8_WAIT_V(8); PG8_WAIT_L(0); PG8_BAR; if (!cur.half) { PG8_MMA(1, 0, At, B0); PG8_MMA(1, 1, At, B1); } PG8_BAR; PG8_SCHED;
;             PG8_LDB(B0, 1, 0); PG8_LDB(B1, 1, 1); PG8_SCHED; PG8_LDA(At, 1, 0); PG8_STAGE(PG8_SA(0, 1), a2 + hstep, voffA);
;             PG8_WAIT_V(8); PG8_WAIT_L(0); PG8_BAR; PG8_MMA(0, 0, At, B0); PG8_MMA(0, 1, At, B1); PG8_BAR; PG8_SCHED;
	s_setprio 1
	s_waitcnt lgkmcnt(0)
	v_mfma_f32_16x16x32_bf16 v[60:63], v[144:147], v[186:189], v[60:63]
	v_mfma_f32_16x16x32_bf16 v[56:59], v[152:155], v[186:189], v[56:59]
	v_mfma_f32_16x16x32_bf16 v[44:47], v[144:147], v[194:197], v[44:47]
	v_mfma_f32_16x16x32_bf16 v[40:43], v[152:155], v[194:197], v[40:43]
	v_mfma_f32_16x16x32_bf16 v[28:31], v[144:147], v[202:205], v[28:31]
	v_mfma_f32_16x16x32_bf16 v[24:27], v[152:155], v[202:205], v[24:27]
	v_mfma_f32_16x16x32_bf16 v[12:15], v[144:147], v[210:213], v[12:15]
	v_mfma_f32_16x16x32_bf16 v[8:11], v[152:155], v[210:213], v[8:11]
	v_mfma_f32_16x16x32_bf16 v[60:63], v[148:151], v[190:193], v[60:63]
	v_mfma_f32_16x16x32_bf16 v[56:59], v[156:159], v[190:193], v[56:59]
	v_mfma_f32_16x16x32_bf16 v[44:47], v[148:151], v[198:201], v[44:47]
	v_mfma_f32_16x16x32_bf16 v[40:43], v[156:159], v[198:201], v[40:43]
	v_mfma_f32_16x16x32_bf16 v[28:31], v[148:151], v[206:209], v[28:31]
	v_mfma_f32_16x16x32_bf16 v[24:27], v[156:159], v[206:209], v[24:27]
	v_mfma_f32_16x16x32_bf16 v[12:15], v[148:151], v[218:221], v[12:15]
	v_mfma_f32_16x16x32_bf16 v[8:11], v[156:159], v[218:221], v[8:11]
	v_mfma_f32_16x16x32_bf16 v[52:55], v[160:163], v[186:189], v[52:55]
	v_mfma_f32_16x16x32_bf16 v[48:51], v[178:181], v[186:189], v[48:51]
	v_mfma_f32_16x16x32_bf16 v[36:39], v[160:163], v[194:197], v[36:39]
	v_mfma_f32_16x16x32_bf16 v[32:35], v[178:181], v[194:197], v[32:35]
	v_mfma_f32_16x16x32_bf16 v[20:23], v[160:163], v[202:205], v[20:23]
	v_mfma_f32_16x16x32_bf16 v[16:19], v[178:181], v[202:205], v[16:19]
	v_mfma_f32_16x16x32_bf16 v[4:7], v[160:163], v[210:213], v[4:7]
	v_mfma_f32_16x16x32_bf16 v[0:3], v[178:181], v[210:213], v[0:3]
	v_mfma_f32_16x16x32_bf16 v[52:55], v[174:177], v[190:193], v[52:55]
	v_mfma_f32_16x16x32_bf16 v[48:51], v[182:185], v[190:193], v[48:51]
	v_mfma_f32_16x16x32_bf16 v[36:39], v[174:177], v[198:201], v[36:39]
	v_mfma_f32_16x16x32_bf16 v[32:35], v[182:185], v[198:201], v[32:35]
	v_mfma_f32_16x16x32_bf16 v[20:23], v[174:177], v[206:209], v[20:23]
	v_mfma_f32_16x16x32_bf16 v[16:19], v[182:185], v[206:209], v[16:19]
	v_mfma_f32_16x16x32_bf16 v[4:7], v[174:177], v[218:221], v[4:7]
	v_mfma_f32_16x16x32_bf16 v[0:3], v[182:185], v[218:221], v[0:3]
	s_setprio 0
	s_barrier
	s_add_i32 s63, 0, 0x18000
	s_add_i32 s68, 0, 0x1c000
	v_add_u32_e32 v156, s63, v168
	v_add_u32_e32 v182, s68, v168
	ds_read_b128 v[144:147], v156
	ds_read_b128 v[148:151], v156 offset:1024
	ds_read_b128 v[152:155], v156 offset:2048
	ds_read_b128 v[156:159], v156 offset:3072
	ds_read_b128 v[160:163], v182
	ds_read_b128 v[174:177], v182 offset:1024
	ds_read_b128 v[178:181], v182 offset:2048
	ds_read_b128 v[182:185], v182 offset:3072
	s_add_u32 s50, s50, 0x40000
	s_addc_u32 s51, s51, 0
	s_mov_b32 m0, s21
	v_lshl_add_u64 v[226:227], s[50:51], 0, v[128:129]
	ds_read_b128 v[186:189], v171 offset:32768
	ds_read_b128 v[190:193], v171 offset:33792
	ds_read_b128 v[194:197], v171 offset:34816
	ds_read_b128 v[198:201], v171 offset:35840
	ds_read_b128 v[202:205], v171 offset:36864
	ds_read_b128 v[206:209], v171 offset:37888
	ds_read_b128 v[210:213], v171 offset:38912
	ds_read_b128 v[218:221], v171 offset:39936
	global_load_lds_dwordx4 v[226:227], off
	v_lshl_add_u64 v[226:227], s[50:51], 0, v[132:133]
	s_mov_b32 m0, s23
	s_nop 0
	global_load_lds_dwordx4 v[226:227], off
	s_waitcnt vmcnt(8)
	s_waitcnt lgkmcnt(0)
	s_barrier
	s_setprio 1
	s_waitcnt lgkmcnt(0)
	v_mfma_f32_16x16x32_bf16 v[124:127], v[144:147], v[186:189], v[124:127]
	v_mfma_f32_16x16x32_bf16 v[120:123], v[152:155], v[186:189], v[120:123]
	v_mfma_f32_16x16x32_bf16 v[108:111], v[144:147], v[194:197], v[108:111]
	v_mfma_f32_16x16x32_bf16 v[104:107], v[152:155], v[194:197], v[104:107]
	v_mfma_f32_16x16x32_bf16 v[92:95], v[144:147], v[202:205], v[92:95]
	v_mfma_f32_16x16x32_bf16 v[88:91], v[152:155], v[202:205], v[88:91]
	v_mfma_f32_16x16x32_bf16 v[76:79], v[144:147], v[210:213], v[76:79]
	v_mfma_f32_16x16x32_bf16 v[72:75], v[152:155], v[210:213], v[72:75]
	v_mfma_f32_16x16x32_bf16 v[124:127], v[148:151], v[190:193], v[124:127]
	v_mfma_f32_16x16x32_bf16 v[120:123], v[156:159], v[190:193], v[120:123]
	v_mfma_f32_16x16x32_bf16 v[108:111], v[148:151], v[198:201], v[108:111]
	v_mfma_f32_16x16x32_bf16 v[104:107], v[156:159], v[198:201], v[104:107]
	v_mfma_f32_16x16x32_bf16 v[92:95], v[148:151], v[206:209], v[92:95]
	v_mfma_f32_16x16x32_bf16 v[88:91], v[156:159], v[206:209], v[88:91]
	v_mfma_f32_16x16x32_bf16 v[76:79], v[148:151], v[218:221], v[76:79]
	v_mfma_f32_16x16x32_bf16 v[72:75], v[156:159], v[218:221], v[72:75]
	v_mfma_f32_16x16x32_bf16 v[116:119], v[160:163], v[186:189], v[116:119]
	v_mfma_f32_16x16x32_bf16 v[112:115], v[178:181], v[186:189], v[112:115]
	v_mfma_f32_16x16x32_bf16 v[100:103], v[160:163], v[194:197], v[100:103]
	v_mfma_f32_16x16x32_bf16 v[96:99], v[178:181], v[194:197], v[96:99]
	v_mfma_f32_16x16x32_bf16 v[84:87], v[160:163], v[202:205], v[84:87]
	v_mfma_f32_16x16x32_bf16 v[80:83], v[178:181], v[202:205], v[80:83]
	v_mfma_f32_16x16x32_bf16 v[68:71], v[160:163], v[210:213], v[68:71]
	v_mfma_f32_16x16x32_bf16 v[64:67], v[178:181], v[210:213], v[64:67]
	v_mfma_f32_16x16x32_bf16 v[116:119], v[174:177], v[190:193], v[116:119]
	v_mfma_f32_16x16x32_bf16 v[112:115], v[182:185], v[190:193], v[112:115]
	v_mfma_f32_16x16x32_bf16 v[100:103], v[174:177], v[198:201], v[100:103]
	v_mfma_f32_16x16x32_bf16 v[96:99], v[182:185], v[198:201], v[96:99]
	v_mfma_f32_16x16x32_bf16 v[84:87], v[174:177], v[206:209], v[84:87]
	v_mfma_f32_16x16x32_bf16 v[80:83], v[182:185], v[206:209], v[80:83]
	v_mfma_f32_16x16x32_bf16 v[68:71], v[174:177], v[218:221], v[68:71]
	v_mfma_f32_16x16x32_bf16 v[64:67], v[182:185], v[218:221], v[64:67]
	s_setprio 0
	s_barrier
; #define PG8_STAGE(bufoff, gbase, voff) do { _Pragma("unroll") for (int _i = 0; _i < 2; ++_i) \
;         __builtin_amdgcn_global_load_lds((const unsigned*)((const char*)(gbase) + (voff)[_i]), (PG8_LAS unsigned*)(lds + (bufoff) + ldsw + _i * 8192), 16, 0, 0); } while (0)
; #define PG8_LDA(dst, b, h) do { _Pragma("unroll") for (int m = 0; m < 4; ++m) _Pragma("unroll") for (int k = 0; k < 2; ++k) dst[m][k] = *(const PG8_LAS bf16x8*)(lds + PG8_SA(b, h) + aoff + m * 2048 + k * 1024); } while (0)
; #define PG8_MMA(ai, bj, At, Bt) do { __builtin_amdgcn_s_setprio(1); _Pragma("unroll") for (int m = 0; m < 4; ++m) _Pragma("unroll") for (int n = 0; n < 2; ++n) _Pragma("unroll") for (int k = 0; k < 2; ++k) \
;         acc[ai][bj][m][n] = __builtin_amdgcn_mfma_f32_16x16x32_bf16(Bt[n][k], At[m][k], acc[ai][bj][m][n], 0, 0, 0); __builtin_amdgcn_s_setprio(0); } while (0)
; #define PG8_WAIT_V(n) asm volatile("s_waitcnt vmcnt(" #n ")" ::: "memory")
; #define PG8_WAIT_L(n) asm volatile("s_waitcnt lgkmcnt(" #n ")" ::: "memory")
; #define PG8_BAR __builtin_amdgcn_s_barrier()
; #define PG8_SCHED __builtin_amdgcn_sched_barrier(0)
; template <class Epi, class Sched, bool ALIGN_EPI = false, bool SP2 = false>
; __device__ __forceinline__ void gemm_phase(PG8_LAS unsigned char* lds, const Gemm g, const Sched& S, const Epi& E, int wave0) {
;     ...
;         for (int t = 0; t < nt; t += 2) {
;             const bool last = (t == nt - 2);
;             const char* a1 = cA + (size_t)(t + 1) * kstep;
;             const char* a2 = last ? nA : cA + (size_t)(t + 2) * kstep; const char* b2 = last ? nB : cB + (size_t)(t + 2) * kstep;
;     ...
;             PG8_LDA(At, 1, 1); PG8_STAGE(PG8_SB(1, 0), b3, voffB); PG8_STAGE(PG8_SB(1, 1), b3 + hstep, voffB); PG8_STAGE(PG8_SA(1, 0), a3, voffA);
;             PG8_WAIT_V(8); PG8_WAIT_L(0); PG8_BAR; if (!cur.half) { PG8_MMA(1, 0, At, B0); PG8_MMA(1, 1, At, B1); } PG8_BAR; PG8_SCHED;
	s_add_i32 s50, s63, s4
	v_lshl_add_u64 v[164:165], v[164:165], 0, s[14:15]
	s_mov_b32 m0, s50
	ds_read_b128 v[186:189], v171 offset:49152
	ds_read_b128 v[190:193], v171 offset:50176
	ds_read_b128 v[194:197], v171 offset:51200
	ds_read_b128 v[198:201], v171 offset:52224
	ds_read_b128 v[202:205], v171 offset:53248
	ds_read_b128 v[206:209], v171 offset:54272
	ds_read_b128 v[210:213], v171 offset:55296
	ds_read_b128 v[218:221], v171 offset:56320
	global_load_lds_dwordx4 v[164:165], off
	s_add_i32 m0, s50, 0x2000
	s_add_u32 s48, s48, 0x40080
	v_lshl_add_u64 v[164:165], v[214:215], 0, s[14:15]
	s_addc_u32 s49, s49, 0
	s_add_i32 s50, s68, s4
	global_load_lds_dwordx4 v[164:165], off
	v_lshl_add_u64 v[164:165], s[48:49], 0, v[130:131]
	s_mov_b32 m0, s50
	s_nop 0
	global_load_lds_dwordx4 v[164:165], off
	v_lshl_add_u64 v[164:165], s[48:49], 0, v[134:135]
	s_add_i32 m0, s50, 0x2000
	s_nop 0
	global_load_lds_dwordx4 v[164:165], off
	v_lshl_add_u64 v[164:165], v[222:223], 0, s[14:15]
	s_mov_b32 m0, s31
	s_nop 0
	global_load_lds_dwordx4 v[164:165], off
	v_lshl_add_u64 v[164:165], v[224:225], 0, s[14:15]
	s_mov_b32 m0, s33
	s_nop 0
	global_load_lds_dwordx4 v[164:165], off
	s_waitcnt vmcnt(8)
	s_waitcnt lgkmcnt(0)
	s_barrier
	s_setprio 1
	s_waitcnt lgkmcnt(0)
	v_mfma_f32_16x16x32_bf16 v[60:63], v[144:147], v[186:189], v[60:63]
	v_mfma_f32_16x16x32_bf16 v[56:59], v[152:155], v[186:189], v[56:59]
	v_mfma_f32_16x16x32_bf16 v[44:47], v[144:147], v[194:197], v[44:47]
	v_mfma_f32_16x16x32_bf16 v[40:43], v[152:155], v[194:197], v[40:43]
	v_mfma_f32_16x16x32_bf16 v[28:31], v[144:147], v[202:205], v[28:31]
	v_mfma_f32_16x16x32_bf16 v[24:27], v[152:155], v[202:205], v[24:27]
	v_mfma_f32_16x16x32_bf16 v[12:15], v[144:147], v[210:213], v[12:15]
	v_mfma_f32_16x16x32_bf16 v[8:11], v[152:155], v[210:213], v[8:11]
	v_mfma_f32_16x16x32_bf16 v[60:63], v[148:151], v[190:193], v[60:63]
	v_mfma_f32_16x16x32_bf16 v[56:59], v[156:159], v[190:193], v[56:59]
	v_mfma_f32_16x16x32_bf16 v[44:47], v[148:151], v[198:201], v[44:47]
	v_mfma_f32_16x16x32_bf16 v[40:43], v[156:159], v[198:201], v[40:43]
	v_mfma_f32_16x16x32_bf16 v[28:31], v[148:151], v[206:209], v[28:31]
	v_mfma_f32_16x16x32_bf16 v[24:27], v[156:159], v[206:209], v[24:27]
	v_mfma_f32_16x16x32_bf16 v[12:15], v[148:151], v[218:221], v[12:15]
	v_mfma_f32_16x16x32_bf16 v[8:11], v[156:159], v[218:221], v[8:11]
	v_mfma_f32_16x16x32_bf16 v[52:55], v[160:163], v[186:189], v[52:55]
	v_mfma_f32_16x16x32_bf16 v[48:51], v[178:181], v[186:189], v[48:51]
	v_mfma_f32_16x16x32_bf16 v[36:39], v[160:163], v[194:197], v[36:39]
	v_mfma_f32_16x16x32_bf16 v[32:35], v[178:181], v[194:197], v[32:35]
	v_mfma_f32_16x16x32_bf16 v[20:23], v[160:163], v[202:205], v[20:23]
	v_mfma_f32_16x16x32_bf16 v[16:19], v[178:181], v[202:205], v[16:19]
	v_mfma_f32_16x16x32_bf16 v[4:7], v[160:163], v[210:213], v[4:7]
	v_mfma_f32_16x16x32_bf16 v[0:3], v[178:181], v[210:213], v[0:3]
	v_mfma_f32_16x16x32_bf16 v[52:55], v[174:177], v[190:193], v[52:55]
	v_mfma_f32_16x16x32_bf16 v[48:51], v[182:185], v[190:193], v[48:51]
	v_mfma_f32_16x16x32_bf16 v[36:39], v[174:177], v[198:201], v[36:39]
	v_mfma_f32_16x16x32_bf16 v[32:35], v[182:185], v[198:201], v[32:35]
	v_mfma_f32_16x16x32_bf16 v[20:23], v[174:177], v[206:209], v[20:23]
	v_mfma_f32_16x16x32_bf16 v[16:19], v[182:185], v[206:209], v[16:19]
	v_mfma_f32_16x16x32_bf16 v[4:7], v[174:177], v[218:221], v[4:7]
	v_mfma_f32_16x16x32_bf16 v[0:3], v[182:185], v[218:221], v[0:3]
	s_setprio 0
	s_barrier
	s_add_i32 s62, s62, 2
	s_add_u32 s46, s46, 0x100
	s_addc_u32 s47, s47, 0
	s_add_u32 s56, s56, 0x100
	s_addc_u32 s57, s57, 0
	s_cmp_gt_u32 s62, 13
	s_cbranch_scc0 .LBB0_2610
	s_nop 0
	s_nop 0
	s_nop 0
	s_nop 0
	s_nop 0
	s_nop 0
	s_nop 0
	s_nop 0
	s_and_b64 vcc, exec, s[16:17]
	s_cbranch_vccz .LBB0_2613
	s_barrier

; #define PG8_STAGE(bufoff, gbase, voff) do { _Pragma("unroll") for (int _i = 0; _i < 2; ++_i) \
;         __builtin_amdgcn_global_load_lds((const unsigned*)((const char*)(gbase) + (voff)[_i]), (PG8_LAS unsigned*)(lds + (bufoff) + ldsw + _i * 8192), 16, 0, 0); } while (0)
; #define PG8_LDA(dst, b, h) do { _Pragma("unroll") for (int m = 0; m < 4; ++m) _Pragma("unroll") for (int k = 0; k < 2; ++k) dst[m][k] = *(const PG8_LAS bf16x8*)(lds + PG8_SA(b, h) + aoff + m * 2048 + k * 1024); } while (0)
; #define PG8_LDB(dst, b, h) do { _Pragma("unroll") for (int n = 0; n < 2; ++n) _Pragma("unroll") for (int k = 0; k < 2; ++k) dst[n][k] = *(const PG8_LAS bf16x8*)(lds + PG8_SB(b, h) + boff + n * 2048 + k * 1024); } while (0)
; #define PG8_MMA(ai, bj, At, Bt) do { __builtin_amdgcn_s_setprio(1); _Pragma("unroll") for (int m = 0; m < 4; ++m) _Pragma("unroll") for (int n = 0; n < 2; ++n) _Pragma("unroll") for (int k = 0; k < 2; ++k) \
;         acc[ai][bj][m][n] = __builtin_amdgcn_mfma_f32_16x16x32_bf16(Bt[n][k], At[m][k], acc[ai][bj][m][n], 0, 0, 0); __builtin_amdgcn_s_setprio(0); } while (0)
; #define PG8_WAIT_V(n) asm volatile("s_waitcnt vmcnt(" #n ")" ::: "memory")
; template <class Epi, class Sched, bool ALIGN_EPI = false, bool SP2 = false>
; __device__ __forceinline__ void gemm_phase(PG8_LAS unsigned char* lds, const Gemm g, const Sched& S, const Epi& E, int wave0) {
;     ...
;         for (int t = 0; t < nt; t += 2) {
;             const bool last = (t == nt - 2);
;             const char* a1 = cA + (size_t)(t + 1) * kstep;
;             const char* a2 = last ? nA : cA + (size_t)(t + 2) * kstep; const char* b2 = last ? nB : cB + (size_t)(t + 2) * kstep;
;             const char* a3 = a2 + kstep; const char* b3 = b2 + kstep;
;             if (last && has_next) S.a_ready(nxt);
;             if constexpr (SP2) {
;             PG8_LDB(B0, 0, 0); PG8_LDB(B1, 0, 1); PG8_SCHED; PG8_LDA(At, 0, 0); PG8_STAGE(PG8_SA(1, 1), a1 + hstep, voffA);
;             PG8_WAIT_V(8); PG8_WAIT_L(0); PG8_BAR; PG8_MMA(0, 0, At, B0); PG8_MMA(0, 1, At, B1); PG8_BAR; PG8_SCHED;
;             PG8_LDA(At, 0, 1); PG8_STAGE(PG8_SB(0, 0), b2, voffB); PG8_STAGE(PG8_SB(0, 1), b2 + hstep, voffB); PG8_STAGE(PG8_SA(0, 0), a2, voffA);
;             PG8_WAIT_V(8); PG8_WAIT_L(0); PG8_BAR; if (!cur.half) { PG8_MMA(1, 0, At, B0); PG8_MMA(1, 1, At, B1); } PG8_BAR; PG8_SCHED;
.LBB0_2836:
	ds_read_b128 v[128:131], v165
	ds_read_b128 v[132:135], v165 offset:1024
	ds_read_b128 v[152:155], v165 offset:2048
	ds_read_b128 v[156:159], v165 offset:3072
	ds_read_b128 v[170:173], v166
	ds_read_b128 v[174:177], v166 offset:1024
	ds_read_b128 v[178:181], v166 offset:2048
	ds_read_b128 v[182:185], v166 offset:3072
	s_add_u32 s26, s24, 0xfffe0080
	s_addc_u32 s27, s25, -1
	s_cmp_eq_u32 s46, 4
	s_cselect_b32 s29, s7, s27
	s_cselect_b32 s28, s19, s26
	s_cselect_b32 s27, s17, s45
	s_cselect_b32 s26, s43, s44
	v_lshl_add_u64 v[160:161], s[24:25], 0, v[144:145]
	s_add_i32 m0, s5, 0xc000
	ds_read_b128 v[186:189], v167
	ds_read_b128 v[190:193], v167 offset:1024
	ds_read_b128 v[194:197], v167 offset:2048
	ds_read_b128 v[198:201], v167 offset:3072
	ds_read_b128 v[202:205], v167 offset:4096
	ds_read_b128 v[206:209], v167 offset:5120
	ds_read_b128 v[210:213], v167 offset:6144
	ds_read_b128 v[218:221], v167 offset:7168
	global_load_lds_dwordx4 v[160:161], off
	v_lshl_add_u64 v[160:161], s[24:25], 0, v[146:147]
	s_add_i32 m0, s5, 0xe000
	s_nop 0
	global_load_lds_dwordx4 v[160:161], off
	s_waitcnt vmcnt(8)
	s_waitcnt lgkmcnt(0)
	s_barrier
	s_setprio 1
	s_waitcnt lgkmcnt(0)
	v_mfma_f32_16x16x32_bf16 v[124:127], v[128:131], v[186:189], v[124:127]
	v_mfma_f32_16x16x32_bf16 v[120:123], v[152:155], v[186:189], v[120:123]
	v_mfma_f32_16x16x32_bf16 v[108:111], v[128:131], v[194:197], v[108:111]
	v_mfma_f32_16x16x32_bf16 v[104:107], v[152:155], v[194:197], v[104:107]
	v_mfma_f32_16x16x32_bf16 v[92:95], v[128:131], v[202:205], v[92:95]
	v_mfma_f32_16x16x32_bf16 v[88:91], v[152:155], v[202:205], v[88:91]
	v_mfma_f32_16x16x32_bf16 v[76:79], v[128:131], v[210:213], v[76:79]
	v_mfma_f32_16x16x32_bf16 v[72:75], v[152:155], v[210:213], v[72:75]
	v_mfma_f32_16x16x32_bf16 v[124:127], v[132:135], v[190:193], v[124:127]
	v_mfma_f32_16x16x32_bf16 v[120:123], v[156:159], v[190:193], v[120:123]
	v_mfma_f32_16x16x32_bf16 v[108:111], v[132:135], v[198:201], v[108:111]
	v_mfma_f32_16x16x32_bf16 v[104:107], v[156:159], v[198:201], v[104:107]
	v_mfma_f32_16x16x32_bf16 v[92:95], v[132:135], v[206:209], v[92:95]
	v_mfma_f32_16x16x32_bf16 v[88:91], v[156:159], v[206:209], v[88:91]
	v_mfma_f32_16x16x32_bf16 v[76:79], v[132:135], v[218:221], v[76:79]
	v_mfma_f32_16x16x32_bf16 v[72:75], v[156:159], v[218:221], v[72:75]
	v_mfma_f32_16x16x32_bf16 v[116:119], v[170:173], v[186:189], v[116:119]
	v_mfma_f32_16x16x32_bf16 v[112:115], v[178:181], v[186:189], v[112:115]
	v_mfma_f32_16x16x32_bf16 v[100:103], v[170:173], v[194:197], v[100:103]
	v_mfma_f32_16x16x32_bf16 v[96:99], v[178:181], v[194:197], v[96:99]
	v_mfma_f32_16x16x32_bf16 v[84:87], v[170:173], v[202:205], v[84:87]
	v_mfma_f32_16x16x32_bf16 v[80:83], v[178:181], v[202:205], v[80:83]
	v_mfma_f32_16x16x32_bf16 v[68:71], v[170:173], v[210:213], v[68:71]
	v_mfma_f32_16x16x32_bf16 v[64:67], v[178:181], v[210:213], v[64:67]
	v_mfma_f32_16x16x32_bf16 v[116:119], v[174:177], v[190:193], v[116:119]
	v_mfma_f32_16x16x32_bf16 v[112:115], v[182:185], v[190:193], v[112:115]
	v_mfma_f32_16x16x32_bf16 v[100:103], v[174:177], v[198:201], v[100:103]
	v_mfma_f32_16x16x32_bf16 v[96:99], v[182:185], v[198:201], v[96:99]
	v_mfma_f32_16x16x32_bf16 v[84:87], v[174:177], v[206:209], v[84:87]
	v_mfma_f32_16x16x32_bf16 v[80:83], v[182:185], v[206:209], v[80:83]
	v_mfma_f32_16x16x32_bf16 v[68:71], v[174:177], v[218:221], v[68:71]
	v_mfma_f32_16x16x32_bf16 v[64:67], v[182:185], v[218:221], v[64:67]
	s_setprio 0
	s_barrier
	s_add_i32 s47, s39, s4
	v_lshl_add_u64 v[160:161], s[26:27], 0, v[138:139]
	s_mov_b32 m0, s47
	ds_read_b128 v[186:189], v167 offset:16384
	ds_read_b128 v[190:193], v167 offset:17408
	ds_read_b128 v[194:197], v167 offset:18432
	ds_read_b128 v[198:201], v167 offset:19456
	ds_read_b128 v[202:205], v167 offset:20480
	ds_read_b128 v[206:209], v167 offset:21504
	ds_read_b128 v[210:213], v167 offset:22528
	ds_read_b128 v[218:221], v167 offset:23552
	global_load_lds_dwordx4 v[160:161], off
	s_add_i32 m0, s47, 0x2000
	s_add_u32 s48, s26, 0x20000
	v_lshl_add_u64 v[214:215], s[26:27], 0, v[142:143]
	s_addc_u32 s49, s27, 0
	s_add_i32 s47, s40, s4
	global_load_lds_dwordx4 v[214:215], off
	v_lshl_add_u64 v[222:223], s[48:49], 0, v[138:139]
	s_mov_b32 m0, s47
	v_lshl_add_u64 v[224:225], s[28:29], 0, v[140:141]
	global_load_lds_dwordx4 v[222:223], off
	v_lshl_add_u64 v[222:223], s[48:49], 0, v[142:143]
	s_add_i32 m0, s47, 0x2000
	s_nop 0
	global_load_lds_dwordx4 v[222:223], off
	v_lshl_add_u64 v[222:223], s[28:29], 0, v[136:137]
	s_mov_b32 m0, s5
	s_nop 0
	global_load_lds_dwordx4 v[222:223], off
	s_mov_b32 m0, s30
	s_nop 0
	global_load_lds_dwordx4 v[224:225], off
	s_waitcnt vmcnt(8)
	s_waitcnt lgkmcnt(0)
	s_barrier
; #define PG8_STAGE(bufoff, gbase, voff) do { _Pragma("unroll") for (int _i = 0; _i < 2; ++_i) \
;         __builtin_amdgcn_global_load_lds((const unsigned*)((const char*)(gbase) + (voff)[_i]), (PG8_LAS unsigned*)(lds + (bufoff) + ldsw + _i * 8192), 16, 0, 0); } while (0)
; #define PG8_LDA(dst, b, h) do { _Pragma("unroll") for (int m = 0; m < 4; ++m) _Pragma("unroll") for (int k = 0; k < 2; ++k) dst[m][k] = *(const PG8_LAS bf16x8*)(lds + PG8_SA(b, h) + aoff + m * 2048 + k * 1024); } while (0)
; #define PG8_LDB(dst, b, h) do { _Pragma("unroll") for (int n = 0; n < 2; ++n) _Pragma("unroll") for (int k = 0; k < 2; ++k) dst[n][k] = *(const PG8_LAS bf16x8*)(lds + PG8_SB(b, h) + boff + n * 2048 + k * 1024); } while (0)
; #define PG8_MMA(ai, bj, At, Bt) do { __builtin_amdgcn_s_setprio(1); _Pragma("unroll") for (int m = 0; m < 4; ++m) _Pragma("unroll") for (int n = 0; n < 2; ++n) _Pragma("unroll") for (int k = 0; k < 2; ++k) \
;         acc[ai][bj][m][n] = __builtin_amdgcn_mfma_f32_16x16x32_bf16(Bt[n][k], At[m][k], acc[ai][bj][m][n], 0, 0, 0); __builtin_amdgcn_s_setprio(0); } while (0)
; #define PG8_WAIT_V(n) asm volatile("s_waitcnt vmcnt(" #n ")" ::: "memory")
; #define PG8_WAIT_L(n) asm volatile("s_waitcnt lgkmcnt(" #n ")" ::: "memory")
; #define PG8_BAR __builtin_amdgcn_s_barrier()
; #define PG8_SCHED __builtin_amdgcn_sched_barrier(0)
; template <class Epi, class Sched, bool ALIGN_EPI = false, bool SP2 = false>
; __device__ __forceinline__ void gemm_phase(PG8_LAS unsigned char* lds, const Gemm g, const Sched& S, const Epi& E, int wave0) {
;     ...
;             PG8_WAIT_V(8); PG8_WAIT_L(0); PG8_BAR; if (!cur.half) { PG8_MMA(1, 0, At, B0); PG8_MMA(1, 1, At, B1); } PG8_BAR; PG8_SCHED;
;             PG8_LDB(B0, 1, 0); PG8_LDB(B1, 1, 1); PG8_SCHED; PG8_LDA(At, 1, 0); PG8_STAGE(PG8_SA(0, 1), a2 + hstep, voffA);
;             PG8_WAIT_V(8); PG8_WAIT_L(0); PG8_BAR; PG8_MMA(0, 0, At, B0); PG8_MMA(0, 1, At, B1); PG8_BAR; PG8_SCHED;
	s_setprio 1
	s_waitcnt lgkmcnt(0)
	v_mfma_f32_16x16x32_bf16 v[60:63], v[128:131], v[186:189], v[60:63]
	v_mfma_f32_16x16x32_bf16 v[56:59], v[152:155], v[186:189], v[56:59]
	v_mfma_f32_16x16x32_bf16 v[44:47], v[128:131], v[194:197], v[44:47]
	v_mfma_f32_16x16x32_bf16 v[40:43], v[152:155], v[194:197], v[40:43]
	v_mfma_f32_16x16x32_bf16 v[28:31], v[128:131], v[202:205], v[28:31]
	v_mfma_f32_16x16x32_bf16 v[24:27], v[152:155], v[202:205], v[24:27]
	v_mfma_f32_16x16x32_bf16 v[12:15], v[128:131], v[210:213], v[12:15]
	v_mfma_f32_16x16x32_bf16 v[8:11], v[152:155], v[210:213], v[8:11]
	v_mfma_f32_16x16x32_bf16 v[60:63], v[132:135], v[190:193], v[60:63]
	v_mfma_f32_16x16x32_bf16 v[56:59], v[156:159], v[190:193], v[56:59]
	v_mfma_f32_16x16x32_bf16 v[44:47], v[132:135], v[198:201], v[44:47]
	v_mfma_f32_16x16x32_bf16 v[40:43], v[156:159], v[198:201], v[40:43]
	v_mfma_f32_16x16x32_bf16 v[28:31], v[132:135], v[206:209], v[28:31]
	v_mfma_f32_16x16x32_bf16 v[24:27], v[156:159], v[206:209], v[24:27]
	v_mfma_f32_16x16x32_bf16 v[12:15], v[132:135], v[218:221], v[12:15]
	v_mfma_f32_16x16x32_bf16 v[8:11], v[156:159], v[218:221], v[8:11]
	v_mfma_f32_16x16x32_bf16 v[52:55], v[170:173], v[186:189], v[52:55]
	v_mfma_f32_16x16x32_bf16 v[48:51], v[178:181], v[186:189], v[48:51]
	v_mfma_f32_16x16x32_bf16 v[36:39], v[170:173], v[194:197], v[36:39]
	v_mfma_f32_16x16x32_bf16 v[32:35], v[178:181], v[194:197], v[32:35]
	v_mfma_f32_16x16x32_bf16 v[20:23], v[170:173], v[202:205], v[20:23]
	v_mfma_f32_16x16x32_bf16 v[16:19], v[178:181], v[202:205], v[16:19]
	v_mfma_f32_16x16x32_bf16 v[4:7], v[170:173], v[210:213], v[4:7]
	v_mfma_f32_16x16x32_bf16 v[0:3], v[178:181], v[210:213], v[0:3]
	v_mfma_f32_16x16x32_bf16 v[52:55], v[174:177], v[190:193], v[52:55]
	v_mfma_f32_16x16x32_bf16 v[48:51], v[182:185], v[190:193], v[48:51]
	v_mfma_f32_16x16x32_bf16 v[36:39], v[174:177], v[198:201], v[36:39]
	v_mfma_f32_16x16x32_bf16 v[32:35], v[182:185], v[198:201], v[32:35]
	v_mfma_f32_16x16x32_bf16 v[20:23], v[174:177], v[206:209], v[20:23]
	v_mfma_f32_16x16x32_bf16 v[16:19], v[182:185], v[206:209], v[16:19]
	v_mfma_f32_16x16x32_bf16 v[4:7], v[174:177], v[218:221], v[4:7]
	v_mfma_f32_16x16x32_bf16 v[0:3], v[182:185], v[218:221], v[0:3]
	s_setprio 0
	s_barrier
	s_add_i32 s47, 0, 0x18000
	s_add_i32 s48, 0, 0x1c000
	v_add_u32_e32 v156, s47, v164
	v_add_u32_e32 v169, s48, v164
	ds_read_b128 v[128:131], v156
	ds_read_b128 v[132:135], v156 offset:1024
	ds_read_b128 v[152:155], v156 offset:2048
	ds_read_b128 v[156:159], v156 offset:3072
	ds_read_b128 v[170:173], v169
	ds_read_b128 v[174:177], v169 offset:1024
	ds_read_b128 v[178:181], v169 offset:2048
	ds_read_b128 v[182:185], v169 offset:3072
	s_add_u32 s28, s28, 0x20000
	s_addc_u32 s29, s29, 0
	s_mov_b32 m0, s31
	v_lshl_add_u64 v[226:227], s[28:29], 0, v[136:137]
	ds_read_b128 v[186:189], v167 offset:32768
	ds_read_b128 v[190:193], v167 offset:33792
	ds_read_b128 v[194:197], v167 offset:34816
	ds_read_b128 v[198:201], v167 offset:35840
	ds_read_b128 v[202:205], v167 offset:36864
	ds_read_b128 v[206:209], v167 offset:37888
	ds_read_b128 v[210:213], v167 offset:38912
	ds_read_b128 v[218:221], v167 offset:39936
	global_load_lds_dwordx4 v[226:227], off
	v_lshl_add_u64 v[226:227], s[28:29], 0, v[140:141]
	s_mov_b32 m0, s33
	s_nop 0
	global_load_lds_dwordx4 v[226:227], off
	s_waitcnt vmcnt(8)
	s_waitcnt lgkmcnt(0)
	s_barrier
	s_setprio 1
	s_waitcnt lgkmcnt(0)
	v_mfma_f32_16x16x32_bf16 v[124:127], v[128:131], v[186:189], v[124:127]
	v_mfma_f32_16x16x32_bf16 v[120:123], v[152:155], v[186:189], v[120:123]
	v_mfma_f32_16x16x32_bf16 v[108:111], v[128:131], v[194:197], v[108:111]
	v_mfma_f32_16x16x32_bf16 v[104:107], v[152:155], v[194:197], v[104:107]
	v_mfma_f32_16x16x32_bf16 v[92:95], v[128:131], v[202:205], v[92:95]
	v_mfma_f32_16x16x32_bf16 v[88:91], v[152:155], v[202:205], v[88:91]
	v_mfma_f32_16x16x32_bf16 v[76:79], v[128:131], v[210:213], v[76:79]
	v_mfma_f32_16x16x32_bf16 v[72:75], v[152:155], v[210:213], v[72:75]
	v_mfma_f32_16x16x32_bf16 v[124:127], v[132:135], v[190:193], v[124:127]
	v_mfma_f32_16x16x32_bf16 v[120:123], v[156:159], v[190:193], v[120:123]
	v_mfma_f32_16x16x32_bf16 v[108:111], v[132:135], v[198:201], v[108:111]
	v_mfma_f32_16x16x32_bf16 v[104:107], v[156:159], v[198:201], v[104:107]
	v_mfma_f32_16x16x32_bf16 v[92:95], v[132:135], v[206:209], v[92:95]
	v_mfma_f32_16x16x32_bf16 v[88:91], v[156:159], v[206:209], v[88:91]
	v_mfma_f32_16x16x32_bf16 v[76:79], v[132:135], v[218:221], v[76:79]
	v_mfma_f32_16x16x32_bf16 v[72:75], v[156:159], v[218:221], v[72:75]
	v_mfma_f32_16x16x32_bf16 v[116:119], v[170:173], v[186:189], v[116:119]
	v_mfma_f32_16x16x32_bf16 v[112:115], v[178:181], v[186:189], v[112:115]
	v_mfma_f32_16x16x32_bf16 v[100:103], v[170:173], v[194:197], v[100:103]
	v_mfma_f32_16x16x32_bf16 v[96:99], v[178:181], v[194:197], v[96:99]
	v_mfma_f32_16x16x32_bf16 v[84:87], v[170:173], v[202:205], v[84:87]
	v_mfma_f32_16x16x32_bf16 v[80:83], v[178:181], v[202:205], v[80:83]
	v_mfma_f32_16x16x32_bf16 v[68:71], v[170:173], v[210:213], v[68:71]
	v_mfma_f32_16x16x32_bf16 v[64:67], v[178:181], v[210:213], v[64:67]
	v_mfma_f32_16x16x32_bf16 v[116:119], v[174:177], v[190:193], v[116:119]
	v_mfma_f32_16x16x32_bf16 v[112:115], v[182:185], v[190:193], v[112:115]
	v_mfma_f32_16x16x32_bf16 v[100:103], v[174:177], v[198:201], v[100:103]
	v_mfma_f32_16x16x32_bf16 v[96:99], v[182:185], v[198:201], v[96:99]
	v_mfma_f32_16x16x32_bf16 v[84:87], v[174:177], v[206:209], v[84:87]
	v_mfma_f32_16x16x32_bf16 v[80:83], v[182:185], v[206:209], v[80:83]
	v_mfma_f32_16x16x32_bf16 v[68:71], v[174:177], v[218:221], v[68:71]
	v_mfma_f32_16x16x32_bf16 v[64:67], v[182:185], v[218:221], v[64:67]
	s_setprio 0
	s_barrier
; #define PG8_STAGE(bufoff, gbase, voff) do { _Pragma("unroll") for (int _i = 0; _i < 2; ++_i) \
;         __builtin_amdgcn_global_load_lds((const unsigned*)((const char*)(gbase) + (voff)[_i]), (PG8_LAS unsigned*)(lds + (bufoff) + ldsw + _i * 8192), 16, 0, 0); } while (0)
; #define PG8_LDA(dst, b, h) do { _Pragma("unroll") for (int m = 0; m < 4; ++m) _Pragma("unroll") for (int k = 0; k < 2; ++k) dst[m][k] = *(const PG8_LAS bf16x8*)(lds + PG8_SA(b, h) + aoff + m * 2048 + k * 1024); } while (0)
; #define PG8_MMA(ai, bj, At, Bt) do { __builtin_amdgcn_s_setprio(1); _Pragma("unroll") for (int m = 0; m < 4; ++m) _Pragma("unroll") for (int n = 0; n < 2; ++n) _Pragma("unroll") for (int k = 0; k < 2; ++k) \
;         acc[ai][bj][m][n] = __builtin_amdgcn_mfma_f32_16x16x32_bf16(Bt[n][k], At[m][k], acc[ai][bj][m][n], 0, 0, 0); __builtin_amdgcn_s_setprio(0); } while (0)
; #define PG8_WAIT_V(n) asm volatile("s_waitcnt vmcnt(" #n ")" ::: "memory")
; #define PG8_WAIT_L(n) asm volatile("s_waitcnt lgkmcnt(" #n ")" ::: "memory")
; #define PG8_BAR __builtin_amdgcn_s_barrier()
; #define PG8_SCHED __builtin_amdgcn_sched_barrier(0)
; template <class Epi, class Sched, bool ALIGN_EPI = false, bool SP2 = false>
; __device__ __forceinline__ void gemm_phase(PG8_LAS unsigned char* lds, const Gemm g, const Sched& S, const Epi& E, int wave0) {
;     ...
;         for (int t = 0; t < nt; t += 2) {
;             const bool last = (t == nt - 2);
;             const char* a1 = cA + (size_t)(t + 1) * kstep;
;             const char* a2 = last ? nA : cA + (size_t)(t + 2) * kstep; const char* b2 = last ? nB : cB + (size_t)(t + 2) * kstep;
;     ...
;             PG8_LDA(At, 1, 1); PG8_STAGE(PG8_SB(1, 0), b3, voffB); PG8_STAGE(PG8_SB(1, 1), b3 + hstep, voffB); PG8_STAGE(PG8_SA(1, 0), a3, voffA);
;             PG8_WAIT_V(8); PG8_WAIT_L(0); PG8_BAR; if (!cur.half) { PG8_MMA(1, 0, At, B0); PG8_MMA(1, 1, At, B1); } PG8_BAR; PG8_SCHED;
	s_add_i32 s28, s47, s4
	v_lshl_add_u64 v[160:161], v[160:161], 0, s[12:13]
	s_mov_b32 m0, s28
	ds_read_b128 v[186:189], v167 offset:49152
	ds_read_b128 v[190:193], v167 offset:50176
	ds_read_b128 v[194:197], v167 offset:51200
	ds_read_b128 v[198:201], v167 offset:52224
	ds_read_b128 v[202:205], v167 offset:53248
	ds_read_b128 v[206:209], v167 offset:54272
	ds_read_b128 v[210:213], v167 offset:55296
	ds_read_b128 v[218:221], v167 offset:56320
	global_load_lds_dwordx4 v[160:161], off
	s_add_i32 m0, s28, 0x2000
	s_add_u32 s26, s26, 0x20080
	v_lshl_add_u64 v[160:161], v[214:215], 0, s[12:13]
	s_addc_u32 s27, s27, 0
	s_add_i32 s28, s48, s4
	global_load_lds_dwordx4 v[160:161], off
	v_lshl_add_u64 v[160:161], s[26:27], 0, v[138:139]
	s_mov_b32 m0, s28
	s_nop 0
	global_load_lds_dwordx4 v[160:161], off
	v_lshl_add_u64 v[160:161], s[26:27], 0, v[142:143]
	s_add_i32 m0, s28, 0x2000
	s_nop 0
	global_load_lds_dwordx4 v[160:161], off
	v_lshl_add_u64 v[160:161], v[222:223], 0, s[12:13]
	s_mov_b32 m0, s37
	s_nop 0
	global_load_lds_dwordx4 v[160:161], off
	v_lshl_add_u64 v[160:161], v[224:225], 0, s[12:13]
	s_mov_b32 m0, s38
	s_nop 0
	global_load_lds_dwordx4 v[160:161], off
	s_waitcnt vmcnt(8)
	s_waitcnt lgkmcnt(0)
	s_barrier
	s_setprio 1
	s_waitcnt lgkmcnt(0)
	v_mfma_f32_16x16x32_bf16 v[60:63], v[128:131], v[186:189], v[60:63]
	v_mfma_f32_16x16x32_bf16 v[56:59], v[152:155], v[186:189], v[56:59]
	v_mfma_f32_16x16x32_bf16 v[44:47], v[128:131], v[194:197], v[44:47]
	v_mfma_f32_16x16x32_bf16 v[40:43], v[152:155], v[194:197], v[40:43]
	v_mfma_f32_16x16x32_bf16 v[28:31], v[128:131], v[202:205], v[28:31]
	v_mfma_f32_16x16x32_bf16 v[24:27], v[152:155], v[202:205], v[24:27]
	v_mfma_f32_16x16x32_bf16 v[12:15], v[128:131], v[210:213], v[12:15]
	v_mfma_f32_16x16x32_bf16 v[8:11], v[152:155], v[210:213], v[8:11]
	v_mfma_f32_16x16x32_bf16 v[60:63], v[132:135], v[190:193], v[60:63]
	v_mfma_f32_16x16x32_bf16 v[56:59], v[156:159], v[190:193], v[56:59]
	v_mfma_f32_16x16x32_bf16 v[44:47], v[132:135], v[198:201], v[44:47]
	v_mfma_f32_16x16x32_bf16 v[40:43], v[156:159], v[198:201], v[40:43]
	v_mfma_f32_16x16x32_bf16 v[28:31], v[132:135], v[206:209], v[28:31]
	v_mfma_f32_16x16x32_bf16 v[24:27], v[156:159], v[206:209], v[24:27]
	v_mfma_f32_16x16x32_bf16 v[12:15], v[132:135], v[218:221], v[12:15]
	v_mfma_f32_16x16x32_bf16 v[8:11], v[156:159], v[218:221], v[8:11]
	v_mfma_f32_16x16x32_bf16 v[52:55], v[170:173], v[186:189], v[52:55]
	v_mfma_f32_16x16x32_bf16 v[48:51], v[178:181], v[186:189], v[48:51]
	v_mfma_f32_16x16x32_bf16 v[36:39], v[170:173], v[194:197], v[36:39]
	v_mfma_f32_16x16x32_bf16 v[32:35], v[178:181], v[194:197], v[32:35]
	v_mfma_f32_16x16x32_bf16 v[20:23], v[170:173], v[202:205], v[20:23]
	v_mfma_f32_16x16x32_bf16 v[16:19], v[178:181], v[202:205], v[16:19]
	v_mfma_f32_16x16x32_bf16 v[4:7], v[170:173], v[210:213], v[4:7]
	v_mfma_f32_16x16x32_bf16 v[0:3], v[178:181], v[210:213], v[0:3]
	v_mfma_f32_16x16x32_bf16 v[52:55], v[174:177], v[190:193], v[52:55]
	v_mfma_f32_16x16x32_bf16 v[48:51], v[182:185], v[190:193], v[48:51]
	v_mfma_f32_16x16x32_bf16 v[36:39], v[174:177], v[198:201], v[36:39]
	v_mfma_f32_16x16x32_bf16 v[32:35], v[182:185], v[198:201], v[32:35]
	v_mfma_f32_16x16x32_bf16 v[20:23], v[174:177], v[206:209], v[20:23]
	v_mfma_f32_16x16x32_bf16 v[16:19], v[182:185], v[206:209], v[16:19]
	v_mfma_f32_16x16x32_bf16 v[4:7], v[174:177], v[218:221], v[4:7]
	v_mfma_f32_16x16x32_bf16 v[0:3], v[182:185], v[218:221], v[0:3]
	s_setprio 0
	s_barrier
	s_add_i32 s46, s46, 2
	s_add_u32 s24, s24, 0x100
	s_addc_u32 s25, s25, 0
	s_add_u32 s44, s44, 0x100
	s_addc_u32 s45, s45, 0
	s_cmp_gt_u32 s46, 5
	s_cbranch_scc0 .LBB0_2836
	s_nop 0
	s_nop 0
	s_nop 0
	s_nop 0
	s_nop 0
	s_nop 0
	s_nop 0
	s_nop 0
	s_and_b64 vcc, exec, s[14:15]
	s_cbranch_vccz .LBB0_2839
	s_barrier

; #define PG8_STAGE(bufoff, gbase, voff) do { _Pragma("unroll") for (int _i = 0; _i < 2; ++_i) \
;         __builtin_amdgcn_global_load_lds((const unsigned*)((const char*)(gbase) + (voff)[_i]), (PG8_LAS unsigned*)(lds + (bufoff) + ldsw + _i * 8192), 16, 0, 0); } while (0)
; #define PG8_LDA(dst, b, h) do { _Pragma("unroll") for (int m = 0; m < 4; ++m) _Pragma("unroll") for (int k = 0; k < 2; ++k) dst[m][k] = *(const PG8_LAS bf16x8*)(lds + PG8_SA(b, h) + aoff + m * 2048 + k * 1024); } while (0)
; #define PG8_LDB(dst, b, h) do { _Pragma("unroll") for (int n = 0; n < 2; ++n) _Pragma("unroll") for (int k = 0; k < 2; ++k) dst[n][k] = *(const PG8_LAS bf16x8*)(lds + PG8_SB(b, h) + boff + n * 2048 + k * 1024); } while (0)
; #define PG8_MMA(ai, bj, At, Bt) do { __builtin_amdgcn_s_setprio(1); _Pragma("unroll") for (int m = 0; m < 4; ++m) _Pragma("unroll") for (int n = 0; n < 2; ++n) _Pragma("unroll") for (int k = 0; k < 2; ++k) \
;         acc[ai][bj][m][n] = __builtin_amdgcn_mfma_f32_16x16x32_bf16(Bt[n][k], At[m][k], acc[ai][bj][m][n], 0, 0, 0); __builtin_amdgcn_s_setprio(0); } while (0)
; #define PG8_WAIT_V(n) asm volatile("s_waitcnt vmcnt(" #n ")" ::: "memory")
; template <class Epi, class Sched, bool ALIGN_EPI = false, bool SP2 = false>
; __device__ __forceinline__ void gemm_phase(PG8_LAS unsigned char* lds, const Gemm g, const Sched& S, const Epi& E, int wave0) {
;     ...
;         for (int t = 0; t < nt; t += 2) {
;             const bool last = (t == nt - 2);
;             const char* a1 = cA + (size_t)(t + 1) * kstep;
;             const char* a2 = last ? nA : cA + (size_t)(t + 2) * kstep; const char* b2 = last ? nB : cB + (size_t)(t + 2) * kstep;
;             const char* a3 = a2 + kstep; const char* b3 = b2 + kstep;
;             if (last && has_next) S.a_ready(nxt);
;             if constexpr (SP2) {
;             PG8_LDB(B0, 0, 0); PG8_LDB(B1, 0, 1); PG8_SCHED; PG8_LDA(At, 0, 0); PG8_STAGE(PG8_SA(1, 1), a1 + hstep, voffA);
;             PG8_WAIT_V(8); PG8_WAIT_L(0); PG8_BAR; PG8_MMA(0, 0, At, B0); PG8_MMA(0, 1, At, B1); PG8_BAR; PG8_SCHED;
;             PG8_LDA(At, 0, 1); PG8_STAGE(PG8_SB(0, 0), b2, voffB); PG8_STAGE(PG8_SB(0, 1), b2 + hstep, voffB); PG8_STAGE(PG8_SA(0, 0), a2, voffA);
;             PG8_WAIT_V(8); PG8_WAIT_L(0); PG8_BAR; if (!cur.half) { PG8_MMA(1, 0, At, B0); PG8_MMA(1, 1, At, B1); } PG8_BAR; PG8_SCHED;
.LBB0_2953:
	ds_read_b128 v[148:151], v220
	ds_read_b128 v[152:155], v220 offset:1024
	ds_read_b128 v[156:159], v220 offset:2048
	ds_read_b128 v[160:163], v220 offset:3072
	ds_read_b128 v[132:135], v221
	ds_read_b128 v[136:139], v221 offset:1024
	ds_read_b128 v[140:143], v221 offset:2048
	ds_read_b128 v[144:147], v221 offset:3072
	s_add_u32 s6, s28, 0xfffc0080
	s_addc_u32 s7, s29, -1
	s_cmp_eq_u32 s58, 12
	s_cselect_b32 s35, s1, s7
	s_cselect_b32 s34, s19, s6
	s_cselect_b32 s31, s17, s57
	s_cselect_b32 s30, s55, s56
	v_lshl_add_u64 v[2:3], s[28:29], 0, v[204:205]
	s_add_i32 m0, s38, 0xc000
	s_waitcnt lgkmcnt(0)
	ds_read_b128 v[164:167], v222
	ds_read_b128 v[168:171], v222 offset:1024
	ds_read_b128 v[172:175], v222 offset:2048
	ds_read_b128 v[176:179], v222 offset:3072
	ds_read_b128 v[180:183], v222 offset:4096
	ds_read_b128 v[184:187], v222 offset:5120
	ds_read_b128 v[188:191], v222 offset:6144
	ds_read_b128 v[192:195], v222 offset:7168
	global_load_lds_dwordx4 v[2:3], off
	v_lshl_add_u64 v[2:3], s[28:29], 0, v[206:207]
	s_add_i32 m0, s38, 0xe000
	s_nop 0
	global_load_lds_dwordx4 v[2:3], off
	s_waitcnt vmcnt(8)
	s_waitcnt lgkmcnt(0)
	s_barrier
	s_setprio 1
	s_waitcnt lgkmcnt(0)
	v_mfma_f32_16x16x32_bf16 v[128:131], v[148:151], v[164:167], v[128:131]
	v_mfma_f32_16x16x32_bf16 v[124:127], v[156:159], v[164:167], v[124:127]
	v_mfma_f32_16x16x32_bf16 v[112:115], v[148:151], v[172:175], v[112:115]
	v_mfma_f32_16x16x32_bf16 v[108:111], v[156:159], v[172:175], v[108:111]
	v_mfma_f32_16x16x32_bf16 v[96:99], v[148:151], v[180:183], v[96:99]
	v_mfma_f32_16x16x32_bf16 v[92:95], v[156:159], v[180:183], v[92:95]
	v_mfma_f32_16x16x32_bf16 v[80:83], v[148:151], v[188:191], v[80:83]
	v_mfma_f32_16x16x32_bf16 v[76:79], v[156:159], v[188:191], v[76:79]
	v_mfma_f32_16x16x32_bf16 v[128:131], v[152:155], v[168:171], v[128:131]
	v_mfma_f32_16x16x32_bf16 v[124:127], v[160:163], v[168:171], v[124:127]
	v_mfma_f32_16x16x32_bf16 v[112:115], v[152:155], v[176:179], v[112:115]
	v_mfma_f32_16x16x32_bf16 v[108:111], v[160:163], v[176:179], v[108:111]
	v_mfma_f32_16x16x32_bf16 v[96:99], v[152:155], v[184:187], v[96:99]
	v_mfma_f32_16x16x32_bf16 v[92:95], v[160:163], v[184:187], v[92:95]
	v_mfma_f32_16x16x32_bf16 v[80:83], v[152:155], v[192:195], v[80:83]
	v_mfma_f32_16x16x32_bf16 v[76:79], v[160:163], v[192:195], v[76:79]
	v_mfma_f32_16x16x32_bf16 v[120:123], v[132:135], v[164:167], v[120:123]
	v_mfma_f32_16x16x32_bf16 v[116:119], v[140:143], v[164:167], v[116:119]
	v_mfma_f32_16x16x32_bf16 v[104:107], v[132:135], v[172:175], v[104:107]
	v_mfma_f32_16x16x32_bf16 v[100:103], v[140:143], v[172:175], v[100:103]
	v_mfma_f32_16x16x32_bf16 v[88:91], v[132:135], v[180:183], v[88:91]
	v_mfma_f32_16x16x32_bf16 v[84:87], v[140:143], v[180:183], v[84:87]
	v_mfma_f32_16x16x32_bf16 v[72:75], v[132:135], v[188:191], v[72:75]
	v_mfma_f32_16x16x32_bf16 v[68:71], v[140:143], v[188:191], v[68:71]
	v_mfma_f32_16x16x32_bf16 v[120:123], v[136:139], v[168:171], v[120:123]
	v_mfma_f32_16x16x32_bf16 v[116:119], v[144:147], v[168:171], v[116:119]
	v_mfma_f32_16x16x32_bf16 v[104:107], v[136:139], v[176:179], v[104:107]
	v_mfma_f32_16x16x32_bf16 v[100:103], v[144:147], v[176:179], v[100:103]
	v_mfma_f32_16x16x32_bf16 v[88:91], v[136:139], v[184:187], v[88:91]
	v_mfma_f32_16x16x32_bf16 v[84:87], v[144:147], v[184:187], v[84:87]
	v_mfma_f32_16x16x32_bf16 v[72:75], v[136:139], v[192:195], v[72:75]
	v_mfma_f32_16x16x32_bf16 v[68:71], v[144:147], v[192:195], v[68:71]
	s_setprio 0
	s_barrier
	s_add_i32 s6, s47, s37
	v_lshl_add_u64 v[2:3], s[30:31], 0, v[198:199]
	s_mov_b32 m0, s6
	ds_read_b128 v[188:191], v222 offset:16384
	ds_read_b128 v[192:195], v222 offset:17408
	ds_read_b128 v[180:183], v222 offset:18432
	ds_read_b128 v[184:187], v222 offset:19456
	ds_read_b128 v[172:175], v222 offset:20480
	ds_read_b128 v[176:179], v222 offset:21504
	ds_read_b128 v[164:167], v222 offset:22528
	ds_read_b128 v[168:171], v222 offset:23552
	global_load_lds_dwordx4 v[2:3], off
	s_add_i32 m0, s6, 0x2000
	s_add_u32 s6, s30, 0x40000
	v_lshl_add_u64 v[210:211], s[30:31], 0, v[202:203]
	s_addc_u32 s7, s31, 0
	s_add_i32 s59, s48, s37
	global_load_lds_dwordx4 v[210:211], off
	v_lshl_add_u64 v[212:213], s[6:7], 0, v[198:199]
	s_mov_b32 m0, s59
	v_lshl_add_u64 v[214:215], s[34:35], 0, v[200:201]
	global_load_lds_dwordx4 v[212:213], off
	v_lshl_add_u64 v[212:213], s[6:7], 0, v[202:203]
	s_add_i32 m0, s59, 0x2000
	v_cmp_ne_u32_e64 s[6:7], 1, v224
	global_load_lds_dwordx4 v[212:213], off
	v_lshl_add_u64 v[212:213], s[34:35], 0, v[196:197]
	s_mov_b32 m0, s38
	s_andn2_b64 vcc, exec, s[26:27]
	global_load_lds_dwordx4 v[212:213], off
	s_mov_b32 m0, s39
	s_nop 0
	global_load_lds_dwordx4 v[214:215], off
	s_waitcnt vmcnt(8)
	s_waitcnt lgkmcnt(0)
	s_barrier
	s_cbranch_vccnz .LBB0_2955
	s_setprio 1
	s_waitcnt lgkmcnt(0)
	v_mfma_f32_16x16x32_bf16 v[64:67], v[148:151], v[188:191], v[64:67]
	v_mfma_f32_16x16x32_bf16 v[60:63], v[156:159], v[188:191], v[60:63]
	v_mfma_f32_16x16x32_bf16 v[48:51], v[148:151], v[180:183], v[48:51]
	v_mfma_f32_16x16x32_bf16 v[44:47], v[156:159], v[180:183], v[44:47]
	v_mfma_f32_16x16x32_bf16 v[32:35], v[148:151], v[172:175], v[32:35]
	v_mfma_f32_16x16x32_bf16 v[28:31], v[156:159], v[172:175], v[28:31]
	v_mfma_f32_16x16x32_bf16 v[16:19], v[148:151], v[164:167], v[16:19]
	v_mfma_f32_16x16x32_bf16 v[12:15], v[156:159], v[164:167], v[12:15]
	v_mfma_f32_16x16x32_bf16 v[64:67], v[152:155], v[192:195], v[64:67]
	v_mfma_f32_16x16x32_bf16 v[60:63], v[160:163], v[192:195], v[60:63]
	v_mfma_f32_16x16x32_bf16 v[48:51], v[152:155], v[184:187], v[48:51]
	v_mfma_f32_16x16x32_bf16 v[44:47], v[160:163], v[184:187], v[44:47]
	v_mfma_f32_16x16x32_bf16 v[32:35], v[152:155], v[176:179], v[32:35]
	v_mfma_f32_16x16x32_bf16 v[28:31], v[160:163], v[176:179], v[28:31]
	v_mfma_f32_16x16x32_bf16 v[16:19], v[152:155], v[168:171], v[16:19]
	v_mfma_f32_16x16x32_bf16 v[12:15], v[160:163], v[168:171], v[12:15]
	v_mfma_f32_16x16x32_bf16 v[56:59], v[132:135], v[188:191], v[56:59]
	v_mfma_f32_16x16x32_bf16 v[52:55], v[140:143], v[188:191], v[52:55]
	v_mfma_f32_16x16x32_bf16 v[40:43], v[132:135], v[180:183], v[40:43]
	v_mfma_f32_16x16x32_bf16 v[36:39], v[140:143], v[180:183], v[36:39]
	v_mfma_f32_16x16x32_bf16 v[24:27], v[132:135], v[172:175], v[24:27]
	v_mfma_f32_16x16x32_bf16 v[20:23], v[140:143], v[172:175], v[20:23]
	v_mfma_f32_16x16x32_bf16 v[8:11], v[132:135], v[164:167], v[8:11]
	v_mfma_f32_16x16x32_bf16 v[4:7], v[140:143], v[164:167], v[4:7]
	v_mfma_f32_16x16x32_bf16 v[56:59], v[136:139], v[192:195], v[56:59]
	v_mfma_f32_16x16x32_bf16 v[52:55], v[144:147], v[192:195], v[52:55]
	v_mfma_f32_16x16x32_bf16 v[40:43], v[136:139], v[184:187], v[40:43]
	v_mfma_f32_16x16x32_bf16 v[36:39], v[144:147], v[184:187], v[36:39]
	v_mfma_f32_16x16x32_bf16 v[24:27], v[136:139], v[176:179], v[24:27]
	v_mfma_f32_16x16x32_bf16 v[20:23], v[144:147], v[176:179], v[20:23]
	v_mfma_f32_16x16x32_bf16 v[8:11], v[136:139], v[168:171], v[8:11]
	v_mfma_f32_16x16x32_bf16 v[4:7], v[144:147], v[168:171], v[4:7]
	s_setprio 0
; #define PG8_STAGE(bufoff, gbase, voff) do { _Pragma("unroll") for (int _i = 0; _i < 2; ++_i) \
;         __builtin_amdgcn_global_load_lds((const unsigned*)((const char*)(gbase) + (voff)[_i]), (PG8_LAS unsigned*)(lds + (bufoff) + ldsw + _i * 8192), 16, 0, 0); } while (0)
; #define PG8_LDA(dst, b, h) do { _Pragma("unroll") for (int m = 0; m < 4; ++m) _Pragma("unroll") for (int k = 0; k < 2; ++k) dst[m][k] = *(const PG8_LAS bf16x8*)(lds + PG8_SA(b, h) + aoff + m * 2048 + k * 1024); } while (0)
; #define PG8_LDB(dst, b, h) do { _Pragma("unroll") for (int n = 0; n < 2; ++n) _Pragma("unroll") for (int k = 0; k < 2; ++k) dst[n][k] = *(const PG8_LAS bf16x8*)(lds + PG8_SB(b, h) + boff + n * 2048 + k * 1024); } while (0)
; #define PG8_MMA(ai, bj, At, Bt) do { __builtin_amdgcn_s_setprio(1); _Pragma("unroll") for (int m = 0; m < 4; ++m) _Pragma("unroll") for (int n = 0; n < 2; ++n) _Pragma("unroll") for (int k = 0; k < 2; ++k) \
;         acc[ai][bj][m][n] = __builtin_amdgcn_mfma_f32_16x16x32_bf16(Bt[n][k], At[m][k], acc[ai][bj][m][n], 0, 0, 0); __builtin_amdgcn_s_setprio(0); } while (0)
; #define PG8_WAIT_V(n) asm volatile("s_waitcnt vmcnt(" #n ")" ::: "memory")
; #define PG8_WAIT_L(n) asm volatile("s_waitcnt lgkmcnt(" #n ")" ::: "memory")
; #define PG8_BAR __builtin_amdgcn_s_barrier()
; #define PG8_SCHED __builtin_amdgcn_sched_barrier(0)
; template <class Epi, class Sched, bool ALIGN_EPI = false, bool SP2 = false>
; __device__ __forceinline__ void gemm_phase(PG8_LAS unsigned char* lds, const Gemm g, const Sched& S, const Epi& E, int wave0) {
;     ...
;         for (int t = 0; t < nt; t += 2) {
;             const bool last = (t == nt - 2);
;             const char* a1 = cA + (size_t)(t + 1) * kstep;
;             const char* a2 = last ? nA : cA + (size_t)(t + 2) * kstep; const char* b2 = last ? nB : cB + (size_t)(t + 2) * kstep;
;     ...
;             PG8_LDB(B0, 1, 0); PG8_LDB(B1, 1, 1); PG8_SCHED; PG8_LDA(At, 1, 0); PG8_STAGE(PG8_SA(0, 1), a2 + hstep, voffA);
;             PG8_WAIT_V(8); PG8_WAIT_L(0); PG8_BAR; PG8_MMA(0, 0, At, B0); PG8_MMA(0, 1, At, B1); PG8_BAR; PG8_SCHED;
;             PG8_LDA(At, 1, 1); PG8_STAGE(PG8_SB(1, 0), b3, voffB); PG8_STAGE(PG8_SB(1, 1), b3 + hstep, voffB); PG8_STAGE(PG8_SA(1, 0), a3, voffA);
;             PG8_WAIT_V(8); PG8_WAIT_L(0); PG8_BAR; if (!cur.half) { PG8_MMA(1, 0, At, B0); PG8_MMA(1, 1, At, B1); } PG8_BAR; PG8_SCHED;
.LBB0_2955:
	s_barrier
	s_add_i32 s59, 0, 0x18000
	v_add_u32_e32 v1, s59, v219
	s_add_i32 s60, 0, 0x1c000
	ds_read_b128 v[148:151], v1
	ds_read_b128 v[152:155], v1 offset:1024
	ds_read_b128 v[156:159], v1 offset:2048
	ds_read_b128 v[160:163], v1 offset:3072
	v_add_u32_e32 v1, s60, v219
	ds_read_b128 v[132:135], v1
	ds_read_b128 v[136:139], v1 offset:1024
	ds_read_b128 v[140:143], v1 offset:2048
	ds_read_b128 v[144:147], v1 offset:3072
	s_add_u32 s34, s34, 0x40000
	s_addc_u32 s35, s35, 0
	s_mov_b32 m0, s40
	v_lshl_add_u64 v[226:227], s[34:35], 0, v[196:197]
	s_waitcnt lgkmcnt(0)
	ds_read_b128 v[164:167], v222 offset:32768
	ds_read_b128 v[168:171], v222 offset:33792
	ds_read_b128 v[172:175], v222 offset:34816
	ds_read_b128 v[176:179], v222 offset:35840
	ds_read_b128 v[180:183], v222 offset:36864
	ds_read_b128 v[184:187], v222 offset:37888
	ds_read_b128 v[188:191], v222 offset:38912
	ds_read_b128 v[192:195], v222 offset:39936
	global_load_lds_dwordx4 v[226:227], off
	v_lshl_add_u64 v[226:227], s[34:35], 0, v[200:201]
	s_mov_b32 m0, s41
	s_nop 0
	global_load_lds_dwordx4 v[226:227], off
	s_waitcnt vmcnt(8)
	s_waitcnt lgkmcnt(0)
	s_barrier
	s_setprio 1
	s_waitcnt lgkmcnt(0)
	v_mfma_f32_16x16x32_bf16 v[128:131], v[148:151], v[164:167], v[128:131]
	v_mfma_f32_16x16x32_bf16 v[124:127], v[156:159], v[164:167], v[124:127]
	v_mfma_f32_16x16x32_bf16 v[112:115], v[148:151], v[172:175], v[112:115]
	v_mfma_f32_16x16x32_bf16 v[108:111], v[156:159], v[172:175], v[108:111]
	v_mfma_f32_16x16x32_bf16 v[96:99], v[148:151], v[180:183], v[96:99]
	v_mfma_f32_16x16x32_bf16 v[92:95], v[156:159], v[180:183], v[92:95]
	v_mfma_f32_16x16x32_bf16 v[80:83], v[148:151], v[188:191], v[80:83]
	v_mfma_f32_16x16x32_bf16 v[76:79], v[156:159], v[188:191], v[76:79]
	v_mfma_f32_16x16x32_bf16 v[128:131], v[152:155], v[168:171], v[128:131]
	v_mfma_f32_16x16x32_bf16 v[124:127], v[160:163], v[168:171], v[124:127]
	v_mfma_f32_16x16x32_bf16 v[112:115], v[152:155], v[176:179], v[112:115]
	v_mfma_f32_16x16x32_bf16 v[108:111], v[160:163], v[176:179], v[108:111]
	v_mfma_f32_16x16x32_bf16 v[96:99], v[152:155], v[184:187], v[96:99]
	v_mfma_f32_16x16x32_bf16 v[92:95], v[160:163], v[184:187], v[92:95]
	v_mfma_f32_16x16x32_bf16 v[80:83], v[152:155], v[192:195], v[80:83]
	v_mfma_f32_16x16x32_bf16 v[76:79], v[160:163], v[192:195], v[76:79]
	v_mfma_f32_16x16x32_bf16 v[120:123], v[132:135], v[164:167], v[120:123]
	v_mfma_f32_16x16x32_bf16 v[116:119], v[140:143], v[164:167], v[116:119]
	v_mfma_f32_16x16x32_bf16 v[104:107], v[132:135], v[172:175], v[104:107]
	v_mfma_f32_16x16x32_bf16 v[100:103], v[140:143], v[172:175], v[100:103]
	v_mfma_f32_16x16x32_bf16 v[88:91], v[132:135], v[180:183], v[88:91]
	v_mfma_f32_16x16x32_bf16 v[84:87], v[140:143], v[180:183], v[84:87]
	v_mfma_f32_16x16x32_bf16 v[72:75], v[132:135], v[188:191], v[72:75]
	v_mfma_f32_16x16x32_bf16 v[68:71], v[140:143], v[188:191], v[68:71]
	v_mfma_f32_16x16x32_bf16 v[120:123], v[136:139], v[168:171], v[120:123]
	v_mfma_f32_16x16x32_bf16 v[116:119], v[144:147], v[168:171], v[116:119]
	v_mfma_f32_16x16x32_bf16 v[104:107], v[136:139], v[176:179], v[104:107]
	v_mfma_f32_16x16x32_bf16 v[100:103], v[144:147], v[176:179], v[100:103]
	v_mfma_f32_16x16x32_bf16 v[88:91], v[136:139], v[184:187], v[88:91]
	v_mfma_f32_16x16x32_bf16 v[84:87], v[144:147], v[184:187], v[84:87]
	v_mfma_f32_16x16x32_bf16 v[72:75], v[136:139], v[192:195], v[72:75]
	v_mfma_f32_16x16x32_bf16 v[68:71], v[144:147], v[192:195], v[68:71]
	s_setprio 0
	s_barrier
	s_add_i32 s34, s59, s37
	v_lshl_add_u64 v[2:3], v[2:3], 0, s[12:13]
	s_mov_b32 m0, s34
	ds_read_b128 v[188:191], v222 offset:49152
	ds_read_b128 v[192:195], v222 offset:50176
	ds_read_b128 v[180:183], v222 offset:51200
	ds_read_b128 v[184:187], v222 offset:52224
	ds_read_b128 v[172:175], v222 offset:53248
	ds_read_b128 v[176:179], v222 offset:54272
	ds_read_b128 v[164:167], v222 offset:55296
	ds_read_b128 v[168:171], v222 offset:56320
	global_load_lds_dwordx4 v[2:3], off
	s_add_i32 m0, s34, 0x2000
	s_add_u32 s30, s30, 0x40080
	v_lshl_add_u64 v[2:3], v[210:211], 0, s[12:13]
	s_addc_u32 s31, s31, 0
	s_add_i32 s34, s60, s37
	global_load_lds_dwordx4 v[2:3], off
	v_lshl_add_u64 v[2:3], s[30:31], 0, v[198:199]
	s_mov_b32 m0, s34
	s_and_b64 vcc, exec, s[6:7]
	global_load_lds_dwordx4 v[2:3], off
	v_lshl_add_u64 v[2:3], s[30:31], 0, v[202:203]
	s_add_i32 m0, s34, 0x2000
	s_nop 0
	global_load_lds_dwordx4 v[2:3], off
	v_lshl_add_u64 v[2:3], v[212:213], 0, s[12:13]
	s_mov_b32 m0, s45
	s_nop 0
	global_load_lds_dwordx4 v[2:3], off
	v_lshl_add_u64 v[2:3], v[214:215], 0, s[12:13]
	s_mov_b32 m0, s46
	s_nop 0
	global_load_lds_dwordx4 v[2:3], off
	s_waitcnt vmcnt(8)
	s_waitcnt lgkmcnt(0)
	s_barrier
	s_cbranch_vccnz .LBB0_2952
	s_setprio 1
	s_waitcnt lgkmcnt(0)
	v_mfma_f32_16x16x32_bf16 v[64:67], v[148:151], v[188:191], v[64:67]
	v_mfma_f32_16x16x32_bf16 v[60:63], v[156:159], v[188:191], v[60:63]
	v_mfma_f32_16x16x32_bf16 v[48:51], v[148:151], v[180:183], v[48:51]
	v_mfma_f32_16x16x32_bf16 v[44:47], v[156:159], v[180:183], v[44:47]
	v_mfma_f32_16x16x32_bf16 v[32:35], v[148:151], v[172:175], v[32:35]
	v_mfma_f32_16x16x32_bf16 v[28:31], v[156:159], v[172:175], v[28:31]
	v_mfma_f32_16x16x32_bf16 v[16:19], v[148:151], v[164:167], v[16:19]
	v_mfma_f32_16x16x32_bf16 v[12:15], v[156:159], v[164:167], v[12:15]
	v_mfma_f32_16x16x32_bf16 v[64:67], v[152:155], v[192:195], v[64:67]
	v_mfma_f32_16x16x32_bf16 v[60:63], v[160:163], v[192:195], v[60:63]
	v_mfma_f32_16x16x32_bf16 v[48:51], v[152:155], v[184:187], v[48:51]
	v_mfma_f32_16x16x32_bf16 v[44:47], v[160:163], v[184:187], v[44:47]
	v_mfma_f32_16x16x32_bf16 v[32:35], v[152:155], v[176:179], v[32:35]
	v_mfma_f32_16x16x32_bf16 v[28:31], v[160:163], v[176:179], v[28:31]
	v_mfma_f32_16x16x32_bf16 v[16:19], v[152:155], v[168:171], v[16:19]
	v_mfma_f32_16x16x32_bf16 v[12:15], v[160:163], v[168:171], v[12:15]
	v_mfma_f32_16x16x32_bf16 v[56:59], v[132:135], v[188:191], v[56:59]
	v_mfma_f32_16x16x32_bf16 v[52:55], v[140:143], v[188:191], v[52:55]
	v_mfma_f32_16x16x32_bf16 v[40:43], v[132:135], v[180:183], v[40:43]
	v_mfma_f32_16x16x32_bf16 v[36:39], v[140:143], v[180:183], v[36:39]
	v_mfma_f32_16x16x32_bf16 v[24:27], v[132:135], v[172:175], v[24:27]
	v_mfma_f32_16x16x32_bf16 v[20:23], v[140:143], v[172:175], v[20:23]
	v_mfma_f32_16x16x32_bf16 v[8:11], v[132:135], v[164:167], v[8:11]
	v_mfma_f32_16x16x32_bf16 v[2:5], v[140:143], v[164:167], v[4:7]
	v_mfma_f32_16x16x32_bf16 v[56:59], v[136:139], v[192:195], v[56:59]
	v_mfma_f32_16x16x32_bf16 v[52:55], v[144:147], v[192:195], v[52:55]
	v_mfma_f32_16x16x32_bf16 v[40:43], v[136:139], v[184:187], v[40:43]
	v_mfma_f32_16x16x32_bf16 v[36:39], v[144:147], v[184:187], v[36:39]
	v_mfma_f32_16x16x32_bf16 v[24:27], v[136:139], v[176:179], v[24:27]
	v_mfma_f32_16x16x32_bf16 v[20:23], v[144:147], v[176:179], v[20:23]
	v_mfma_f32_16x16x32_bf16 v[8:11], v[136:139], v[168:171], v[8:11]
	v_mfma_f32_16x16x32_bf16 v[4:7], v[144:147], v[168:171], v[2:5]
	s_setprio 0
	s_branch .LBB0_2952
	s_nop 0
	s_nop 0
	s_nop 0
	s_nop 0
	s_nop 0
	s_nop 0
	s_nop 0
	s_nop 0

; #define PG8_STAGE(bufoff, gbase, voff) do { _Pragma("unroll") for (int _i = 0; _i < 2; ++_i) \
;         __builtin_amdgcn_global_load_lds((const unsigned*)((const char*)(gbase) + (voff)[_i]), (PG8_LAS unsigned*)(lds + (bufoff) + ldsw + _i * 8192), 16, 0, 0); } while (0)
; #define PG8_LDA(dst, b, h) do { _Pragma("unroll") for (int m = 0; m < 4; ++m) _Pragma("unroll") for (int k = 0; k < 2; ++k) dst[m][k] = *(const PG8_LAS bf16x8*)(lds + PG8_SA(b, h) + aoff + m * 2048 + k * 1024); } while (0)
; #define PG8_LDB(dst, b, h) do { _Pragma("unroll") for (int n = 0; n < 2; ++n) _Pragma("unroll") for (int k = 0; k < 2; ++k) dst[n][k] = *(const PG8_LAS bf16x8*)(lds + PG8_SB(b, h) + boff + n * 2048 + k * 1024); } while (0)
; #define PG8_MMA(ai, bj, At, Bt) do { __builtin_amdgcn_s_setprio(1); _Pragma("unroll") for (int m = 0; m < 4; ++m) _Pragma("unroll") for (int n = 0; n < 2; ++n) _Pragma("unroll") for (int k = 0; k < 2; ++k) \
;         acc[ai][bj][m][n] = __builtin_amdgcn_mfma_f32_16x16x32_bf16(Bt[n][k], At[m][k], acc[ai][bj][m][n], 0, 0, 0); __builtin_amdgcn_s_setprio(0); } while (0)
; #define PG8_WAIT_V(n) asm volatile("s_waitcnt vmcnt(" #n ")" ::: "memory")
; template <class Epi, class Sched, bool ALIGN_EPI = false, bool SP2 = false>
; __device__ __forceinline__ void gemm_phase(PG8_LAS unsigned char* lds, const Gemm g, const Sched& S, const Epi& E, int wave0) {
;     ...
;         for (int t = 0; t < nt; t += 2) {
;             const bool last = (t == nt - 2);
;             const char* a1 = cA + (size_t)(t + 1) * kstep;
;             const char* a2 = last ? nA : cA + (size_t)(t + 2) * kstep; const char* b2 = last ? nB : cB + (size_t)(t + 2) * kstep;
;             const char* a3 = a2 + kstep; const char* b3 = b2 + kstep;
;             if (last && has_next) S.a_ready(nxt);
;             if constexpr (SP2) {
;             PG8_LDB(B0, 0, 0); PG8_LDB(B1, 0, 1); PG8_SCHED; PG8_LDA(At, 0, 0); PG8_STAGE(PG8_SA(1, 1), a1 + hstep, voffA);
;             PG8_WAIT_V(8); PG8_WAIT_L(0); PG8_BAR; PG8_MMA(0, 0, At, B0); PG8_MMA(0, 1, At, B1); PG8_BAR; PG8_SCHED;
;             PG8_LDA(At, 0, 1); PG8_STAGE(PG8_SB(0, 0), b2, voffB); PG8_STAGE(PG8_SB(0, 1), b2 + hstep, voffB); PG8_STAGE(PG8_SA(0, 0), a2, voffA);
;             PG8_WAIT_V(8); PG8_WAIT_L(0); PG8_BAR; if (!cur.half) { PG8_MMA(1, 0, At, B0); PG8_MMA(1, 1, At, B1); } PG8_BAR; PG8_SCHED;
.LBB0_3132:
	ds_read_b128 v[148:151], v220
	ds_read_b128 v[152:155], v220 offset:1024
	ds_read_b128 v[156:159], v220 offset:2048
	ds_read_b128 v[160:163], v220 offset:3072
	ds_read_b128 v[132:135], v221
	ds_read_b128 v[136:139], v221 offset:1024
	ds_read_b128 v[140:143], v221 offset:2048
	ds_read_b128 v[144:147], v221 offset:3072
	s_add_u32 s0, s6, 0xfffc0080
	s_addc_u32 s1, s7, -1
	s_cmp_eq_u32 s76, 12
	s_cselect_b32 s57, s49, s1
	s_cselect_b32 s56, s68, s0
	s_cselect_b32 s9, s47, s75
	s_cselect_b32 s8, s69, s74
	v_lshl_add_u64 v[2:3], s[6:7], 0, v[204:205]
	s_add_i32 m0, s33, 0xc000
	s_waitcnt lgkmcnt(0)
	ds_read_b128 v[164:167], v222
	ds_read_b128 v[168:171], v222 offset:1024
	ds_read_b128 v[172:175], v222 offset:2048
	ds_read_b128 v[176:179], v222 offset:3072
	ds_read_b128 v[180:183], v222 offset:4096
	ds_read_b128 v[184:187], v222 offset:5120
	ds_read_b128 v[188:191], v222 offset:6144
	ds_read_b128 v[192:195], v222 offset:7168
	global_load_lds_dwordx4 v[2:3], off
	v_lshl_add_u64 v[2:3], s[6:7], 0, v[206:207]
	s_add_i32 m0, s33, 0xe000
	s_nop 0
	global_load_lds_dwordx4 v[2:3], off
	s_waitcnt vmcnt(8)
	s_waitcnt lgkmcnt(0)
	s_barrier
	s_setprio 1
	s_waitcnt lgkmcnt(0)
	v_mfma_f32_16x16x32_bf16 v[128:131], v[148:151], v[164:167], v[128:131]
	v_mfma_f32_16x16x32_bf16 v[124:127], v[156:159], v[164:167], v[124:127]
	v_mfma_f32_16x16x32_bf16 v[120:123], v[148:151], v[172:175], v[120:123]
	v_mfma_f32_16x16x32_bf16 v[116:119], v[156:159], v[172:175], v[116:119]
	v_mfma_f32_16x16x32_bf16 v[112:115], v[148:151], v[180:183], v[112:115]
	v_mfma_f32_16x16x32_bf16 v[108:111], v[156:159], v[180:183], v[108:111]
	v_mfma_f32_16x16x32_bf16 v[104:107], v[148:151], v[188:191], v[104:107]
	v_mfma_f32_16x16x32_bf16 v[100:103], v[156:159], v[188:191], v[100:103]
	v_mfma_f32_16x16x32_bf16 v[128:131], v[152:155], v[168:171], v[128:131]
	v_mfma_f32_16x16x32_bf16 v[124:127], v[160:163], v[168:171], v[124:127]
	v_mfma_f32_16x16x32_bf16 v[120:123], v[152:155], v[176:179], v[120:123]
	v_mfma_f32_16x16x32_bf16 v[116:119], v[160:163], v[176:179], v[116:119]
	v_mfma_f32_16x16x32_bf16 v[112:115], v[152:155], v[184:187], v[112:115]
	v_mfma_f32_16x16x32_bf16 v[108:111], v[160:163], v[184:187], v[108:111]
	v_mfma_f32_16x16x32_bf16 v[104:107], v[152:155], v[192:195], v[104:107]
	v_mfma_f32_16x16x32_bf16 v[100:103], v[160:163], v[192:195], v[100:103]
	v_mfma_f32_16x16x32_bf16 v[68:71], v[132:135], v[164:167], v[68:71]
	v_mfma_f32_16x16x32_bf16 v[60:63], v[140:143], v[164:167], v[60:63]
	v_mfma_f32_16x16x32_bf16 v[56:59], v[132:135], v[172:175], v[56:59]
	v_mfma_f32_16x16x32_bf16 v[52:55], v[140:143], v[172:175], v[52:55]
	v_mfma_f32_16x16x32_bf16 v[48:51], v[132:135], v[180:183], v[48:51]
	v_mfma_f32_16x16x32_bf16 v[44:47], v[140:143], v[180:183], v[44:47]
	v_mfma_f32_16x16x32_bf16 v[40:43], v[132:135], v[188:191], v[40:43]
	v_mfma_f32_16x16x32_bf16 v[36:39], v[140:143], v[188:191], v[36:39]
	v_mfma_f32_16x16x32_bf16 v[68:71], v[136:139], v[168:171], v[68:71]
	v_mfma_f32_16x16x32_bf16 v[60:63], v[144:147], v[168:171], v[60:63]
	v_mfma_f32_16x16x32_bf16 v[56:59], v[136:139], v[176:179], v[56:59]
	v_mfma_f32_16x16x32_bf16 v[52:55], v[144:147], v[176:179], v[52:55]
	v_mfma_f32_16x16x32_bf16 v[48:51], v[136:139], v[184:187], v[48:51]
	v_mfma_f32_16x16x32_bf16 v[44:47], v[144:147], v[184:187], v[44:47]
	v_mfma_f32_16x16x32_bf16 v[40:43], v[136:139], v[192:195], v[40:43]
	v_mfma_f32_16x16x32_bf16 v[36:39], v[144:147], v[192:195], v[36:39]
	s_setprio 0
	s_barrier
	s_add_i32 s0, s62, s31
	v_lshl_add_u64 v[2:3], s[8:9], 0, v[198:199]
	s_mov_b32 m0, s0
	ds_read_b128 v[188:191], v222 offset:16384
	ds_read_b128 v[192:195], v222 offset:17408
	ds_read_b128 v[180:183], v222 offset:18432
	ds_read_b128 v[184:187], v222 offset:19456
	ds_read_b128 v[172:175], v222 offset:20480
	ds_read_b128 v[176:179], v222 offset:21504
	ds_read_b128 v[164:167], v222 offset:22528
	ds_read_b128 v[168:171], v222 offset:23552
	global_load_lds_dwordx4 v[2:3], off
	s_add_i32 m0, s0, 0x2000
	s_add_u32 s0, s8, 0x40000
	v_lshl_add_u64 v[210:211], s[8:9], 0, v[202:203]
	s_addc_u32 s1, s9, 0
	s_add_i32 s77, s63, s31
	global_load_lds_dwordx4 v[210:211], off
	v_lshl_add_u64 v[212:213], s[0:1], 0, v[198:199]
	s_mov_b32 m0, s77
	v_lshl_add_u64 v[214:215], s[56:57], 0, v[200:201]
	global_load_lds_dwordx4 v[212:213], off
	v_lshl_add_u64 v[212:213], s[0:1], 0, v[202:203]
	s_add_i32 m0, s77, 0x2000
	v_cmp_ne_u32_e64 s[0:1], 1, v225
	global_load_lds_dwordx4 v[212:213], off
	v_lshl_add_u64 v[212:213], s[56:57], 0, v[196:197]
	s_mov_b32 m0, s33
	s_andn2_b64 vcc, exec, s[2:3]
	global_load_lds_dwordx4 v[212:213], off
	s_mov_b32 m0, s35
	s_nop 0
	global_load_lds_dwordx4 v[214:215], off
	s_waitcnt vmcnt(8)
	s_waitcnt lgkmcnt(0)
	s_barrier
	s_cbranch_vccnz .LBB0_3134
	s_setprio 1
	s_waitcnt lgkmcnt(0)
	v_mfma_f32_16x16x32_bf16 v[96:99], v[148:151], v[188:191], v[96:99]
	v_mfma_f32_16x16x32_bf16 v[92:95], v[156:159], v[188:191], v[92:95]
	v_mfma_f32_16x16x32_bf16 v[88:91], v[148:151], v[180:183], v[88:91]
	v_mfma_f32_16x16x32_bf16 v[84:87], v[156:159], v[180:183], v[84:87]
	v_mfma_f32_16x16x32_bf16 v[80:83], v[148:151], v[172:175], v[80:83]
	v_mfma_f32_16x16x32_bf16 v[76:79], v[156:159], v[172:175], v[76:79]
	v_mfma_f32_16x16x32_bf16 v[72:75], v[148:151], v[164:167], v[72:75]
	v_mfma_f32_16x16x32_bf16 v[64:67], v[156:159], v[164:167], v[64:67]
	v_mfma_f32_16x16x32_bf16 v[96:99], v[152:155], v[192:195], v[96:99]
	v_mfma_f32_16x16x32_bf16 v[92:95], v[160:163], v[192:195], v[92:95]
	v_mfma_f32_16x16x32_bf16 v[88:91], v[152:155], v[184:187], v[88:91]
	v_mfma_f32_16x16x32_bf16 v[84:87], v[160:163], v[184:187], v[84:87]
	v_mfma_f32_16x16x32_bf16 v[80:83], v[152:155], v[176:179], v[80:83]
	v_mfma_f32_16x16x32_bf16 v[76:79], v[160:163], v[176:179], v[76:79]
	v_mfma_f32_16x16x32_bf16 v[72:75], v[152:155], v[168:171], v[72:75]
	v_mfma_f32_16x16x32_bf16 v[64:67], v[160:163], v[168:171], v[64:67]
	v_mfma_f32_16x16x32_bf16 v[32:35], v[132:135], v[188:191], v[32:35]
	v_mfma_f32_16x16x32_bf16 v[28:31], v[140:143], v[188:191], v[28:31]
	v_mfma_f32_16x16x32_bf16 v[24:27], v[132:135], v[180:183], v[24:27]
	v_mfma_f32_16x16x32_bf16 v[20:23], v[140:143], v[180:183], v[20:23]
	v_mfma_f32_16x16x32_bf16 v[16:19], v[132:135], v[172:175], v[16:19]
	v_mfma_f32_16x16x32_bf16 v[12:15], v[140:143], v[172:175], v[12:15]
	v_mfma_f32_16x16x32_bf16 v[8:11], v[132:135], v[164:167], v[8:11]
	v_mfma_f32_16x16x32_bf16 v[4:7], v[140:143], v[164:167], v[4:7]
	v_mfma_f32_16x16x32_bf16 v[32:35], v[136:139], v[192:195], v[32:35]
	v_mfma_f32_16x16x32_bf16 v[28:31], v[144:147], v[192:195], v[28:31]
	v_mfma_f32_16x16x32_bf16 v[24:27], v[136:139], v[184:187], v[24:27]
	v_mfma_f32_16x16x32_bf16 v[20:23], v[144:147], v[184:187], v[20:23]
	v_mfma_f32_16x16x32_bf16 v[16:19], v[136:139], v[176:179], v[16:19]
	v_mfma_f32_16x16x32_bf16 v[12:15], v[144:147], v[176:179], v[12:15]
	v_mfma_f32_16x16x32_bf16 v[8:11], v[136:139], v[168:171], v[8:11]
	v_mfma_f32_16x16x32_bf16 v[4:7], v[144:147], v[168:171], v[4:7]
	s_setprio 0
; #define PG8_STAGE(bufoff, gbase, voff) do { _Pragma("unroll") for (int _i = 0; _i < 2; ++_i) \
;         __builtin_amdgcn_global_load_lds((const unsigned*)((const char*)(gbase) + (voff)[_i]), (PG8_LAS unsigned*)(lds + (bufoff) + ldsw + _i * 8192), 16, 0, 0); } while (0)
; #define PG8_LDA(dst, b, h) do { _Pragma("unroll") for (int m = 0; m < 4; ++m) _Pragma("unroll") for (int k = 0; k < 2; ++k) dst[m][k] = *(const PG8_LAS bf16x8*)(lds + PG8_SA(b, h) + aoff + m * 2048 + k * 1024); } while (0)
; #define PG8_LDB(dst, b, h) do { _Pragma("unroll") for (int n = 0; n < 2; ++n) _Pragma("unroll") for (int k = 0; k < 2; ++k) dst[n][k] = *(const PG8_LAS bf16x8*)(lds + PG8_SB(b, h) + boff + n * 2048 + k * 1024); } while (0)
; #define PG8_MMA(ai, bj, At, Bt) do { __builtin_amdgcn_s_setprio(1); _Pragma("unroll") for (int m = 0; m < 4; ++m) _Pragma("unroll") for (int n = 0; n < 2; ++n) _Pragma("unroll") for (int k = 0; k < 2; ++k) \
;         acc[ai][bj][m][n] = __builtin_amdgcn_mfma_f32_16x16x32_bf16(Bt[n][k], At[m][k], acc[ai][bj][m][n], 0, 0, 0); __builtin_amdgcn_s_setprio(0); } while (0)
; #define PG8_WAIT_V(n) asm volatile("s_waitcnt vmcnt(" #n ")" ::: "memory")
; #define PG8_WAIT_L(n) asm volatile("s_waitcnt lgkmcnt(" #n ")" ::: "memory")
; #define PG8_BAR __builtin_amdgcn_s_barrier()
; #define PG8_SCHED __builtin_amdgcn_sched_barrier(0)
; template <class Epi, class Sched, bool ALIGN_EPI = false, bool SP2 = false>
; __device__ __forceinline__ void gemm_phase(PG8_LAS unsigned char* lds, const Gemm g, const Sched& S, const Epi& E, int wave0) {
;     ...
;         for (int t = 0; t < nt; t += 2) {
;             const bool last = (t == nt - 2);
;             const char* a1 = cA + (size_t)(t + 1) * kstep;
;             const char* a2 = last ? nA : cA + (size_t)(t + 2) * kstep; const char* b2 = last ? nB : cB + (size_t)(t + 2) * kstep;
;     ...
;             PG8_LDB(B0, 1, 0); PG8_LDB(B1, 1, 1); PG8_SCHED; PG8_LDA(At, 1, 0); PG8_STAGE(PG8_SA(0, 1), a2 + hstep, voffA);
;             PG8_WAIT_V(8); PG8_WAIT_L(0); PG8_BAR; PG8_MMA(0, 0, At, B0); PG8_MMA(0, 1, At, B1); PG8_BAR; PG8_SCHED;
;             PG8_LDA(At, 1, 1); PG8_STAGE(PG8_SB(1, 0), b3, voffB); PG8_STAGE(PG8_SB(1, 1), b3 + hstep, voffB); PG8_STAGE(PG8_SA(1, 0), a3, voffA);
;             PG8_WAIT_V(8); PG8_WAIT_L(0); PG8_BAR; if (!cur.half) { PG8_MMA(1, 0, At, B0); PG8_MMA(1, 1, At, B1); } PG8_BAR; PG8_SCHED;
.LBB0_3134:
	s_barrier
	s_add_i32 s77, 0, 0x18000
	v_add_u32_e32 v1, s77, v219
	s_add_i32 s78, 0, 0x1c000
	ds_read_b128 v[148:151], v1
	ds_read_b128 v[152:155], v1 offset:1024
	ds_read_b128 v[156:159], v1 offset:2048
	ds_read_b128 v[160:163], v1 offset:3072
	v_add_u32_e32 v1, s78, v219
	ds_read_b128 v[132:135], v1
	ds_read_b128 v[136:139], v1 offset:1024
	ds_read_b128 v[140:143], v1 offset:2048
	ds_read_b128 v[144:147], v1 offset:3072
	s_add_u32 s56, s56, 0x40000
	s_addc_u32 s57, s57, 0
	s_mov_b32 m0, s37
	v_lshl_add_u64 v[226:227], s[56:57], 0, v[196:197]
	s_waitcnt lgkmcnt(0)
	ds_read_b128 v[164:167], v222 offset:32768
	ds_read_b128 v[168:171], v222 offset:33792
	ds_read_b128 v[172:175], v222 offset:34816
	ds_read_b128 v[176:179], v222 offset:35840
	ds_read_b128 v[180:183], v222 offset:36864
	ds_read_b128 v[184:187], v222 offset:37888
	ds_read_b128 v[188:191], v222 offset:38912
	ds_read_b128 v[192:195], v222 offset:39936
	global_load_lds_dwordx4 v[226:227], off
	v_lshl_add_u64 v[226:227], s[56:57], 0, v[200:201]
	s_mov_b32 m0, s39
	s_nop 0
	global_load_lds_dwordx4 v[226:227], off
	s_waitcnt vmcnt(8)
	s_waitcnt lgkmcnt(0)
	s_barrier
	s_setprio 1
	s_waitcnt lgkmcnt(0)
	v_mfma_f32_16x16x32_bf16 v[128:131], v[148:151], v[164:167], v[128:131]
	v_mfma_f32_16x16x32_bf16 v[124:127], v[156:159], v[164:167], v[124:127]
	v_mfma_f32_16x16x32_bf16 v[120:123], v[148:151], v[172:175], v[120:123]
	v_mfma_f32_16x16x32_bf16 v[116:119], v[156:159], v[172:175], v[116:119]
	v_mfma_f32_16x16x32_bf16 v[112:115], v[148:151], v[180:183], v[112:115]
	v_mfma_f32_16x16x32_bf16 v[108:111], v[156:159], v[180:183], v[108:111]
	v_mfma_f32_16x16x32_bf16 v[104:107], v[148:151], v[188:191], v[104:107]
	v_mfma_f32_16x16x32_bf16 v[100:103], v[156:159], v[188:191], v[100:103]
	v_mfma_f32_16x16x32_bf16 v[128:131], v[152:155], v[168:171], v[128:131]
	v_mfma_f32_16x16x32_bf16 v[124:127], v[160:163], v[168:171], v[124:127]
	v_mfma_f32_16x16x32_bf16 v[120:123], v[152:155], v[176:179], v[120:123]
	v_mfma_f32_16x16x32_bf16 v[116:119], v[160:163], v[176:179], v[116:119]
	v_mfma_f32_16x16x32_bf16 v[112:115], v[152:155], v[184:187], v[112:115]
	v_mfma_f32_16x16x32_bf16 v[108:111], v[160:163], v[184:187], v[108:111]
	v_mfma_f32_16x16x32_bf16 v[104:107], v[152:155], v[192:195], v[104:107]
	v_mfma_f32_16x16x32_bf16 v[100:103], v[160:163], v[192:195], v[100:103]
	v_mfma_f32_16x16x32_bf16 v[68:71], v[132:135], v[164:167], v[68:71]
	v_mfma_f32_16x16x32_bf16 v[60:63], v[140:143], v[164:167], v[60:63]
	v_mfma_f32_16x16x32_bf16 v[56:59], v[132:135], v[172:175], v[56:59]
	v_mfma_f32_16x16x32_bf16 v[52:55], v[140:143], v[172:175], v[52:55]
	v_mfma_f32_16x16x32_bf16 v[48:51], v[132:135], v[180:183], v[48:51]
	v_mfma_f32_16x16x32_bf16 v[44:47], v[140:143], v[180:183], v[44:47]
	v_mfma_f32_16x16x32_bf16 v[40:43], v[132:135], v[188:191], v[40:43]
	v_mfma_f32_16x16x32_bf16 v[36:39], v[140:143], v[188:191], v[36:39]
	v_mfma_f32_16x16x32_bf16 v[68:71], v[136:139], v[168:171], v[68:71]
	v_mfma_f32_16x16x32_bf16 v[60:63], v[144:147], v[168:171], v[60:63]
	v_mfma_f32_16x16x32_bf16 v[56:59], v[136:139], v[176:179], v[56:59]
	v_mfma_f32_16x16x32_bf16 v[52:55], v[144:147], v[176:179], v[52:55]
	v_mfma_f32_16x16x32_bf16 v[48:51], v[136:139], v[184:187], v[48:51]
	v_mfma_f32_16x16x32_bf16 v[44:47], v[144:147], v[184:187], v[44:47]
	v_mfma_f32_16x16x32_bf16 v[40:43], v[136:139], v[192:195], v[40:43]
	v_mfma_f32_16x16x32_bf16 v[36:39], v[144:147], v[192:195], v[36:39]
	s_setprio 0
	s_barrier
	s_add_i32 s56, s77, s31
	v_lshl_add_u64 v[2:3], v[2:3], 0, s[22:23]
	s_mov_b32 m0, s56
	ds_read_b128 v[188:191], v222 offset:49152
	ds_read_b128 v[192:195], v222 offset:50176
	ds_read_b128 v[180:183], v222 offset:51200
	ds_read_b128 v[184:187], v222 offset:52224
	ds_read_b128 v[172:175], v222 offset:53248
	ds_read_b128 v[176:179], v222 offset:54272
	ds_read_b128 v[164:167], v222 offset:55296
	ds_read_b128 v[168:171], v222 offset:56320
	global_load_lds_dwordx4 v[2:3], off
	s_add_i32 m0, s56, 0x2000
	s_add_u32 s8, s8, 0x40080
	v_lshl_add_u64 v[2:3], v[210:211], 0, s[22:23]
	s_addc_u32 s9, s9, 0
	s_add_i32 s56, s78, s31
	global_load_lds_dwordx4 v[2:3], off
	v_lshl_add_u64 v[2:3], s[8:9], 0, v[198:199]
	s_mov_b32 m0, s56
	s_and_b64 vcc, exec, s[0:1]
	global_load_lds_dwordx4 v[2:3], off
	v_lshl_add_u64 v[2:3], s[8:9], 0, v[202:203]
	s_add_i32 m0, s56, 0x2000
	s_nop 0
	global_load_lds_dwordx4 v[2:3], off
	v_lshl_add_u64 v[2:3], v[212:213], 0, s[22:23]
	s_mov_b32 m0, s60
	s_nop 0
	global_load_lds_dwordx4 v[2:3], off
	v_lshl_add_u64 v[2:3], v[214:215], 0, s[22:23]
	s_mov_b32 m0, s61
	s_nop 0
	global_load_lds_dwordx4 v[2:3], off
	s_waitcnt vmcnt(8)
	s_waitcnt lgkmcnt(0)
	s_barrier
	s_cbranch_vccnz .LBB0_3131
	s_setprio 1
	s_waitcnt lgkmcnt(0)
	v_mfma_f32_16x16x32_bf16 v[96:99], v[148:151], v[188:191], v[96:99]
	v_mfma_f32_16x16x32_bf16 v[92:95], v[156:159], v[188:191], v[92:95]
	v_mfma_f32_16x16x32_bf16 v[88:91], v[148:151], v[180:183], v[88:91]
	v_mfma_f32_16x16x32_bf16 v[84:87], v[156:159], v[180:183], v[84:87]
	v_mfma_f32_16x16x32_bf16 v[80:83], v[148:151], v[172:175], v[80:83]
	v_mfma_f32_16x16x32_bf16 v[76:79], v[156:159], v[172:175], v[76:79]
	v_mfma_f32_16x16x32_bf16 v[72:75], v[148:151], v[164:167], v[72:75]
	v_mfma_f32_16x16x32_bf16 v[64:67], v[156:159], v[164:167], v[64:67]
	v_mfma_f32_16x16x32_bf16 v[96:99], v[152:155], v[192:195], v[96:99]
	v_mfma_f32_16x16x32_bf16 v[92:95], v[160:163], v[192:195], v[92:95]
	v_mfma_f32_16x16x32_bf16 v[88:91], v[152:155], v[184:187], v[88:91]
	v_mfma_f32_16x16x32_bf16 v[84:87], v[160:163], v[184:187], v[84:87]
	v_mfma_f32_16x16x32_bf16 v[80:83], v[152:155], v[176:179], v[80:83]
	v_mfma_f32_16x16x32_bf16 v[76:79], v[160:163], v[176:179], v[76:79]
	v_mfma_f32_16x16x32_bf16 v[72:75], v[152:155], v[168:171], v[72:75]
	v_mfma_f32_16x16x32_bf16 v[64:67], v[160:163], v[168:171], v[64:67]
	v_mfma_f32_16x16x32_bf16 v[32:35], v[132:135], v[188:191], v[32:35]
	v_mfma_f32_16x16x32_bf16 v[28:31], v[140:143], v[188:191], v[28:31]
	v_mfma_f32_16x16x32_bf16 v[24:27], v[132:135], v[180:183], v[24:27]
	v_mfma_f32_16x16x32_bf16 v[20:23], v[140:143], v[180:183], v[20:23]
	v_mfma_f32_16x16x32_bf16 v[16:19], v[132:135], v[172:175], v[16:19]
	v_mfma_f32_16x16x32_bf16 v[12:15], v[140:143], v[172:175], v[12:15]
	v_mfma_f32_16x16x32_bf16 v[8:11], v[132:135], v[164:167], v[8:11]
	v_mfma_f32_16x16x32_bf16 v[2:5], v[140:143], v[164:167], v[4:7]
	v_mfma_f32_16x16x32_bf16 v[32:35], v[136:139], v[192:195], v[32:35]
	v_mfma_f32_16x16x32_bf16 v[28:31], v[144:147], v[192:195], v[28:31]
	v_mfma_f32_16x16x32_bf16 v[24:27], v[136:139], v[184:187], v[24:27]
	v_mfma_f32_16x16x32_bf16 v[20:23], v[144:147], v[184:187], v[20:23]
	v_mfma_f32_16x16x32_bf16 v[16:19], v[136:139], v[176:179], v[16:19]
	v_mfma_f32_16x16x32_bf16 v[12:15], v[144:147], v[176:179], v[12:15]
	v_mfma_f32_16x16x32_bf16 v[8:11], v[136:139], v[168:171], v[8:11]
	v_mfma_f32_16x16x32_bf16 v[4:7], v[144:147], v[168:171], v[2:5]
	s_setprio 0
	s_branch .LBB0_3131
	s_nop 0
	s_nop 0
	s_nop 0
	s_nop 0
	s_nop 0
	s_nop 0
	s_nop 0
	s_nop 0

; #define PG8_STAGE(bufoff, gbase, voff) do { _Pragma("unroll") for (int _i = 0; _i < 2; ++_i) \
;         __builtin_amdgcn_global_load_lds((const unsigned*)((const char*)(gbase) + (voff)[_i]), (PG8_LAS unsigned*)(lds + (bufoff) + ldsw + _i * 8192), 16, 0, 0); } while (0)
; #define PG8_LDA(dst, b, h) do { _Pragma("unroll") for (int m = 0; m < 4; ++m) _Pragma("unroll") for (int k = 0; k < 2; ++k) dst[m][k] = *(const PG8_LAS bf16x8*)(lds + PG8_SA(b, h) + aoff + m * 2048 + k * 1024); } while (0)
; #define PG8_LDB(dst, b, h) do { _Pragma("unroll") for (int n = 0; n < 2; ++n) _Pragma("unroll") for (int k = 0; k < 2; ++k) dst[n][k] = *(const PG8_LAS bf16x8*)(lds + PG8_SB(b, h) + boff + n * 2048 + k * 1024); } while (0)
; #define PG8_MMA(ai, bj, At, Bt) do { __builtin_amdgcn_s_setprio(1); _Pragma("unroll") for (int m = 0; m < 4; ++m) _Pragma("unroll") for (int n = 0; n < 2; ++n) _Pragma("unroll") for (int k = 0; k < 2; ++k) \
;         acc[ai][bj][m][n] = __builtin_amdgcn_mfma_f32_16x16x32_bf16(Bt[n][k], At[m][k], acc[ai][bj][m][n], 0, 0, 0); __builtin_amdgcn_s_setprio(0); } while (0)
; #define PG8_WAIT_V(n) asm volatile("s_waitcnt vmcnt(" #n ")" ::: "memory")
; template <class Epi, class Sched, bool ALIGN_EPI = false, bool SP2 = false>
; __device__ __forceinline__ void gemm_phase(PG8_LAS unsigned char* lds, const Gemm g, const Sched& S, const Epi& E, int wave0) {
;     ...
;         for (int t = 0; t < nt; t += 2) {
;             const bool last = (t == nt - 2);
;             const char* a1 = cA + (size_t)(t + 1) * kstep;
;             const char* a2 = last ? nA : cA + (size_t)(t + 2) * kstep; const char* b2 = last ? nB : cB + (size_t)(t + 2) * kstep;
;             const char* a3 = a2 + kstep; const char* b3 = b2 + kstep;
;             if (last && has_next) S.a_ready(nxt);
;             if constexpr (SP2) {
;             PG8_LDB(B0, 0, 0); PG8_LDB(B1, 0, 1); PG8_SCHED; PG8_LDA(At, 0, 0); PG8_STAGE(PG8_SA(1, 1), a1 + hstep, voffA);
;             PG8_WAIT_V(8); PG8_WAIT_L(0); PG8_BAR; PG8_MMA(0, 0, At, B0); PG8_MMA(0, 1, At, B1); PG8_BAR; PG8_SCHED;
;             PG8_LDA(At, 0, 1); PG8_STAGE(PG8_SB(0, 0), b2, voffB); PG8_STAGE(PG8_SB(0, 1), b2 + hstep, voffB); PG8_STAGE(PG8_SA(0, 0), a2, voffA);
;             PG8_WAIT_V(8); PG8_WAIT_L(0); PG8_BAR; if (!cur.half) { PG8_MMA(1, 0, At, B0); PG8_MMA(1, 1, At, B1); } PG8_BAR; PG8_SCHED;
.LBB0_3229:
	ds_read_b128 v[144:147], v153
	ds_read_b128 v[156:159], v153 offset:1024
	ds_read_b128 v[160:163], v153 offset:2048
	ds_read_b128 v[164:167], v153 offset:3072
	ds_read_b128 v[168:171], v154
	ds_read_b128 v[172:175], v154 offset:1024
	ds_read_b128 v[176:179], v154 offset:2048
	ds_read_b128 v[180:183], v154 offset:3072
	s_add_u32 s18, s16, 0x100
	s_addc_u32 s19, s17, 0
	s_cmp_eq_u32 s44, 40
	s_cselect_b32 s23, s7, s19
	s_cselect_b32 s22, s6, s18
	s_cselect_b32 s21, s15, s43
	s_cselect_b32 s20, s14, s42
	v_lshl_add_u64 v[148:149], s[16:17], 0, v[136:137]
	s_add_i32 m0, s25, 0xc000
	ds_read_b128 v[184:187], v155
	ds_read_b128 v[188:191], v155 offset:1024
	ds_read_b128 v[192:195], v155 offset:2048
	ds_read_b128 v[196:199], v155 offset:3072
	ds_read_b128 v[200:203], v155 offset:4096
	ds_read_b128 v[204:207], v155 offset:5120
	ds_read_b128 v[208:211], v155 offset:6144
	ds_read_b128 v[212:215], v155 offset:7168
	global_load_lds_dwordx4 v[148:149], off
	v_lshl_add_u64 v[148:149], s[16:17], 0, v[138:139]
	s_add_i32 m0, s25, 0xe000
	s_nop 0
	global_load_lds_dwordx4 v[148:149], off
	s_waitcnt vmcnt(8)
	s_waitcnt lgkmcnt(0)
	s_barrier
	s_setprio 1
	s_waitcnt lgkmcnt(0)
	v_mfma_f32_16x16x32_bf16 v[124:127], v[144:147], v[184:187], v[124:127]
	v_mfma_f32_16x16x32_bf16 v[120:123], v[160:163], v[184:187], v[120:123]
	v_mfma_f32_16x16x32_bf16 v[116:119], v[144:147], v[192:195], v[116:119]
	v_mfma_f32_16x16x32_bf16 v[108:111], v[160:163], v[192:195], v[108:111]
	v_mfma_f32_16x16x32_bf16 v[92:95], v[144:147], v[200:203], v[92:95]
	v_mfma_f32_16x16x32_bf16 v[88:91], v[160:163], v[200:203], v[88:91]
	v_mfma_f32_16x16x32_bf16 v[84:87], v[144:147], v[208:211], v[84:87]
	v_mfma_f32_16x16x32_bf16 v[80:83], v[160:163], v[208:211], v[80:83]
	v_mfma_f32_16x16x32_bf16 v[124:127], v[156:159], v[188:191], v[124:127]
	v_mfma_f32_16x16x32_bf16 v[120:123], v[164:167], v[188:191], v[120:123]
	v_mfma_f32_16x16x32_bf16 v[116:119], v[156:159], v[196:199], v[116:119]
	v_mfma_f32_16x16x32_bf16 v[108:111], v[164:167], v[196:199], v[108:111]
	v_mfma_f32_16x16x32_bf16 v[92:95], v[156:159], v[204:207], v[92:95]
	v_mfma_f32_16x16x32_bf16 v[88:91], v[164:167], v[204:207], v[88:91]
	v_mfma_f32_16x16x32_bf16 v[84:87], v[156:159], v[212:215], v[84:87]
	v_mfma_f32_16x16x32_bf16 v[80:83], v[164:167], v[212:215], v[80:83]
	v_mfma_f32_16x16x32_bf16 v[112:115], v[168:171], v[184:187], v[112:115]
	v_mfma_f32_16x16x32_bf16 v[104:107], v[176:179], v[184:187], v[104:107]
	v_mfma_f32_16x16x32_bf16 v[100:103], v[168:171], v[192:195], v[100:103]
	v_mfma_f32_16x16x32_bf16 v[96:99], v[176:179], v[192:195], v[96:99]
	v_mfma_f32_16x16x32_bf16 v[76:79], v[168:171], v[200:203], v[76:79]
	v_mfma_f32_16x16x32_bf16 v[72:75], v[176:179], v[200:203], v[72:75]
	v_mfma_f32_16x16x32_bf16 v[68:71], v[168:171], v[208:211], v[68:71]
	v_mfma_f32_16x16x32_bf16 v[64:67], v[176:179], v[208:211], v[64:67]
	v_mfma_f32_16x16x32_bf16 v[112:115], v[172:175], v[188:191], v[112:115]
	v_mfma_f32_16x16x32_bf16 v[104:107], v[180:183], v[188:191], v[104:107]
	v_mfma_f32_16x16x32_bf16 v[100:103], v[172:175], v[196:199], v[100:103]
	v_mfma_f32_16x16x32_bf16 v[96:99], v[180:183], v[196:199], v[96:99]
	v_mfma_f32_16x16x32_bf16 v[76:79], v[172:175], v[204:207], v[76:79]
	v_mfma_f32_16x16x32_bf16 v[72:75], v[180:183], v[204:207], v[72:75]
	v_mfma_f32_16x16x32_bf16 v[68:71], v[172:175], v[212:215], v[68:71]
	v_mfma_f32_16x16x32_bf16 v[64:67], v[180:183], v[212:215], v[64:67]
	s_setprio 0
	s_barrier
	s_add_i32 s16, s35, s24
	v_lshl_add_u64 v[148:149], s[20:21], 0, v[130:131]
	s_mov_b32 m0, s16
	ds_read_b128 v[184:187], v155 offset:16384
	ds_read_b128 v[188:191], v155 offset:17408
	ds_read_b128 v[192:195], v155 offset:18432
	ds_read_b128 v[196:199], v155 offset:19456
	ds_read_b128 v[200:203], v155 offset:20480
	ds_read_b128 v[204:207], v155 offset:21504
	ds_read_b128 v[208:211], v155 offset:22528
	ds_read_b128 v[212:215], v155 offset:23552
	global_load_lds_dwordx4 v[148:149], off
	s_add_i32 m0, s16, 0x2000
	s_add_u32 s16, s20, 0xb0000
	v_lshl_add_u64 v[218:219], s[20:21], 0, v[134:135]
	s_addc_u32 s17, s21, 0
	s_add_i32 s45, s36, s24
	global_load_lds_dwordx4 v[218:219], off
	v_lshl_add_u64 v[220:221], s[16:17], 0, v[130:131]
	s_mov_b32 m0, s45
	v_lshl_add_u64 v[222:223], s[22:23], 0, v[132:133]
	global_load_lds_dwordx4 v[220:221], off
	v_lshl_add_u64 v[220:221], s[16:17], 0, v[134:135]
	s_add_i32 m0, s45, 0x2000
	s_nop 0
	global_load_lds_dwordx4 v[220:221], off
	v_lshl_add_u64 v[220:221], s[22:23], 0, v[128:129]
	s_mov_b32 m0, s25
	s_nop 0
	global_load_lds_dwordx4 v[220:221], off
	s_mov_b32 m0, s26
	s_nop 0
	global_load_lds_dwordx4 v[222:223], off
	s_waitcnt vmcnt(8)
	s_waitcnt lgkmcnt(0)
	s_barrier
; #define PG8_STAGE(bufoff, gbase, voff) do { _Pragma("unroll") for (int _i = 0; _i < 2; ++_i) \
;         __builtin_amdgcn_global_load_lds((const unsigned*)((const char*)(gbase) + (voff)[_i]), (PG8_LAS unsigned*)(lds + (bufoff) + ldsw + _i * 8192), 16, 0, 0); } while (0)
; #define PG8_LDA(dst, b, h) do { _Pragma("unroll") for (int m = 0; m < 4; ++m) _Pragma("unroll") for (int k = 0; k < 2; ++k) dst[m][k] = *(const PG8_LAS bf16x8*)(lds + PG8_SA(b, h) + aoff + m * 2048 + k * 1024); } while (0)
; #define PG8_LDB(dst, b, h) do { _Pragma("unroll") for (int n = 0; n < 2; ++n) _Pragma("unroll") for (int k = 0; k < 2; ++k) dst[n][k] = *(const PG8_LAS bf16x8*)(lds + PG8_SB(b, h) + boff + n * 2048 + k * 1024); } while (0)
; #define PG8_MMA(ai, bj, At, Bt) do { __builtin_amdgcn_s_setprio(1); _Pragma("unroll") for (int m = 0; m < 4; ++m) _Pragma("unroll") for (int n = 0; n < 2; ++n) _Pragma("unroll") for (int k = 0; k < 2; ++k) \
;         acc[ai][bj][m][n] = __builtin_amdgcn_mfma_f32_16x16x32_bf16(Bt[n][k], At[m][k], acc[ai][bj][m][n], 0, 0, 0); __builtin_amdgcn_s_setprio(0); } while (0)
; #define PG8_WAIT_V(n) asm volatile("s_waitcnt vmcnt(" #n ")" ::: "memory")
; #define PG8_WAIT_L(n) asm volatile("s_waitcnt lgkmcnt(" #n ")" ::: "memory")
; #define PG8_BAR __builtin_amdgcn_s_barrier()
; #define PG8_SCHED __builtin_amdgcn_sched_barrier(0)
; template <class Epi, class Sched, bool ALIGN_EPI = false, bool SP2 = false>
; __device__ __forceinline__ void gemm_phase(PG8_LAS unsigned char* lds, const Gemm g, const Sched& S, const Epi& E, int wave0) {
;     ...
;             PG8_WAIT_V(8); PG8_WAIT_L(0); PG8_BAR; if (!cur.half) { PG8_MMA(1, 0, At, B0); PG8_MMA(1, 1, At, B1); } PG8_BAR; PG8_SCHED;
;             PG8_LDB(B0, 1, 0); PG8_LDB(B1, 1, 1); PG8_SCHED; PG8_LDA(At, 1, 0); PG8_STAGE(PG8_SA(0, 1), a2 + hstep, voffA);
;             PG8_WAIT_V(8); PG8_WAIT_L(0); PG8_BAR; PG8_MMA(0, 0, At, B0); PG8_MMA(0, 1, At, B1); PG8_BAR; PG8_SCHED;
	s_setprio 1
	s_waitcnt lgkmcnt(0)
	v_mfma_f32_16x16x32_bf16 v[60:63], v[144:147], v[184:187], v[60:63]
	v_mfma_f32_16x16x32_bf16 v[56:59], v[160:163], v[184:187], v[56:59]
	v_mfma_f32_16x16x32_bf16 v[52:55], v[144:147], v[192:195], v[52:55]
	v_mfma_f32_16x16x32_bf16 v[48:51], v[160:163], v[192:195], v[48:51]
	v_mfma_f32_16x16x32_bf16 v[28:31], v[144:147], v[200:203], v[28:31]
	v_mfma_f32_16x16x32_bf16 v[24:27], v[160:163], v[200:203], v[24:27]
	v_mfma_f32_16x16x32_bf16 v[20:23], v[144:147], v[208:211], v[20:23]
	v_mfma_f32_16x16x32_bf16 v[16:19], v[160:163], v[208:211], v[16:19]
	v_mfma_f32_16x16x32_bf16 v[60:63], v[156:159], v[188:191], v[60:63]
	v_mfma_f32_16x16x32_bf16 v[56:59], v[164:167], v[188:191], v[56:59]
	v_mfma_f32_16x16x32_bf16 v[52:55], v[156:159], v[196:199], v[52:55]
	v_mfma_f32_16x16x32_bf16 v[48:51], v[164:167], v[196:199], v[48:51]
	v_mfma_f32_16x16x32_bf16 v[28:31], v[156:159], v[204:207], v[28:31]
	v_mfma_f32_16x16x32_bf16 v[24:27], v[164:167], v[204:207], v[24:27]
	v_mfma_f32_16x16x32_bf16 v[20:23], v[156:159], v[212:215], v[20:23]
	v_mfma_f32_16x16x32_bf16 v[16:19], v[164:167], v[212:215], v[16:19]
	v_mfma_f32_16x16x32_bf16 v[44:47], v[168:171], v[184:187], v[44:47]
	v_mfma_f32_16x16x32_bf16 v[40:43], v[176:179], v[184:187], v[40:43]
	v_mfma_f32_16x16x32_bf16 v[36:39], v[168:171], v[192:195], v[36:39]
	v_mfma_f32_16x16x32_bf16 v[32:35], v[176:179], v[192:195], v[32:35]
	v_mfma_f32_16x16x32_bf16 v[12:15], v[168:171], v[200:203], v[12:15]
	v_mfma_f32_16x16x32_bf16 v[8:11], v[176:179], v[200:203], v[8:11]
	v_mfma_f32_16x16x32_bf16 v[4:7], v[168:171], v[208:211], v[4:7]
	v_mfma_f32_16x16x32_bf16 v[0:3], v[176:179], v[208:211], v[0:3]
	v_mfma_f32_16x16x32_bf16 v[44:47], v[172:175], v[188:191], v[44:47]
	v_mfma_f32_16x16x32_bf16 v[40:43], v[180:183], v[188:191], v[40:43]
	v_mfma_f32_16x16x32_bf16 v[36:39], v[172:175], v[196:199], v[36:39]
	v_mfma_f32_16x16x32_bf16 v[32:35], v[180:183], v[196:199], v[32:35]
	v_mfma_f32_16x16x32_bf16 v[12:15], v[172:175], v[204:207], v[12:15]
	v_mfma_f32_16x16x32_bf16 v[8:11], v[180:183], v[204:207], v[8:11]
	v_mfma_f32_16x16x32_bf16 v[4:7], v[172:175], v[212:215], v[4:7]
	v_mfma_f32_16x16x32_bf16 v[0:3], v[180:183], v[212:215], v[0:3]
	s_setprio 0
	s_barrier
	s_add_i32 s45, 0, 0x18000
	s_add_i32 s46, 0, 0x1c000
	v_add_u32_e32 v164, s45, v152
	v_add_u32_e32 v180, s46, v152
	ds_read_b128 v[144:147], v164
	ds_read_b128 v[156:159], v164 offset:1024
	ds_read_b128 v[160:163], v164 offset:2048
	ds_read_b128 v[164:167], v164 offset:3072
	ds_read_b128 v[168:171], v180
	ds_read_b128 v[172:175], v180 offset:1024
	ds_read_b128 v[176:179], v180 offset:2048
	ds_read_b128 v[180:183], v180 offset:3072
	s_add_u32 s16, s22, 0xb0000
	s_addc_u32 s17, s23, 0
	s_mov_b32 m0, s27
	v_lshl_add_u64 v[224:225], s[16:17], 0, v[128:129]
	ds_read_b128 v[184:187], v155 offset:32768
	ds_read_b128 v[188:191], v155 offset:33792
	ds_read_b128 v[192:195], v155 offset:34816
	ds_read_b128 v[196:199], v155 offset:35840
	ds_read_b128 v[200:203], v155 offset:36864
	ds_read_b128 v[204:207], v155 offset:37888
	ds_read_b128 v[208:211], v155 offset:38912
	ds_read_b128 v[212:215], v155 offset:39936
	global_load_lds_dwordx4 v[224:225], off
	v_lshl_add_u64 v[224:225], s[16:17], 0, v[132:133]
	s_mov_b32 m0, s28
	s_nop 0
	global_load_lds_dwordx4 v[224:225], off
	s_waitcnt vmcnt(8)
	s_waitcnt lgkmcnt(0)
	s_barrier
	s_setprio 1
	s_waitcnt lgkmcnt(0)
	v_mfma_f32_16x16x32_bf16 v[124:127], v[144:147], v[184:187], v[124:127]
	v_mfma_f32_16x16x32_bf16 v[120:123], v[160:163], v[184:187], v[120:123]
	v_mfma_f32_16x16x32_bf16 v[116:119], v[144:147], v[192:195], v[116:119]
	v_mfma_f32_16x16x32_bf16 v[108:111], v[160:163], v[192:195], v[108:111]
	v_mfma_f32_16x16x32_bf16 v[92:95], v[144:147], v[200:203], v[92:95]
	v_mfma_f32_16x16x32_bf16 v[88:91], v[160:163], v[200:203], v[88:91]
	v_mfma_f32_16x16x32_bf16 v[84:87], v[144:147], v[208:211], v[84:87]
	v_mfma_f32_16x16x32_bf16 v[80:83], v[160:163], v[208:211], v[80:83]
	v_mfma_f32_16x16x32_bf16 v[124:127], v[156:159], v[188:191], v[124:127]
	v_mfma_f32_16x16x32_bf16 v[120:123], v[164:167], v[188:191], v[120:123]
	v_mfma_f32_16x16x32_bf16 v[116:119], v[156:159], v[196:199], v[116:119]
	v_mfma_f32_16x16x32_bf16 v[108:111], v[164:167], v[196:199], v[108:111]
	v_mfma_f32_16x16x32_bf16 v[92:95], v[156:159], v[204:207], v[92:95]
	v_mfma_f32_16x16x32_bf16 v[88:91], v[164:167], v[204:207], v[88:91]
	v_mfma_f32_16x16x32_bf16 v[84:87], v[156:159], v[212:215], v[84:87]
	v_mfma_f32_16x16x32_bf16 v[80:83], v[164:167], v[212:215], v[80:83]
	v_mfma_f32_16x16x32_bf16 v[112:115], v[168:171], v[184:187], v[112:115]
	v_mfma_f32_16x16x32_bf16 v[104:107], v[176:179], v[184:187], v[104:107]
	v_mfma_f32_16x16x32_bf16 v[100:103], v[168:171], v[192:195], v[100:103]
	v_mfma_f32_16x16x32_bf16 v[96:99], v[176:179], v[192:195], v[96:99]
	v_mfma_f32_16x16x32_bf16 v[76:79], v[168:171], v[200:203], v[76:79]
	v_mfma_f32_16x16x32_bf16 v[72:75], v[176:179], v[200:203], v[72:75]
	v_mfma_f32_16x16x32_bf16 v[68:71], v[168:171], v[208:211], v[68:71]
	v_mfma_f32_16x16x32_bf16 v[64:67], v[176:179], v[208:211], v[64:67]
	v_mfma_f32_16x16x32_bf16 v[112:115], v[172:175], v[188:191], v[112:115]
	v_mfma_f32_16x16x32_bf16 v[104:107], v[180:183], v[188:191], v[104:107]
	v_mfma_f32_16x16x32_bf16 v[100:103], v[172:175], v[196:199], v[100:103]
	v_mfma_f32_16x16x32_bf16 v[96:99], v[180:183], v[196:199], v[96:99]
	v_mfma_f32_16x16x32_bf16 v[76:79], v[172:175], v[204:207], v[76:79]
	v_mfma_f32_16x16x32_bf16 v[72:75], v[180:183], v[204:207], v[72:75]
	v_mfma_f32_16x16x32_bf16 v[68:71], v[172:175], v[212:215], v[68:71]
	v_mfma_f32_16x16x32_bf16 v[64:67], v[180:183], v[212:215], v[64:67]
	s_setprio 0
	s_barrier
; #define PG8_STAGE(bufoff, gbase, voff) do { _Pragma("unroll") for (int _i = 0; _i < 2; ++_i) \
;         __builtin_amdgcn_global_load_lds((const unsigned*)((const char*)(gbase) + (voff)[_i]), (PG8_LAS unsigned*)(lds + (bufoff) + ldsw + _i * 8192), 16, 0, 0); } while (0)
; #define PG8_LDA(dst, b, h) do { _Pragma("unroll") for (int m = 0; m < 4; ++m) _Pragma("unroll") for (int k = 0; k < 2; ++k) dst[m][k] = *(const PG8_LAS bf16x8*)(lds + PG8_SA(b, h) + aoff + m * 2048 + k * 1024); } while (0)
; #define PG8_MMA(ai, bj, At, Bt) do { __builtin_amdgcn_s_setprio(1); _Pragma("unroll") for (int m = 0; m < 4; ++m) _Pragma("unroll") for (int n = 0; n < 2; ++n) _Pragma("unroll") for (int k = 0; k < 2; ++k) \
;         acc[ai][bj][m][n] = __builtin_amdgcn_mfma_f32_16x16x32_bf16(Bt[n][k], At[m][k], acc[ai][bj][m][n], 0, 0, 0); __builtin_amdgcn_s_setprio(0); } while (0)
; #define PG8_WAIT_V(n) asm volatile("s_waitcnt vmcnt(" #n ")" ::: "memory")
; #define PG8_WAIT_L(n) asm volatile("s_waitcnt lgkmcnt(" #n ")" ::: "memory")
; #define PG8_BAR __builtin_amdgcn_s_barrier()
; #define PG8_SCHED __builtin_amdgcn_sched_barrier(0)
; template <class Epi, class Sched, bool ALIGN_EPI = false, bool SP2 = false>
; __device__ __forceinline__ void gemm_phase(PG8_LAS unsigned char* lds, const Gemm g, const Sched& S, const Epi& E, int wave0) {
;     ...
;         for (int t = 0; t < nt; t += 2) {
;             const bool last = (t == nt - 2);
;             const char* a1 = cA + (size_t)(t + 1) * kstep;
;             const char* a2 = last ? nA : cA + (size_t)(t + 2) * kstep; const char* b2 = last ? nB : cB + (size_t)(t + 2) * kstep;
;     ...
;             PG8_LDA(At, 1, 1); PG8_STAGE(PG8_SB(1, 0), b3, voffB); PG8_STAGE(PG8_SB(1, 1), b3 + hstep, voffB); PG8_STAGE(PG8_SA(1, 0), a3, voffA);
;             PG8_WAIT_V(8); PG8_WAIT_L(0); PG8_BAR; if (!cur.half) { PG8_MMA(1, 0, At, B0); PG8_MMA(1, 1, At, B1); } PG8_BAR; PG8_SCHED;
	s_add_i32 s16, s45, s24
	v_lshl_add_u64 v[148:149], v[148:149], 0, s[8:9]
	s_mov_b32 m0, s16
	ds_read_b128 v[184:187], v155 offset:49152
	ds_read_b128 v[188:191], v155 offset:50176
	ds_read_b128 v[192:195], v155 offset:51200
	ds_read_b128 v[196:199], v155 offset:52224
	ds_read_b128 v[200:203], v155 offset:53248
	ds_read_b128 v[204:207], v155 offset:54272
	ds_read_b128 v[208:211], v155 offset:55296
	ds_read_b128 v[212:215], v155 offset:56320
	global_load_lds_dwordx4 v[148:149], off
	s_add_i32 m0, s16, 0x2000
	s_add_u32 s16, s20, 0xb0080
	v_lshl_add_u64 v[148:149], v[218:219], 0, s[8:9]
	s_addc_u32 s17, s21, 0
	s_add_i32 s20, s46, s24
	global_load_lds_dwordx4 v[148:149], off
	v_lshl_add_u64 v[148:149], s[16:17], 0, v[130:131]
	s_mov_b32 m0, s20
	s_nop 0
	global_load_lds_dwordx4 v[148:149], off
	v_lshl_add_u64 v[148:149], s[16:17], 0, v[134:135]
	s_add_i32 m0, s20, 0x2000
	s_nop 0
	global_load_lds_dwordx4 v[148:149], off
	v_lshl_add_u64 v[148:149], v[220:221], 0, s[8:9]
	s_mov_b32 m0, s33
	s_nop 0
	global_load_lds_dwordx4 v[148:149], off
	v_lshl_add_u64 v[148:149], v[222:223], 0, s[8:9]
	s_mov_b32 m0, s34
	s_nop 0
	global_load_lds_dwordx4 v[148:149], off
	s_waitcnt vmcnt(8)
	s_waitcnt lgkmcnt(0)
	s_barrier
	s_setprio 1
	s_waitcnt lgkmcnt(0)
	v_mfma_f32_16x16x32_bf16 v[60:63], v[144:147], v[184:187], v[60:63]
	v_mfma_f32_16x16x32_bf16 v[56:59], v[160:163], v[184:187], v[56:59]
	v_mfma_f32_16x16x32_bf16 v[52:55], v[144:147], v[192:195], v[52:55]
	v_mfma_f32_16x16x32_bf16 v[48:51], v[160:163], v[192:195], v[48:51]
	v_mfma_f32_16x16x32_bf16 v[28:31], v[144:147], v[200:203], v[28:31]
	v_mfma_f32_16x16x32_bf16 v[24:27], v[160:163], v[200:203], v[24:27]
	v_mfma_f32_16x16x32_bf16 v[20:23], v[144:147], v[208:211], v[20:23]
	v_mfma_f32_16x16x32_bf16 v[16:19], v[160:163], v[208:211], v[16:19]
	v_mfma_f32_16x16x32_bf16 v[60:63], v[156:159], v[188:191], v[60:63]
	v_mfma_f32_16x16x32_bf16 v[56:59], v[164:167], v[188:191], v[56:59]
	v_mfma_f32_16x16x32_bf16 v[52:55], v[156:159], v[196:199], v[52:55]
	v_mfma_f32_16x16x32_bf16 v[48:51], v[164:167], v[196:199], v[48:51]
	v_mfma_f32_16x16x32_bf16 v[28:31], v[156:159], v[204:207], v[28:31]
	v_mfma_f32_16x16x32_bf16 v[24:27], v[164:167], v[204:207], v[24:27]
	v_mfma_f32_16x16x32_bf16 v[20:23], v[156:159], v[212:215], v[20:23]
	v_mfma_f32_16x16x32_bf16 v[16:19], v[164:167], v[212:215], v[16:19]
	v_mfma_f32_16x16x32_bf16 v[44:47], v[168:171], v[184:187], v[44:47]
	v_mfma_f32_16x16x32_bf16 v[40:43], v[176:179], v[184:187], v[40:43]
	v_mfma_f32_16x16x32_bf16 v[36:39], v[168:171], v[192:195], v[36:39]
	v_mfma_f32_16x16x32_bf16 v[32:35], v[176:179], v[192:195], v[32:35]
	v_mfma_f32_16x16x32_bf16 v[12:15], v[168:171], v[200:203], v[12:15]
	v_mfma_f32_16x16x32_bf16 v[8:11], v[176:179], v[200:203], v[8:11]
	v_mfma_f32_16x16x32_bf16 v[4:7], v[168:171], v[208:211], v[4:7]
	v_mfma_f32_16x16x32_bf16 v[0:3], v[176:179], v[208:211], v[0:3]
	v_mfma_f32_16x16x32_bf16 v[44:47], v[172:175], v[188:191], v[44:47]
	v_mfma_f32_16x16x32_bf16 v[40:43], v[180:183], v[188:191], v[40:43]
	v_mfma_f32_16x16x32_bf16 v[36:39], v[172:175], v[196:199], v[36:39]
	v_mfma_f32_16x16x32_bf16 v[32:35], v[180:183], v[196:199], v[32:35]
	v_mfma_f32_16x16x32_bf16 v[12:15], v[172:175], v[204:207], v[12:15]
	v_mfma_f32_16x16x32_bf16 v[8:11], v[180:183], v[204:207], v[8:11]
	v_mfma_f32_16x16x32_bf16 v[4:7], v[172:175], v[212:215], v[4:7]
	v_mfma_f32_16x16x32_bf16 v[0:3], v[180:183], v[212:215], v[0:3]
	s_setprio 0
	s_barrier
	s_add_i32 s44, s44, 2
	s_add_u32 s42, s42, 0x100
	s_addc_u32 s43, s43, 0
	s_cmp_gt_u32 s44, 41
	s_mov_b64 s[16:17], s[18:19]
	s_cbranch_scc0 .LBB0_3229
	s_nop 0
	s_nop 0
	s_nop 0
	s_nop 0
	s_nop 0
	s_nop 0
	s_nop 0
	s_nop 0
	s_and_b64 vcc, exec, s[10:11]
	s_cbranch_vccz .LBB0_3232
	s_barrier
